# LDS-DMA loads use SGPR base + 32-bit VGPR offset (150 sites), v_lshl_add_u64 address adds removed
# speedup vs baseline: 1.0103x; 1.0017x over previous
.LBB0_388:
	s_add_u32 s26, s6, 0x40000
	s_addc_u32 s27, s7, 0
	s_add_u32 s28, s6, 0x4700000
	s_addc_u32 s29, s7, 0
	s_add_u32 s30, s6, 0x7700000
	s_addc_u32 s31, s7, 0
	s_add_u32 s34, s6, 0x7b00000
	s_addc_u32 s35, s7, 0
	s_add_u32 s38, s6, 0x6700000
	s_addc_u32 s39, s7, 0
	s_add_u32 s40, s6, 0xaf00000
	s_addc_u32 s41, s7, 0
	s_add_u32 s42, s6, 0xbf00000
	s_addc_u32 s43, s7, 0
	s_add_u32 s44, s6, 0x7f00000
	s_addc_u32 s45, s7, 0
	s_add_i32 m0, s63, 0x18000
	v_lshl_add_u64 v[6:7], v[6:7], 0, s[12:13]
	s_lshl_b32 s9, s52, 13
	s_lshl_b32 s53, s69, 12
	s_waitcnt vmcnt(2)
	s_barrier
	global_load_lds_dwordx4 v[6:7], off
	v_lshl_add_u64 v[4:5], v[4:5], 0, s[12:13]
	s_add_i32 m0, s63, 0x1a000
	s_add_i32 s78, s63, 0x8000
	s_add_i32 s79, s63, 0xa000
	global_load_lds_dwordx4 v[4:5], off
	v_lshl_add_u64 v[0:1], v[0:1], 0, s[12:13]
	s_mov_b32 m0, s78
	s_add_u32 s54, s48, 0x40080
	global_load_lds_dwordx4 v[0:1], off
	v_lshl_add_u64 v[0:1], v[2:3], 0, s[12:13]
	s_mov_b32 m0, s79
	s_addc_u32 s55, s49, 0
	global_load_lds_dwordx4 v[0:1], off
	s_add_i32 m0, s63, 0x1c000
	s_nop 0
	global_load_lds_dwordx4 v136, s[54:55]
	s_add_i32 m0, s63, 0x1e000
	v_and_b32_e32 v2, 15, v8
	global_load_lds_dwordx4 v140, s[54:55]
	v_or_b32_e32 v167, s51, v2
	v_lshlrev_b32_e32 v0, 6, v167
	v_and_b32_e32 v1, 48, v8
	s_movk_i32 s51, 0x3c0
	v_lshlrev_b32_e32 v3, 2, v167
	v_and_or_b32 v0, v0, s51, v1
	v_and_b32_e32 v3, 32, v3
	v_lshrrev_b32_e32 v165, 4, v9
	v_bitop3_b32 v3, v0, s9, v3 bitop3:0xde
	v_lshl_or_b32 v0, v2, 6, v1
	v_lshlrev_b32_e32 v1, 2, v8
	v_and_b32_e32 v1, 32, v1
	v_lshlrev_b32_e32 v128, 5, v165
	v_bitop3_b32 v173, s53, v0, v1 bitop3:0xf6
	v_lshl_add_u64 v[0:1], s[6:7], 0, v[128:129]
	s_mov_b64 s[6:7], 0x80000
	v_lshl_add_u64 v[144:145], v[0:1], 0, s[6:7]
	v_lshlrev_b32_e32 v0, 14, v10
	v_and_b32_e32 v0, 0xffff8000, v0
	v_lshl_add_u32 v0, v11, 11, v0
	v_and_b32_e32 v1, 1, v10
	v_lshl_or_b32 v0, v1, 6, v0
	s_cmpk_lt_u32 s50, 0x100
	v_lshl_add_u32 v148, v12, 1, v0
	v_lshlrev_b32_e32 v0, 14, v13
	s_cselect_b64 s[50:51], -1, 0
	s_lshl_b32 s9, s52, 11
	v_and_b32_e32 v0, 0xffff8000, v0
	s_waitcnt vmcnt(6)
	s_add_i32 s80, s9, 0
	v_lshl_add_u32 v0, v14, 11, v0
	v_and_b32_e32 v1, 1, v13
	v_lshlrev_b32_e32 v142, 3, v165
	s_add_i32 s80, s80, 0x21000
	v_lshl_or_b32 v0, v1, 6, v0
	s_ashr_i32 s81, s68, 31
	v_lshl_add_u64 v[146:147], s[26:27], 0, v[128:129]
	v_lshl_add_u32 v175, v2, 4, s80
	v_mov_b32_e32 v149, v129
	v_lshl_add_u32 v150, v15, 1, v0
	v_mov_b32_e32 v151, v129
	s_mov_b32 s84, 0
	v_add_u32_e32 v200, 0, v3
	v_lshlrev_b32_e32 v152, 2, v142
	s_barrier
	s_branch .LBB0_391

.LBB0_398:
	s_add_u32 s48, s10, 0xfffc0080
	s_addc_u32 s49, s11, -1
	s_add_i32 s83, 0, 0x10000
	s_cmp_eq_u32 s67, 12
	s_cselect_b32 s61, s9, s49
	s_cselect_b32 s60, s55, s48
	v_add_u32_e32 v128, s83, v173
	s_cselect_b32 s49, s53, s66
	s_cselect_b32 s48, s64, s65
	s_add_i32 s85, 0, 0x14000
	ds_read_b128 v[168:171], v128
	ds_read_b128 v[176:179], v128 offset:1024
	ds_read_b128 v[180:183], v128 offset:2048
	ds_read_b128 v[184:187], v128 offset:3072
	v_add_u32_e32 v128, s85, v173
	ds_read_b128 v[188:191], v128
	ds_read_b128 v[192:195], v128 offset:1024
	ds_read_b128 v[196:199], v128 offset:2048
	ds_read_b128 v[202:205], v128 offset:3072
	s_add_i32 m0, s63, 0xc000
	ds_read_b128 v[206:209], v200
	ds_read_b128 v[210:213], v200 offset:1024
	ds_read_b128 v[218:221], v200 offset:2048
	ds_read_b128 v[222:225], v200 offset:3072
	ds_read_b128 v[226:229], v200 offset:4096
	ds_read_b128 v[234:237], v200 offset:5120
	ds_read_b128 v[238:241], v200 offset:6144
	ds_read_b128 v[242:245], v200 offset:7168
	global_load_lds_dwordx4 v148, s[10:11]
	s_add_i32 m0, s63, 0xe000
	s_nop 0
	global_load_lds_dwordx4 v150, s[10:11]
	s_waitcnt vmcnt(8)
	s_waitcnt lgkmcnt(0)
	s_barrier
	s_setprio 1
	s_waitcnt lgkmcnt(0)
	v_mfma_f32_16x16x32_bf16 v[124:127], v[168:171], v[206:209], v[124:127]
	v_mfma_f32_16x16x32_bf16 v[120:123], v[180:183], v[206:209], v[120:123]
	v_mfma_f32_16x16x32_bf16 v[108:111], v[168:171], v[218:221], v[108:111]
	v_mfma_f32_16x16x32_bf16 v[104:107], v[180:183], v[218:221], v[104:107]
	v_mfma_f32_16x16x32_bf16 v[92:95], v[168:171], v[226:229], v[92:95]
	v_mfma_f32_16x16x32_bf16 v[88:91], v[180:183], v[226:229], v[88:91]
	v_mfma_f32_16x16x32_bf16 v[76:79], v[168:171], v[238:241], v[76:79]
	v_mfma_f32_16x16x32_bf16 v[72:75], v[180:183], v[238:241], v[72:75]
	v_mfma_f32_16x16x32_bf16 v[124:127], v[176:179], v[210:213], v[124:127]
	v_mfma_f32_16x16x32_bf16 v[120:123], v[184:187], v[210:213], v[120:123]
	v_mfma_f32_16x16x32_bf16 v[108:111], v[176:179], v[222:225], v[108:111]
	v_mfma_f32_16x16x32_bf16 v[104:107], v[184:187], v[222:225], v[104:107]
	v_mfma_f32_16x16x32_bf16 v[92:95], v[176:179], v[234:237], v[92:95]
	v_mfma_f32_16x16x32_bf16 v[88:91], v[184:187], v[234:237], v[88:91]
	v_mfma_f32_16x16x32_bf16 v[76:79], v[176:179], v[242:245], v[76:79]
	v_mfma_f32_16x16x32_bf16 v[72:75], v[184:187], v[242:245], v[72:75]
	s_setprio 0
	s_setprio 1
	v_mfma_f32_16x16x32_bf16 v[116:119], v[188:191], v[206:209], v[116:119]
	v_mfma_f32_16x16x32_bf16 v[112:115], v[196:199], v[206:209], v[112:115]
	v_mfma_f32_16x16x32_bf16 v[100:103], v[188:191], v[218:221], v[100:103]
	v_mfma_f32_16x16x32_bf16 v[96:99], v[196:199], v[218:221], v[96:99]
	v_mfma_f32_16x16x32_bf16 v[84:87], v[188:191], v[226:229], v[84:87]
	v_mfma_f32_16x16x32_bf16 v[80:83], v[196:199], v[226:229], v[80:83]
	v_mfma_f32_16x16x32_bf16 v[68:71], v[188:191], v[238:241], v[68:71]
	v_mfma_f32_16x16x32_bf16 v[64:67], v[196:199], v[238:241], v[64:67]
	v_mfma_f32_16x16x32_bf16 v[116:119], v[192:195], v[210:213], v[116:119]
	v_mfma_f32_16x16x32_bf16 v[112:115], v[202:205], v[210:213], v[112:115]
	v_mfma_f32_16x16x32_bf16 v[100:103], v[192:195], v[222:225], v[100:103]
	v_mfma_f32_16x16x32_bf16 v[96:99], v[202:205], v[222:225], v[96:99]
	v_mfma_f32_16x16x32_bf16 v[84:87], v[192:195], v[234:237], v[84:87]
	v_mfma_f32_16x16x32_bf16 v[80:83], v[202:205], v[234:237], v[80:83]
	v_mfma_f32_16x16x32_bf16 v[68:71], v[192:195], v[242:245], v[68:71]
	v_mfma_f32_16x16x32_bf16 v[64:67], v[202:205], v[242:245], v[64:67]
	s_setprio 0
	s_barrier
	s_add_i32 s83, s83, s74
	v_lshl_add_u64 v[156:157], s[48:49], 0, v[136:137]
	s_mov_b32 m0, s83
	ds_read_b128 v[206:209], v200 offset:16384
	ds_read_b128 v[210:213], v200 offset:17408
	ds_read_b128 v[218:221], v200 offset:18432
	ds_read_b128 v[222:225], v200 offset:19456
	ds_read_b128 v[226:229], v200 offset:20480
	ds_read_b128 v[234:237], v200 offset:21504
	ds_read_b128 v[238:241], v200 offset:22528
	ds_read_b128 v[242:245], v200 offset:23552
	global_load_lds_dwordx4 v[156:157], off
	s_add_i32 m0, s83, 0x2000
	s_add_u32 s86, s48, 0x40000
	v_lshl_add_u64 v[230:231], s[48:49], 0, v[140:141]
	s_addc_u32 s87, s49, 0
	s_add_i32 s83, s85, s74
	global_load_lds_dwordx4 v[230:231], off
	s_mov_b32 m0, s83
	v_lshl_add_u64 v[248:249], s[60:61], 0, v[138:139]
	global_load_lds_dwordx4 v136, s[86:87]
	s_add_i32 m0, s83, 0x2000
	s_nop 0
	global_load_lds_dwordx4 v140, s[86:87]
	v_lshl_add_u64 v[246:247], s[60:61], 0, v[134:135]
	s_mov_b32 m0, s63
	s_nop 0
	global_load_lds_dwordx4 v[246:247], off
	s_mov_b32 m0, s75
	s_nop 0
	global_load_lds_dwordx4 v[248:249], off
	s_waitcnt vmcnt(8)
	s_waitcnt lgkmcnt(0)
	s_barrier
	s_setprio 1
	s_waitcnt lgkmcnt(0)
	v_mfma_f32_16x16x32_bf16 v[60:63], v[168:171], v[206:209], v[60:63]
	v_mfma_f32_16x16x32_bf16 v[56:59], v[180:183], v[206:209], v[56:59]
	v_mfma_f32_16x16x32_bf16 v[44:47], v[168:171], v[218:221], v[44:47]
	v_mfma_f32_16x16x32_bf16 v[40:43], v[180:183], v[218:221], v[40:43]
	v_mfma_f32_16x16x32_bf16 v[28:31], v[168:171], v[226:229], v[28:31]
	v_mfma_f32_16x16x32_bf16 v[24:27], v[180:183], v[226:229], v[24:27]
	v_mfma_f32_16x16x32_bf16 v[12:15], v[168:171], v[238:241], v[12:15]
	v_mfma_f32_16x16x32_bf16 v[8:11], v[180:183], v[238:241], v[8:11]
	v_mfma_f32_16x16x32_bf16 v[60:63], v[176:179], v[210:213], v[60:63]
	v_mfma_f32_16x16x32_bf16 v[56:59], v[184:187], v[210:213], v[56:59]
	v_mfma_f32_16x16x32_bf16 v[44:47], v[176:179], v[222:225], v[44:47]
	v_mfma_f32_16x16x32_bf16 v[40:43], v[184:187], v[222:225], v[40:43]
	v_mfma_f32_16x16x32_bf16 v[28:31], v[176:179], v[234:237], v[28:31]
	v_mfma_f32_16x16x32_bf16 v[24:27], v[184:187], v[234:237], v[24:27]
	v_mfma_f32_16x16x32_bf16 v[12:15], v[176:179], v[242:245], v[12:15]
	v_mfma_f32_16x16x32_bf16 v[8:11], v[184:187], v[242:245], v[8:11]
	s_setprio 0
	s_setprio 1
	v_mfma_f32_16x16x32_bf16 v[52:55], v[188:191], v[206:209], v[52:55]
	v_mfma_f32_16x16x32_bf16 v[48:51], v[196:199], v[206:209], v[48:51]
	v_mfma_f32_16x16x32_bf16 v[36:39], v[188:191], v[218:221], v[36:39]
	v_mfma_f32_16x16x32_bf16 v[32:35], v[196:199], v[218:221], v[32:35]
	v_mfma_f32_16x16x32_bf16 v[20:23], v[188:191], v[226:229], v[20:23]
	v_mfma_f32_16x16x32_bf16 v[16:19], v[196:199], v[226:229], v[16:19]
	v_mfma_f32_16x16x32_bf16 v[4:7], v[188:191], v[238:241], v[4:7]
	v_mfma_f32_16x16x32_bf16 v[0:3], v[196:199], v[238:241], v[0:3]
	v_mfma_f32_16x16x32_bf16 v[52:55], v[192:195], v[210:213], v[52:55]
	v_mfma_f32_16x16x32_bf16 v[48:51], v[202:205], v[210:213], v[48:51]
	v_mfma_f32_16x16x32_bf16 v[36:39], v[192:195], v[222:225], v[36:39]
	v_mfma_f32_16x16x32_bf16 v[32:35], v[202:205], v[222:225], v[32:35]
	v_mfma_f32_16x16x32_bf16 v[20:23], v[192:195], v[234:237], v[20:23]
	v_mfma_f32_16x16x32_bf16 v[16:19], v[202:205], v[234:237], v[16:19]
	v_mfma_f32_16x16x32_bf16 v[4:7], v[192:195], v[242:245], v[4:7]
	v_mfma_f32_16x16x32_bf16 v[0:3], v[202:205], v[242:245], v[0:3]
	s_setprio 0
	s_barrier
	v_add_u32_e32 v128, s0, v173
	s_add_i32 s83, 0, 0x1c000
	ds_read_b128 v[168:171], v128
	ds_read_b128 v[176:179], v128 offset:1024
	ds_read_b128 v[180:183], v128 offset:2048
	ds_read_b128 v[184:187], v128 offset:3072
	v_add_u32_e32 v128, s83, v173
	ds_read_b128 v[188:191], v128
	ds_read_b128 v[192:195], v128 offset:1024
	ds_read_b128 v[196:199], v128 offset:2048
	ds_read_b128 v[202:205], v128 offset:3072
	s_add_u32 s60, s60, 0x40000
	s_addc_u32 s61, s61, 0
	s_mov_b32 m0, s76
	ds_read_b128 v[206:209], v200 offset:32768
	ds_read_b128 v[210:213], v200 offset:33792
	ds_read_b128 v[218:221], v200 offset:34816
	ds_read_b128 v[222:225], v200 offset:35840
	ds_read_b128 v[226:229], v200 offset:36864
	ds_read_b128 v[234:237], v200 offset:37888
	ds_read_b128 v[238:241], v200 offset:38912
	ds_read_b128 v[242:245], v200 offset:39936
	global_load_lds_dwordx4 v134, s[60:61]
	v_lshl_add_u64 v[250:251], s[60:61], 0, v[138:139]
	s_mov_b32 m0, s77
	s_nop 0
	global_load_lds_dwordx4 v[250:251], off
	s_waitcnt vmcnt(8)
	s_waitcnt lgkmcnt(0)
	s_barrier
	s_setprio 1
	s_waitcnt lgkmcnt(0)
	v_mfma_f32_16x16x32_bf16 v[124:127], v[168:171], v[206:209], v[124:127]
	v_mfma_f32_16x16x32_bf16 v[120:123], v[180:183], v[206:209], v[120:123]
	v_mfma_f32_16x16x32_bf16 v[108:111], v[168:171], v[218:221], v[108:111]
	v_mfma_f32_16x16x32_bf16 v[104:107], v[180:183], v[218:221], v[104:107]
	v_mfma_f32_16x16x32_bf16 v[92:95], v[168:171], v[226:229], v[92:95]
	v_mfma_f32_16x16x32_bf16 v[88:91], v[180:183], v[226:229], v[88:91]
	v_mfma_f32_16x16x32_bf16 v[76:79], v[168:171], v[238:241], v[76:79]
	v_mfma_f32_16x16x32_bf16 v[72:75], v[180:183], v[238:241], v[72:75]
	v_mfma_f32_16x16x32_bf16 v[124:127], v[176:179], v[210:213], v[124:127]
	v_mfma_f32_16x16x32_bf16 v[120:123], v[184:187], v[210:213], v[120:123]
	v_mfma_f32_16x16x32_bf16 v[108:111], v[176:179], v[222:225], v[108:111]
	v_mfma_f32_16x16x32_bf16 v[104:107], v[184:187], v[222:225], v[104:107]
	v_mfma_f32_16x16x32_bf16 v[92:95], v[176:179], v[234:237], v[92:95]
	v_mfma_f32_16x16x32_bf16 v[88:91], v[184:187], v[234:237], v[88:91]
	v_mfma_f32_16x16x32_bf16 v[76:79], v[176:179], v[242:245], v[76:79]
	v_mfma_f32_16x16x32_bf16 v[72:75], v[184:187], v[242:245], v[72:75]
	s_setprio 0
	s_setprio 1
	v_mfma_f32_16x16x32_bf16 v[116:119], v[188:191], v[206:209], v[116:119]
	v_mfma_f32_16x16x32_bf16 v[112:115], v[196:199], v[206:209], v[112:115]
	v_mfma_f32_16x16x32_bf16 v[100:103], v[188:191], v[218:221], v[100:103]
	v_mfma_f32_16x16x32_bf16 v[96:99], v[196:199], v[218:221], v[96:99]
	v_mfma_f32_16x16x32_bf16 v[84:87], v[188:191], v[226:229], v[84:87]
	v_mfma_f32_16x16x32_bf16 v[80:83], v[196:199], v[226:229], v[80:83]
	v_mfma_f32_16x16x32_bf16 v[68:71], v[188:191], v[238:241], v[68:71]
	v_mfma_f32_16x16x32_bf16 v[64:67], v[196:199], v[238:241], v[64:67]
	v_mfma_f32_16x16x32_bf16 v[116:119], v[192:195], v[210:213], v[116:119]
	v_mfma_f32_16x16x32_bf16 v[112:115], v[202:205], v[210:213], v[112:115]
	v_mfma_f32_16x16x32_bf16 v[100:103], v[192:195], v[222:225], v[100:103]
	v_mfma_f32_16x16x32_bf16 v[96:99], v[202:205], v[222:225], v[96:99]
	v_mfma_f32_16x16x32_bf16 v[84:87], v[192:195], v[234:237], v[84:87]
	v_mfma_f32_16x16x32_bf16 v[80:83], v[202:205], v[234:237], v[80:83]
	v_mfma_f32_16x16x32_bf16 v[68:71], v[192:195], v[242:245], v[68:71]
	v_mfma_f32_16x16x32_bf16 v[64:67], v[202:205], v[242:245], v[64:67]
	s_setprio 0
	s_barrier
	s_add_i32 s60, s0, s74
	v_lshl_add_u64 v[156:157], v[156:157], 0, s[12:13]
	s_mov_b32 m0, s60
	ds_read_b128 v[206:209], v200 offset:49152
	ds_read_b128 v[210:213], v200 offset:50176
	ds_read_b128 v[218:221], v200 offset:51200
	ds_read_b128 v[222:225], v200 offset:52224
	ds_read_b128 v[226:229], v200 offset:53248
	ds_read_b128 v[234:237], v200 offset:54272
	ds_read_b128 v[238:241], v200 offset:55296
	ds_read_b128 v[242:245], v200 offset:56320
	global_load_lds_dwordx4 v[156:157], off
	s_add_i32 m0, s60, 0x2000
	s_add_u32 s48, s48, 0x40080
	v_lshl_add_u64 v[156:157], v[230:231], 0, s[12:13]
	s_addc_u32 s49, s49, 0
	s_add_i32 s60, s83, s74
	global_load_lds_dwordx4 v[156:157], off
	s_mov_b32 m0, s60
	s_nop 0
	global_load_lds_dwordx4 v136, s[48:49]
	s_add_i32 m0, s60, 0x2000
	s_nop 0
	global_load_lds_dwordx4 v140, s[48:49]
	v_lshl_add_u64 v[156:157], v[246:247], 0, s[12:13]
	s_mov_b32 m0, s78
	s_nop 0
	global_load_lds_dwordx4 v[156:157], off
	v_lshl_add_u64 v[156:157], v[248:249], 0, s[12:13]
	s_mov_b32 m0, s79
	s_nop 0
	global_load_lds_dwordx4 v[156:157], off
	s_waitcnt vmcnt(8)
	s_waitcnt lgkmcnt(0)
	s_barrier
	s_setprio 1
	s_waitcnt lgkmcnt(0)
	v_mfma_f32_16x16x32_bf16 v[60:63], v[168:171], v[206:209], v[60:63]
	v_mfma_f32_16x16x32_bf16 v[56:59], v[180:183], v[206:209], v[56:59]
	v_mfma_f32_16x16x32_bf16 v[44:47], v[168:171], v[218:221], v[44:47]
	v_mfma_f32_16x16x32_bf16 v[40:43], v[180:183], v[218:221], v[40:43]
	v_mfma_f32_16x16x32_bf16 v[28:31], v[168:171], v[226:229], v[28:31]
	v_mfma_f32_16x16x32_bf16 v[24:27], v[180:183], v[226:229], v[24:27]
	v_mfma_f32_16x16x32_bf16 v[12:15], v[168:171], v[238:241], v[12:15]
	v_mfma_f32_16x16x32_bf16 v[8:11], v[180:183], v[238:241], v[8:11]
	v_mfma_f32_16x16x32_bf16 v[60:63], v[176:179], v[210:213], v[60:63]
	v_mfma_f32_16x16x32_bf16 v[56:59], v[184:187], v[210:213], v[56:59]
	v_mfma_f32_16x16x32_bf16 v[44:47], v[176:179], v[222:225], v[44:47]
	v_mfma_f32_16x16x32_bf16 v[40:43], v[184:187], v[222:225], v[40:43]
	v_mfma_f32_16x16x32_bf16 v[28:31], v[176:179], v[234:237], v[28:31]
	v_mfma_f32_16x16x32_bf16 v[24:27], v[184:187], v[234:237], v[24:27]
	v_mfma_f32_16x16x32_bf16 v[12:15], v[176:179], v[242:245], v[12:15]
	v_mfma_f32_16x16x32_bf16 v[8:11], v[184:187], v[242:245], v[8:11]
	s_setprio 0
	s_setprio 1
	v_mfma_f32_16x16x32_bf16 v[52:55], v[188:191], v[206:209], v[52:55]
	v_mfma_f32_16x16x32_bf16 v[48:51], v[196:199], v[206:209], v[48:51]
	v_mfma_f32_16x16x32_bf16 v[36:39], v[188:191], v[218:221], v[36:39]
	v_mfma_f32_16x16x32_bf16 v[32:35], v[196:199], v[218:221], v[32:35]
	v_mfma_f32_16x16x32_bf16 v[20:23], v[188:191], v[226:229], v[20:23]
	v_mfma_f32_16x16x32_bf16 v[16:19], v[196:199], v[226:229], v[16:19]
	v_mfma_f32_16x16x32_bf16 v[4:7], v[188:191], v[238:241], v[4:7]
	v_mfma_f32_16x16x32_bf16 v[0:3], v[196:199], v[238:241], v[0:3]
	v_mfma_f32_16x16x32_bf16 v[52:55], v[192:195], v[210:213], v[52:55]
	v_mfma_f32_16x16x32_bf16 v[48:51], v[202:205], v[210:213], v[48:51]
	v_mfma_f32_16x16x32_bf16 v[36:39], v[192:195], v[222:225], v[36:39]
	v_mfma_f32_16x16x32_bf16 v[32:35], v[202:205], v[222:225], v[32:35]
	v_mfma_f32_16x16x32_bf16 v[20:23], v[192:195], v[234:237], v[20:23]
	v_mfma_f32_16x16x32_bf16 v[16:19], v[202:205], v[234:237], v[16:19]
	v_mfma_f32_16x16x32_bf16 v[4:7], v[192:195], v[242:245], v[4:7]
	v_mfma_f32_16x16x32_bf16 v[0:3], v[202:205], v[242:245], v[0:3]
	s_setprio 0
	s_barrier
	s_add_i32 s67, s67, 2
	s_add_u32 s10, s10, 0x100
	s_addc_u32 s11, s11, 0
	s_add_u32 s65, s65, 0x100
	s_addc_u32 s66, s66, 0
	s_cmp_gt_u32 s67, 13
	s_cbranch_scc0 .LBB0_398
	s_and_b64 vcc, exec, s[50:51]
	s_cbranch_vccz .LBB0_401
	s_barrier

.LBB0_473:
	s_add_u32 s34, s6, 0x40000
	s_addc_u32 s35, s7, 0
	s_add_u32 s38, s6, 0x4700000
	s_addc_u32 s39, s7, 0
	s_add_u32 s40, s6, 0x7700000
	s_addc_u32 s41, s7, 0
	s_add_u32 s42, s6, 0x7b00000
	s_addc_u32 s43, s7, 0
	s_add_u32 s44, s6, 0x6700000
	s_addc_u32 s45, s7, 0
	s_add_u32 s50, s6, 0xaf00000
	s_addc_u32 s51, s7, 0
	s_add_u32 s52, s6, 0xbf00000
	v_and_b32_e32 v16, 15, v1
	s_addc_u32 s53, s7, 0
	v_or_b32_e32 v224, s57, v16
	s_add_u32 s54, s6, 0x7f00000
	v_lshlrev_b32_e32 v17, 6, v224
	v_and_b32_e32 v18, 48, v1
	s_movk_i32 s9, 0x3c0
	v_lshlrev_b32_e32 v19, 2, v224
	s_addc_u32 s55, s7, 0
	v_and_or_b32 v17, v17, s9, v18
	s_lshl_b32 s9, s60, 13
	v_and_b32_e32 v19, 32, v19
	s_add_i32 m0, s4, 0x18000
	v_lshl_add_u64 v[8:9], v[8:9], 0, s[14:15]
	v_bitop3_b32 v17, v17, s9, v19 bitop3:0xde
	s_lshl_b32 s9, s3, 12
	s_waitcnt vmcnt(2)
	s_barrier
	global_load_lds_dwordx4 v[8:9], off
	v_lshl_add_u64 v[6:7], v[6:7], 0, s[14:15]
	s_add_i32 m0, s4, 0x1a000
	s_add_i32 s84, s4, 0x8000
	s_add_i32 s74, s4, 0xa000
	global_load_lds_dwordx4 v[6:7], off
	v_lshl_add_u64 v[2:3], v[2:3], 0, s[14:15]
	s_mov_b32 m0, s84
	s_add_u32 s62, s66, 0x20080
	global_load_lds_dwordx4 v[2:3], off
	v_lshl_add_u64 v[2:3], v[4:5], 0, s[14:15]
	s_mov_b32 m0, s74
	s_addc_u32 s63, s67, 0
	global_load_lds_dwordx4 v[2:3], off
	s_add_i32 m0, s4, 0x1c000
	s_nop 0
	global_load_lds_dwordx4 v154, s[62:63]
	s_add_i32 m0, s4, 0x1e000
	v_lshlrev_b32_e32 v1, 2, v1
	global_load_lds_dwordx4 v158, s[62:63]
	v_lshl_or_b32 v18, v16, 6, v18
	v_and_b32_e32 v1, 32, v1
	v_bitop3_b32 v225, s9, v18, v1 bitop3:0xf6
	v_mov_b32_e32 v1, v145
	v_lshl_add_u64 v[166:167], s[58:59], 0, v[0:1]
	v_lshlrev_b32_e32 v0, 13, v10
	v_and_b32_e32 v0, 0xffffc000, v0
	v_lshl_add_u32 v0, v11, 10, v0
	v_and_b32_e32 v1, 1, v10
	s_cmpk_lt_u32 s56, 0x100
	v_lshl_or_b32 v0, v1, 6, v0
	s_cselect_b64 s[56:57], -1, 0
	s_lshl_b32 s9, s60, 11
	v_lshl_add_u32 v168, v12, 1, v0
	v_lshlrev_b32_e32 v0, 13, v13
	s_add_i32 s78, s9, 0
	s_lshl_b32 s9, s3, 7
	v_and_b32_e32 v0, 0xffffc000, v0
	s_waitcnt vmcnt(6)
	s_add_i32 s9, s9, 0
	v_lshlrev_b32_e32 v144, 5, v150
	v_lshl_add_u32 v0, v14, 10, v0
	v_and_b32_e32 v1, 1, v13
	v_lshlrev_b32_e32 v160, 3, v150
	s_add_i32 s78, s78, 0x21000
	s_add_i32 s9, s9, 0x23000
	v_lshl_add_u64 v[2:3], s[6:7], 0, v[144:145]
	s_mov_b64 s[6:7], 0x80000
	v_lshl_or_b32 v0, v1, 6, v0
	s_ashr_i32 s79, s10, 31
	v_add_u32_e32 v226, s9, v144
	v_lshl_add_u64 v[162:163], v[2:3], 0, s[6:7]
	v_lshl_add_u64 v[164:165], s[34:35], 0, v[144:145]
	v_lshl_add_u32 v227, v16, 4, s78
	v_mov_b32_e32 v169, v145
	v_lshl_add_u32 v170, v15, 1, v0
	v_mov_b32_e32 v171, v145
	s_mov_b32 s69, 0
	v_add_u32_e32 v228, 0, v17
	v_lshlrev_b32_e32 v172, 2, v160
	s_barrier
	s_branch .LBB0_476

.LBB0_479:
	s_add_u32 s66, s48, 0xfffe0080
	s_addc_u32 s67, s49, -1
	s_add_i32 s90, 0, 0x10000
	s_cmp_eq_u32 vcc_lo, 4
	s_cselect_b32 s71, s9, s67
	s_cselect_b32 s70, s61, s66
	s_cselect_b32 s67, s59, s83
	s_cselect_b32 s66, s72, s73
	s_add_i32 vcc_hi, 0, 0x14000
	v_add_u32_e32 v140, s90, v225
	v_add_u32_e32 v144, vcc_hi, v225
	ds_read_b128 v[128:131], v140
	ds_read_b128 v[132:135], v140 offset:1024
	ds_read_b128 v[136:139], v140 offset:2048
	ds_read_b128 v[140:143], v140 offset:3072
	ds_read_b128 v[174:177], v144
	ds_read_b128 v[178:181], v144 offset:1024
	ds_read_b128 v[182:185], v144 offset:2048
	ds_read_b128 v[186:189], v144 offset:3072
	s_add_i32 m0, s4, 0xc000
	ds_read_b128 v[190:193], v228
	ds_read_b128 v[194:197], v228 offset:1024
	ds_read_b128 v[198:201], v228 offset:2048
	ds_read_b128 v[202:205], v228 offset:3072
	ds_read_b128 v[206:209], v228 offset:4096
	ds_read_b128 v[210:213], v228 offset:5120
	ds_read_b128 v[234:237], v228 offset:6144
	ds_read_b128 v[238:241], v228 offset:7168
	global_load_lds_dwordx4 v168, s[48:49]
	s_add_i32 m0, s4, 0xe000
	s_nop 0
	global_load_lds_dwordx4 v170, s[48:49]
	s_waitcnt vmcnt(8)
	s_waitcnt lgkmcnt(0)
	s_barrier
	s_setprio 1
	s_waitcnt lgkmcnt(0)
	v_mfma_i32_16x16x64_i8 v[124:127], v[128:131], v[190:193], v[124:127]
	v_mfma_i32_16x16x64_i8 v[120:123], v[136:139], v[190:193], v[120:123]
	v_mfma_i32_16x16x64_i8 v[116:119], v[128:131], v[198:201], v[116:119]
	v_mfma_i32_16x16x64_i8 v[112:115], v[136:139], v[198:201], v[112:115]
	v_mfma_i32_16x16x64_i8 v[108:111], v[128:131], v[206:209], v[108:111]
	v_mfma_i32_16x16x64_i8 v[104:107], v[136:139], v[206:209], v[104:107]
	v_mfma_i32_16x16x64_i8 v[100:103], v[128:131], v[234:237], v[100:103]
	v_mfma_i32_16x16x64_i8 v[96:99], v[136:139], v[234:237], v[96:99]
	v_mfma_i32_16x16x64_i8 v[124:127], v[132:135], v[194:197], v[124:127]
	v_mfma_i32_16x16x64_i8 v[120:123], v[140:143], v[194:197], v[120:123]
	v_mfma_i32_16x16x64_i8 v[116:119], v[132:135], v[202:205], v[116:119]
	v_mfma_i32_16x16x64_i8 v[112:115], v[140:143], v[202:205], v[112:115]
	v_mfma_i32_16x16x64_i8 v[108:111], v[132:135], v[210:213], v[108:111]
	v_mfma_i32_16x16x64_i8 v[104:107], v[140:143], v[210:213], v[104:107]
	v_mfma_i32_16x16x64_i8 v[100:103], v[132:135], v[238:241], v[100:103]
	v_mfma_i32_16x16x64_i8 v[96:99], v[140:143], v[238:241], v[96:99]
	s_setprio 0
	s_setprio 1
	v_mfma_i32_16x16x64_i8 v[92:95], v[174:177], v[190:193], v[92:95]
	v_mfma_i32_16x16x64_i8 v[88:91], v[182:185], v[190:193], v[88:91]
	v_mfma_i32_16x16x64_i8 v[84:87], v[174:177], v[198:201], v[84:87]
	v_mfma_i32_16x16x64_i8 v[80:83], v[182:185], v[198:201], v[80:83]
	v_mfma_i32_16x16x64_i8 v[76:79], v[174:177], v[206:209], v[76:79]
	v_mfma_i32_16x16x64_i8 v[72:75], v[182:185], v[206:209], v[72:75]
	v_mfma_i32_16x16x64_i8 v[68:71], v[174:177], v[234:237], v[68:71]
	v_mfma_i32_16x16x64_i8 v[64:67], v[182:185], v[234:237], v[64:67]
	v_mfma_i32_16x16x64_i8 v[92:95], v[178:181], v[194:197], v[92:95]
	v_mfma_i32_16x16x64_i8 v[88:91], v[186:189], v[194:197], v[88:91]
	v_mfma_i32_16x16x64_i8 v[84:87], v[178:181], v[202:205], v[84:87]
	v_mfma_i32_16x16x64_i8 v[80:83], v[186:189], v[202:205], v[80:83]
	v_mfma_i32_16x16x64_i8 v[76:79], v[178:181], v[210:213], v[76:79]
	v_mfma_i32_16x16x64_i8 v[72:75], v[186:189], v[210:213], v[72:75]
	v_mfma_i32_16x16x64_i8 v[68:71], v[178:181], v[238:241], v[68:71]
	v_mfma_i32_16x16x64_i8 v[64:67], v[186:189], v[238:241], v[64:67]
	s_setprio 0
	s_barrier
	s_add_i32 s90, s90, s77
	v_lshl_add_u64 v[230:231], s[66:67], 0, v[154:155]
	s_mov_b32 m0, s90
	ds_read_b128 v[190:193], v228 offset:16384
	ds_read_b128 v[194:197], v228 offset:17408
	ds_read_b128 v[198:201], v228 offset:18432
	ds_read_b128 v[202:205], v228 offset:19456
	ds_read_b128 v[206:209], v228 offset:20480
	ds_read_b128 v[210:213], v228 offset:21504
	ds_read_b128 v[234:237], v228 offset:22528
	ds_read_b128 v[238:241], v228 offset:23552
	global_load_lds_dwordx4 v[230:231], off
	s_add_i32 m0, s90, 0x2000
	s_add_u32 s90, s66, 0x20000
	v_lshl_add_u64 v[242:243], s[66:67], 0, v[158:159]
	s_addc_u32 s91, s67, 0
	s_add_i32 vcc_hi, vcc_hi, s77
	global_load_lds_dwordx4 v[242:243], off
	s_mov_b32 m0, vcc_hi
	v_lshl_add_u64 v[246:247], s[70:71], 0, v[156:157]
	global_load_lds_dwordx4 v154, s[90:91]
	s_add_i32 m0, vcc_hi, 0x2000
	s_nop 0
	global_load_lds_dwordx4 v158, s[90:91]
	v_lshl_add_u64 v[244:245], s[70:71], 0, v[152:153]
	s_mov_b32 m0, s4
	s_nop 0
	global_load_lds_dwordx4 v[244:245], off
	s_mov_b32 m0, s5
	s_nop 0
	global_load_lds_dwordx4 v[246:247], off
	s_waitcnt vmcnt(8)
	s_waitcnt lgkmcnt(0)
	s_barrier
	s_setprio 1
	s_waitcnt lgkmcnt(0)
	v_mfma_i32_16x16x64_i8 v[60:63], v[128:131], v[190:193], v[60:63]
	v_mfma_i32_16x16x64_i8 v[56:59], v[136:139], v[190:193], v[56:59]
	v_mfma_i32_16x16x64_i8 v[52:55], v[128:131], v[198:201], v[52:55]
	v_mfma_i32_16x16x64_i8 v[48:51], v[136:139], v[198:201], v[48:51]
	v_mfma_i32_16x16x64_i8 v[44:47], v[128:131], v[206:209], v[44:47]
	v_mfma_i32_16x16x64_i8 v[40:43], v[136:139], v[206:209], v[40:43]
	v_mfma_i32_16x16x64_i8 v[36:39], v[128:131], v[234:237], v[36:39]
	v_mfma_i32_16x16x64_i8 v[32:35], v[136:139], v[234:237], v[32:35]
	v_mfma_i32_16x16x64_i8 v[60:63], v[132:135], v[194:197], v[60:63]
	v_mfma_i32_16x16x64_i8 v[56:59], v[140:143], v[194:197], v[56:59]
	v_mfma_i32_16x16x64_i8 v[52:55], v[132:135], v[202:205], v[52:55]
	v_mfma_i32_16x16x64_i8 v[48:51], v[140:143], v[202:205], v[48:51]
	v_mfma_i32_16x16x64_i8 v[44:47], v[132:135], v[210:213], v[44:47]
	v_mfma_i32_16x16x64_i8 v[40:43], v[140:143], v[210:213], v[40:43]
	v_mfma_i32_16x16x64_i8 v[36:39], v[132:135], v[238:241], v[36:39]
	v_mfma_i32_16x16x64_i8 v[32:35], v[140:143], v[238:241], v[32:35]
	s_setprio 0
	s_setprio 1
	v_mfma_i32_16x16x64_i8 v[28:31], v[174:177], v[190:193], v[28:31]
	v_mfma_i32_16x16x64_i8 v[24:27], v[182:185], v[190:193], v[24:27]
	v_mfma_i32_16x16x64_i8 v[20:23], v[174:177], v[198:201], v[20:23]
	v_mfma_i32_16x16x64_i8 v[16:19], v[182:185], v[198:201], v[16:19]
	v_mfma_i32_16x16x64_i8 v[12:15], v[174:177], v[206:209], v[12:15]
	v_mfma_i32_16x16x64_i8 v[8:11], v[182:185], v[206:209], v[8:11]
	v_mfma_i32_16x16x64_i8 v[4:7], v[174:177], v[234:237], v[4:7]
	v_mfma_i32_16x16x64_i8 v[0:3], v[182:185], v[234:237], v[0:3]
	v_mfma_i32_16x16x64_i8 v[28:31], v[178:181], v[194:197], v[28:31]
	v_mfma_i32_16x16x64_i8 v[24:27], v[186:189], v[194:197], v[24:27]
	v_mfma_i32_16x16x64_i8 v[20:23], v[178:181], v[202:205], v[20:23]
	v_mfma_i32_16x16x64_i8 v[16:19], v[186:189], v[202:205], v[16:19]
	v_mfma_i32_16x16x64_i8 v[12:15], v[178:181], v[210:213], v[12:15]
	v_mfma_i32_16x16x64_i8 v[8:11], v[186:189], v[210:213], v[8:11]
	v_mfma_i32_16x16x64_i8 v[4:7], v[178:181], v[238:241], v[4:7]
	v_mfma_i32_16x16x64_i8 v[0:3], v[186:189], v[238:241], v[0:3]
	s_setprio 0
	s_barrier
	s_add_i32 s90, 0, 0x1c000
	v_add_u32_e32 v140, s0, v225
	v_add_u32_e32 v144, s90, v225
	ds_read_b128 v[128:131], v140
	ds_read_b128 v[132:135], v140 offset:1024
	ds_read_b128 v[136:139], v140 offset:2048
	ds_read_b128 v[140:143], v140 offset:3072
	ds_read_b128 v[174:177], v144
	ds_read_b128 v[178:181], v144 offset:1024
	ds_read_b128 v[182:185], v144 offset:2048
	ds_read_b128 v[186:189], v144 offset:3072
	s_add_u32 s70, s70, 0x20000
	s_addc_u32 s71, s71, 0
	s_mov_b32 m0, s80
	ds_read_b128 v[190:193], v228 offset:32768
	ds_read_b128 v[194:197], v228 offset:33792
	ds_read_b128 v[198:201], v228 offset:34816
	ds_read_b128 v[202:205], v228 offset:35840
	ds_read_b128 v[206:209], v228 offset:36864
	ds_read_b128 v[210:213], v228 offset:37888
	ds_read_b128 v[234:237], v228 offset:38912
	ds_read_b128 v[238:241], v228 offset:39936
	global_load_lds_dwordx4 v152, s[70:71]
	v_lshl_add_u64 v[248:249], s[70:71], 0, v[156:157]
	s_mov_b32 m0, s82
	s_nop 0
	global_load_lds_dwordx4 v[248:249], off
	s_waitcnt vmcnt(8)
	s_waitcnt lgkmcnt(0)
	s_barrier
	s_setprio 1
	s_waitcnt lgkmcnt(0)
	v_mfma_i32_16x16x64_i8 v[124:127], v[128:131], v[190:193], v[124:127]
	v_mfma_i32_16x16x64_i8 v[120:123], v[136:139], v[190:193], v[120:123]
	v_mfma_i32_16x16x64_i8 v[116:119], v[128:131], v[198:201], v[116:119]
	v_mfma_i32_16x16x64_i8 v[112:115], v[136:139], v[198:201], v[112:115]
	v_mfma_i32_16x16x64_i8 v[108:111], v[128:131], v[206:209], v[108:111]
	v_mfma_i32_16x16x64_i8 v[104:107], v[136:139], v[206:209], v[104:107]
	v_mfma_i32_16x16x64_i8 v[100:103], v[128:131], v[234:237], v[100:103]
	v_mfma_i32_16x16x64_i8 v[96:99], v[136:139], v[234:237], v[96:99]
	v_mfma_i32_16x16x64_i8 v[124:127], v[132:135], v[194:197], v[124:127]
	v_mfma_i32_16x16x64_i8 v[120:123], v[140:143], v[194:197], v[120:123]
	v_mfma_i32_16x16x64_i8 v[116:119], v[132:135], v[202:205], v[116:119]
	v_mfma_i32_16x16x64_i8 v[112:115], v[140:143], v[202:205], v[112:115]
	v_mfma_i32_16x16x64_i8 v[108:111], v[132:135], v[210:213], v[108:111]
	v_mfma_i32_16x16x64_i8 v[104:107], v[140:143], v[210:213], v[104:107]
	v_mfma_i32_16x16x64_i8 v[100:103], v[132:135], v[238:241], v[100:103]
	v_mfma_i32_16x16x64_i8 v[96:99], v[140:143], v[238:241], v[96:99]
	s_setprio 0
	s_setprio 1
	v_mfma_i32_16x16x64_i8 v[92:95], v[174:177], v[190:193], v[92:95]
	v_mfma_i32_16x16x64_i8 v[88:91], v[182:185], v[190:193], v[88:91]
	v_mfma_i32_16x16x64_i8 v[84:87], v[174:177], v[198:201], v[84:87]
	v_mfma_i32_16x16x64_i8 v[80:83], v[182:185], v[198:201], v[80:83]
	v_mfma_i32_16x16x64_i8 v[76:79], v[174:177], v[206:209], v[76:79]
	v_mfma_i32_16x16x64_i8 v[72:75], v[182:185], v[206:209], v[72:75]
	v_mfma_i32_16x16x64_i8 v[68:71], v[174:177], v[234:237], v[68:71]
	v_mfma_i32_16x16x64_i8 v[64:67], v[182:185], v[234:237], v[64:67]
	v_mfma_i32_16x16x64_i8 v[92:95], v[178:181], v[194:197], v[92:95]
	v_mfma_i32_16x16x64_i8 v[88:91], v[186:189], v[194:197], v[88:91]
	v_mfma_i32_16x16x64_i8 v[84:87], v[178:181], v[202:205], v[84:87]
	v_mfma_i32_16x16x64_i8 v[80:83], v[186:189], v[202:205], v[80:83]
	v_mfma_i32_16x16x64_i8 v[76:79], v[178:181], v[210:213], v[76:79]
	v_mfma_i32_16x16x64_i8 v[72:75], v[186:189], v[210:213], v[72:75]
	v_mfma_i32_16x16x64_i8 v[68:71], v[178:181], v[238:241], v[68:71]
	v_mfma_i32_16x16x64_i8 v[64:67], v[186:189], v[238:241], v[64:67]
	s_setprio 0
	s_barrier
	s_add_i32 s70, s0, s77
	v_lshl_add_u64 v[230:231], v[230:231], 0, s[14:15]
	s_mov_b32 m0, s70
	ds_read_b128 v[190:193], v228 offset:49152
	ds_read_b128 v[194:197], v228 offset:50176
	ds_read_b128 v[198:201], v228 offset:51200
	ds_read_b128 v[202:205], v228 offset:52224
	ds_read_b128 v[206:209], v228 offset:53248
	ds_read_b128 v[210:213], v228 offset:54272
	ds_read_b128 v[234:237], v228 offset:55296
	ds_read_b128 v[238:241], v228 offset:56320
	global_load_lds_dwordx4 v[230:231], off
	s_add_i32 m0, s70, 0x2000
	s_add_u32 s66, s66, 0x20080
	v_lshl_add_u64 v[230:231], v[242:243], 0, s[14:15]
	s_addc_u32 s67, s67, 0
	s_add_i32 s70, s90, s77
	global_load_lds_dwordx4 v[230:231], off
	s_mov_b32 m0, s70
	s_nop 0
	global_load_lds_dwordx4 v154, s[66:67]
	s_add_i32 m0, s70, 0x2000
	s_nop 0
	global_load_lds_dwordx4 v158, s[66:67]
	v_lshl_add_u64 v[230:231], v[244:245], 0, s[14:15]
	s_mov_b32 m0, s84
	s_nop 0
	global_load_lds_dwordx4 v[230:231], off
	v_lshl_add_u64 v[230:231], v[246:247], 0, s[14:15]
	s_mov_b32 m0, s74
	s_nop 0
	global_load_lds_dwordx4 v[230:231], off
	s_waitcnt vmcnt(8)
	s_waitcnt lgkmcnt(0)
	s_barrier
	s_setprio 1
	s_waitcnt lgkmcnt(0)
	v_mfma_i32_16x16x64_i8 v[60:63], v[128:131], v[190:193], v[60:63]
	v_mfma_i32_16x16x64_i8 v[56:59], v[136:139], v[190:193], v[56:59]
	v_mfma_i32_16x16x64_i8 v[52:55], v[128:131], v[198:201], v[52:55]
	v_mfma_i32_16x16x64_i8 v[48:51], v[136:139], v[198:201], v[48:51]
	v_mfma_i32_16x16x64_i8 v[44:47], v[128:131], v[206:209], v[44:47]
	v_mfma_i32_16x16x64_i8 v[40:43], v[136:139], v[206:209], v[40:43]
	v_mfma_i32_16x16x64_i8 v[36:39], v[128:131], v[234:237], v[36:39]
	v_mfma_i32_16x16x64_i8 v[32:35], v[136:139], v[234:237], v[32:35]
	v_mfma_i32_16x16x64_i8 v[60:63], v[132:135], v[194:197], v[60:63]
	v_mfma_i32_16x16x64_i8 v[56:59], v[140:143], v[194:197], v[56:59]
	v_mfma_i32_16x16x64_i8 v[52:55], v[132:135], v[202:205], v[52:55]
	v_mfma_i32_16x16x64_i8 v[48:51], v[140:143], v[202:205], v[48:51]
	v_mfma_i32_16x16x64_i8 v[44:47], v[132:135], v[210:213], v[44:47]
	v_mfma_i32_16x16x64_i8 v[40:43], v[140:143], v[210:213], v[40:43]
	v_mfma_i32_16x16x64_i8 v[36:39], v[132:135], v[238:241], v[36:39]
	v_mfma_i32_16x16x64_i8 v[32:35], v[140:143], v[238:241], v[32:35]
	s_setprio 0
	s_setprio 1
	v_mfma_i32_16x16x64_i8 v[28:31], v[174:177], v[190:193], v[28:31]
	v_mfma_i32_16x16x64_i8 v[24:27], v[182:185], v[190:193], v[24:27]
	v_mfma_i32_16x16x64_i8 v[20:23], v[174:177], v[198:201], v[20:23]
	v_mfma_i32_16x16x64_i8 v[16:19], v[182:185], v[198:201], v[16:19]
	v_mfma_i32_16x16x64_i8 v[12:15], v[174:177], v[206:209], v[12:15]
	v_mfma_i32_16x16x64_i8 v[8:11], v[182:185], v[206:209], v[8:11]
	v_mfma_i32_16x16x64_i8 v[4:7], v[174:177], v[234:237], v[4:7]
	v_mfma_i32_16x16x64_i8 v[0:3], v[182:185], v[234:237], v[0:3]
	v_mfma_i32_16x16x64_i8 v[28:31], v[178:181], v[194:197], v[28:31]
	v_mfma_i32_16x16x64_i8 v[24:27], v[186:189], v[194:197], v[24:27]
	v_mfma_i32_16x16x64_i8 v[20:23], v[178:181], v[202:205], v[20:23]
	v_mfma_i32_16x16x64_i8 v[16:19], v[186:189], v[202:205], v[16:19]
	v_mfma_i32_16x16x64_i8 v[12:15], v[178:181], v[210:213], v[12:15]
	v_mfma_i32_16x16x64_i8 v[8:11], v[186:189], v[210:213], v[8:11]
	v_mfma_i32_16x16x64_i8 v[4:7], v[178:181], v[238:241], v[4:7]
	v_mfma_i32_16x16x64_i8 v[0:3], v[186:189], v[238:241], v[0:3]
	s_setprio 0
	s_barrier
	s_add_i32 vcc_lo, vcc_lo, 2
	s_add_u32 s48, s48, 0x100
	s_addc_u32 s49, s49, 0
	s_add_u32 s73, s73, 0x100
	s_addc_u32 s83, s83, 0
	s_cmp_gt_u32 vcc_lo, 5
	s_cbranch_scc0 .LBB0_479
	s_and_b64 vcc, exec, s[56:57]
	s_cbranch_vccz .LBB0_482
	s_barrier

.LBB0_915:
	s_add_i32 m0, s12, 0x18000
	v_lshl_add_u64 v[8:9], v[8:9], 0, s[14:15]
	s_lshl_b32 s44, s5, 13
	s_lshl_b32 s45, s4, 12
	s_waitcnt vmcnt(2)
	s_barrier
	global_load_lds_dwordx4 v[8:9], off
	v_lshl_add_u64 v[6:7], v[6:7], 0, s[14:15]
	s_add_i32 m0, s12, 0x1a000
	s_add_i32 s72, s12, 0x8000
	s_add_i32 s73, s12, 0xa000
	global_load_lds_dwordx4 v[6:7], off
	v_lshl_add_u64 v[2:3], v[2:3], 0, s[14:15]
	s_mov_b32 m0, s72
	s_add_u32 s42, s58, 0x20080
	global_load_lds_dwordx4 v[2:3], off
	v_lshl_add_u64 v[2:3], v[4:5], 0, s[14:15]
	s_mov_b32 m0, s73
	s_addc_u32 s43, s59, 0
	global_load_lds_dwordx4 v[2:3], off
	s_add_i32 m0, s12, 0x1c000
	s_nop 0
	global_load_lds_dwordx4 v0, s[42:43]
	s_add_i32 m0, s12, 0x1e000
	s_cmpk_lt_u32 s40, 0x100
	global_load_lds_dwordx4 v164, s[42:43]
	v_or_b32_e32 v2, s41, v179
	v_and_b32_e32 v3, 48, v130
	v_lshlrev_b32_e32 v4, 6, v2
	s_movk_i32 s41, 0x3c0
	v_lshlrev_b32_e32 v2, 2, v2
	v_and_or_b32 v4, v4, s41, v3
	v_and_b32_e32 v2, 32, v2
	v_bitop3_b32 v4, v4, s44, v2 bitop3:0xde
	v_or_b32_e32 v2, v178, v3
	s_cselect_b64 s[40:41], -1, 0
	s_lshl_b32 s4, s4, 7
	v_bitop3_b32 v182, s45, v2, v180 bitop3:0xf6
	v_lshlrev_b32_e32 v2, 1, v10
	s_add_i32 s4, s4, 0
	v_and_b32_e32 v3, 0x60, v2
	s_add_i32 s4, s4, 0x23000
	v_add_u32_e32 v183, s4, v3
	v_lshlrev_b32_e32 v3, 13, v172
	v_and_b32_e32 v3, 0xffffc000, v3
	v_lshl_add_u32 v3, v173, 10, v3
	v_and_b32_e32 v5, 1, v172
	v_lshl_or_b32 v3, v5, 6, v3
	v_lshl_add_u32 v134, v174, 1, v3
	v_lshlrev_b32_e32 v3, 13, v175
	s_lshl_b32 s5, s5, 11
	v_and_b32_e32 v3, 0xffffc000, v3
	s_waitcnt vmcnt(6)
	s_add_i32 s74, s5, 0
	v_lshl_add_u32 v3, v176, 10, v3
	v_and_b32_e32 v5, 1, v175
	s_add_i32 s74, s74, 0x21000
	v_lshlrev_b32_e32 v2, 2, v10
	v_lshl_or_b32 v3, v5, 6, v3
	v_lshl_add_u64 v[132:133], v[130:131], 4, s[6:7]
	v_lshl_add_u32 v184, v179, 4, s74
	v_mov_b32_e32 v135, v1
	v_lshl_add_u32 v136, v177, 1, v3
	v_mov_b32_e32 v137, v1
	s_mov_b32 s77, 0
	v_add_u32_e32 v185, 0, v4
	v_lshlrev_b32_e32 v188, 2, v2
	s_mov_b32 s78, 0
	s_barrier
	s_branch .LBB0_918

.LBB0_925:
	s_add_u32 s58, s56, 0xfffe0080
	s_addc_u32 s59, s57, -1
	s_add_i32 s83, 0, 0x10000
	s_cmp_eq_u32 s82, 4
	s_cselect_b32 s61, s51, s59
	s_cselect_b32 s60, s79, s58
	s_cselect_b32 s59, s43, s81
	s_cselect_b32 s58, s45, s80
	s_add_i32 s86, 0, 0x14000
	v_add_u32_e32 v150, s83, v182
	v_add_u32_e32 v154, s86, v182
	ds_read_b128 v[138:141], v150
	ds_read_b128 v[142:145], v150 offset:1024
	ds_read_b128 v[146:149], v150 offset:2048
	ds_read_b128 v[150:153], v150 offset:3072
	ds_read_b128 v[166:169], v154
	ds_read_b128 v[190:193], v154 offset:1024
	ds_read_b128 v[194:197], v154 offset:2048
	ds_read_b128 v[198:201], v154 offset:3072
	s_add_i32 m0, s12, 0xc000
	ds_read_b128 v[202:205], v185
	ds_read_b128 v[206:209], v185 offset:1024
	ds_read_b128 v[210:213], v185 offset:2048
	ds_read_b128 v[214:217], v185 offset:3072
	ds_read_b128 v[218:221], v185 offset:4096
	ds_read_b128 v[222:225], v185 offset:5120
	ds_read_b128 v[226:229], v185 offset:6144
	ds_read_b128 v[234:237], v185 offset:7168
	global_load_lds_dwordx4 v134, s[56:57]
	s_add_i32 m0, s12, 0xe000
	s_nop 0
	global_load_lds_dwordx4 v136, s[56:57]
	s_waitcnt vmcnt(8)
	s_waitcnt lgkmcnt(0)
	s_barrier
	s_setprio 1
	s_waitcnt lgkmcnt(0)
	v_mfma_i32_16x16x64_i8 v[126:129], v[138:141], v[202:205], v[126:129]
	v_mfma_i32_16x16x64_i8 v[122:125], v[146:149], v[202:205], v[122:125]
	v_mfma_i32_16x16x64_i8 v[110:113], v[138:141], v[210:213], v[110:113]
	v_mfma_i32_16x16x64_i8 v[106:109], v[146:149], v[210:213], v[106:109]
	v_mfma_i32_16x16x64_i8 v[94:97], v[138:141], v[218:221], v[94:97]
	v_mfma_i32_16x16x64_i8 v[90:93], v[146:149], v[218:221], v[90:93]
	v_mfma_i32_16x16x64_i8 v[78:81], v[138:141], v[226:229], v[78:81]
	v_mfma_i32_16x16x64_i8 v[74:77], v[146:149], v[226:229], v[74:77]
	v_mfma_i32_16x16x64_i8 v[126:129], v[142:145], v[206:209], v[126:129]
	v_mfma_i32_16x16x64_i8 v[122:125], v[150:153], v[206:209], v[122:125]
	v_mfma_i32_16x16x64_i8 v[110:113], v[142:145], v[214:217], v[110:113]
	v_mfma_i32_16x16x64_i8 v[106:109], v[150:153], v[214:217], v[106:109]
	v_mfma_i32_16x16x64_i8 v[94:97], v[142:145], v[222:225], v[94:97]
	v_mfma_i32_16x16x64_i8 v[90:93], v[150:153], v[222:225], v[90:93]
	v_mfma_i32_16x16x64_i8 v[78:81], v[142:145], v[234:237], v[78:81]
	v_mfma_i32_16x16x64_i8 v[74:77], v[150:153], v[234:237], v[74:77]
	s_setprio 0
	s_setprio 1
	v_mfma_i32_16x16x64_i8 v[118:121], v[166:169], v[202:205], v[118:121]
	v_mfma_i32_16x16x64_i8 v[114:117], v[194:197], v[202:205], v[114:117]
	v_mfma_i32_16x16x64_i8 v[102:105], v[166:169], v[210:213], v[102:105]
	v_mfma_i32_16x16x64_i8 v[98:101], v[194:197], v[210:213], v[98:101]
	v_mfma_i32_16x16x64_i8 v[86:89], v[166:169], v[218:221], v[86:89]
	v_mfma_i32_16x16x64_i8 v[82:85], v[194:197], v[218:221], v[82:85]
	v_mfma_i32_16x16x64_i8 v[70:73], v[166:169], v[226:229], v[70:73]
	v_mfma_i32_16x16x64_i8 v[66:69], v[194:197], v[226:229], v[66:69]
	v_mfma_i32_16x16x64_i8 v[118:121], v[190:193], v[206:209], v[118:121]
	v_mfma_i32_16x16x64_i8 v[114:117], v[198:201], v[206:209], v[114:117]
	v_mfma_i32_16x16x64_i8 v[102:105], v[190:193], v[214:217], v[102:105]
	v_mfma_i32_16x16x64_i8 v[98:101], v[198:201], v[214:217], v[98:101]
	v_mfma_i32_16x16x64_i8 v[86:89], v[190:193], v[222:225], v[86:89]
	v_mfma_i32_16x16x64_i8 v[82:85], v[198:201], v[222:225], v[82:85]
	v_mfma_i32_16x16x64_i8 v[70:73], v[190:193], v[234:237], v[70:73]
	v_mfma_i32_16x16x64_i8 v[66:69], v[198:201], v[234:237], v[66:69]
	s_setprio 0
	s_barrier
	s_add_i32 s83, s83, s69
	v_lshl_add_u64 v[154:155], s[58:59], 0, v[0:1]
	s_mov_b32 m0, s83
	ds_read_b128 v[202:205], v185 offset:16384
	ds_read_b128 v[206:209], v185 offset:17408
	ds_read_b128 v[210:213], v185 offset:18432
	ds_read_b128 v[214:217], v185 offset:19456
	ds_read_b128 v[218:221], v185 offset:20480
	ds_read_b128 v[222:225], v185 offset:21504
	ds_read_b128 v[226:229], v185 offset:22528
	ds_read_b128 v[234:237], v185 offset:23552
	global_load_lds_dwordx4 v[154:155], off
	s_add_i32 m0, s83, 0x2000
	s_add_u32 s84, s58, 0x20000
	v_lshl_add_u64 v[170:171], s[58:59], 0, v[164:165]
	s_addc_u32 s85, s59, 0
	s_add_i32 s83, s86, s69
	global_load_lds_dwordx4 v[170:171], off
	s_mov_b32 m0, s83
	v_lshl_add_u64 v[238:239], s[60:61], 0, v[162:163]
	global_load_lds_dwordx4 v0, s[84:85]
	s_add_i32 m0, s83, 0x2000
	s_nop 0
	global_load_lds_dwordx4 v164, s[84:85]
	v_lshl_add_u64 v[230:231], s[60:61], 0, v[160:161]
	s_mov_b32 m0, s12
	s_nop 0
	global_load_lds_dwordx4 v[230:231], off
	s_mov_b32 m0, s49
	s_nop 0
	global_load_lds_dwordx4 v[238:239], off
	s_waitcnt vmcnt(8)
	s_waitcnt lgkmcnt(0)
	s_barrier
	s_setprio 1
	s_waitcnt lgkmcnt(0)
	v_mfma_i32_16x16x64_i8 v[62:65], v[138:141], v[202:205], v[62:65]
	v_mfma_i32_16x16x64_i8 v[58:61], v[146:149], v[202:205], v[58:61]
	v_mfma_i32_16x16x64_i8 v[46:49], v[138:141], v[210:213], v[46:49]
	v_mfma_i32_16x16x64_i8 v[42:45], v[146:149], v[210:213], v[42:45]
	v_mfma_i32_16x16x64_i8 v[30:33], v[138:141], v[218:221], v[30:33]
	v_mfma_i32_16x16x64_i8 v[26:29], v[146:149], v[218:221], v[26:29]
	v_mfma_i32_16x16x64_i8 v[10:13], v[138:141], v[226:229], v[10:13]
	v_mfma_i32_16x16x64_i8 v[2:5], v[146:149], v[226:229], v[2:5]
	v_mfma_i32_16x16x64_i8 v[62:65], v[142:145], v[206:209], v[62:65]
	v_mfma_i32_16x16x64_i8 v[58:61], v[150:153], v[206:209], v[58:61]
	v_mfma_i32_16x16x64_i8 v[46:49], v[142:145], v[214:217], v[46:49]
	v_mfma_i32_16x16x64_i8 v[42:45], v[150:153], v[214:217], v[42:45]
	v_mfma_i32_16x16x64_i8 v[30:33], v[142:145], v[222:225], v[30:33]
	v_mfma_i32_16x16x64_i8 v[26:29], v[150:153], v[222:225], v[26:29]
	v_mfma_i32_16x16x64_i8 v[10:13], v[142:145], v[234:237], v[10:13]
	v_mfma_i32_16x16x64_i8 v[2:5], v[150:153], v[234:237], v[2:5]
	s_setprio 0
	s_setprio 1
	v_mfma_i32_16x16x64_i8 v[54:57], v[166:169], v[202:205], v[54:57]
	v_mfma_i32_16x16x64_i8 v[50:53], v[194:197], v[202:205], v[50:53]
	v_mfma_i32_16x16x64_i8 v[38:41], v[166:169], v[210:213], v[38:41]
	v_mfma_i32_16x16x64_i8 v[34:37], v[194:197], v[210:213], v[34:37]
	v_mfma_i32_16x16x64_i8 v[22:25], v[166:169], v[218:221], v[22:25]
	v_mfma_i32_16x16x64_i8 v[18:21], v[194:197], v[218:221], v[18:21]
	v_mfma_i32_16x16x64_i8 v[14:17], v[166:169], v[226:229], v[14:17]
	v_mfma_i32_16x16x64_i8 v[6:9], v[194:197], v[226:229], v[6:9]
	v_mfma_i32_16x16x64_i8 v[54:57], v[190:193], v[206:209], v[54:57]
	v_mfma_i32_16x16x64_i8 v[50:53], v[198:201], v[206:209], v[50:53]
	v_mfma_i32_16x16x64_i8 v[38:41], v[190:193], v[214:217], v[38:41]
	v_mfma_i32_16x16x64_i8 v[34:37], v[198:201], v[214:217], v[34:37]
	v_mfma_i32_16x16x64_i8 v[22:25], v[190:193], v[222:225], v[22:25]
	v_mfma_i32_16x16x64_i8 v[18:21], v[198:201], v[222:225], v[18:21]
	v_mfma_i32_16x16x64_i8 v[14:17], v[190:193], v[234:237], v[14:17]
	v_mfma_i32_16x16x64_i8 v[6:9], v[198:201], v[234:237], v[6:9]
	s_setprio 0
	s_barrier
	s_add_i32 s83, 0, 0x18000
	s_add_i32 s84, 0, 0x1c000
	v_add_u32_e32 v150, s83, v182
	v_add_u32_e32 v189, s84, v182
	ds_read_b128 v[138:141], v150
	ds_read_b128 v[142:145], v150 offset:1024
	ds_read_b128 v[146:149], v150 offset:2048
	ds_read_b128 v[150:153], v150 offset:3072
	ds_read_b128 v[166:169], v189
	ds_read_b128 v[190:193], v189 offset:1024
	ds_read_b128 v[194:197], v189 offset:2048
	ds_read_b128 v[198:201], v189 offset:3072
	s_add_u32 s60, s60, 0x20000
	s_addc_u32 s61, s61, 0
	s_mov_b32 m0, s70
	ds_read_b128 v[202:205], v185 offset:32768
	ds_read_b128 v[206:209], v185 offset:33792
	ds_read_b128 v[210:213], v185 offset:34816
	ds_read_b128 v[214:217], v185 offset:35840
	ds_read_b128 v[218:221], v185 offset:36864
	ds_read_b128 v[222:225], v185 offset:37888
	ds_read_b128 v[226:229], v185 offset:38912
	ds_read_b128 v[234:237], v185 offset:39936
	global_load_lds_dwordx4 v160, s[60:61]
	s_mov_b32 m0, s71
	s_nop 0
	global_load_lds_dwordx4 v162, s[60:61]
	s_waitcnt vmcnt(8)
	s_waitcnt lgkmcnt(0)
	s_barrier
	s_setprio 1
	s_waitcnt lgkmcnt(0)
	v_mfma_i32_16x16x64_i8 v[126:129], v[138:141], v[202:205], v[126:129]
	v_mfma_i32_16x16x64_i8 v[122:125], v[146:149], v[202:205], v[122:125]
	v_mfma_i32_16x16x64_i8 v[110:113], v[138:141], v[210:213], v[110:113]
	v_mfma_i32_16x16x64_i8 v[106:109], v[146:149], v[210:213], v[106:109]
	v_mfma_i32_16x16x64_i8 v[94:97], v[138:141], v[218:221], v[94:97]
	v_mfma_i32_16x16x64_i8 v[90:93], v[146:149], v[218:221], v[90:93]
	v_mfma_i32_16x16x64_i8 v[78:81], v[138:141], v[226:229], v[78:81]
	v_mfma_i32_16x16x64_i8 v[74:77], v[146:149], v[226:229], v[74:77]
	v_mfma_i32_16x16x64_i8 v[126:129], v[142:145], v[206:209], v[126:129]
	v_mfma_i32_16x16x64_i8 v[122:125], v[150:153], v[206:209], v[122:125]
	v_mfma_i32_16x16x64_i8 v[110:113], v[142:145], v[214:217], v[110:113]
	v_mfma_i32_16x16x64_i8 v[106:109], v[150:153], v[214:217], v[106:109]
	v_mfma_i32_16x16x64_i8 v[94:97], v[142:145], v[222:225], v[94:97]
	v_mfma_i32_16x16x64_i8 v[90:93], v[150:153], v[222:225], v[90:93]
	v_mfma_i32_16x16x64_i8 v[78:81], v[142:145], v[234:237], v[78:81]
	v_mfma_i32_16x16x64_i8 v[74:77], v[150:153], v[234:237], v[74:77]
	s_setprio 0
	s_setprio 1
	v_mfma_i32_16x16x64_i8 v[118:121], v[166:169], v[202:205], v[118:121]
	v_mfma_i32_16x16x64_i8 v[114:117], v[194:197], v[202:205], v[114:117]
	v_mfma_i32_16x16x64_i8 v[102:105], v[166:169], v[210:213], v[102:105]
	v_mfma_i32_16x16x64_i8 v[98:101], v[194:197], v[210:213], v[98:101]
	v_mfma_i32_16x16x64_i8 v[86:89], v[166:169], v[218:221], v[86:89]
	v_mfma_i32_16x16x64_i8 v[82:85], v[194:197], v[218:221], v[82:85]
	v_mfma_i32_16x16x64_i8 v[70:73], v[166:169], v[226:229], v[70:73]
	v_mfma_i32_16x16x64_i8 v[66:69], v[194:197], v[226:229], v[66:69]
	v_mfma_i32_16x16x64_i8 v[118:121], v[190:193], v[206:209], v[118:121]
	v_mfma_i32_16x16x64_i8 v[114:117], v[198:201], v[206:209], v[114:117]
	v_mfma_i32_16x16x64_i8 v[102:105], v[190:193], v[214:217], v[102:105]
	v_mfma_i32_16x16x64_i8 v[98:101], v[198:201], v[214:217], v[98:101]
	v_mfma_i32_16x16x64_i8 v[86:89], v[190:193], v[222:225], v[86:89]
	v_mfma_i32_16x16x64_i8 v[82:85], v[198:201], v[222:225], v[82:85]
	v_mfma_i32_16x16x64_i8 v[70:73], v[190:193], v[234:237], v[70:73]
	v_mfma_i32_16x16x64_i8 v[66:69], v[198:201], v[234:237], v[66:69]
	s_setprio 0
	s_barrier
	s_add_i32 s60, s83, s69
	v_lshl_add_u64 v[154:155], v[154:155], 0, s[14:15]
	s_mov_b32 m0, s60
	ds_read_b128 v[202:205], v185 offset:49152
	ds_read_b128 v[206:209], v185 offset:50176
	ds_read_b128 v[210:213], v185 offset:51200
	ds_read_b128 v[214:217], v185 offset:52224
	ds_read_b128 v[218:221], v185 offset:53248
	ds_read_b128 v[222:225], v185 offset:54272
	ds_read_b128 v[226:229], v185 offset:55296
	ds_read_b128 v[234:237], v185 offset:56320
	global_load_lds_dwordx4 v[154:155], off
	s_add_i32 m0, s60, 0x2000
	s_add_u32 s58, s58, 0x20080
	v_lshl_add_u64 v[154:155], v[170:171], 0, s[14:15]
	s_addc_u32 s59, s59, 0
	s_add_i32 s60, s84, s69
	global_load_lds_dwordx4 v[154:155], off
	s_mov_b32 m0, s60
	s_nop 0
	global_load_lds_dwordx4 v0, s[58:59]
	s_add_i32 m0, s60, 0x2000
	s_nop 0
	global_load_lds_dwordx4 v164, s[58:59]
	v_lshl_add_u64 v[154:155], v[230:231], 0, s[14:15]
	s_mov_b32 m0, s72
	s_nop 0
	global_load_lds_dwordx4 v[154:155], off
	v_lshl_add_u64 v[154:155], v[238:239], 0, s[14:15]
	s_mov_b32 m0, s73
	s_nop 0
	global_load_lds_dwordx4 v[154:155], off
	s_waitcnt vmcnt(8)
	s_waitcnt lgkmcnt(0)
	s_barrier
	s_setprio 1
	s_waitcnt lgkmcnt(0)
	v_mfma_i32_16x16x64_i8 v[62:65], v[138:141], v[202:205], v[62:65]
	v_mfma_i32_16x16x64_i8 v[58:61], v[146:149], v[202:205], v[58:61]
	v_mfma_i32_16x16x64_i8 v[46:49], v[138:141], v[210:213], v[46:49]
	v_mfma_i32_16x16x64_i8 v[42:45], v[146:149], v[210:213], v[42:45]
	v_mfma_i32_16x16x64_i8 v[30:33], v[138:141], v[218:221], v[30:33]
	v_mfma_i32_16x16x64_i8 v[26:29], v[146:149], v[218:221], v[26:29]
	v_mfma_i32_16x16x64_i8 v[10:13], v[138:141], v[226:229], v[10:13]
	v_mfma_i32_16x16x64_i8 v[2:5], v[146:149], v[226:229], v[2:5]
	v_mfma_i32_16x16x64_i8 v[62:65], v[142:145], v[206:209], v[62:65]
	v_mfma_i32_16x16x64_i8 v[58:61], v[150:153], v[206:209], v[58:61]
	v_mfma_i32_16x16x64_i8 v[46:49], v[142:145], v[214:217], v[46:49]
	v_mfma_i32_16x16x64_i8 v[42:45], v[150:153], v[214:217], v[42:45]
	v_mfma_i32_16x16x64_i8 v[30:33], v[142:145], v[222:225], v[30:33]
	v_mfma_i32_16x16x64_i8 v[26:29], v[150:153], v[222:225], v[26:29]
	v_mfma_i32_16x16x64_i8 v[10:13], v[142:145], v[234:237], v[10:13]
	v_mfma_i32_16x16x64_i8 v[2:5], v[150:153], v[234:237], v[2:5]
	s_setprio 0
	s_setprio 1
	v_mfma_i32_16x16x64_i8 v[54:57], v[166:169], v[202:205], v[54:57]
	v_mfma_i32_16x16x64_i8 v[50:53], v[194:197], v[202:205], v[50:53]
	v_mfma_i32_16x16x64_i8 v[38:41], v[166:169], v[210:213], v[38:41]
	v_mfma_i32_16x16x64_i8 v[34:37], v[194:197], v[210:213], v[34:37]
	v_mfma_i32_16x16x64_i8 v[22:25], v[166:169], v[218:221], v[22:25]
	v_mfma_i32_16x16x64_i8 v[18:21], v[194:197], v[218:221], v[18:21]
	v_mfma_i32_16x16x64_i8 v[14:17], v[166:169], v[226:229], v[14:17]
	v_mfma_i32_16x16x64_i8 v[6:9], v[194:197], v[226:229], v[6:9]
	v_mfma_i32_16x16x64_i8 v[54:57], v[190:193], v[206:209], v[54:57]
	v_mfma_i32_16x16x64_i8 v[50:53], v[198:201], v[206:209], v[50:53]
	v_mfma_i32_16x16x64_i8 v[38:41], v[190:193], v[214:217], v[38:41]
	v_mfma_i32_16x16x64_i8 v[34:37], v[198:201], v[214:217], v[34:37]
	v_mfma_i32_16x16x64_i8 v[22:25], v[190:193], v[222:225], v[22:25]
	v_mfma_i32_16x16x64_i8 v[18:21], v[198:201], v[222:225], v[18:21]
	v_mfma_i32_16x16x64_i8 v[14:17], v[190:193], v[234:237], v[14:17]
	v_mfma_i32_16x16x64_i8 v[6:9], v[198:201], v[234:237], v[6:9]
	s_setprio 0
	s_barrier
	s_add_i32 s82, s82, 2
	s_add_u32 s56, s56, 0x100
	s_addc_u32 s57, s57, 0
	s_add_u32 s80, s80, 0x100
	s_addc_u32 s81, s81, 0
	s_cmp_gt_u32 s82, 5
	s_cbranch_scc0 .LBB0_925
	s_and_b64 vcc, exec, s[40:41]
	s_cbranch_vccz .LBB0_928
	s_barrier

.LBB0_945:
	s_add_u32 s30, s62, 0xcf00000
	s_addc_u32 s31, s63, 0
	s_lshl_b32 s5, s5, 5
	s_and_b32 s62, s5, 0x60
	s_add_i32 m0, s45, 0x18000
	v_lshl_add_u64 v[8:9], v[8:9], 0, s[14:15]
	s_lshl_b32 s38, s4, 13
	s_lshl_b32 s5, s62, 7
	s_waitcnt vmcnt(2)
	s_barrier
	global_load_lds_dwordx4 v[8:9], off
	v_lshl_add_u64 v[6:7], v[6:7], 0, s[14:15]
	s_add_i32 m0, s45, 0x1a000
	s_add_i32 s63, s45, 0x8000
	s_add_i32 s64, s45, 0xa000
	global_load_lds_dwordx4 v[6:7], off
	v_lshl_add_u64 v[2:3], v[2:3], 0, s[14:15]
	s_mov_b32 m0, s63
	s_add_u32 s34, s8, 0x20080
	global_load_lds_dwordx4 v[2:3], off
	v_lshl_add_u64 v[2:3], v[4:5], 0, s[14:15]
	s_mov_b32 m0, s64
	s_addc_u32 s35, s9, 0
	global_load_lds_dwordx4 v[2:3], off
	s_add_i32 m0, s45, 0x1c000
	s_nop 0
	global_load_lds_dwordx4 v166, s[34:35]
	s_add_i32 m0, s45, 0x1e000
	v_lshrrev_b32_e32 v0, 1, v130
	global_load_lds_dwordx4 v164, s[34:35]
	v_and_b32_e32 v168, 24, v0
	v_lshlrev_b32_e32 v0, 1, v168
	v_lshl_or_b32 v2, v179, 6, v0
	v_or_b32_e32 v0, v0, v178
	v_lshlrev_b32_e32 v3, 2, v179
	v_bitop3_b32 v188, s5, v0, v180 bitop3:0xf6
	v_lshlrev_b32_e32 v0, 13, v172
	v_and_b32_e32 v3, 32, v3
	v_and_b32_e32 v0, 0xffffc000, v0
	v_bitop3_b32 v4, v2, s38, v3 bitop3:0xde
	v_lshl_add_u32 v0, v173, 10, v0
	v_and_b32_e32 v2, 1, v172
	v_lshl_or_b32 v0, v2, 6, v0
	v_lshl_add_u32 v172, v174, 1, v0
	v_lshlrev_b32_e32 v0, 13, v175
	v_and_b32_e32 v0, 0xffffc000, v0
	v_lshl_add_u32 v0, v176, 10, v0
	v_and_b32_e32 v2, 1, v175
	s_waitcnt vmcnt(6)
	v_lshl_or_b32 v0, v2, 6, v0
	v_mov_b32_e32 v2, v1
	v_mov_b32_e32 v3, v1
	v_lshl_or_b32 v169, s4, 6, v179
	s_cmpk_lt_u32 s12, 0x100
	v_lshl_add_u64 v[170:171], v[130:131], 4, s[6:7]
	v_lshl_add_u32 v174, v177, 1, v0
	v_mov_b32_e32 v0, v1
	v_add_u32_e32 v196, 0, v4
	v_mov_b64_e32 v[6:7], v[2:3]
	v_mov_b64_e32 v[10:11], v[2:3]
	v_mov_b64_e32 v[14:15], v[2:3]
	v_mov_b64_e32 v[18:19], v[2:3]
	v_mov_b64_e32 v[22:23], v[2:3]
	v_mov_b64_e32 v[26:27], v[2:3]
	v_mov_b64_e32 v[30:31], v[2:3]
	v_mov_b64_e32 v[34:35], v[2:3]
	v_mov_b64_e32 v[38:39], v[2:3]
	v_mov_b64_e32 v[42:43], v[2:3]
	v_mov_b64_e32 v[46:47], v[2:3]
	v_mov_b64_e32 v[50:51], v[2:3]
	v_mov_b64_e32 v[54:55], v[2:3]
	v_mov_b64_e32 v[58:59], v[2:3]
	v_mov_b64_e32 v[62:63], v[2:3]
	v_mov_b64_e32 v[66:67], v[2:3]
	v_mov_b64_e32 v[70:71], v[2:3]
	v_mov_b64_e32 v[74:75], v[2:3]
	v_mov_b64_e32 v[78:79], v[2:3]
	v_mov_b64_e32 v[82:83], v[2:3]
	v_mov_b64_e32 v[86:87], v[2:3]
	v_mov_b64_e32 v[90:91], v[2:3]
	v_mov_b64_e32 v[94:95], v[2:3]
	v_mov_b64_e32 v[98:99], v[2:3]
	v_mov_b64_e32 v[102:103], v[2:3]
	v_mov_b64_e32 v[106:107], v[2:3]
	v_mov_b64_e32 v[110:111], v[2:3]
	v_mov_b64_e32 v[114:115], v[2:3]
	v_mov_b64_e32 v[118:119], v[2:3]
	v_mov_b64_e32 v[122:123], v[2:3]
	v_mov_b64_e32 v[126:127], v[2:3]
	v_mov_b64_e32 v[130:131], v[2:3]
	s_cselect_b64 s[34:35], -1, 0
	v_or_b32_e32 v189, 16, v169
	v_or_b32_e32 v190, 32, v169
	v_or_b32_e32 v191, 48, v169
	v_add_u32_e32 v192, 0x80, v169
	v_add_u32_e32 v193, 0x90, v169
	v_add_u32_e32 v194, 0xa0, v169
	v_add_u32_e32 v195, 0xb0, v169
	s_ashr_i32 s65, s33, 31
	v_mov_b32_e32 v173, v1
	v_mov_b32_e32 v175, v1
	s_mov_b32 s12, 0
	v_mov_b64_e32 v[4:5], v[0:1]
	v_mov_b64_e32 v[8:9], v[0:1]
	v_mov_b64_e32 v[12:13], v[0:1]
	v_mov_b64_e32 v[16:17], v[0:1]
	v_mov_b64_e32 v[20:21], v[0:1]
	v_mov_b64_e32 v[24:25], v[0:1]
	v_mov_b64_e32 v[28:29], v[0:1]
	v_mov_b64_e32 v[32:33], v[0:1]
	v_mov_b64_e32 v[36:37], v[0:1]
	v_mov_b64_e32 v[40:41], v[0:1]
	v_mov_b64_e32 v[44:45], v[0:1]
	v_mov_b64_e32 v[48:49], v[0:1]
	v_mov_b64_e32 v[52:53], v[0:1]
	v_mov_b64_e32 v[56:57], v[0:1]
	v_mov_b64_e32 v[60:61], v[0:1]
	v_mov_b64_e32 v[64:65], v[0:1]
	v_mov_b64_e32 v[68:69], v[0:1]
	v_mov_b64_e32 v[72:73], v[0:1]
	v_mov_b64_e32 v[76:77], v[0:1]
	v_mov_b64_e32 v[80:81], v[0:1]
	v_mov_b64_e32 v[84:85], v[0:1]
	v_mov_b64_e32 v[88:89], v[0:1]
	v_mov_b64_e32 v[92:93], v[0:1]
	v_mov_b64_e32 v[96:97], v[0:1]
	v_mov_b64_e32 v[100:101], v[0:1]
	v_mov_b64_e32 v[104:105], v[0:1]
	v_mov_b64_e32 v[108:109], v[0:1]
	v_mov_b64_e32 v[112:113], v[0:1]
	v_mov_b64_e32 v[116:117], v[0:1]
	v_mov_b64_e32 v[120:121], v[0:1]
	v_mov_b64_e32 v[124:125], v[0:1]
	v_mov_b64_e32 v[128:129], v[0:1]
	s_mov_b32 s66, 0
	s_barrier
	s_branch .LBB0_948

.LBB0_955:
	s_add_u32 s8, s6, 0xfffe0080
	s_addc_u32 s9, s7, -1
	s_add_i32 s70, 0, 0x10000
	s_cmp_eq_u32 s69, 4
	s_cselect_b32 s55, s43, s9
	s_cselect_b32 s54, s49, s8
	v_add_u32_e32 v0, s70, v188
	s_cselect_b32 s9, s39, s68
	s_cselect_b32 s8, s41, s67
	s_add_i32 s72, 0, 0x14000
	ds_read_b128 v[132:135], v0
	ds_read_b128 v[136:139], v0 offset:1024
	ds_read_b128 v[140:143], v0 offset:2048
	ds_read_b128 v[144:147], v0 offset:3072
	v_add_u32_e32 v0, s72, v188
	ds_read_b128 v[148:151], v0
	ds_read_b128 v[152:155], v0 offset:1024
	ds_read_b128 v[176:179], v0 offset:2048
	ds_read_b128 v[180:183], v0 offset:3072
	s_add_i32 m0, s45, 0xc000
	ds_read_b128 v[198:201], v196
	ds_read_b128 v[202:205], v196 offset:1024
	ds_read_b128 v[206:209], v196 offset:2048
	ds_read_b128 v[210:213], v196 offset:3072
	ds_read_b128 v[214:217], v196 offset:4096
	ds_read_b128 v[218:221], v196 offset:5120
	ds_read_b128 v[222:225], v196 offset:6144
	ds_read_b128 v[226:229], v196 offset:7168
	global_load_lds_dwordx4 v172, s[6:7]
	s_add_i32 m0, s45, 0xe000
	s_nop 0
	global_load_lds_dwordx4 v174, s[6:7]
	s_waitcnt vmcnt(8)
	s_waitcnt lgkmcnt(0)
	s_barrier
	s_setprio 1
	s_waitcnt lgkmcnt(0)
	v_mfma_f32_16x16x32_bf16 v[128:131], v[132:135], v[198:201], v[128:131]
	v_mfma_f32_16x16x32_bf16 v[124:127], v[140:143], v[198:201], v[124:127]
	v_mfma_f32_16x16x32_bf16 v[120:123], v[132:135], v[206:209], v[120:123]
	v_mfma_f32_16x16x32_bf16 v[116:119], v[140:143], v[206:209], v[116:119]
	v_mfma_f32_16x16x32_bf16 v[112:115], v[132:135], v[214:217], v[112:115]
	v_mfma_f32_16x16x32_bf16 v[108:111], v[140:143], v[214:217], v[108:111]
	v_mfma_f32_16x16x32_bf16 v[104:107], v[132:135], v[222:225], v[104:107]
	v_mfma_f32_16x16x32_bf16 v[100:103], v[140:143], v[222:225], v[100:103]
	v_mfma_f32_16x16x32_bf16 v[128:131], v[136:139], v[202:205], v[128:131]
	v_mfma_f32_16x16x32_bf16 v[124:127], v[144:147], v[202:205], v[124:127]
	v_mfma_f32_16x16x32_bf16 v[120:123], v[136:139], v[210:213], v[120:123]
	v_mfma_f32_16x16x32_bf16 v[116:119], v[144:147], v[210:213], v[116:119]
	v_mfma_f32_16x16x32_bf16 v[112:115], v[136:139], v[218:221], v[112:115]
	v_mfma_f32_16x16x32_bf16 v[108:111], v[144:147], v[218:221], v[108:111]
	v_mfma_f32_16x16x32_bf16 v[104:107], v[136:139], v[226:229], v[104:107]
	v_mfma_f32_16x16x32_bf16 v[100:103], v[144:147], v[226:229], v[100:103]
	s_setprio 0
	s_setprio 1
	v_mfma_f32_16x16x32_bf16 v[96:99], v[148:151], v[198:201], v[96:99]
	v_mfma_f32_16x16x32_bf16 v[92:95], v[176:179], v[198:201], v[92:95]
	v_mfma_f32_16x16x32_bf16 v[88:91], v[148:151], v[206:209], v[88:91]
	v_mfma_f32_16x16x32_bf16 v[84:87], v[176:179], v[206:209], v[84:87]
	v_mfma_f32_16x16x32_bf16 v[80:83], v[148:151], v[214:217], v[80:83]
	v_mfma_f32_16x16x32_bf16 v[76:79], v[176:179], v[214:217], v[76:79]
	v_mfma_f32_16x16x32_bf16 v[72:75], v[148:151], v[222:225], v[72:75]
	v_mfma_f32_16x16x32_bf16 v[68:71], v[176:179], v[222:225], v[68:71]
	v_mfma_f32_16x16x32_bf16 v[96:99], v[152:155], v[202:205], v[96:99]
	v_mfma_f32_16x16x32_bf16 v[92:95], v[180:183], v[202:205], v[92:95]
	v_mfma_f32_16x16x32_bf16 v[88:91], v[152:155], v[210:213], v[88:91]
	v_mfma_f32_16x16x32_bf16 v[84:87], v[180:183], v[210:213], v[84:87]
	v_mfma_f32_16x16x32_bf16 v[80:83], v[152:155], v[218:221], v[80:83]
	v_mfma_f32_16x16x32_bf16 v[76:79], v[180:183], v[218:221], v[76:79]
	v_mfma_f32_16x16x32_bf16 v[72:75], v[152:155], v[226:229], v[72:75]
	v_mfma_f32_16x16x32_bf16 v[68:71], v[180:183], v[226:229], v[68:71]
	s_setprio 0
	s_barrier
	s_add_i32 s70, s70, s58
	v_lshl_add_u64 v[184:185], s[8:9], 0, v[166:167]
	s_mov_b32 m0, s70
	ds_read_b128 v[198:201], v196 offset:16384
	ds_read_b128 v[202:205], v196 offset:17408
	ds_read_b128 v[206:209], v196 offset:18432
	ds_read_b128 v[210:213], v196 offset:19456
	ds_read_b128 v[214:217], v196 offset:20480
	ds_read_b128 v[218:221], v196 offset:21504
	ds_read_b128 v[222:225], v196 offset:22528
	ds_read_b128 v[226:229], v196 offset:23552
	global_load_lds_dwordx4 v[184:185], off
	s_add_i32 m0, s70, 0x2000
	s_add_u32 s70, s8, 0x20000
	v_lshl_add_u64 v[230:231], s[8:9], 0, v[164:165]
	s_addc_u32 s71, s9, 0
	s_add_i32 s72, s72, s58
	global_load_lds_dwordx4 v[230:231], off
	s_mov_b32 m0, s72
	v_lshl_add_u64 v[234:235], s[54:55], 0, v[160:161]
	global_load_lds_dwordx4 v166, s[70:71]
	s_add_i32 m0, s72, 0x2000
	v_lshl_add_u64 v[236:237], s[54:55], 0, v[162:163]
	global_load_lds_dwordx4 v164, s[70:71]
	s_mov_b32 m0, s45
	s_nop 0
	global_load_lds_dwordx4 v[234:235], off
	s_mov_b32 m0, s59
	s_nop 0
	global_load_lds_dwordx4 v[236:237], off
	s_waitcnt vmcnt(8)
	s_waitcnt lgkmcnt(0)
	s_barrier
	s_setprio 1
	s_waitcnt lgkmcnt(0)
	v_mfma_f32_16x16x32_bf16 v[64:67], v[132:135], v[198:201], v[64:67]
	v_mfma_f32_16x16x32_bf16 v[60:63], v[140:143], v[198:201], v[60:63]
	v_mfma_f32_16x16x32_bf16 v[56:59], v[132:135], v[206:209], v[56:59]
	v_mfma_f32_16x16x32_bf16 v[52:55], v[140:143], v[206:209], v[52:55]
	v_mfma_f32_16x16x32_bf16 v[48:51], v[132:135], v[214:217], v[48:51]
	v_mfma_f32_16x16x32_bf16 v[44:47], v[140:143], v[214:217], v[44:47]
	v_mfma_f32_16x16x32_bf16 v[40:43], v[132:135], v[222:225], v[40:43]
	v_mfma_f32_16x16x32_bf16 v[36:39], v[140:143], v[222:225], v[36:39]
	v_mfma_f32_16x16x32_bf16 v[64:67], v[136:139], v[202:205], v[64:67]
	v_mfma_f32_16x16x32_bf16 v[60:63], v[144:147], v[202:205], v[60:63]
	v_mfma_f32_16x16x32_bf16 v[56:59], v[136:139], v[210:213], v[56:59]
	v_mfma_f32_16x16x32_bf16 v[52:55], v[144:147], v[210:213], v[52:55]
	v_mfma_f32_16x16x32_bf16 v[48:51], v[136:139], v[218:221], v[48:51]
	v_mfma_f32_16x16x32_bf16 v[44:47], v[144:147], v[218:221], v[44:47]
	v_mfma_f32_16x16x32_bf16 v[40:43], v[136:139], v[226:229], v[40:43]
	v_mfma_f32_16x16x32_bf16 v[36:39], v[144:147], v[226:229], v[36:39]
	s_setprio 0
	s_setprio 1
	v_mfma_f32_16x16x32_bf16 v[32:35], v[148:151], v[198:201], v[32:35]
	v_mfma_f32_16x16x32_bf16 v[28:31], v[176:179], v[198:201], v[28:31]
	v_mfma_f32_16x16x32_bf16 v[24:27], v[148:151], v[206:209], v[24:27]
	v_mfma_f32_16x16x32_bf16 v[20:23], v[176:179], v[206:209], v[20:23]
	v_mfma_f32_16x16x32_bf16 v[16:19], v[148:151], v[214:217], v[16:19]
	v_mfma_f32_16x16x32_bf16 v[12:15], v[176:179], v[214:217], v[12:15]
	v_mfma_f32_16x16x32_bf16 v[8:11], v[148:151], v[222:225], v[8:11]
	v_mfma_f32_16x16x32_bf16 v[2:5], v[176:179], v[222:225], v[4:7]
	v_mfma_f32_16x16x32_bf16 v[32:35], v[152:155], v[202:205], v[32:35]
	v_mfma_f32_16x16x32_bf16 v[28:31], v[180:183], v[202:205], v[28:31]
	v_mfma_f32_16x16x32_bf16 v[24:27], v[152:155], v[210:213], v[24:27]
	v_mfma_f32_16x16x32_bf16 v[20:23], v[180:183], v[210:213], v[20:23]
	v_mfma_f32_16x16x32_bf16 v[16:19], v[152:155], v[218:221], v[16:19]
	v_mfma_f32_16x16x32_bf16 v[12:15], v[180:183], v[218:221], v[12:15]
	v_mfma_f32_16x16x32_bf16 v[8:11], v[152:155], v[226:229], v[8:11]
	v_mfma_f32_16x16x32_bf16 v[2:5], v[180:183], v[226:229], v[2:5]
	s_setprio 0
	s_barrier
	s_add_i32 s70, 0, 0x18000
	v_add_u32_e32 v0, s70, v188
	s_add_i32 s71, 0, 0x1c000
	ds_read_b128 v[132:135], v0
	ds_read_b128 v[136:139], v0 offset:1024
	ds_read_b128 v[140:143], v0 offset:2048
	ds_read_b128 v[144:147], v0 offset:3072
	v_add_u32_e32 v0, s71, v188
	ds_read_b128 v[148:151], v0
	ds_read_b128 v[152:155], v0 offset:1024
	ds_read_b128 v[176:179], v0 offset:2048
	ds_read_b128 v[180:183], v0 offset:3072
	s_add_u32 s54, s54, 0x20000
	s_addc_u32 s55, s55, 0
	s_mov_b32 m0, s60
	ds_read_b128 v[198:201], v196 offset:32768
	ds_read_b128 v[202:205], v196 offset:33792
	ds_read_b128 v[206:209], v196 offset:34816
	ds_read_b128 v[210:213], v196 offset:35840
	ds_read_b128 v[214:217], v196 offset:36864
	ds_read_b128 v[218:221], v196 offset:37888
	ds_read_b128 v[222:225], v196 offset:38912
	ds_read_b128 v[226:229], v196 offset:39936
	global_load_lds_dwordx4 v160, s[54:55]
	s_mov_b32 m0, s61
	s_nop 0
	global_load_lds_dwordx4 v162, s[54:55]
	s_waitcnt vmcnt(8)
	s_waitcnt lgkmcnt(0)
	s_barrier
	s_setprio 1
	s_waitcnt lgkmcnt(0)
	v_mfma_f32_16x16x32_bf16 v[128:131], v[132:135], v[198:201], v[128:131]
	v_mfma_f32_16x16x32_bf16 v[124:127], v[140:143], v[198:201], v[124:127]
	v_mfma_f32_16x16x32_bf16 v[120:123], v[132:135], v[206:209], v[120:123]
	v_mfma_f32_16x16x32_bf16 v[116:119], v[140:143], v[206:209], v[116:119]
	v_mfma_f32_16x16x32_bf16 v[112:115], v[132:135], v[214:217], v[112:115]
	v_mfma_f32_16x16x32_bf16 v[108:111], v[140:143], v[214:217], v[108:111]
	v_mfma_f32_16x16x32_bf16 v[104:107], v[132:135], v[222:225], v[104:107]
	v_mfma_f32_16x16x32_bf16 v[100:103], v[140:143], v[222:225], v[100:103]
	v_mfma_f32_16x16x32_bf16 v[128:131], v[136:139], v[202:205], v[128:131]
	v_mfma_f32_16x16x32_bf16 v[124:127], v[144:147], v[202:205], v[124:127]
	v_mfma_f32_16x16x32_bf16 v[120:123], v[136:139], v[210:213], v[120:123]
	v_mfma_f32_16x16x32_bf16 v[116:119], v[144:147], v[210:213], v[116:119]
	v_mfma_f32_16x16x32_bf16 v[112:115], v[136:139], v[218:221], v[112:115]
	v_mfma_f32_16x16x32_bf16 v[108:111], v[144:147], v[218:221], v[108:111]
	v_mfma_f32_16x16x32_bf16 v[104:107], v[136:139], v[226:229], v[104:107]
	v_mfma_f32_16x16x32_bf16 v[100:103], v[144:147], v[226:229], v[100:103]
	s_setprio 0
	s_setprio 1
	v_mfma_f32_16x16x32_bf16 v[96:99], v[148:151], v[198:201], v[96:99]
	v_mfma_f32_16x16x32_bf16 v[92:95], v[176:179], v[198:201], v[92:95]
	v_mfma_f32_16x16x32_bf16 v[88:91], v[148:151], v[206:209], v[88:91]
	v_mfma_f32_16x16x32_bf16 v[84:87], v[176:179], v[206:209], v[84:87]
	v_mfma_f32_16x16x32_bf16 v[80:83], v[148:151], v[214:217], v[80:83]
	v_mfma_f32_16x16x32_bf16 v[76:79], v[176:179], v[214:217], v[76:79]
	v_mfma_f32_16x16x32_bf16 v[72:75], v[148:151], v[222:225], v[72:75]
	v_mfma_f32_16x16x32_bf16 v[68:71], v[176:179], v[222:225], v[68:71]
	v_mfma_f32_16x16x32_bf16 v[96:99], v[152:155], v[202:205], v[96:99]
	v_mfma_f32_16x16x32_bf16 v[92:95], v[180:183], v[202:205], v[92:95]
	v_mfma_f32_16x16x32_bf16 v[88:91], v[152:155], v[210:213], v[88:91]
	v_mfma_f32_16x16x32_bf16 v[84:87], v[180:183], v[210:213], v[84:87]
	v_mfma_f32_16x16x32_bf16 v[80:83], v[152:155], v[218:221], v[80:83]
	v_mfma_f32_16x16x32_bf16 v[76:79], v[180:183], v[218:221], v[76:79]
	v_mfma_f32_16x16x32_bf16 v[72:75], v[152:155], v[226:229], v[72:75]
	v_mfma_f32_16x16x32_bf16 v[68:71], v[180:183], v[226:229], v[68:71]
	s_setprio 0
	s_barrier
	s_add_i32 s54, s70, s58
	v_lshl_add_u64 v[6:7], v[184:185], 0, s[14:15]
	s_mov_b32 m0, s54
	ds_read_b128 v[198:201], v196 offset:49152
	ds_read_b128 v[202:205], v196 offset:50176
	ds_read_b128 v[206:209], v196 offset:51200
	ds_read_b128 v[210:213], v196 offset:52224
	ds_read_b128 v[214:217], v196 offset:53248
	ds_read_b128 v[218:221], v196 offset:54272
	ds_read_b128 v[222:225], v196 offset:55296
	ds_read_b128 v[226:229], v196 offset:56320
	global_load_lds_dwordx4 v[6:7], off
	s_add_i32 m0, s54, 0x2000
	s_add_u32 s8, s8, 0x20080
	v_lshl_add_u64 v[6:7], v[230:231], 0, s[14:15]
	s_addc_u32 s9, s9, 0
	s_add_i32 s54, s71, s58
	global_load_lds_dwordx4 v[6:7], off
	s_mov_b32 m0, s54
	s_nop 0
	global_load_lds_dwordx4 v166, s[8:9]
	s_add_i32 m0, s54, 0x2000
	s_nop 0
	global_load_lds_dwordx4 v164, s[8:9]
	v_lshl_add_u64 v[6:7], v[234:235], 0, s[14:15]
	s_mov_b32 m0, s63
	s_nop 0
	global_load_lds_dwordx4 v[6:7], off
	v_lshl_add_u64 v[6:7], v[236:237], 0, s[14:15]
	s_mov_b32 m0, s64
	s_nop 0
	global_load_lds_dwordx4 v[6:7], off
	s_waitcnt vmcnt(8)
	s_waitcnt lgkmcnt(0)
	s_barrier
	s_setprio 1
	s_waitcnt lgkmcnt(0)
	v_mfma_f32_16x16x32_bf16 v[64:67], v[132:135], v[198:201], v[64:67]
	v_mfma_f32_16x16x32_bf16 v[60:63], v[140:143], v[198:201], v[60:63]
	v_mfma_f32_16x16x32_bf16 v[56:59], v[132:135], v[206:209], v[56:59]
	v_mfma_f32_16x16x32_bf16 v[52:55], v[140:143], v[206:209], v[52:55]
	v_mfma_f32_16x16x32_bf16 v[48:51], v[132:135], v[214:217], v[48:51]
	v_mfma_f32_16x16x32_bf16 v[44:47], v[140:143], v[214:217], v[44:47]
	v_mfma_f32_16x16x32_bf16 v[40:43], v[132:135], v[222:225], v[40:43]
	v_mfma_f32_16x16x32_bf16 v[36:39], v[140:143], v[222:225], v[36:39]
	v_mfma_f32_16x16x32_bf16 v[64:67], v[136:139], v[202:205], v[64:67]
	v_mfma_f32_16x16x32_bf16 v[60:63], v[144:147], v[202:205], v[60:63]
	v_mfma_f32_16x16x32_bf16 v[56:59], v[136:139], v[210:213], v[56:59]
	v_mfma_f32_16x16x32_bf16 v[52:55], v[144:147], v[210:213], v[52:55]
	v_mfma_f32_16x16x32_bf16 v[48:51], v[136:139], v[218:221], v[48:51]
	v_mfma_f32_16x16x32_bf16 v[44:47], v[144:147], v[218:221], v[44:47]
	v_mfma_f32_16x16x32_bf16 v[40:43], v[136:139], v[226:229], v[40:43]
	v_mfma_f32_16x16x32_bf16 v[36:39], v[144:147], v[226:229], v[36:39]
	s_setprio 0
	s_setprio 1
	v_mfma_f32_16x16x32_bf16 v[32:35], v[148:151], v[198:201], v[32:35]
	v_mfma_f32_16x16x32_bf16 v[28:31], v[176:179], v[198:201], v[28:31]
	v_mfma_f32_16x16x32_bf16 v[24:27], v[148:151], v[206:209], v[24:27]
	v_mfma_f32_16x16x32_bf16 v[20:23], v[176:179], v[206:209], v[20:23]
	v_mfma_f32_16x16x32_bf16 v[16:19], v[148:151], v[214:217], v[16:19]
	v_mfma_f32_16x16x32_bf16 v[12:15], v[176:179], v[214:217], v[12:15]
	v_mfma_f32_16x16x32_bf16 v[6:9], v[148:151], v[222:225], v[8:11]
	v_mfma_f32_16x16x32_bf16 v[2:5], v[176:179], v[222:225], v[2:5]
	v_mfma_f32_16x16x32_bf16 v[32:35], v[152:155], v[202:205], v[32:35]
	v_mfma_f32_16x16x32_bf16 v[28:31], v[180:183], v[202:205], v[28:31]
	v_mfma_f32_16x16x32_bf16 v[24:27], v[152:155], v[210:213], v[24:27]
	v_mfma_f32_16x16x32_bf16 v[20:23], v[180:183], v[210:213], v[20:23]
	v_mfma_f32_16x16x32_bf16 v[16:19], v[152:155], v[218:221], v[16:19]
	v_mfma_f32_16x16x32_bf16 v[12:15], v[180:183], v[218:221], v[12:15]
	v_mfma_f32_16x16x32_bf16 v[8:11], v[152:155], v[226:229], v[6:9]
	v_mfma_f32_16x16x32_bf16 v[4:7], v[180:183], v[226:229], v[2:5]
	s_setprio 0
	s_barrier
	s_add_i32 s69, s69, 2
	s_add_u32 s6, s6, 0x100
	s_addc_u32 s7, s7, 0
	s_add_u32 s67, s67, 0x100
	s_addc_u32 s68, s68, 0
	s_cmp_gt_u32 s69, 5
	s_cbranch_scc0 .LBB0_955
	s_and_b64 vcc, exec, s[34:35]
	s_cbranch_vccz .LBB0_958
	s_barrier

.LBB0_1157:
	s_cmp_ge_u32 s72, s1
	s_cselect_b64 s[20:21], -1, 0
	s_add_u32 s22, s10, 0x2700000
	s_addc_u32 s23, s11, 0
	s_add_u32 s24, s10, 0x300000
	s_addc_u32 s25, s11, 0
	s_add_u32 s9, s10, 0xef00000
	v_readlane_b32 s6, v254, 6
	s_addc_u32 s14, s11, 0
	v_readlane_b32 s7, v254, 7
	s_and_b64 s[6:7], s[6:7], exec
	s_cselect_b32 s27, s14, 0
	s_cselect_b32 s26, s9, 0
	s_add_u32 s28, s10, 0x380000
	s_addc_u32 s29, s11, 0
	s_add_u32 s30, s10, 0xff00000
	s_addc_u32 s31, s11, 0
	s_add_u32 s83, s10, 0x208000
	s_addc_u32 s84, s11, 0
	s_and_b32 s9, s4, 3
	s_add_i32 m0, s79, 0x18000
	v_lshl_add_u64 v[8:9], v[8:9], 0, s[16:17]
	s_lshl_b32 s4, s5, 13
	s_lshl_b32 s34, s9, 5
	s_lshl_b32 s14, s9, 12
	s_waitcnt vmcnt(2)
	s_barrier
	global_load_lds_dwordx4 v[8:9], off
	v_lshl_add_u64 v[6:7], v[6:7], 0, s[16:17]
	s_add_i32 m0, s79, 0x1a000
	s_add_i32 s85, s79, 0x8000
	s_add_i32 s86, s79, 0xa000
	global_load_lds_dwordx4 v[6:7], off
	v_lshl_add_u64 v[2:3], v[2:3], 0, s[16:17]
	s_mov_b32 m0, s85
	s_add_u32 s6, s60, 0x40080
	global_load_lds_dwordx4 v[2:3], off
	v_lshl_add_u64 v[2:3], v[4:5], 0, s[16:17]
	s_mov_b32 m0, s86
	s_addc_u32 s7, s61, 0
	global_load_lds_dwordx4 v[2:3], off
	s_add_i32 m0, s79, 0x1c000
	s_nop 0
	global_load_lds_dwordx4 v136, s[6:7]
	s_add_i32 m0, s79, 0x1e000
	v_lshlrev_b32_e32 v6, 2, v166
	global_load_lds_dwordx4 v140, s[6:7]
	v_bfe_u32 v2, v166, 4, 2
	v_and_b32_e32 v3, 15, v166
	v_lshl_or_b32 v168, s5, 6, v3
	v_lshlrev_b32_e32 v4, 4, v2
	v_lshl_or_b32 v3, v3, 6, v4
	v_lshlrev_b32_e32 v4, 2, v168
	v_and_b32_e32 v5, 32, v4
	v_and_b32_e32 v6, 32, v6
	v_bitop3_b32 v5, v3, s4, v5 bitop3:0xde
	v_bitop3_b32 v169, v3, s14, v6 bitop3:0xde
	v_lshlrev_b32_e32 v3, 14, v0
	s_cmpk_lt_u32 s8, 0x100
	v_and_b32_e32 v3, 0xffff8000, v3
	s_cselect_b64 s[38:39], -1, 0
	s_lshl_b32 s6, s9, 2
	v_lshl_add_u32 v3, v10, 11, v3
	v_and_b32_e32 v0, 1, v0
	v_add_u32_e32 v170, 0x80, v168
	s_add_i32 s6, s6, s33
	v_lshl_or_b32 v0, v0, 6, v3
	v_lshlrev_b32_e32 v142, 3, v2
	v_cmp_eq_u32_e64 s[4:5], 0, v2
	v_lshl_add_u32 v177, v168, 4, s6
	v_lshl_add_u32 v178, v170, 4, s6
	s_movk_i32 s6, 0x100
	v_and_b32_e32 v2, 63, v166
	v_lshl_add_u32 v144, v11, 1, v0
	v_lshlrev_b32_e32 v0, 14, v12
	v_cmp_gt_i32_e64 s[6:7], s6, v166
	v_cmp_eq_u32_e32 vcc, 0, v2
	v_and_b32_e32 v0, 0xffff8000, v0
	s_waitcnt vmcnt(6)
	s_ashr_i32 s88, s73, 31
	s_and_b64 s[40:41], s[6:7], vcc
	v_lshl_add_u32 v0, v13, 11, v0
	v_and_b32_e32 v3, 1, v12
	v_or_b32_e32 v171, 16, v168
	v_or_b32_e32 v172, 32, v168
	v_or_b32_e32 v173, 48, v168
	v_add_u32_e32 v174, 0x90, v168
	v_add_u32_e32 v175, 0xa0, v168
	v_add_u32_e32 v176, 0xb0, v168
	v_add_u32_e32 v179, s33, v167
	s_add_u32 s42, s10, 0x200200
	v_mul_lo_u32 v2, v166, -12
	v_lshl_or_b32 v0, v3, 6, v0
	s_mov_b32 s87, 0
	s_mov_b32 s35, s15
	v_mov_b32_e32 v143, v1
	v_cmp_eq_u32_e64 s[8:9], 0, v166
	s_addc_u32 s43, s11, 0
	s_waitcnt vmcnt(0)
	v_add_u32_e32 v180, s33, v4
	v_lshl_add_u32 v181, v171, 2, s33
	v_lshl_add_u32 v182, v172, 2, s33
	v_lshl_add_u32 v183, v173, 2, s33
	v_lshl_add_u32 v184, v170, 2, s33
	v_lshl_add_u32 v185, v174, 2, s33
	v_lshl_add_u32 v186, v175, 2, s33
	v_lshl_add_u32 v187, v176, 2, s33
	v_mov_b32_e32 v145, v1
	v_lshl_add_u32 v146, v14, 1, v0
	v_mov_b32_e32 v147, v1
	v_add_u32_e32 v188, 0, v5
	v_add_u32_e32 v189, v179, v2
	s_barrier
	s_branch .LBB0_1160

.LBB0_1167:
	s_add_u32 s60, s48, 0xfffc0080
	s_addc_u32 s61, s49, -1
	s_add_i32 s66, 0, 0x10000
	s_cmp_eq_u32 s65, 12
	s_cselect_b32 s63, s14, s61
	s_cselect_b32 s62, s51, s60
	v_add_u32_e32 v0, s66, v169
	s_cselect_b32 s61, s45, s64
	s_cselect_b32 s60, s57, s59
	s_add_i32 s68, 0, 0x14000
	ds_read_b128 v[148:151], v0
	ds_read_b128 v[152:155], v0 offset:1024
	ds_read_b128 v[156:159], v0 offset:2048
	ds_read_b128 v[190:193], v0 offset:3072
	v_add_u32_e32 v0, s68, v169
	ds_read_b128 v[194:197], v0
	ds_read_b128 v[198:201], v0 offset:1024
	ds_read_b128 v[202:205], v0 offset:2048
	ds_read_b128 v[206:209], v0 offset:3072
	s_add_i32 m0, s79, 0xc000
	ds_read_b128 v[210:213], v188
	ds_read_b128 v[214:217], v188 offset:1024
	ds_read_b128 v[218:221], v188 offset:2048
	ds_read_b128 v[222:225], v188 offset:3072
	ds_read_b128 v[226:229], v188 offset:4096
	ds_read_b128 v[234:237], v188 offset:5120
	ds_read_b128 v[238:241], v188 offset:6144
	ds_read_b128 v[242:245], v188 offset:7168
	global_load_lds_dwordx4 v144, s[48:49]
	s_add_i32 m0, s79, 0xe000
	s_nop 0
	global_load_lds_dwordx4 v146, s[48:49]
	s_waitcnt vmcnt(8)
	s_waitcnt lgkmcnt(0)
	s_barrier
	s_setprio 1
	s_waitcnt lgkmcnt(0)
	v_mfma_f32_16x16x32_bf16 v[126:129], v[148:151], v[210:213], v[126:129]
	v_mfma_f32_16x16x32_bf16 v[122:125], v[156:159], v[210:213], v[122:125]
	v_mfma_f32_16x16x32_bf16 v[110:113], v[148:151], v[218:221], v[110:113]
	v_mfma_f32_16x16x32_bf16 v[106:109], v[156:159], v[218:221], v[106:109]
	v_mfma_f32_16x16x32_bf16 v[94:97], v[148:151], v[226:229], v[94:97]
	v_mfma_f32_16x16x32_bf16 v[90:93], v[156:159], v[226:229], v[90:93]
	v_mfma_f32_16x16x32_bf16 v[78:81], v[148:151], v[238:241], v[78:81]
	v_mfma_f32_16x16x32_bf16 v[74:77], v[156:159], v[238:241], v[74:77]
	v_mfma_f32_16x16x32_bf16 v[126:129], v[152:155], v[214:217], v[126:129]
	v_mfma_f32_16x16x32_bf16 v[122:125], v[190:193], v[214:217], v[122:125]
	v_mfma_f32_16x16x32_bf16 v[110:113], v[152:155], v[222:225], v[110:113]
	v_mfma_f32_16x16x32_bf16 v[106:109], v[190:193], v[222:225], v[106:109]
	v_mfma_f32_16x16x32_bf16 v[94:97], v[152:155], v[234:237], v[94:97]
	v_mfma_f32_16x16x32_bf16 v[90:93], v[190:193], v[234:237], v[90:93]
	v_mfma_f32_16x16x32_bf16 v[78:81], v[152:155], v[242:245], v[78:81]
	v_mfma_f32_16x16x32_bf16 v[74:77], v[190:193], v[242:245], v[74:77]
	s_setprio 0
	s_setprio 1
	v_mfma_f32_16x16x32_bf16 v[118:121], v[194:197], v[210:213], v[118:121]
	v_mfma_f32_16x16x32_bf16 v[114:117], v[202:205], v[210:213], v[114:117]
	v_mfma_f32_16x16x32_bf16 v[102:105], v[194:197], v[218:221], v[102:105]
	v_mfma_f32_16x16x32_bf16 v[98:101], v[202:205], v[218:221], v[98:101]
	v_mfma_f32_16x16x32_bf16 v[86:89], v[194:197], v[226:229], v[86:89]
	v_mfma_f32_16x16x32_bf16 v[82:85], v[202:205], v[226:229], v[82:85]
	v_mfma_f32_16x16x32_bf16 v[70:73], v[194:197], v[238:241], v[70:73]
	v_mfma_f32_16x16x32_bf16 v[66:69], v[202:205], v[238:241], v[66:69]
	v_mfma_f32_16x16x32_bf16 v[118:121], v[198:201], v[214:217], v[118:121]
	v_mfma_f32_16x16x32_bf16 v[114:117], v[206:209], v[214:217], v[114:117]
	v_mfma_f32_16x16x32_bf16 v[102:105], v[198:201], v[222:225], v[102:105]
	v_mfma_f32_16x16x32_bf16 v[98:101], v[206:209], v[222:225], v[98:101]
	v_mfma_f32_16x16x32_bf16 v[86:89], v[198:201], v[234:237], v[86:89]
	v_mfma_f32_16x16x32_bf16 v[82:85], v[206:209], v[234:237], v[82:85]
	v_mfma_f32_16x16x32_bf16 v[70:73], v[198:201], v[242:245], v[70:73]
	v_mfma_f32_16x16x32_bf16 v[66:69], v[206:209], v[242:245], v[66:69]
	s_setprio 0
	s_barrier
	s_add_i32 s66, s66, s78
	v_lshl_add_u64 v[230:231], s[60:61], 0, v[136:137]
	s_mov_b32 m0, s66
	ds_read_b128 v[210:213], v188 offset:16384
	ds_read_b128 v[214:217], v188 offset:17408
	ds_read_b128 v[218:221], v188 offset:18432
	ds_read_b128 v[222:225], v188 offset:19456
	ds_read_b128 v[226:229], v188 offset:20480
	ds_read_b128 v[234:237], v188 offset:21504
	ds_read_b128 v[238:241], v188 offset:22528
	ds_read_b128 v[242:245], v188 offset:23552
	global_load_lds_dwordx4 v[230:231], off
	s_add_i32 m0, s66, 0x2000
	s_add_u32 s66, s60, 0x40000
	v_lshl_add_u64 v[246:247], s[60:61], 0, v[140:141]
	s_addc_u32 s67, s61, 0
	s_add_i32 s68, s68, s78
	global_load_lds_dwordx4 v[246:247], off
	s_mov_b32 m0, s68
	v_lshl_add_u64 v[250:251], s[62:63], 0, v[138:139]
	global_load_lds_dwordx4 v136, s[66:67]
	s_add_i32 m0, s68, 0x2000
	s_nop 0
	global_load_lds_dwordx4 v140, s[66:67]
	v_lshl_add_u64 v[248:249], s[62:63], 0, v[134:135]
	s_mov_b32 m0, s79
	s_nop 0
	global_load_lds_dwordx4 v[248:249], off
	s_mov_b32 m0, s80
	s_nop 0
	global_load_lds_dwordx4 v[250:251], off
	s_waitcnt vmcnt(8)
	s_waitcnt lgkmcnt(0)
	s_barrier
	s_setprio 1
	s_waitcnt lgkmcnt(0)
	v_mfma_f32_16x16x32_bf16 v[62:65], v[148:151], v[210:213], v[62:65]
	v_mfma_f32_16x16x32_bf16 v[58:61], v[156:159], v[210:213], v[58:61]
	v_mfma_f32_16x16x32_bf16 v[46:49], v[148:151], v[218:221], v[46:49]
	v_mfma_f32_16x16x32_bf16 v[42:45], v[156:159], v[218:221], v[42:45]
	v_mfma_f32_16x16x32_bf16 v[30:33], v[148:151], v[226:229], v[30:33]
	v_mfma_f32_16x16x32_bf16 v[26:29], v[156:159], v[226:229], v[26:29]
	v_mfma_f32_16x16x32_bf16 v[14:17], v[148:151], v[238:241], v[14:17]
	v_mfma_f32_16x16x32_bf16 v[10:13], v[156:159], v[238:241], v[10:13]
	v_mfma_f32_16x16x32_bf16 v[62:65], v[152:155], v[214:217], v[62:65]
	v_mfma_f32_16x16x32_bf16 v[58:61], v[190:193], v[214:217], v[58:61]
	v_mfma_f32_16x16x32_bf16 v[46:49], v[152:155], v[222:225], v[46:49]
	v_mfma_f32_16x16x32_bf16 v[42:45], v[190:193], v[222:225], v[42:45]
	v_mfma_f32_16x16x32_bf16 v[30:33], v[152:155], v[234:237], v[30:33]
	v_mfma_f32_16x16x32_bf16 v[26:29], v[190:193], v[234:237], v[26:29]
	v_mfma_f32_16x16x32_bf16 v[14:17], v[152:155], v[242:245], v[14:17]
	v_mfma_f32_16x16x32_bf16 v[10:13], v[190:193], v[242:245], v[10:13]
	s_setprio 0
	s_setprio 1
	v_mfma_f32_16x16x32_bf16 v[54:57], v[194:197], v[210:213], v[54:57]
	v_mfma_f32_16x16x32_bf16 v[50:53], v[202:205], v[210:213], v[50:53]
	v_mfma_f32_16x16x32_bf16 v[38:41], v[194:197], v[218:221], v[38:41]
	v_mfma_f32_16x16x32_bf16 v[34:37], v[202:205], v[218:221], v[34:37]
	v_mfma_f32_16x16x32_bf16 v[22:25], v[194:197], v[226:229], v[22:25]
	v_mfma_f32_16x16x32_bf16 v[18:21], v[202:205], v[226:229], v[18:21]
	v_mfma_f32_16x16x32_bf16 v[6:9], v[194:197], v[238:241], v[6:9]
	v_mfma_f32_16x16x32_bf16 v[2:5], v[202:205], v[238:241], v[2:5]
	v_mfma_f32_16x16x32_bf16 v[54:57], v[198:201], v[214:217], v[54:57]
	v_mfma_f32_16x16x32_bf16 v[50:53], v[206:209], v[214:217], v[50:53]
	v_mfma_f32_16x16x32_bf16 v[38:41], v[198:201], v[222:225], v[38:41]
	v_mfma_f32_16x16x32_bf16 v[34:37], v[206:209], v[222:225], v[34:37]
	v_mfma_f32_16x16x32_bf16 v[22:25], v[198:201], v[234:237], v[22:25]
	v_mfma_f32_16x16x32_bf16 v[18:21], v[206:209], v[234:237], v[18:21]
	v_mfma_f32_16x16x32_bf16 v[6:9], v[198:201], v[242:245], v[6:9]
	v_mfma_f32_16x16x32_bf16 v[2:5], v[206:209], v[242:245], v[2:5]
	s_setprio 0
	s_barrier
	s_add_i32 s66, 0, 0x18000
	v_add_u32_e32 v0, s66, v169
	s_add_i32 s67, 0, 0x1c000
	ds_read_b128 v[148:151], v0
	ds_read_b128 v[152:155], v0 offset:1024
	ds_read_b128 v[156:159], v0 offset:2048
	ds_read_b128 v[190:193], v0 offset:3072
	v_add_u32_e32 v0, s67, v169
	ds_read_b128 v[194:197], v0
	ds_read_b128 v[198:201], v0 offset:1024
	ds_read_b128 v[202:205], v0 offset:2048
	ds_read_b128 v[206:209], v0 offset:3072
	s_add_u32 s62, s62, 0x40000
	s_addc_u32 s63, s63, 0
	s_mov_b32 m0, s81
	ds_read_b128 v[210:213], v188 offset:32768
	ds_read_b128 v[214:217], v188 offset:33792
	ds_read_b128 v[218:221], v188 offset:34816
	ds_read_b128 v[222:225], v188 offset:35840
	ds_read_b128 v[226:229], v188 offset:36864
	ds_read_b128 v[234:237], v188 offset:37888
	ds_read_b128 v[238:241], v188 offset:38912
	ds_read_b128 v[242:245], v188 offset:39936
	global_load_lds_dwordx4 v134, s[62:63]
	s_mov_b32 m0, s82
	s_nop 0
	global_load_lds_dwordx4 v138, s[62:63]
	s_waitcnt vmcnt(8)
	s_waitcnt lgkmcnt(0)
	s_barrier
	s_setprio 1
	s_waitcnt lgkmcnt(0)
	v_mfma_f32_16x16x32_bf16 v[126:129], v[148:151], v[210:213], v[126:129]
	v_mfma_f32_16x16x32_bf16 v[122:125], v[156:159], v[210:213], v[122:125]
	v_mfma_f32_16x16x32_bf16 v[110:113], v[148:151], v[218:221], v[110:113]
	v_mfma_f32_16x16x32_bf16 v[106:109], v[156:159], v[218:221], v[106:109]
	v_mfma_f32_16x16x32_bf16 v[94:97], v[148:151], v[226:229], v[94:97]
	v_mfma_f32_16x16x32_bf16 v[90:93], v[156:159], v[226:229], v[90:93]
	v_mfma_f32_16x16x32_bf16 v[78:81], v[148:151], v[238:241], v[78:81]
	v_mfma_f32_16x16x32_bf16 v[74:77], v[156:159], v[238:241], v[74:77]
	v_mfma_f32_16x16x32_bf16 v[126:129], v[152:155], v[214:217], v[126:129]
	v_mfma_f32_16x16x32_bf16 v[122:125], v[190:193], v[214:217], v[122:125]
	v_mfma_f32_16x16x32_bf16 v[110:113], v[152:155], v[222:225], v[110:113]
	v_mfma_f32_16x16x32_bf16 v[106:109], v[190:193], v[222:225], v[106:109]
	v_mfma_f32_16x16x32_bf16 v[94:97], v[152:155], v[234:237], v[94:97]
	v_mfma_f32_16x16x32_bf16 v[90:93], v[190:193], v[234:237], v[90:93]
	v_mfma_f32_16x16x32_bf16 v[78:81], v[152:155], v[242:245], v[78:81]
	v_mfma_f32_16x16x32_bf16 v[74:77], v[190:193], v[242:245], v[74:77]
	s_setprio 0
	s_setprio 1
	v_mfma_f32_16x16x32_bf16 v[118:121], v[194:197], v[210:213], v[118:121]
	v_mfma_f32_16x16x32_bf16 v[114:117], v[202:205], v[210:213], v[114:117]
	v_mfma_f32_16x16x32_bf16 v[102:105], v[194:197], v[218:221], v[102:105]
	v_mfma_f32_16x16x32_bf16 v[98:101], v[202:205], v[218:221], v[98:101]
	v_mfma_f32_16x16x32_bf16 v[86:89], v[194:197], v[226:229], v[86:89]
	v_mfma_f32_16x16x32_bf16 v[82:85], v[202:205], v[226:229], v[82:85]
	v_mfma_f32_16x16x32_bf16 v[70:73], v[194:197], v[238:241], v[70:73]
	v_mfma_f32_16x16x32_bf16 v[66:69], v[202:205], v[238:241], v[66:69]
	v_mfma_f32_16x16x32_bf16 v[118:121], v[198:201], v[214:217], v[118:121]
	v_mfma_f32_16x16x32_bf16 v[114:117], v[206:209], v[214:217], v[114:117]
	v_mfma_f32_16x16x32_bf16 v[102:105], v[198:201], v[222:225], v[102:105]
	v_mfma_f32_16x16x32_bf16 v[98:101], v[206:209], v[222:225], v[98:101]
	v_mfma_f32_16x16x32_bf16 v[86:89], v[198:201], v[234:237], v[86:89]
	v_mfma_f32_16x16x32_bf16 v[82:85], v[206:209], v[234:237], v[82:85]
	v_mfma_f32_16x16x32_bf16 v[70:73], v[198:201], v[242:245], v[70:73]
	v_mfma_f32_16x16x32_bf16 v[66:69], v[206:209], v[242:245], v[66:69]
	s_setprio 0
	s_barrier
	s_add_i32 s62, s66, s78
	v_lshl_add_u64 v[230:231], v[230:231], 0, s[16:17]
	s_mov_b32 m0, s62
	ds_read_b128 v[210:213], v188 offset:49152
	ds_read_b128 v[214:217], v188 offset:50176
	ds_read_b128 v[218:221], v188 offset:51200
	ds_read_b128 v[222:225], v188 offset:52224
	ds_read_b128 v[226:229], v188 offset:53248
	ds_read_b128 v[234:237], v188 offset:54272
	ds_read_b128 v[238:241], v188 offset:55296
	ds_read_b128 v[242:245], v188 offset:56320
	global_load_lds_dwordx4 v[230:231], off
	s_add_i32 m0, s62, 0x2000
	s_add_u32 s60, s60, 0x40080
	v_lshl_add_u64 v[230:231], v[246:247], 0, s[16:17]
	s_addc_u32 s61, s61, 0
	s_add_i32 s62, s67, s78
	global_load_lds_dwordx4 v[230:231], off
	s_mov_b32 m0, s62
	s_nop 0
	global_load_lds_dwordx4 v136, s[60:61]
	s_add_i32 m0, s62, 0x2000
	s_nop 0
	global_load_lds_dwordx4 v140, s[60:61]
	v_lshl_add_u64 v[230:231], v[248:249], 0, s[16:17]
	s_mov_b32 m0, s85
	s_nop 0
	global_load_lds_dwordx4 v[230:231], off
	v_lshl_add_u64 v[230:231], v[250:251], 0, s[16:17]
	s_mov_b32 m0, s86
	s_nop 0
	global_load_lds_dwordx4 v[230:231], off
	s_waitcnt vmcnt(8)
	s_waitcnt lgkmcnt(0)
	s_barrier
	s_setprio 1
	s_waitcnt lgkmcnt(0)
	v_mfma_f32_16x16x32_bf16 v[62:65], v[148:151], v[210:213], v[62:65]
	v_mfma_f32_16x16x32_bf16 v[58:61], v[156:159], v[210:213], v[58:61]
	v_mfma_f32_16x16x32_bf16 v[46:49], v[148:151], v[218:221], v[46:49]
	v_mfma_f32_16x16x32_bf16 v[42:45], v[156:159], v[218:221], v[42:45]
	v_mfma_f32_16x16x32_bf16 v[30:33], v[148:151], v[226:229], v[30:33]
	v_mfma_f32_16x16x32_bf16 v[26:29], v[156:159], v[226:229], v[26:29]
	v_mfma_f32_16x16x32_bf16 v[14:17], v[148:151], v[238:241], v[14:17]
	v_mfma_f32_16x16x32_bf16 v[10:13], v[156:159], v[238:241], v[10:13]
	v_mfma_f32_16x16x32_bf16 v[62:65], v[152:155], v[214:217], v[62:65]
	v_mfma_f32_16x16x32_bf16 v[58:61], v[190:193], v[214:217], v[58:61]
	v_mfma_f32_16x16x32_bf16 v[46:49], v[152:155], v[222:225], v[46:49]
	v_mfma_f32_16x16x32_bf16 v[42:45], v[190:193], v[222:225], v[42:45]
	v_mfma_f32_16x16x32_bf16 v[30:33], v[152:155], v[234:237], v[30:33]
	v_mfma_f32_16x16x32_bf16 v[26:29], v[190:193], v[234:237], v[26:29]
	v_mfma_f32_16x16x32_bf16 v[14:17], v[152:155], v[242:245], v[14:17]
	v_mfma_f32_16x16x32_bf16 v[10:13], v[190:193], v[242:245], v[10:13]
	s_setprio 0
	s_setprio 1
	v_mfma_f32_16x16x32_bf16 v[54:57], v[194:197], v[210:213], v[54:57]
	v_mfma_f32_16x16x32_bf16 v[50:53], v[202:205], v[210:213], v[50:53]
	v_mfma_f32_16x16x32_bf16 v[38:41], v[194:197], v[218:221], v[38:41]
	v_mfma_f32_16x16x32_bf16 v[34:37], v[202:205], v[218:221], v[34:37]
	v_mfma_f32_16x16x32_bf16 v[22:25], v[194:197], v[226:229], v[22:25]
	v_mfma_f32_16x16x32_bf16 v[18:21], v[202:205], v[226:229], v[18:21]
	v_mfma_f32_16x16x32_bf16 v[6:9], v[194:197], v[238:241], v[6:9]
	v_mfma_f32_16x16x32_bf16 v[2:5], v[202:205], v[238:241], v[2:5]
	v_mfma_f32_16x16x32_bf16 v[54:57], v[198:201], v[214:217], v[54:57]
	v_mfma_f32_16x16x32_bf16 v[50:53], v[206:209], v[214:217], v[50:53]
	v_mfma_f32_16x16x32_bf16 v[38:41], v[198:201], v[222:225], v[38:41]
	v_mfma_f32_16x16x32_bf16 v[34:37], v[206:209], v[222:225], v[34:37]
	v_mfma_f32_16x16x32_bf16 v[22:25], v[198:201], v[234:237], v[22:25]
	v_mfma_f32_16x16x32_bf16 v[18:21], v[206:209], v[234:237], v[18:21]
	v_mfma_f32_16x16x32_bf16 v[6:9], v[198:201], v[242:245], v[6:9]
	v_mfma_f32_16x16x32_bf16 v[2:5], v[206:209], v[242:245], v[2:5]
	s_setprio 0
	s_barrier
	s_add_i32 s65, s65, 2
	s_add_u32 s48, s48, 0x100
	s_addc_u32 s49, s49, 0
	s_add_u32 s59, s59, 0x100
	s_addc_u32 s64, s64, 0
	s_cmp_gt_u32 s65, 13
	s_cbranch_scc0 .LBB0_1167
	s_and_b64 vcc, exec, s[38:39]
	s_cbranch_vccz .LBB0_1171
	s_barrier
	s_andn2_b64 vcc, exec, s[20:21]
	s_cbranch_vccz .LBB0_1172

.LBB0_1464:
	s_cmp_ge_u32 s67, s0
	v_and_b32_e32 v18, 15, v1
	s_cselect_b64 s[34:35], -1, 0
	s_add_u32 s30, s30, 0x7700000
	v_or_b32_e32 v221, s38, v18
	s_addc_u32 s31, s31, 0
	v_lshlrev_b32_e32 v19, 6, v221
	v_and_b32_e32 v20, 48, v1
	s_movk_i32 s38, 0x3c0
	v_lshlrev_b32_e32 v21, 2, v221
	s_add_i32 s80, s55, 0x18000
	v_and_or_b32 v19, v19, s38, v20
	s_lshl_b32 s38, s43, 13
	v_and_b32_e32 v21, 32, v21
	v_lshlrev_b32_e32 v1, 2, v1
	v_lshl_add_u64 v[10:11], v[10:11], 0, s[20:21]
	s_mov_b32 m0, s80
	s_add_i32 s81, s55, 0x1a000
	s_or_b64 s[34:35], s[34:35], s[18:19]
	v_bitop3_b32 v19, v19, s38, v21 bitop3:0xde
	s_lshl_b32 s79, s42, 5
	v_lshl_or_b32 v20, v18, 6, v20
	s_lshl_b32 s38, s42, 12
	v_and_b32_e32 v1, 32, v1
	s_waitcnt vmcnt(2)
	s_barrier
	global_load_lds_dwordx4 v[10:11], off
	v_lshl_add_u64 v[8:9], v[8:9], 0, s[20:21]
	s_mov_b32 m0, s81
	s_add_i32 s82, s55, 0x8000
	s_add_i32 s83, s55, 0xa000
	v_bitop3_b32 v1, s38, v20, v1 bitop3:0xf6
	global_load_lds_dwordx4 v[8:9], off
	v_lshl_add_u64 v[4:5], v[4:5], 0, s[20:21]
	s_mov_b32 m0, s82
	s_add_u32 s38, s6, 0x20080
	global_load_lds_dwordx4 v[4:5], off
	v_lshl_add_u64 v[4:5], v[6:7], 0, s[20:21]
	s_mov_b32 m0, s83
	s_addc_u32 s39, s7, 0
	s_add_i32 s84, s55, 0x1c000
	global_load_lds_dwordx4 v[4:5], off
	s_mov_b32 m0, s84
	s_add_i32 s85, s55, 0x1e000
	global_load_lds_dwordx4 v200, s[38:39]
	v_lshl_add_u64 v[4:5], s[38:39], 0, v[204:205]
	s_mov_b32 m0, s85
	s_cmpk_lt_u32 s12, 0x100
	global_load_lds_dwordx4 v[4:5], off
	s_cselect_b64 s[38:39], -1, 0
	s_lshl_b32 s12, s43, 11
	s_add_i32 s86, s12, 0
	s_lshl_b32 s12, s42, 7
	s_add_i32 s12, s12, 0
	v_lshrrev_b32_e32 v3, 4, v3
	s_add_i32 s12, s12, 0x23000
	v_lshl_add_u32 v229, v3, 5, s12
	s_ashr_i32 s12, s68, 1
	s_add_i32 s12, s14, s12
	s_ashr_i32 s42, s12, 31
	s_lshr_b32 s42, s42, 29
	s_add_i32 s42, s12, s42
	s_ashr_i32 s43, s42, 3
	s_and_b32 s42, s42, -8
	s_and_b32 s88, s68, 1
	s_add_i32 s86, s86, 0x21000
	s_ashr_i32 s87, s68, 31
	s_sub_i32 s12, s12, s42
	s_add_i32 s88, s88, 1
	s_cmp_lt_i32 s12, 0
	s_cselect_b32 s42, s3, 0xb0
	s_mul_i32 s12, s42, s12
	s_add_i32 s42, s12, s43
	s_mul_hi_i32 s12, s42, 0x2e8ba2e9
	s_lshr_b32 s43, s12, 31
	s_ashr_i32 s12, s12, 5
	s_add_i32 s43, s12, s43
	s_lshl_b32 s44, s43, 3
	s_sub_i32 s12, 64, s44
	s_min_i32 s45, s12, 8
	s_abs_i32 s48, s45
	v_cvt_f32_u32_e32 v4, s48
	v_lshlrev_b32_e32 v206, 3, v3
	v_mov_b32_e32 v3, v0
	v_lshl_add_u64 v[208:209], s[40:41], 0, v[2:3]
	v_rcp_iflag_f32_e32 v2, v4
	s_mulk_i32 s43, 0xb0
	s_sub_i32 s40, s42, s43
	s_sub_i32 s43, 0, s48
	v_mul_f32_e32 v2, 0x4f7ffffe, v2
	v_cvt_u32_f32_e32 v2, v2
	s_abs_i32 s42, s40
	s_xor_b32 s41, s40, s45
	s_ashr_i32 s41, s41, 31
	v_readfirstlane_b32 s49, v2
	s_mul_i32 s43, s43, s49
	s_mul_hi_u32 s43, s49, s43
	s_add_i32 s49, s49, s43
	s_mul_hi_u32 s43, s42, s49
	s_mul_i32 s49, s43, s48
	s_sub_i32 s42, s42, s49
	s_add_i32 s49, s43, 1
	s_sub_i32 s50, s42, s48
	s_cmp_ge_u32 s42, s48
	s_cselect_b32 s43, s49, s43
	v_lshlrev_b32_e32 v2, 13, v12
	s_cselect_b32 s42, s50, s42
	s_add_i32 s49, s43, 1
	v_and_b32_e32 v2, 0xffffc000, v2
	s_cmp_ge_u32 s42, s48
	v_lshl_add_u32 v2, v13, 10, v2
	v_and_b32_e32 v3, 1, v12
	s_cselect_b32 s42, s49, s43
	v_lshl_or_b32 v2, v3, 6, v2
	s_xor_b32 s42, s42, s41
	v_lshl_add_u32 v210, v14, 1, v2
	v_lshlrev_b32_e32 v2, 13, v15
	s_sub_i32 s89, s42, s41
	v_and_b32_e32 v2, 0xffffc000, v2
	s_waitcnt vmcnt(6)
	s_mul_i32 s41, s89, s45
	v_lshl_add_u32 v2, v16, 10, v2
	v_and_b32_e32 v3, 1, v15
	s_sub_i32 s90, s40, s41
	v_lshl_or_b32 v2, v3, 6, v2
	v_or_b32_e32 v222, 16, v221
	v_or_b32_e32 v223, 32, v221
	v_or_b32_e32 v224, 48, v221
	v_add_u32_e32 v225, 0x80, v221
	v_add_u32_e32 v226, 0x90, v221
	v_add_u32_e32 v227, 0xa0, v221
	v_add_u32_e32 v228, 0xb0, v221
	s_mov_b32 s12, 0
	s_add_i32 s90, s90, s44
	v_lshl_add_u32 v230, v18, 4, s86
	v_mov_b32_e32 v211, v0
	v_lshl_add_u32 v212, v17, 1, v2
	v_mov_b32_e32 v213, v0
	v_add_u32_e32 v231, 0, v1
	v_add_u32_e32 v233, 0, v19
	s_barrier
	s_branch .LBB0_1467

.LBB0_1478:
	s_add_i32 m0, s55, 0xc000
	s_and_b64 vcc, exec, s[8:9]
	global_load_lds_dwordx4 v210, s[60:61]
	s_add_i32 m0, s55, 0xe000
	s_nop 0
	global_load_lds_dwordx4 v212, s[60:61]
	s_waitcnt vmcnt(8)
	s_waitcnt lgkmcnt(0)
	s_barrier
	s_cbranch_vccnz .LBB0_1480
	s_setprio 1
	s_waitcnt lgkmcnt(0)
	v_mfma_i32_16x16x64_i8 v[176:179], v[180:183], v[4:7], v[176:179]
	v_mfma_i32_16x16x64_i8 v[168:171], v[188:191], v[4:7], v[168:171]
	v_mfma_i32_16x16x64_i8 v[160:163], v[180:183], v[12:15], v[160:163]
	v_mfma_i32_16x16x64_i8 v[152:155], v[188:191], v[12:15], v[152:155]
	v_mfma_i32_16x16x64_i8 v[144:147], v[180:183], v[20:23], v[144:147]
	v_mfma_i32_16x16x64_i8 v[136:139], v[188:191], v[20:23], v[136:139]
	v_mfma_i32_16x16x64_i8 v[120:123], v[180:183], v[28:31], v[120:123]
	v_mfma_i32_16x16x64_i8 v[104:107], v[188:191], v[28:31], v[104:107]
	v_mfma_i32_16x16x64_i8 v[176:179], v[184:187], v[8:11], v[176:179]
	v_mfma_i32_16x16x64_i8 v[168:171], v[192:195], v[8:11], v[168:171]
	v_mfma_i32_16x16x64_i8 v[160:163], v[184:187], v[16:19], v[160:163]
	v_mfma_i32_16x16x64_i8 v[152:155], v[192:195], v[16:19], v[152:155]
	v_mfma_i32_16x16x64_i8 v[144:147], v[184:187], v[24:27], v[144:147]
	v_mfma_i32_16x16x64_i8 v[136:139], v[192:195], v[24:27], v[136:139]
	v_mfma_i32_16x16x64_i8 v[120:123], v[184:187], v[32:35], v[120:123]
	v_mfma_i32_16x16x64_i8 v[104:107], v[192:195], v[32:35], v[104:107]
	s_setprio 0
	s_setprio 1
	v_mfma_i32_16x16x64_i8 v[172:175], v[108:111], v[4:7], v[172:175]
	v_mfma_i32_16x16x64_i8 v[164:167], v[124:127], v[4:7], v[164:167]
	v_mfma_i32_16x16x64_i8 v[156:159], v[108:111], v[12:15], v[156:159]
	v_mfma_i32_16x16x64_i8 v[148:151], v[124:127], v[12:15], v[148:151]
	v_mfma_i32_16x16x64_i8 v[140:143], v[108:111], v[20:23], v[140:143]
	v_mfma_i32_16x16x64_i8 v[132:135], v[124:127], v[20:23], v[132:135]
	v_mfma_i32_16x16x64_i8 v[116:119], v[108:111], v[28:31], v[116:119]
	v_mfma_i32_16x16x64_i8 v[100:103], v[124:127], v[28:31], v[100:103]
	v_mfma_i32_16x16x64_i8 v[172:175], v[112:115], v[8:11], v[172:175]
	v_mfma_i32_16x16x64_i8 v[164:167], v[128:131], v[8:11], v[164:167]
	v_mfma_i32_16x16x64_i8 v[156:159], v[112:115], v[16:19], v[156:159]
	v_mfma_i32_16x16x64_i8 v[148:151], v[128:131], v[16:19], v[148:151]
	v_mfma_i32_16x16x64_i8 v[140:143], v[112:115], v[24:27], v[140:143]
	v_mfma_i32_16x16x64_i8 v[132:135], v[128:131], v[24:27], v[132:135]
	v_mfma_i32_16x16x64_i8 v[116:119], v[112:115], v[32:35], v[116:119]
	v_mfma_i32_16x16x64_i8 v[100:103], v[128:131], v[32:35], v[100:103]
	s_setprio 0

.LBB0_1486:
	s_add_u32 s64, s64, 0x20000
	s_addc_u32 s65, s65, 0
	s_mov_b32 m0, s77
	s_nop 0
	global_load_lds_dwordx4 v198, s[64:65]
	s_mov_b32 m0, s78
	s_and_b64 vcc, exec, s[8:9]
	global_load_lds_dwordx4 v202, s[64:65]
	s_waitcnt vmcnt(8)
	s_waitcnt lgkmcnt(0)
	s_barrier
	s_cbranch_vccnz .LBB0_1488
	s_setprio 1
	s_waitcnt lgkmcnt(0)
	v_mfma_i32_16x16x64_i8 v[176:179], v[180:183], v[4:7], v[176:179]
	v_mfma_i32_16x16x64_i8 v[168:171], v[188:191], v[4:7], v[168:171]
	v_mfma_i32_16x16x64_i8 v[160:163], v[180:183], v[12:15], v[160:163]
	v_mfma_i32_16x16x64_i8 v[152:155], v[188:191], v[12:15], v[152:155]
	v_mfma_i32_16x16x64_i8 v[144:147], v[180:183], v[20:23], v[144:147]
	v_mfma_i32_16x16x64_i8 v[136:139], v[188:191], v[20:23], v[136:139]
	v_mfma_i32_16x16x64_i8 v[120:123], v[180:183], v[28:31], v[120:123]
	v_mfma_i32_16x16x64_i8 v[104:107], v[188:191], v[28:31], v[104:107]
	v_mfma_i32_16x16x64_i8 v[176:179], v[184:187], v[8:11], v[176:179]
	v_mfma_i32_16x16x64_i8 v[168:171], v[192:195], v[8:11], v[168:171]
	v_mfma_i32_16x16x64_i8 v[160:163], v[184:187], v[16:19], v[160:163]
	v_mfma_i32_16x16x64_i8 v[152:155], v[192:195], v[16:19], v[152:155]
	v_mfma_i32_16x16x64_i8 v[144:147], v[184:187], v[24:27], v[144:147]
	v_mfma_i32_16x16x64_i8 v[136:139], v[192:195], v[24:27], v[136:139]
	v_mfma_i32_16x16x64_i8 v[120:123], v[184:187], v[32:35], v[120:123]
	v_mfma_i32_16x16x64_i8 v[104:107], v[192:195], v[32:35], v[104:107]
	s_setprio 0
	s_setprio 1
	v_mfma_i32_16x16x64_i8 v[172:175], v[108:111], v[4:7], v[172:175]
	v_mfma_i32_16x16x64_i8 v[164:167], v[124:127], v[4:7], v[164:167]
	v_mfma_i32_16x16x64_i8 v[156:159], v[108:111], v[12:15], v[156:159]
	v_mfma_i32_16x16x64_i8 v[148:151], v[124:127], v[12:15], v[148:151]
	v_mfma_i32_16x16x64_i8 v[140:143], v[108:111], v[20:23], v[140:143]
	v_mfma_i32_16x16x64_i8 v[132:135], v[124:127], v[20:23], v[132:135]
	v_mfma_i32_16x16x64_i8 v[116:119], v[108:111], v[28:31], v[116:119]
	v_mfma_i32_16x16x64_i8 v[100:103], v[124:127], v[28:31], v[100:103]
	v_mfma_i32_16x16x64_i8 v[172:175], v[112:115], v[8:11], v[172:175]
	v_mfma_i32_16x16x64_i8 v[164:167], v[128:131], v[8:11], v[164:167]
	v_mfma_i32_16x16x64_i8 v[156:159], v[112:115], v[16:19], v[156:159]
	v_mfma_i32_16x16x64_i8 v[148:151], v[128:131], v[16:19], v[148:151]
	v_mfma_i32_16x16x64_i8 v[140:143], v[112:115], v[24:27], v[140:143]
	v_mfma_i32_16x16x64_i8 v[132:135], v[128:131], v[24:27], v[132:135]
	v_mfma_i32_16x16x64_i8 v[116:119], v[112:115], v[32:35], v[116:119]
	v_mfma_i32_16x16x64_i8 v[100:103], v[128:131], v[32:35], v[100:103]
	s_setprio 0

.LBB0_1490:
	s_mov_b32 m0, s80
	v_lshl_add_u64 v[2:3], v[2:3], 0, s[20:21]
	s_add_u32 s8, s62, 0x20080
	global_load_lds_dwordx4 v[2:3], off
	v_lshl_add_u64 v[2:3], v[214:215], 0, s[20:21]
	s_mov_b32 m0, s81
	s_addc_u32 s9, s63, 0
	global_load_lds_dwordx4 v[2:3], off
	s_mov_b32 m0, s84
	s_and_b64 vcc, exec, s[6:7]
	global_load_lds_dwordx4 v200, s[8:9]
	s_mov_b32 m0, s85
	s_nop 0
	global_load_lds_dwordx4 v204, s[8:9]
	v_lshl_add_u64 v[2:3], v[216:217], 0, s[20:21]
	s_mov_b32 m0, s82
	s_nop 0
	global_load_lds_dwordx4 v[2:3], off
	v_lshl_add_u64 v[2:3], v[218:219], 0, s[20:21]
	s_mov_b32 m0, s83
	s_nop 0
	global_load_lds_dwordx4 v[2:3], off
	s_waitcnt vmcnt(8)
	s_waitcnt lgkmcnt(0)
	s_barrier
	s_cbranch_vccnz .LBB0_1475
	s_setprio 1
	s_waitcnt lgkmcnt(0)
	v_mfma_i32_16x16x64_i8 v[96:99], v[180:183], v[4:7], v[96:99]
	v_mfma_i32_16x16x64_i8 v[88:91], v[188:191], v[4:7], v[88:91]
	v_mfma_i32_16x16x64_i8 v[80:83], v[180:183], v[12:15], v[80:83]
	v_mfma_i32_16x16x64_i8 v[72:75], v[188:191], v[12:15], v[72:75]
	v_mfma_i32_16x16x64_i8 v[64:67], v[180:183], v[20:23], v[64:67]
	v_mfma_i32_16x16x64_i8 v[56:59], v[188:191], v[20:23], v[56:59]
	v_mfma_i32_16x16x64_i8 v[48:51], v[180:183], v[28:31], v[48:51]
	v_mfma_i32_16x16x64_i8 v[40:43], v[188:191], v[28:31], v[40:43]
	v_mfma_i32_16x16x64_i8 v[96:99], v[184:187], v[8:11], v[96:99]
	v_mfma_i32_16x16x64_i8 v[88:91], v[192:195], v[8:11], v[88:91]
	v_mfma_i32_16x16x64_i8 v[80:83], v[184:187], v[16:19], v[80:83]
	v_mfma_i32_16x16x64_i8 v[72:75], v[192:195], v[16:19], v[72:75]
	v_mfma_i32_16x16x64_i8 v[64:67], v[184:187], v[24:27], v[64:67]
	v_mfma_i32_16x16x64_i8 v[56:59], v[192:195], v[24:27], v[56:59]
	v_mfma_i32_16x16x64_i8 v[48:51], v[184:187], v[32:35], v[48:51]
	v_mfma_i32_16x16x64_i8 v[40:43], v[192:195], v[32:35], v[40:43]
	s_setprio 0
	s_setprio 1
	v_mfma_i32_16x16x64_i8 v[92:95], v[108:111], v[4:7], v[92:95]
	v_mfma_i32_16x16x64_i8 v[84:87], v[124:127], v[4:7], v[84:87]
	v_mfma_i32_16x16x64_i8 v[76:79], v[108:111], v[12:15], v[76:79]
	v_mfma_i32_16x16x64_i8 v[68:71], v[124:127], v[12:15], v[68:71]
	v_mfma_i32_16x16x64_i8 v[60:63], v[108:111], v[20:23], v[60:63]
	v_mfma_i32_16x16x64_i8 v[52:55], v[124:127], v[20:23], v[52:55]
	v_mfma_i32_16x16x64_i8 v[44:47], v[108:111], v[28:31], v[44:47]
	v_mfma_i32_16x16x64_i8 v[36:39], v[124:127], v[28:31], v[36:39]
	v_mfma_i32_16x16x64_i8 v[92:95], v[112:115], v[8:11], v[92:95]
	v_mfma_i32_16x16x64_i8 v[84:87], v[128:131], v[8:11], v[84:87]
	v_mfma_i32_16x16x64_i8 v[76:79], v[112:115], v[16:19], v[76:79]
	v_mfma_i32_16x16x64_i8 v[68:71], v[128:131], v[16:19], v[68:71]
	v_mfma_i32_16x16x64_i8 v[60:63], v[112:115], v[24:27], v[60:63]
	v_mfma_i32_16x16x64_i8 v[52:55], v[128:131], v[24:27], v[52:55]
	v_mfma_i32_16x16x64_i8 v[44:47], v[112:115], v[32:35], v[44:47]
	v_mfma_i32_16x16x64_i8 v[36:39], v[128:131], v[32:35], v[36:39]
	s_setprio 0
	s_branch .LBB0_1475

.LBB0_1622:
	s_cmp_ge_u32 s72, s1
	s_cselect_b64 s[24:25], -1, 0
	s_add_u32 s26, s10, 0x2700000
	s_addc_u32 s27, s11, 0
	s_add_u32 s28, s10, 0x280000
	s_addc_u32 s29, s11, 0
	s_add_u32 s9, s10, 0xef00000
	v_readlane_b32 s6, v254, 6
	s_addc_u32 s12, s11, 0
	v_readlane_b32 s7, v254, 7
	s_and_b64 s[6:7], s[6:7], exec
	s_cselect_b32 s31, s12, 0
	s_cselect_b32 s30, s9, 0
	s_add_u32 s34, s10, 0x380000
	s_addc_u32 s35, s11, 0
	s_add_u32 s38, s10, 0xff00000
	s_addc_u32 s39, s11, 0
	s_add_u32 s83, s10, 0x208000
	s_addc_u32 s84, s11, 0
	s_and_b32 s9, s4, 3
	s_add_i32 m0, s79, 0x18000
	v_lshl_add_u64 v[8:9], v[8:9], 0, s[18:19]
	s_lshl_b32 s4, s5, 13
	s_lshl_b32 s40, s9, 5
	s_lshl_b32 s12, s9, 12
	s_waitcnt vmcnt(2)
	s_barrier
	global_load_lds_dwordx4 v[8:9], off
	v_lshl_add_u64 v[6:7], v[6:7], 0, s[18:19]
	s_add_i32 m0, s79, 0x1a000
	s_add_i32 s85, s79, 0x8000
	s_add_i32 s86, s79, 0xa000
	global_load_lds_dwordx4 v[6:7], off
	v_lshl_add_u64 v[2:3], v[2:3], 0, s[18:19]
	s_mov_b32 m0, s85
	s_add_u32 s6, s56, 0xb0080
	global_load_lds_dwordx4 v[2:3], off
	v_lshl_add_u64 v[2:3], v[4:5], 0, s[18:19]
	s_mov_b32 m0, s86
	s_addc_u32 s7, s57, 0
	global_load_lds_dwordx4 v[2:3], off
	s_add_i32 m0, s79, 0x1c000
	s_nop 0
	global_load_lds_dwordx4 v136, s[6:7]
	s_add_i32 m0, s79, 0x1e000
	s_cmpk_lt_u32 s8, 0x100
	global_load_lds_dwordx4 v140, s[6:7]
	v_bfe_u32 v2, v166, 4, 2
	v_and_b32_e32 v3, 15, v166
	v_lshl_or_b32 v168, s5, 6, v3
	v_lshlrev_b32_e32 v4, 4, v2
	v_lshl_or_b32 v3, v3, 6, v4
	v_lshlrev_b32_e32 v4, 2, v168
	s_cselect_b64 s[42:43], -1, 0
	s_lshl_b32 s6, s9, 2
	v_and_b32_e32 v5, 32, v4
	v_add_u32_e32 v170, 0x80, v168
	s_add_i32 s6, s6, s36
	v_lshlrev_b32_e32 v142, 3, v2
	v_bitop3_b32 v5, v3, s4, v5 bitop3:0xde
	v_cmp_eq_u32_e64 s[4:5], 0, v2
	v_lshl_add_u32 v177, v168, 4, s6
	v_lshl_add_u32 v178, v170, 4, s6
	s_movk_i32 s6, 0x100
	v_and_b32_e32 v2, 63, v166
	v_cmp_gt_i32_e64 s[6:7], s6, v166
	v_cmp_eq_u32_e32 vcc, 0, v2
	v_lshlrev_b32_e32 v6, 2, v166
	s_ashr_i32 s88, s73, 31
	s_and_b64 s[44:45], s[6:7], vcc
	v_and_b32_e32 v6, 32, v6
	s_add_u32 s50, s10, 0x200200
	v_lshrrev_b32_e32 v2, 1, v0
	v_mul_lo_u32 v0, v10, s33
	v_bitop3_b32 v169, v3, s12, v6 bitop3:0xde
	s_addc_u32 s51, s11, 0
	v_mad_u64_u32 v[2:3], s[10:11], v2, s37, v[0:1]
	v_or_b32_e32 v0, v2, v11
	v_add_lshl_u32 v0, v0, v12, 1
	v_lshl_add_u64 v[144:145], v[0:1], 0, s[20:21]
	v_lshrrev_b32_e32 v2, 1, v13
	v_mul_lo_u32 v0, v14, s33
	v_mad_u64_u32 v[2:3], s[10:11], v2, s37, v[0:1]
	s_waitcnt vmcnt(6)
	v_or_b32_e32 v0, v2, v15
	v_or_b32_e32 v171, 16, v168
	v_or_b32_e32 v172, 32, v168
	v_or_b32_e32 v173, 48, v168
	v_add_u32_e32 v174, 0x90, v168
	v_add_u32_e32 v175, 0xa0, v168
	v_add_u32_e32 v176, 0xb0, v168
	v_add_u32_e32 v179, s36, v167
	v_mul_lo_u32 v6, v166, -12
	v_add_lshl_u32 v0, v0, v16, 1
	s_mov_b32 s87, 0
	s_mov_b32 s41, s17
	v_mov_b32_e32 v143, v1
	v_cmp_eq_u32_e64 s[8:9], 0, v166
	s_waitcnt vmcnt(0)
	v_add_u32_e32 v180, s36, v4
	v_lshl_add_u32 v181, v171, 2, s36
	v_lshl_add_u32 v182, v172, 2, s36
	v_lshl_add_u32 v183, v173, 2, s36
	v_lshl_add_u32 v184, v170, 2, s36
	v_lshl_add_u32 v185, v174, 2, s36
	v_lshl_add_u32 v186, v175, 2, s36
	v_lshl_add_u32 v187, v176, 2, s36
	v_lshl_add_u64 v[146:147], v[0:1], 0, s[20:21]
	v_add_u32_e32 v188, 0, v5
	v_add_u32_e32 v189, v179, v6
	s_barrier
	s_branch .LBB0_1625

.LBB0_1636:
	s_add_u32 s56, s48, 0x100
	s_addc_u32 s57, s49, 0
	s_add_i32 s64, 0, 0x10000
	s_cmp_eq_u32 s63, 40
	s_cselect_b32 s61, s13, s57
	s_cselect_b32 s60, s12, s56
	v_add_u32_e32 v0, s64, v169
	s_cselect_b32 s59, s53, s55
	s_cselect_b32 s58, s52, s16
	s_add_i32 s65, 0, 0x14000
	ds_read_b128 v[148:151], v0
	ds_read_b128 v[152:155], v0 offset:1024
	ds_read_b128 v[156:159], v0 offset:2048
	ds_read_b128 v[190:193], v0 offset:3072
	v_add_u32_e32 v0, s65, v169
	ds_read_b128 v[194:197], v0
	ds_read_b128 v[198:201], v0 offset:1024
	ds_read_b128 v[202:205], v0 offset:2048
	ds_read_b128 v[206:209], v0 offset:3072
	v_lshl_add_u64 v[230:231], s[48:49], 0, v[144:145]
	s_add_i32 m0, s79, 0xc000
	ds_read_b128 v[210:213], v188
	ds_read_b128 v[214:217], v188 offset:1024
	ds_read_b128 v[218:221], v188 offset:2048
	ds_read_b128 v[222:225], v188 offset:3072
	ds_read_b128 v[226:229], v188 offset:4096
	ds_read_b128 v[234:237], v188 offset:5120
	ds_read_b128 v[238:241], v188 offset:6144
	ds_read_b128 v[242:245], v188 offset:7168
	global_load_lds_dwordx4 v[230:231], off
	v_lshl_add_u64 v[230:231], s[48:49], 0, v[146:147]
	s_add_i32 m0, s79, 0xe000
	s_nop 0
	global_load_lds_dwordx4 v[230:231], off
	s_waitcnt vmcnt(8)
	s_waitcnt lgkmcnt(0)
	s_barrier
	s_setprio 1
	s_waitcnt lgkmcnt(0)
	v_mfma_f32_16x16x32_bf16 v[126:129], v[148:151], v[210:213], v[126:129]
	v_mfma_f32_16x16x32_bf16 v[122:125], v[156:159], v[210:213], v[122:125]
	v_mfma_f32_16x16x32_bf16 v[110:113], v[148:151], v[218:221], v[110:113]
	v_mfma_f32_16x16x32_bf16 v[106:109], v[156:159], v[218:221], v[106:109]
	v_mfma_f32_16x16x32_bf16 v[94:97], v[148:151], v[226:229], v[94:97]
	v_mfma_f32_16x16x32_bf16 v[90:93], v[156:159], v[226:229], v[90:93]
	v_mfma_f32_16x16x32_bf16 v[78:81], v[148:151], v[238:241], v[78:81]
	v_mfma_f32_16x16x32_bf16 v[74:77], v[156:159], v[238:241], v[74:77]
	v_mfma_f32_16x16x32_bf16 v[126:129], v[152:155], v[214:217], v[126:129]
	v_mfma_f32_16x16x32_bf16 v[122:125], v[190:193], v[214:217], v[122:125]
	v_mfma_f32_16x16x32_bf16 v[110:113], v[152:155], v[222:225], v[110:113]
	v_mfma_f32_16x16x32_bf16 v[106:109], v[190:193], v[222:225], v[106:109]
	v_mfma_f32_16x16x32_bf16 v[94:97], v[152:155], v[234:237], v[94:97]
	v_mfma_f32_16x16x32_bf16 v[90:93], v[190:193], v[234:237], v[90:93]
	v_mfma_f32_16x16x32_bf16 v[78:81], v[152:155], v[242:245], v[78:81]
	v_mfma_f32_16x16x32_bf16 v[74:77], v[190:193], v[242:245], v[74:77]
	s_setprio 0
	s_setprio 1
	v_mfma_f32_16x16x32_bf16 v[118:121], v[194:197], v[210:213], v[118:121]
	v_mfma_f32_16x16x32_bf16 v[114:117], v[202:205], v[210:213], v[114:117]
	v_mfma_f32_16x16x32_bf16 v[102:105], v[194:197], v[218:221], v[102:105]
	v_mfma_f32_16x16x32_bf16 v[98:101], v[202:205], v[218:221], v[98:101]
	v_mfma_f32_16x16x32_bf16 v[86:89], v[194:197], v[226:229], v[86:89]
	v_mfma_f32_16x16x32_bf16 v[82:85], v[202:205], v[226:229], v[82:85]
	v_mfma_f32_16x16x32_bf16 v[70:73], v[194:197], v[238:241], v[70:73]
	v_mfma_f32_16x16x32_bf16 v[66:69], v[202:205], v[238:241], v[66:69]
	v_mfma_f32_16x16x32_bf16 v[118:121], v[198:201], v[214:217], v[118:121]
	v_mfma_f32_16x16x32_bf16 v[114:117], v[206:209], v[214:217], v[114:117]
	v_mfma_f32_16x16x32_bf16 v[102:105], v[198:201], v[222:225], v[102:105]
	v_mfma_f32_16x16x32_bf16 v[98:101], v[206:209], v[222:225], v[98:101]
	v_mfma_f32_16x16x32_bf16 v[86:89], v[198:201], v[234:237], v[86:89]
	v_mfma_f32_16x16x32_bf16 v[82:85], v[206:209], v[234:237], v[82:85]
	v_mfma_f32_16x16x32_bf16 v[70:73], v[198:201], v[242:245], v[70:73]
	v_mfma_f32_16x16x32_bf16 v[66:69], v[206:209], v[242:245], v[66:69]
	s_setprio 0
	s_barrier
	s_add_i32 s48, s64, s78
	v_lshl_add_u64 v[230:231], s[58:59], 0, v[136:137]
	s_mov_b32 m0, s48
	ds_read_b128 v[210:213], v188 offset:16384
	ds_read_b128 v[214:217], v188 offset:17408
	ds_read_b128 v[218:221], v188 offset:18432
	ds_read_b128 v[222:225], v188 offset:19456
	ds_read_b128 v[226:229], v188 offset:20480
	ds_read_b128 v[234:237], v188 offset:21504
	ds_read_b128 v[238:241], v188 offset:22528
	ds_read_b128 v[242:245], v188 offset:23552
	global_load_lds_dwordx4 v[230:231], off
	s_add_i32 m0, s48, 0x2000
	s_add_u32 s48, s58, 0xb0000
	v_lshl_add_u64 v[246:247], s[58:59], 0, v[140:141]
	s_addc_u32 s49, s59, 0
	s_add_i32 s64, s65, s78
	global_load_lds_dwordx4 v[246:247], off
	s_mov_b32 m0, s64
	v_lshl_add_u64 v[250:251], s[60:61], 0, v[138:139]
	global_load_lds_dwordx4 v136, s[48:49]
	s_add_i32 m0, s64, 0x2000
	s_nop 0
	global_load_lds_dwordx4 v140, s[48:49]
	v_lshl_add_u64 v[248:249], s[60:61], 0, v[134:135]
	s_mov_b32 m0, s79
	s_nop 0
	global_load_lds_dwordx4 v[248:249], off
	s_mov_b32 m0, s80
	s_nop 0
	global_load_lds_dwordx4 v[250:251], off
	s_waitcnt vmcnt(8)
	s_waitcnt lgkmcnt(0)
	s_barrier
	s_setprio 1
	s_waitcnt lgkmcnt(0)
	v_mfma_f32_16x16x32_bf16 v[62:65], v[148:151], v[210:213], v[62:65]
	v_mfma_f32_16x16x32_bf16 v[58:61], v[156:159], v[210:213], v[58:61]
	v_mfma_f32_16x16x32_bf16 v[46:49], v[148:151], v[218:221], v[46:49]
	v_mfma_f32_16x16x32_bf16 v[42:45], v[156:159], v[218:221], v[42:45]
	v_mfma_f32_16x16x32_bf16 v[30:33], v[148:151], v[226:229], v[30:33]
	v_mfma_f32_16x16x32_bf16 v[26:29], v[156:159], v[226:229], v[26:29]
	v_mfma_f32_16x16x32_bf16 v[14:17], v[148:151], v[238:241], v[14:17]
	v_mfma_f32_16x16x32_bf16 v[10:13], v[156:159], v[238:241], v[10:13]
	v_mfma_f32_16x16x32_bf16 v[62:65], v[152:155], v[214:217], v[62:65]
	v_mfma_f32_16x16x32_bf16 v[58:61], v[190:193], v[214:217], v[58:61]
	v_mfma_f32_16x16x32_bf16 v[46:49], v[152:155], v[222:225], v[46:49]
	v_mfma_f32_16x16x32_bf16 v[42:45], v[190:193], v[222:225], v[42:45]
	v_mfma_f32_16x16x32_bf16 v[30:33], v[152:155], v[234:237], v[30:33]
	v_mfma_f32_16x16x32_bf16 v[26:29], v[190:193], v[234:237], v[26:29]
	v_mfma_f32_16x16x32_bf16 v[14:17], v[152:155], v[242:245], v[14:17]
	v_mfma_f32_16x16x32_bf16 v[10:13], v[190:193], v[242:245], v[10:13]
	s_setprio 0
	s_setprio 1
	v_mfma_f32_16x16x32_bf16 v[54:57], v[194:197], v[210:213], v[54:57]
	v_mfma_f32_16x16x32_bf16 v[50:53], v[202:205], v[210:213], v[50:53]
	v_mfma_f32_16x16x32_bf16 v[38:41], v[194:197], v[218:221], v[38:41]
	v_mfma_f32_16x16x32_bf16 v[34:37], v[202:205], v[218:221], v[34:37]
	v_mfma_f32_16x16x32_bf16 v[22:25], v[194:197], v[226:229], v[22:25]
	v_mfma_f32_16x16x32_bf16 v[18:21], v[202:205], v[226:229], v[18:21]
	v_mfma_f32_16x16x32_bf16 v[6:9], v[194:197], v[238:241], v[6:9]
	v_mfma_f32_16x16x32_bf16 v[2:5], v[202:205], v[238:241], v[2:5]
	v_mfma_f32_16x16x32_bf16 v[54:57], v[198:201], v[214:217], v[54:57]
	v_mfma_f32_16x16x32_bf16 v[50:53], v[206:209], v[214:217], v[50:53]
	v_mfma_f32_16x16x32_bf16 v[38:41], v[198:201], v[222:225], v[38:41]
	v_mfma_f32_16x16x32_bf16 v[34:37], v[206:209], v[222:225], v[34:37]
	v_mfma_f32_16x16x32_bf16 v[22:25], v[198:201], v[234:237], v[22:25]
	v_mfma_f32_16x16x32_bf16 v[18:21], v[206:209], v[234:237], v[18:21]
	v_mfma_f32_16x16x32_bf16 v[6:9], v[198:201], v[242:245], v[6:9]
	v_mfma_f32_16x16x32_bf16 v[2:5], v[206:209], v[242:245], v[2:5]
	s_setprio 0
	s_barrier
	s_add_i32 s64, 0, 0x18000
	v_add_u32_e32 v0, s64, v169
	s_add_i32 s65, 0, 0x1c000
	ds_read_b128 v[148:151], v0
	ds_read_b128 v[152:155], v0 offset:1024
	ds_read_b128 v[156:159], v0 offset:2048
	ds_read_b128 v[190:193], v0 offset:3072
	v_add_u32_e32 v0, s65, v169
	ds_read_b128 v[194:197], v0
	ds_read_b128 v[198:201], v0 offset:1024
	ds_read_b128 v[202:205], v0 offset:2048
	ds_read_b128 v[206:209], v0 offset:3072
	s_add_u32 s48, s60, 0xb0000
	s_addc_u32 s49, s61, 0
	s_mov_b32 m0, s81
	ds_read_b128 v[210:213], v188 offset:32768
	ds_read_b128 v[214:217], v188 offset:33792
	ds_read_b128 v[218:221], v188 offset:34816
	ds_read_b128 v[222:225], v188 offset:35840
	ds_read_b128 v[226:229], v188 offset:36864
	ds_read_b128 v[234:237], v188 offset:37888
	ds_read_b128 v[238:241], v188 offset:38912
	ds_read_b128 v[242:245], v188 offset:39936
	global_load_lds_dwordx4 v134, s[48:49]
	s_mov_b32 m0, s82
	s_nop 0
	global_load_lds_dwordx4 v138, s[48:49]
	s_waitcnt vmcnt(8)
	s_waitcnt lgkmcnt(0)
	s_barrier
	s_setprio 1
	s_waitcnt lgkmcnt(0)
	v_mfma_f32_16x16x32_bf16 v[126:129], v[148:151], v[210:213], v[126:129]
	v_mfma_f32_16x16x32_bf16 v[122:125], v[156:159], v[210:213], v[122:125]
	v_mfma_f32_16x16x32_bf16 v[110:113], v[148:151], v[218:221], v[110:113]
	v_mfma_f32_16x16x32_bf16 v[106:109], v[156:159], v[218:221], v[106:109]
	v_mfma_f32_16x16x32_bf16 v[94:97], v[148:151], v[226:229], v[94:97]
	v_mfma_f32_16x16x32_bf16 v[90:93], v[156:159], v[226:229], v[90:93]
	v_mfma_f32_16x16x32_bf16 v[78:81], v[148:151], v[238:241], v[78:81]
	v_mfma_f32_16x16x32_bf16 v[74:77], v[156:159], v[238:241], v[74:77]
	v_mfma_f32_16x16x32_bf16 v[126:129], v[152:155], v[214:217], v[126:129]
	v_mfma_f32_16x16x32_bf16 v[122:125], v[190:193], v[214:217], v[122:125]
	v_mfma_f32_16x16x32_bf16 v[110:113], v[152:155], v[222:225], v[110:113]
	v_mfma_f32_16x16x32_bf16 v[106:109], v[190:193], v[222:225], v[106:109]
	v_mfma_f32_16x16x32_bf16 v[94:97], v[152:155], v[234:237], v[94:97]
	v_mfma_f32_16x16x32_bf16 v[90:93], v[190:193], v[234:237], v[90:93]
	v_mfma_f32_16x16x32_bf16 v[78:81], v[152:155], v[242:245], v[78:81]
	v_mfma_f32_16x16x32_bf16 v[74:77], v[190:193], v[242:245], v[74:77]
	s_setprio 0
	s_setprio 1
	v_mfma_f32_16x16x32_bf16 v[118:121], v[194:197], v[210:213], v[118:121]
	v_mfma_f32_16x16x32_bf16 v[114:117], v[202:205], v[210:213], v[114:117]
	v_mfma_f32_16x16x32_bf16 v[102:105], v[194:197], v[218:221], v[102:105]
	v_mfma_f32_16x16x32_bf16 v[98:101], v[202:205], v[218:221], v[98:101]
	v_mfma_f32_16x16x32_bf16 v[86:89], v[194:197], v[226:229], v[86:89]
	v_mfma_f32_16x16x32_bf16 v[82:85], v[202:205], v[226:229], v[82:85]
	v_mfma_f32_16x16x32_bf16 v[70:73], v[194:197], v[238:241], v[70:73]
	v_mfma_f32_16x16x32_bf16 v[66:69], v[202:205], v[238:241], v[66:69]
	v_mfma_f32_16x16x32_bf16 v[118:121], v[198:201], v[214:217], v[118:121]
	v_mfma_f32_16x16x32_bf16 v[114:117], v[206:209], v[214:217], v[114:117]
	v_mfma_f32_16x16x32_bf16 v[102:105], v[198:201], v[222:225], v[102:105]
	v_mfma_f32_16x16x32_bf16 v[98:101], v[206:209], v[222:225], v[98:101]
	v_mfma_f32_16x16x32_bf16 v[86:89], v[198:201], v[234:237], v[86:89]
	v_mfma_f32_16x16x32_bf16 v[82:85], v[206:209], v[234:237], v[82:85]
	v_mfma_f32_16x16x32_bf16 v[70:73], v[198:201], v[242:245], v[70:73]
	v_mfma_f32_16x16x32_bf16 v[66:69], v[206:209], v[242:245], v[66:69]
	s_setprio 0
	s_barrier
	s_add_i32 s48, s64, s78
	v_lshl_add_u64 v[230:231], v[230:231], 0, s[18:19]
	s_mov_b32 m0, s48
	ds_read_b128 v[210:213], v188 offset:49152
	ds_read_b128 v[214:217], v188 offset:50176
	ds_read_b128 v[218:221], v188 offset:51200
	ds_read_b128 v[222:225], v188 offset:52224
	ds_read_b128 v[226:229], v188 offset:53248
	ds_read_b128 v[234:237], v188 offset:54272
	ds_read_b128 v[238:241], v188 offset:55296
	ds_read_b128 v[242:245], v188 offset:56320
	global_load_lds_dwordx4 v[230:231], off
	s_add_i32 m0, s48, 0x2000
	s_add_u32 s48, s58, 0xb0080
	v_lshl_add_u64 v[230:231], v[246:247], 0, s[18:19]
	s_addc_u32 s49, s59, 0
	s_add_i32 s58, s65, s78
	global_load_lds_dwordx4 v[230:231], off
	s_mov_b32 m0, s58
	s_nop 0
	global_load_lds_dwordx4 v136, s[48:49]
	s_add_i32 m0, s58, 0x2000
	s_nop 0
	global_load_lds_dwordx4 v140, s[48:49]
	v_lshl_add_u64 v[230:231], v[248:249], 0, s[18:19]
	s_mov_b32 m0, s85
	s_nop 0
	global_load_lds_dwordx4 v[230:231], off
	v_lshl_add_u64 v[230:231], v[250:251], 0, s[18:19]
	s_mov_b32 m0, s86
	s_nop 0
	global_load_lds_dwordx4 v[230:231], off
	s_waitcnt vmcnt(8)
	s_waitcnt lgkmcnt(0)
	s_barrier
	s_setprio 1
	s_waitcnt lgkmcnt(0)
	v_mfma_f32_16x16x32_bf16 v[62:65], v[148:151], v[210:213], v[62:65]
	v_mfma_f32_16x16x32_bf16 v[58:61], v[156:159], v[210:213], v[58:61]
	v_mfma_f32_16x16x32_bf16 v[46:49], v[148:151], v[218:221], v[46:49]
	v_mfma_f32_16x16x32_bf16 v[42:45], v[156:159], v[218:221], v[42:45]
	v_mfma_f32_16x16x32_bf16 v[30:33], v[148:151], v[226:229], v[30:33]
	v_mfma_f32_16x16x32_bf16 v[26:29], v[156:159], v[226:229], v[26:29]
	v_mfma_f32_16x16x32_bf16 v[14:17], v[148:151], v[238:241], v[14:17]
	v_mfma_f32_16x16x32_bf16 v[10:13], v[156:159], v[238:241], v[10:13]
	v_mfma_f32_16x16x32_bf16 v[62:65], v[152:155], v[214:217], v[62:65]
	v_mfma_f32_16x16x32_bf16 v[58:61], v[190:193], v[214:217], v[58:61]
	v_mfma_f32_16x16x32_bf16 v[46:49], v[152:155], v[222:225], v[46:49]
	v_mfma_f32_16x16x32_bf16 v[42:45], v[190:193], v[222:225], v[42:45]
	v_mfma_f32_16x16x32_bf16 v[30:33], v[152:155], v[234:237], v[30:33]
	v_mfma_f32_16x16x32_bf16 v[26:29], v[190:193], v[234:237], v[26:29]
	v_mfma_f32_16x16x32_bf16 v[14:17], v[152:155], v[242:245], v[14:17]
	v_mfma_f32_16x16x32_bf16 v[10:13], v[190:193], v[242:245], v[10:13]
	s_setprio 0
	s_setprio 1
	v_mfma_f32_16x16x32_bf16 v[54:57], v[194:197], v[210:213], v[54:57]
	v_mfma_f32_16x16x32_bf16 v[50:53], v[202:205], v[210:213], v[50:53]
	v_mfma_f32_16x16x32_bf16 v[38:41], v[194:197], v[218:221], v[38:41]
	v_mfma_f32_16x16x32_bf16 v[34:37], v[202:205], v[218:221], v[34:37]
	v_mfma_f32_16x16x32_bf16 v[22:25], v[194:197], v[226:229], v[22:25]
	v_mfma_f32_16x16x32_bf16 v[18:21], v[202:205], v[226:229], v[18:21]
	v_mfma_f32_16x16x32_bf16 v[6:9], v[194:197], v[238:241], v[6:9]
	v_mfma_f32_16x16x32_bf16 v[2:5], v[202:205], v[238:241], v[2:5]
	v_mfma_f32_16x16x32_bf16 v[54:57], v[198:201], v[214:217], v[54:57]
	v_mfma_f32_16x16x32_bf16 v[50:53], v[206:209], v[214:217], v[50:53]
	v_mfma_f32_16x16x32_bf16 v[38:41], v[198:201], v[222:225], v[38:41]
	v_mfma_f32_16x16x32_bf16 v[34:37], v[206:209], v[222:225], v[34:37]
	v_mfma_f32_16x16x32_bf16 v[22:25], v[198:201], v[234:237], v[22:25]
	v_mfma_f32_16x16x32_bf16 v[18:21], v[206:209], v[234:237], v[18:21]
	v_mfma_f32_16x16x32_bf16 v[6:9], v[198:201], v[242:245], v[6:9]
	v_mfma_f32_16x16x32_bf16 v[2:5], v[206:209], v[242:245], v[2:5]
	s_setprio 0
	s_barrier
	s_add_i32 s63, s63, 2
	s_add_u32 s16, s16, 0x100
	s_addc_u32 s55, s55, 0
	s_cmp_gt_u32 s63, 41
	s_mov_b64 s[48:49], s[56:57]
	s_cbranch_scc0 .LBB0_1636
	s_and_b64 vcc, exec, s[42:43]
	s_cbranch_vccz .LBB0_1640
	s_barrier
	s_andn2_b64 vcc, exec, s[24:25]
	s_cbranch_vccz .LBB0_1641

.LBB0_2098:
	s_add_u32 s34, s4, 0x40000
	s_addc_u32 s35, s5, 0
	s_add_u32 s36, s4, 0x4700000
	s_addc_u32 s37, s5, 0
	s_add_u32 s38, s4, 0x7700000
	s_addc_u32 s39, s5, 0
	s_add_u32 s40, s4, 0x7b00000
	s_addc_u32 s41, s5, 0
	s_add_u32 s42, s4, 0x6700000
	s_addc_u32 s43, s5, 0
	s_add_u32 s44, s4, 0xaf00000
	s_addc_u32 s45, s5, 0
	s_add_u32 s50, s4, 0xbf00000
	s_addc_u32 s51, s5, 0
	s_add_u32 s52, s4, 0x7f00000
	s_addc_u32 s53, s5, 0
	s_add_i32 m0, s67, 0x18000
	v_lshl_add_u64 v[6:7], v[6:7], 0, s[14:15]
	s_lshl_b32 s7, s56, 13
	s_lshl_b32 s55, s72, 12
	s_waitcnt vmcnt(2)
	s_barrier
	global_load_lds_dwordx4 v[6:7], off
	v_lshl_add_u64 v[4:5], v[4:5], 0, s[14:15]
	s_add_i32 m0, s67, 0x1a000
	s_add_i32 s81, s67, 0x8000
	s_add_i32 s82, s67, 0xa000
	global_load_lds_dwordx4 v[4:5], off
	v_lshl_add_u64 v[0:1], v[0:1], 0, s[14:15]
	s_mov_b32 m0, s81
	s_add_u32 s58, s48, 0x40080
	global_load_lds_dwordx4 v[0:1], off
	v_lshl_add_u64 v[0:1], v[2:3], 0, s[14:15]
	s_mov_b32 m0, s82
	s_addc_u32 s59, s49, 0
	global_load_lds_dwordx4 v[0:1], off
	s_add_i32 m0, s67, 0x1c000
	s_nop 0
	global_load_lds_dwordx4 v136, s[58:59]
	s_add_i32 m0, s67, 0x1e000
	v_and_b32_e32 v2, 15, v8
	global_load_lds_dwordx4 v140, s[58:59]
	v_or_b32_e32 v169, s54, v2
	v_lshlrev_b32_e32 v0, 6, v169
	v_and_b32_e32 v1, 48, v8
	s_movk_i32 s54, 0x3c0
	v_lshlrev_b32_e32 v3, 2, v169
	v_and_or_b32 v0, v0, s54, v1
	v_and_b32_e32 v3, 32, v3
	v_lshrrev_b32_e32 v165, 4, v9
	v_bitop3_b32 v3, v0, s7, v3 bitop3:0xde
	v_lshl_or_b32 v0, v2, 6, v1
	v_lshlrev_b32_e32 v1, 2, v8
	v_and_b32_e32 v1, 32, v1
	v_lshlrev_b32_e32 v128, 5, v165
	v_bitop3_b32 v173, s55, v0, v1 bitop3:0xf6
	v_lshl_add_u64 v[0:1], s[4:5], 0, v[128:129]
	v_lshl_add_u64 v[144:145], v[0:1], 0, s[16:17]
	v_lshlrev_b32_e32 v0, 14, v10
	v_and_b32_e32 v0, 0xffff8000, v0
	v_lshl_add_u32 v0, v11, 11, v0
	v_and_b32_e32 v1, 1, v10
	v_lshl_or_b32 v0, v1, 6, v0
	s_cmpk_lt_u32 s12, 0x100
	s_waitcnt vmcnt(0)
	v_lshl_add_u32 v148, v12, 1, v0
	v_lshlrev_b32_e32 v0, 14, v13
	s_cselect_b64 s[54:55], -1, 0
	s_lshl_b32 s7, s56, 11
	v_and_b32_e32 v0, 0xffff8000, v0
	s_waitcnt vmcnt(6)
	s_add_i32 s83, s7, 0
	v_lshl_add_u32 v0, v14, 11, v0
	v_and_b32_e32 v1, 1, v13
	v_lshlrev_b32_e32 v142, 3, v165
	s_add_i32 s83, s83, 0x21000
	v_lshl_or_b32 v0, v1, 6, v0
	s_ashr_i32 s84, s33, 31
	v_lshl_add_u64 v[146:147], s[34:35], 0, v[128:129]
	v_lshl_add_u32 v179, v2, 4, s83
	v_mov_b32_e32 v149, v129
	v_lshl_add_u32 v150, v15, 1, v0
	v_mov_b32_e32 v151, v129
	s_mov_b32 s86, 0
	v_add_u32_e32 v200, 0, v3
	v_lshlrev_b32_e32 v152, 2, v142
	s_barrier
	s_branch .LBB0_2101

.LBB0_2108:
	s_add_u32 s48, s8, 0xfffc0080
	s_addc_u32 s49, s9, -1
	s_add_i32 s85, 0, 0x10000
	s_cmp_eq_u32 s71, 12
	s_cselect_b32 s65, s7, s49
	s_cselect_b32 s64, s57, s48
	v_add_u32_e32 v128, s85, v173
	s_cselect_b32 s49, s59, s70
	s_cselect_b32 s48, s68, s69
	s_add_i32 s87, 0, 0x14000
	ds_read_b128 v[174:177], v128
	ds_read_b128 v[180:183], v128 offset:1024
	ds_read_b128 v[184:187], v128 offset:2048
	ds_read_b128 v[188:191], v128 offset:3072
	v_add_u32_e32 v128, s87, v173
	ds_read_b128 v[192:195], v128
	ds_read_b128 v[196:199], v128 offset:1024
	ds_read_b128 v[202:205], v128 offset:2048
	ds_read_b128 v[206:209], v128 offset:3072
	s_add_i32 m0, s67, 0xc000
	ds_read_b128 v[216:219], v200
	ds_read_b128 v[220:223], v200 offset:1024
	ds_read_b128 v[224:227], v200 offset:2048
	ds_read_b128 v[228:231], v200 offset:3072
	ds_read_b128 v[234:237], v200 offset:4096
	ds_read_b128 v[238:241], v200 offset:5120
	ds_read_b128 v[242:245], v200 offset:6144
	ds_read_b128 v[246:249], v200 offset:7168
	global_load_lds_dwordx4 v148, s[8:9]
	s_add_i32 m0, s67, 0xe000
	s_nop 0
	global_load_lds_dwordx4 v150, s[8:9]
	s_waitcnt vmcnt(8)
	s_waitcnt lgkmcnt(0)
	s_barrier
	s_setprio 1
	s_waitcnt lgkmcnt(0)
	v_mfma_f32_16x16x32_bf16 v[124:127], v[174:177], v[216:219], v[124:127]
	v_mfma_f32_16x16x32_bf16 v[120:123], v[184:187], v[216:219], v[120:123]
	v_mfma_f32_16x16x32_bf16 v[108:111], v[174:177], v[224:227], v[108:111]
	v_mfma_f32_16x16x32_bf16 v[104:107], v[184:187], v[224:227], v[104:107]
	v_mfma_f32_16x16x32_bf16 v[92:95], v[174:177], v[234:237], v[92:95]
	v_mfma_f32_16x16x32_bf16 v[88:91], v[184:187], v[234:237], v[88:91]
	v_mfma_f32_16x16x32_bf16 v[76:79], v[174:177], v[242:245], v[76:79]
	v_mfma_f32_16x16x32_bf16 v[72:75], v[184:187], v[242:245], v[72:75]
	v_mfma_f32_16x16x32_bf16 v[124:127], v[180:183], v[220:223], v[124:127]
	v_mfma_f32_16x16x32_bf16 v[120:123], v[188:191], v[220:223], v[120:123]
	v_mfma_f32_16x16x32_bf16 v[108:111], v[180:183], v[228:231], v[108:111]
	v_mfma_f32_16x16x32_bf16 v[104:107], v[188:191], v[228:231], v[104:107]
	v_mfma_f32_16x16x32_bf16 v[92:95], v[180:183], v[238:241], v[92:95]
	v_mfma_f32_16x16x32_bf16 v[88:91], v[188:191], v[238:241], v[88:91]
	v_mfma_f32_16x16x32_bf16 v[76:79], v[180:183], v[246:249], v[76:79]
	v_mfma_f32_16x16x32_bf16 v[72:75], v[188:191], v[246:249], v[72:75]
	s_setprio 0
	s_setprio 1
	v_mfma_f32_16x16x32_bf16 v[116:119], v[192:195], v[216:219], v[116:119]
	v_mfma_f32_16x16x32_bf16 v[112:115], v[202:205], v[216:219], v[112:115]
	v_mfma_f32_16x16x32_bf16 v[100:103], v[192:195], v[224:227], v[100:103]
	v_mfma_f32_16x16x32_bf16 v[96:99], v[202:205], v[224:227], v[96:99]
	v_mfma_f32_16x16x32_bf16 v[84:87], v[192:195], v[234:237], v[84:87]
	v_mfma_f32_16x16x32_bf16 v[80:83], v[202:205], v[234:237], v[80:83]
	v_mfma_f32_16x16x32_bf16 v[68:71], v[192:195], v[242:245], v[68:71]
	v_mfma_f32_16x16x32_bf16 v[64:67], v[202:205], v[242:245], v[64:67]
	v_mfma_f32_16x16x32_bf16 v[116:119], v[196:199], v[220:223], v[116:119]
	v_mfma_f32_16x16x32_bf16 v[112:115], v[206:209], v[220:223], v[112:115]
	v_mfma_f32_16x16x32_bf16 v[100:103], v[196:199], v[228:231], v[100:103]
	v_mfma_f32_16x16x32_bf16 v[96:99], v[206:209], v[228:231], v[96:99]
	v_mfma_f32_16x16x32_bf16 v[84:87], v[196:199], v[238:241], v[84:87]
	v_mfma_f32_16x16x32_bf16 v[80:83], v[206:209], v[238:241], v[80:83]
	v_mfma_f32_16x16x32_bf16 v[68:71], v[196:199], v[246:249], v[68:71]
	v_mfma_f32_16x16x32_bf16 v[64:67], v[206:209], v[246:249], v[64:67]
	s_setprio 0
	s_barrier
	s_add_i32 s85, s85, s77
	v_lshl_add_u64 v[156:157], s[48:49], 0, v[136:137]
	s_mov_b32 m0, s85
	ds_read_b128 v[216:219], v200 offset:16384
	ds_read_b128 v[220:223], v200 offset:17408
	ds_read_b128 v[224:227], v200 offset:18432
	ds_read_b128 v[228:231], v200 offset:19456
	ds_read_b128 v[234:237], v200 offset:20480
	ds_read_b128 v[238:241], v200 offset:21504
	ds_read_b128 v[242:245], v200 offset:22528
	ds_read_b128 v[246:249], v200 offset:23552
	global_load_lds_dwordx4 v[156:157], off
	s_add_i32 m0, s85, 0x2000
	s_add_u32 s88, s48, 0x40000
	v_lshl_add_u64 v[166:167], s[48:49], 0, v[140:141]
	s_addc_u32 s89, s49, 0
	s_add_i32 s85, s87, s77
	global_load_lds_dwordx4 v[166:167], off
	s_mov_b32 m0, s85
	v_lshl_add_u64 v[210:211], s[64:65], 0, v[138:139]
	global_load_lds_dwordx4 v136, s[88:89]
	s_add_i32 m0, s85, 0x2000
	s_nop 0
	global_load_lds_dwordx4 v140, s[88:89]
	v_lshl_add_u64 v[170:171], s[64:65], 0, v[134:135]
	s_mov_b32 m0, s67
	s_nop 0
	global_load_lds_dwordx4 v[170:171], off
	s_mov_b32 m0, s78
	s_nop 0
	global_load_lds_dwordx4 v[210:211], off
	s_waitcnt vmcnt(8)
	s_waitcnt lgkmcnt(0)
	s_barrier
	s_setprio 1
	s_waitcnt lgkmcnt(0)
	v_mfma_f32_16x16x32_bf16 v[60:63], v[174:177], v[216:219], v[60:63]
	v_mfma_f32_16x16x32_bf16 v[56:59], v[184:187], v[216:219], v[56:59]
	v_mfma_f32_16x16x32_bf16 v[44:47], v[174:177], v[224:227], v[44:47]
	v_mfma_f32_16x16x32_bf16 v[40:43], v[184:187], v[224:227], v[40:43]
	v_mfma_f32_16x16x32_bf16 v[28:31], v[174:177], v[234:237], v[28:31]
	v_mfma_f32_16x16x32_bf16 v[24:27], v[184:187], v[234:237], v[24:27]
	v_mfma_f32_16x16x32_bf16 v[12:15], v[174:177], v[242:245], v[12:15]
	v_mfma_f32_16x16x32_bf16 v[8:11], v[184:187], v[242:245], v[8:11]
	v_mfma_f32_16x16x32_bf16 v[60:63], v[180:183], v[220:223], v[60:63]
	v_mfma_f32_16x16x32_bf16 v[56:59], v[188:191], v[220:223], v[56:59]
	v_mfma_f32_16x16x32_bf16 v[44:47], v[180:183], v[228:231], v[44:47]
	v_mfma_f32_16x16x32_bf16 v[40:43], v[188:191], v[228:231], v[40:43]
	v_mfma_f32_16x16x32_bf16 v[28:31], v[180:183], v[238:241], v[28:31]
	v_mfma_f32_16x16x32_bf16 v[24:27], v[188:191], v[238:241], v[24:27]
	v_mfma_f32_16x16x32_bf16 v[12:15], v[180:183], v[246:249], v[12:15]
	v_mfma_f32_16x16x32_bf16 v[8:11], v[188:191], v[246:249], v[8:11]
	s_setprio 0
	s_setprio 1
	v_mfma_f32_16x16x32_bf16 v[52:55], v[192:195], v[216:219], v[52:55]
	v_mfma_f32_16x16x32_bf16 v[48:51], v[202:205], v[216:219], v[48:51]
	v_mfma_f32_16x16x32_bf16 v[36:39], v[192:195], v[224:227], v[36:39]
	v_mfma_f32_16x16x32_bf16 v[32:35], v[202:205], v[224:227], v[32:35]
	v_mfma_f32_16x16x32_bf16 v[20:23], v[192:195], v[234:237], v[20:23]
	v_mfma_f32_16x16x32_bf16 v[16:19], v[202:205], v[234:237], v[16:19]
	v_mfma_f32_16x16x32_bf16 v[4:7], v[192:195], v[242:245], v[4:7]
	v_mfma_f32_16x16x32_bf16 v[0:3], v[202:205], v[242:245], v[0:3]
	v_mfma_f32_16x16x32_bf16 v[52:55], v[196:199], v[220:223], v[52:55]
	v_mfma_f32_16x16x32_bf16 v[48:51], v[206:209], v[220:223], v[48:51]
	v_mfma_f32_16x16x32_bf16 v[36:39], v[196:199], v[228:231], v[36:39]
	v_mfma_f32_16x16x32_bf16 v[32:35], v[206:209], v[228:231], v[32:35]
	v_mfma_f32_16x16x32_bf16 v[20:23], v[196:199], v[238:241], v[20:23]
	v_mfma_f32_16x16x32_bf16 v[16:19], v[206:209], v[238:241], v[16:19]
	v_mfma_f32_16x16x32_bf16 v[4:7], v[196:199], v[246:249], v[4:7]
	v_mfma_f32_16x16x32_bf16 v[0:3], v[206:209], v[246:249], v[0:3]
	s_setprio 0
	s_barrier
	v_add_u32_e32 v128, s0, v173
	s_add_i32 s85, 0, 0x1c000
	ds_read_b128 v[174:177], v128
	ds_read_b128 v[180:183], v128 offset:1024
	ds_read_b128 v[184:187], v128 offset:2048
	ds_read_b128 v[188:191], v128 offset:3072
	v_add_u32_e32 v128, s85, v173
	ds_read_b128 v[192:195], v128
	ds_read_b128 v[196:199], v128 offset:1024
	ds_read_b128 v[202:205], v128 offset:2048
	ds_read_b128 v[206:209], v128 offset:3072
	s_add_u32 s64, s64, 0x40000
	s_addc_u32 s65, s65, 0
	s_mov_b32 m0, s79
	ds_read_b128 v[216:219], v200 offset:32768
	ds_read_b128 v[220:223], v200 offset:33792
	ds_read_b128 v[224:227], v200 offset:34816
	ds_read_b128 v[228:231], v200 offset:35840
	ds_read_b128 v[234:237], v200 offset:36864
	ds_read_b128 v[238:241], v200 offset:37888
	ds_read_b128 v[242:245], v200 offset:38912
	ds_read_b128 v[246:249], v200 offset:39936
	global_load_lds_dwordx4 v134, s[64:65]
	s_mov_b32 m0, s80
	s_nop 0
	global_load_lds_dwordx4 v138, s[64:65]
	s_waitcnt vmcnt(8)
	s_waitcnt lgkmcnt(0)
	s_barrier
	s_setprio 1
	s_waitcnt lgkmcnt(0)
	v_mfma_f32_16x16x32_bf16 v[124:127], v[174:177], v[216:219], v[124:127]
	v_mfma_f32_16x16x32_bf16 v[120:123], v[184:187], v[216:219], v[120:123]
	v_mfma_f32_16x16x32_bf16 v[108:111], v[174:177], v[224:227], v[108:111]
	v_mfma_f32_16x16x32_bf16 v[104:107], v[184:187], v[224:227], v[104:107]
	v_mfma_f32_16x16x32_bf16 v[92:95], v[174:177], v[234:237], v[92:95]
	v_mfma_f32_16x16x32_bf16 v[88:91], v[184:187], v[234:237], v[88:91]
	v_mfma_f32_16x16x32_bf16 v[76:79], v[174:177], v[242:245], v[76:79]
	v_mfma_f32_16x16x32_bf16 v[72:75], v[184:187], v[242:245], v[72:75]
	v_mfma_f32_16x16x32_bf16 v[124:127], v[180:183], v[220:223], v[124:127]
	v_mfma_f32_16x16x32_bf16 v[120:123], v[188:191], v[220:223], v[120:123]
	v_mfma_f32_16x16x32_bf16 v[108:111], v[180:183], v[228:231], v[108:111]
	v_mfma_f32_16x16x32_bf16 v[104:107], v[188:191], v[228:231], v[104:107]
	v_mfma_f32_16x16x32_bf16 v[92:95], v[180:183], v[238:241], v[92:95]
	v_mfma_f32_16x16x32_bf16 v[88:91], v[188:191], v[238:241], v[88:91]
	v_mfma_f32_16x16x32_bf16 v[76:79], v[180:183], v[246:249], v[76:79]
	v_mfma_f32_16x16x32_bf16 v[72:75], v[188:191], v[246:249], v[72:75]
	s_setprio 0
	s_setprio 1
	v_mfma_f32_16x16x32_bf16 v[116:119], v[192:195], v[216:219], v[116:119]
	v_mfma_f32_16x16x32_bf16 v[112:115], v[202:205], v[216:219], v[112:115]
	v_mfma_f32_16x16x32_bf16 v[100:103], v[192:195], v[224:227], v[100:103]
	v_mfma_f32_16x16x32_bf16 v[96:99], v[202:205], v[224:227], v[96:99]
	v_mfma_f32_16x16x32_bf16 v[84:87], v[192:195], v[234:237], v[84:87]
	v_mfma_f32_16x16x32_bf16 v[80:83], v[202:205], v[234:237], v[80:83]
	v_mfma_f32_16x16x32_bf16 v[68:71], v[192:195], v[242:245], v[68:71]
	v_mfma_f32_16x16x32_bf16 v[64:67], v[202:205], v[242:245], v[64:67]
	v_mfma_f32_16x16x32_bf16 v[116:119], v[196:199], v[220:223], v[116:119]
	v_mfma_f32_16x16x32_bf16 v[112:115], v[206:209], v[220:223], v[112:115]
	v_mfma_f32_16x16x32_bf16 v[100:103], v[196:199], v[228:231], v[100:103]
	v_mfma_f32_16x16x32_bf16 v[96:99], v[206:209], v[228:231], v[96:99]
	v_mfma_f32_16x16x32_bf16 v[84:87], v[196:199], v[238:241], v[84:87]
	v_mfma_f32_16x16x32_bf16 v[80:83], v[206:209], v[238:241], v[80:83]
	v_mfma_f32_16x16x32_bf16 v[68:71], v[196:199], v[246:249], v[68:71]
	v_mfma_f32_16x16x32_bf16 v[64:67], v[206:209], v[246:249], v[64:67]
	s_setprio 0
	s_barrier
	s_add_i32 s64, s0, s77
	v_lshl_add_u64 v[156:157], v[156:157], 0, s[14:15]
	s_mov_b32 m0, s64
	ds_read_b128 v[216:219], v200 offset:49152
	ds_read_b128 v[220:223], v200 offset:50176
	ds_read_b128 v[224:227], v200 offset:51200
	ds_read_b128 v[228:231], v200 offset:52224
	ds_read_b128 v[234:237], v200 offset:53248
	ds_read_b128 v[238:241], v200 offset:54272
	ds_read_b128 v[242:245], v200 offset:55296
	ds_read_b128 v[246:249], v200 offset:56320
	global_load_lds_dwordx4 v[156:157], off
	s_add_i32 m0, s64, 0x2000
	s_add_u32 s48, s48, 0x40080
	v_lshl_add_u64 v[156:157], v[166:167], 0, s[14:15]
	s_addc_u32 s49, s49, 0
	s_add_i32 s64, s85, s77
	global_load_lds_dwordx4 v[156:157], off
	s_mov_b32 m0, s64
	s_nop 0
	global_load_lds_dwordx4 v136, s[48:49]
	s_add_i32 m0, s64, 0x2000
	s_nop 0
	global_load_lds_dwordx4 v140, s[48:49]
	v_lshl_add_u64 v[156:157], v[170:171], 0, s[14:15]
	s_mov_b32 m0, s81
	s_nop 0
	global_load_lds_dwordx4 v[156:157], off
	v_lshl_add_u64 v[156:157], v[210:211], 0, s[14:15]
	s_mov_b32 m0, s82
	s_nop 0
	global_load_lds_dwordx4 v[156:157], off
	s_waitcnt vmcnt(8)
	s_waitcnt lgkmcnt(0)
	s_barrier
	s_setprio 1
	s_waitcnt lgkmcnt(0)
	v_mfma_f32_16x16x32_bf16 v[60:63], v[174:177], v[216:219], v[60:63]
	v_mfma_f32_16x16x32_bf16 v[56:59], v[184:187], v[216:219], v[56:59]
	v_mfma_f32_16x16x32_bf16 v[44:47], v[174:177], v[224:227], v[44:47]
	v_mfma_f32_16x16x32_bf16 v[40:43], v[184:187], v[224:227], v[40:43]
	v_mfma_f32_16x16x32_bf16 v[28:31], v[174:177], v[234:237], v[28:31]
	v_mfma_f32_16x16x32_bf16 v[24:27], v[184:187], v[234:237], v[24:27]
	v_mfma_f32_16x16x32_bf16 v[12:15], v[174:177], v[242:245], v[12:15]
	v_mfma_f32_16x16x32_bf16 v[8:11], v[184:187], v[242:245], v[8:11]
	v_mfma_f32_16x16x32_bf16 v[60:63], v[180:183], v[220:223], v[60:63]
	v_mfma_f32_16x16x32_bf16 v[56:59], v[188:191], v[220:223], v[56:59]
	v_mfma_f32_16x16x32_bf16 v[44:47], v[180:183], v[228:231], v[44:47]
	v_mfma_f32_16x16x32_bf16 v[40:43], v[188:191], v[228:231], v[40:43]
	v_mfma_f32_16x16x32_bf16 v[28:31], v[180:183], v[238:241], v[28:31]
	v_mfma_f32_16x16x32_bf16 v[24:27], v[188:191], v[238:241], v[24:27]
	v_mfma_f32_16x16x32_bf16 v[12:15], v[180:183], v[246:249], v[12:15]
	v_mfma_f32_16x16x32_bf16 v[8:11], v[188:191], v[246:249], v[8:11]
	s_setprio 0
	s_setprio 1
	v_mfma_f32_16x16x32_bf16 v[52:55], v[192:195], v[216:219], v[52:55]
	v_mfma_f32_16x16x32_bf16 v[48:51], v[202:205], v[216:219], v[48:51]
	v_mfma_f32_16x16x32_bf16 v[36:39], v[192:195], v[224:227], v[36:39]
	v_mfma_f32_16x16x32_bf16 v[32:35], v[202:205], v[224:227], v[32:35]
	v_mfma_f32_16x16x32_bf16 v[20:23], v[192:195], v[234:237], v[20:23]
	v_mfma_f32_16x16x32_bf16 v[16:19], v[202:205], v[234:237], v[16:19]
	v_mfma_f32_16x16x32_bf16 v[4:7], v[192:195], v[242:245], v[4:7]
	v_mfma_f32_16x16x32_bf16 v[0:3], v[202:205], v[242:245], v[0:3]
	v_mfma_f32_16x16x32_bf16 v[52:55], v[196:199], v[220:223], v[52:55]
	v_mfma_f32_16x16x32_bf16 v[48:51], v[206:209], v[220:223], v[48:51]
	v_mfma_f32_16x16x32_bf16 v[36:39], v[196:199], v[228:231], v[36:39]
	v_mfma_f32_16x16x32_bf16 v[32:35], v[206:209], v[228:231], v[32:35]
	v_mfma_f32_16x16x32_bf16 v[20:23], v[196:199], v[238:241], v[20:23]
	v_mfma_f32_16x16x32_bf16 v[16:19], v[206:209], v[238:241], v[16:19]
	v_mfma_f32_16x16x32_bf16 v[4:7], v[196:199], v[246:249], v[4:7]
	v_mfma_f32_16x16x32_bf16 v[0:3], v[206:209], v[246:249], v[0:3]
	s_setprio 0
	s_barrier
	s_add_i32 s71, s71, 2
	s_add_u32 s8, s8, 0x100
	s_addc_u32 s9, s9, 0
	s_add_u32 s69, s69, 0x100
	s_addc_u32 s70, s70, 0
	s_cmp_gt_u32 s71, 13
	s_cbranch_scc0 .LBB0_2108
	s_and_b64 vcc, exec, s[54:55]
	s_cbranch_vccz .LBB0_2111
	s_barrier

.LBB0_2183:
	s_add_u32 s38, s4, 0x40000
	s_addc_u32 s39, s5, 0
	s_add_u32 s40, s4, 0x4700000
	s_addc_u32 s41, s5, 0
	s_add_u32 s42, s4, 0x7700000
	s_addc_u32 s43, s5, 0
	s_add_u32 s44, s4, 0x7b00000
	s_addc_u32 s45, s5, 0
	s_add_u32 s50, s4, 0x6700000
	s_addc_u32 s51, s5, 0
	s_add_u32 s52, s4, 0xaf00000
	s_addc_u32 s53, s5, 0
	s_add_u32 s54, s4, 0xbf00000
	v_and_b32_e32 v16, 15, v1
	s_addc_u32 s55, s5, 0
	v_or_b32_e32 v224, s9, v16
	s_add_u32 s56, s4, 0x7f00000
	v_lshlrev_b32_e32 v17, 6, v224
	v_and_b32_e32 v18, 48, v1
	s_movk_i32 s7, 0x3c0
	v_lshlrev_b32_e32 v19, 2, v224
	s_addc_u32 s57, s5, 0
	v_and_or_b32 v17, v17, s7, v18
	s_lshl_b32 s7, s8, 13
	v_and_b32_e32 v19, 32, v19
	s_add_i32 m0, s18, 0x18000
	v_lshl_add_u64 v[8:9], v[8:9], 0, s[24:25]
	v_bitop3_b32 v17, v17, s7, v19 bitop3:0xde
	s_lshl_b32 s7, s3, 12
	s_waitcnt vmcnt(2)
	s_barrier
	global_load_lds_dwordx4 v[8:9], off
	v_lshl_add_u64 v[6:7], v[6:7], 0, s[24:25]
	s_add_i32 m0, s18, 0x1a000
	s_add_i32 s77, s18, 0x8000
	s_add_i32 s84, s18, 0xa000
	global_load_lds_dwordx4 v[6:7], off
	v_lshl_add_u64 v[2:3], v[2:3], 0, s[24:25]
	s_mov_b32 m0, s77
	s_add_u32 s58, s68, 0x20080
	global_load_lds_dwordx4 v[2:3], off
	v_lshl_add_u64 v[2:3], v[4:5], 0, s[24:25]
	s_mov_b32 m0, s84
	s_addc_u32 s59, s69, 0
	global_load_lds_dwordx4 v[2:3], off
	s_add_i32 m0, s18, 0x1c000
	s_nop 0
	global_load_lds_dwordx4 v152, s[58:59]
	s_add_i32 m0, s18, 0x1e000
	v_lshlrev_b32_e32 v1, 2, v1
	global_load_lds_dwordx4 v156, s[58:59]
	v_lshl_or_b32 v18, v16, 6, v18
	v_and_b32_e32 v1, 32, v1
	v_bitop3_b32 v225, s7, v18, v1 bitop3:0xf6
	v_mov_b32_e32 v1, v145
	v_lshl_add_u64 v[164:165], s[60:61], 0, v[0:1]
	v_lshlrev_b32_e32 v0, 13, v10
	v_and_b32_e32 v0, 0xffffc000, v0
	v_lshl_add_u32 v0, v11, 10, v0
	v_and_b32_e32 v1, 1, v10
	s_cmpk_lt_u32 s1, 0x100
	v_lshl_or_b32 v0, v1, 6, v0
	s_cselect_b64 s[58:59], -1, 0
	s_lshl_b32 s1, s8, 11
	v_lshl_add_u32 v166, v12, 1, v0
	v_lshlrev_b32_e32 v0, 13, v13
	s_add_i32 s8, s1, 0
	s_lshl_b32 s1, s3, 7
	v_and_b32_e32 v0, 0xffffc000, v0
	s_waitcnt vmcnt(6)
	s_add_i32 s1, s1, 0
	v_lshlrev_b32_e32 v144, 5, v221
	v_lshl_add_u32 v0, v14, 10, v0
	v_and_b32_e32 v1, 1, v13
	v_lshlrev_b32_e32 v158, 3, v221
	s_add_i32 s8, s8, 0x21000
	s_add_i32 s1, s1, 0x23000
	v_lshl_add_u64 v[2:3], s[4:5], 0, v[144:145]
	s_mov_b64 s[4:5], 0x80200
	v_lshl_or_b32 v0, v1, 6, v0
	s_ashr_i32 s9, s95, 31
	v_add_u32_e32 v226, s1, v144
	v_lshl_add_u64 v[160:161], v[2:3], 0, s[4:5]
	v_lshl_add_u64 v[162:163], s[38:39], 0, v[144:145]
	v_lshl_add_u32 v227, v16, 4, s8
	v_mov_b32_e32 v167, v145
	v_lshl_add_u32 v168, v15, 1, v0
	v_mov_b32_e32 v169, v145
	s_mov_b32 s71, 0
	v_add_u32_e32 v228, 0, v17
	v_lshlrev_b32_e32 v170, 2, v158
	s_barrier
	s_branch .LBB0_2186

.LBB0_2189:
	s_add_u32 s68, s48, 0xfffe0080
	s_addc_u32 s69, s49, -1
	s_add_i32 s78, 0, 0x10000
	s_cmp_eq_u32 vcc_lo, 4
	s_cselect_b32 s73, s1, s69
	s_cselect_b32 s72, s7, s68
	s_cselect_b32 s69, s61, s75
	s_cselect_b32 s68, s63, s74
	s_add_i32 vcc_hi, 0, 0x14000
	v_add_u32_e32 v140, s78, v225
	v_add_u32_e32 v144, vcc_hi, v225
	ds_read_b128 v[128:131], v140
	ds_read_b128 v[132:135], v140 offset:1024
	ds_read_b128 v[136:139], v140 offset:2048
	ds_read_b128 v[140:143], v140 offset:3072
	ds_read_b128 v[172:175], v144
	ds_read_b128 v[176:179], v144 offset:1024
	ds_read_b128 v[180:183], v144 offset:2048
	ds_read_b128 v[184:187], v144 offset:3072
	s_add_i32 m0, s18, 0xc000
	ds_read_b128 v[188:191], v228
	ds_read_b128 v[192:195], v228 offset:1024
	ds_read_b128 v[196:199], v228 offset:2048
	ds_read_b128 v[200:203], v228 offset:3072
	ds_read_b128 v[204:207], v228 offset:4096
	ds_read_b128 v[208:211], v228 offset:5120
	ds_read_b128 v[234:237], v228 offset:6144
	ds_read_b128 v[238:241], v228 offset:7168
	global_load_lds_dwordx4 v166, s[48:49]
	s_add_i32 m0, s18, 0xe000
	s_nop 0
	global_load_lds_dwordx4 v168, s[48:49]
	s_waitcnt vmcnt(8)
	s_waitcnt lgkmcnt(0)
	s_barrier
	s_setprio 1
	s_waitcnt lgkmcnt(0)
	v_mfma_i32_16x16x64_i8 v[124:127], v[128:131], v[188:191], v[124:127]
	v_mfma_i32_16x16x64_i8 v[120:123], v[136:139], v[188:191], v[120:123]
	v_mfma_i32_16x16x64_i8 v[116:119], v[128:131], v[196:199], v[116:119]
	v_mfma_i32_16x16x64_i8 v[112:115], v[136:139], v[196:199], v[112:115]
	v_mfma_i32_16x16x64_i8 v[108:111], v[128:131], v[204:207], v[108:111]
	v_mfma_i32_16x16x64_i8 v[104:107], v[136:139], v[204:207], v[104:107]
	v_mfma_i32_16x16x64_i8 v[100:103], v[128:131], v[234:237], v[100:103]
	v_mfma_i32_16x16x64_i8 v[96:99], v[136:139], v[234:237], v[96:99]
	v_mfma_i32_16x16x64_i8 v[124:127], v[132:135], v[192:195], v[124:127]
	v_mfma_i32_16x16x64_i8 v[120:123], v[140:143], v[192:195], v[120:123]
	v_mfma_i32_16x16x64_i8 v[116:119], v[132:135], v[200:203], v[116:119]
	v_mfma_i32_16x16x64_i8 v[112:115], v[140:143], v[200:203], v[112:115]
	v_mfma_i32_16x16x64_i8 v[108:111], v[132:135], v[208:211], v[108:111]
	v_mfma_i32_16x16x64_i8 v[104:107], v[140:143], v[208:211], v[104:107]
	v_mfma_i32_16x16x64_i8 v[100:103], v[132:135], v[238:241], v[100:103]
	v_mfma_i32_16x16x64_i8 v[96:99], v[140:143], v[238:241], v[96:99]
	s_setprio 0
	s_setprio 1
	v_mfma_i32_16x16x64_i8 v[92:95], v[172:175], v[188:191], v[92:95]
	v_mfma_i32_16x16x64_i8 v[88:91], v[180:183], v[188:191], v[88:91]
	v_mfma_i32_16x16x64_i8 v[84:87], v[172:175], v[196:199], v[84:87]
	v_mfma_i32_16x16x64_i8 v[80:83], v[180:183], v[196:199], v[80:83]
	v_mfma_i32_16x16x64_i8 v[76:79], v[172:175], v[204:207], v[76:79]
	v_mfma_i32_16x16x64_i8 v[72:75], v[180:183], v[204:207], v[72:75]
	v_mfma_i32_16x16x64_i8 v[68:71], v[172:175], v[234:237], v[68:71]
	v_mfma_i32_16x16x64_i8 v[64:67], v[180:183], v[234:237], v[64:67]
	v_mfma_i32_16x16x64_i8 v[92:95], v[176:179], v[192:195], v[92:95]
	v_mfma_i32_16x16x64_i8 v[88:91], v[184:187], v[192:195], v[88:91]
	v_mfma_i32_16x16x64_i8 v[84:87], v[176:179], v[200:203], v[84:87]
	v_mfma_i32_16x16x64_i8 v[80:83], v[184:187], v[200:203], v[80:83]
	v_mfma_i32_16x16x64_i8 v[76:79], v[176:179], v[208:211], v[76:79]
	v_mfma_i32_16x16x64_i8 v[72:75], v[184:187], v[208:211], v[72:75]
	v_mfma_i32_16x16x64_i8 v[68:71], v[176:179], v[238:241], v[68:71]
	v_mfma_i32_16x16x64_i8 v[64:67], v[184:187], v[238:241], v[64:67]
	s_setprio 0
	s_barrier
	s_add_i32 s78, s78, s11
	v_lshl_add_u64 v[230:231], s[68:69], 0, v[152:153]
	s_mov_b32 m0, s78
	ds_read_b128 v[188:191], v228 offset:16384
	ds_read_b128 v[192:195], v228 offset:17408
	ds_read_b128 v[196:199], v228 offset:18432
	ds_read_b128 v[200:203], v228 offset:19456
	ds_read_b128 v[204:207], v228 offset:20480
	ds_read_b128 v[208:211], v228 offset:21504
	ds_read_b128 v[234:237], v228 offset:22528
	ds_read_b128 v[238:241], v228 offset:23552
	global_load_lds_dwordx4 v[230:231], off
	s_add_i32 m0, s78, 0x2000
	s_add_u32 s78, s68, 0x20000
	v_lshl_add_u64 v[242:243], s[68:69], 0, v[156:157]
	s_addc_u32 s79, s69, 0
	s_add_i32 vcc_hi, vcc_hi, s11
	global_load_lds_dwordx4 v[242:243], off
	s_mov_b32 m0, vcc_hi
	v_lshl_add_u64 v[246:247], s[72:73], 0, v[154:155]
	global_load_lds_dwordx4 v152, s[78:79]
	s_add_i32 m0, vcc_hi, 0x2000
	s_nop 0
	global_load_lds_dwordx4 v156, s[78:79]
	v_lshl_add_u64 v[244:245], s[72:73], 0, v[150:151]
	s_mov_b32 m0, s18
	s_nop 0
	global_load_lds_dwordx4 v[244:245], off
	s_mov_b32 m0, s19
	s_nop 0
	global_load_lds_dwordx4 v[246:247], off
	s_waitcnt vmcnt(8)
	s_waitcnt lgkmcnt(0)
	s_barrier
	s_setprio 1
	s_waitcnt lgkmcnt(0)
	v_mfma_i32_16x16x64_i8 v[60:63], v[128:131], v[188:191], v[60:63]
	v_mfma_i32_16x16x64_i8 v[56:59], v[136:139], v[188:191], v[56:59]
	v_mfma_i32_16x16x64_i8 v[52:55], v[128:131], v[196:199], v[52:55]
	v_mfma_i32_16x16x64_i8 v[48:51], v[136:139], v[196:199], v[48:51]
	v_mfma_i32_16x16x64_i8 v[44:47], v[128:131], v[204:207], v[44:47]
	v_mfma_i32_16x16x64_i8 v[40:43], v[136:139], v[204:207], v[40:43]
	v_mfma_i32_16x16x64_i8 v[36:39], v[128:131], v[234:237], v[36:39]
	v_mfma_i32_16x16x64_i8 v[32:35], v[136:139], v[234:237], v[32:35]
	v_mfma_i32_16x16x64_i8 v[60:63], v[132:135], v[192:195], v[60:63]
	v_mfma_i32_16x16x64_i8 v[56:59], v[140:143], v[192:195], v[56:59]
	v_mfma_i32_16x16x64_i8 v[52:55], v[132:135], v[200:203], v[52:55]
	v_mfma_i32_16x16x64_i8 v[48:51], v[140:143], v[200:203], v[48:51]
	v_mfma_i32_16x16x64_i8 v[44:47], v[132:135], v[208:211], v[44:47]
	v_mfma_i32_16x16x64_i8 v[40:43], v[140:143], v[208:211], v[40:43]
	v_mfma_i32_16x16x64_i8 v[36:39], v[132:135], v[238:241], v[36:39]
	v_mfma_i32_16x16x64_i8 v[32:35], v[140:143], v[238:241], v[32:35]
	s_setprio 0
	s_setprio 1
	v_mfma_i32_16x16x64_i8 v[28:31], v[172:175], v[188:191], v[28:31]
	v_mfma_i32_16x16x64_i8 v[24:27], v[180:183], v[188:191], v[24:27]
	v_mfma_i32_16x16x64_i8 v[20:23], v[172:175], v[196:199], v[20:23]
	v_mfma_i32_16x16x64_i8 v[16:19], v[180:183], v[196:199], v[16:19]
	v_mfma_i32_16x16x64_i8 v[12:15], v[172:175], v[204:207], v[12:15]
	v_mfma_i32_16x16x64_i8 v[8:11], v[180:183], v[204:207], v[8:11]
	v_mfma_i32_16x16x64_i8 v[4:7], v[172:175], v[234:237], v[4:7]
	v_mfma_i32_16x16x64_i8 v[0:3], v[180:183], v[234:237], v[0:3]
	v_mfma_i32_16x16x64_i8 v[28:31], v[176:179], v[192:195], v[28:31]
	v_mfma_i32_16x16x64_i8 v[24:27], v[184:187], v[192:195], v[24:27]
	v_mfma_i32_16x16x64_i8 v[20:23], v[176:179], v[200:203], v[20:23]
	v_mfma_i32_16x16x64_i8 v[16:19], v[184:187], v[200:203], v[16:19]
	v_mfma_i32_16x16x64_i8 v[12:15], v[176:179], v[208:211], v[12:15]
	v_mfma_i32_16x16x64_i8 v[8:11], v[184:187], v[208:211], v[8:11]
	v_mfma_i32_16x16x64_i8 v[4:7], v[176:179], v[238:241], v[4:7]
	v_mfma_i32_16x16x64_i8 v[0:3], v[184:187], v[238:241], v[0:3]
	s_setprio 0
	s_barrier
	s_add_i32 s78, 0, 0x1c000
	v_add_u32_e32 v140, s0, v225
	v_add_u32_e32 v144, s78, v225
	ds_read_b128 v[128:131], v140
	ds_read_b128 v[132:135], v140 offset:1024
	ds_read_b128 v[136:139], v140 offset:2048
	ds_read_b128 v[140:143], v140 offset:3072
	ds_read_b128 v[172:175], v144
	ds_read_b128 v[176:179], v144 offset:1024
	ds_read_b128 v[180:183], v144 offset:2048
	ds_read_b128 v[184:187], v144 offset:3072
	s_add_u32 s72, s72, 0x20000
	s_addc_u32 s73, s73, 0
	s_mov_b32 m0, s20
	ds_read_b128 v[188:191], v228 offset:32768
	ds_read_b128 v[192:195], v228 offset:33792
	ds_read_b128 v[196:199], v228 offset:34816
	ds_read_b128 v[200:203], v228 offset:35840
	ds_read_b128 v[204:207], v228 offset:36864
	ds_read_b128 v[208:211], v228 offset:37888
	ds_read_b128 v[234:237], v228 offset:38912
	ds_read_b128 v[238:241], v228 offset:39936
	global_load_lds_dwordx4 v150, s[72:73]
	s_mov_b32 m0, s21
	s_nop 0
	global_load_lds_dwordx4 v154, s[72:73]
	s_waitcnt vmcnt(8)
	s_waitcnt lgkmcnt(0)
	s_barrier
	s_setprio 1
	s_waitcnt lgkmcnt(0)
	v_mfma_i32_16x16x64_i8 v[124:127], v[128:131], v[188:191], v[124:127]
	v_mfma_i32_16x16x64_i8 v[120:123], v[136:139], v[188:191], v[120:123]
	v_mfma_i32_16x16x64_i8 v[116:119], v[128:131], v[196:199], v[116:119]
	v_mfma_i32_16x16x64_i8 v[112:115], v[136:139], v[196:199], v[112:115]
	v_mfma_i32_16x16x64_i8 v[108:111], v[128:131], v[204:207], v[108:111]
	v_mfma_i32_16x16x64_i8 v[104:107], v[136:139], v[204:207], v[104:107]
	v_mfma_i32_16x16x64_i8 v[100:103], v[128:131], v[234:237], v[100:103]
	v_mfma_i32_16x16x64_i8 v[96:99], v[136:139], v[234:237], v[96:99]
	v_mfma_i32_16x16x64_i8 v[124:127], v[132:135], v[192:195], v[124:127]
	v_mfma_i32_16x16x64_i8 v[120:123], v[140:143], v[192:195], v[120:123]
	v_mfma_i32_16x16x64_i8 v[116:119], v[132:135], v[200:203], v[116:119]
	v_mfma_i32_16x16x64_i8 v[112:115], v[140:143], v[200:203], v[112:115]
	v_mfma_i32_16x16x64_i8 v[108:111], v[132:135], v[208:211], v[108:111]
	v_mfma_i32_16x16x64_i8 v[104:107], v[140:143], v[208:211], v[104:107]
	v_mfma_i32_16x16x64_i8 v[100:103], v[132:135], v[238:241], v[100:103]
	v_mfma_i32_16x16x64_i8 v[96:99], v[140:143], v[238:241], v[96:99]
	s_setprio 0
	s_setprio 1
	v_mfma_i32_16x16x64_i8 v[92:95], v[172:175], v[188:191], v[92:95]
	v_mfma_i32_16x16x64_i8 v[88:91], v[180:183], v[188:191], v[88:91]
	v_mfma_i32_16x16x64_i8 v[84:87], v[172:175], v[196:199], v[84:87]
	v_mfma_i32_16x16x64_i8 v[80:83], v[180:183], v[196:199], v[80:83]
	v_mfma_i32_16x16x64_i8 v[76:79], v[172:175], v[204:207], v[76:79]
	v_mfma_i32_16x16x64_i8 v[72:75], v[180:183], v[204:207], v[72:75]
	v_mfma_i32_16x16x64_i8 v[68:71], v[172:175], v[234:237], v[68:71]
	v_mfma_i32_16x16x64_i8 v[64:67], v[180:183], v[234:237], v[64:67]
	v_mfma_i32_16x16x64_i8 v[92:95], v[176:179], v[192:195], v[92:95]
	v_mfma_i32_16x16x64_i8 v[88:91], v[184:187], v[192:195], v[88:91]
	v_mfma_i32_16x16x64_i8 v[84:87], v[176:179], v[200:203], v[84:87]
	v_mfma_i32_16x16x64_i8 v[80:83], v[184:187], v[200:203], v[80:83]
	v_mfma_i32_16x16x64_i8 v[76:79], v[176:179], v[208:211], v[76:79]
	v_mfma_i32_16x16x64_i8 v[72:75], v[184:187], v[208:211], v[72:75]
	v_mfma_i32_16x16x64_i8 v[68:71], v[176:179], v[238:241], v[68:71]
	v_mfma_i32_16x16x64_i8 v[64:67], v[184:187], v[238:241], v[64:67]
	s_setprio 0
	s_barrier
	s_add_i32 s72, s0, s11
	v_lshl_add_u64 v[230:231], v[230:231], 0, s[24:25]
	s_mov_b32 m0, s72
	ds_read_b128 v[188:191], v228 offset:49152
	ds_read_b128 v[192:195], v228 offset:50176
	ds_read_b128 v[196:199], v228 offset:51200
	ds_read_b128 v[200:203], v228 offset:52224
	ds_read_b128 v[204:207], v228 offset:53248
	ds_read_b128 v[208:211], v228 offset:54272
	ds_read_b128 v[234:237], v228 offset:55296
	ds_read_b128 v[238:241], v228 offset:56320
	global_load_lds_dwordx4 v[230:231], off
	s_add_i32 m0, s72, 0x2000
	s_add_u32 s68, s68, 0x20080
	v_lshl_add_u64 v[230:231], v[242:243], 0, s[24:25]
	s_addc_u32 s69, s69, 0
	s_add_i32 s72, s78, s11
	global_load_lds_dwordx4 v[230:231], off
	s_mov_b32 m0, s72
	s_nop 0
	global_load_lds_dwordx4 v152, s[68:69]
	s_add_i32 m0, s72, 0x2000
	s_nop 0
	global_load_lds_dwordx4 v156, s[68:69]
	v_lshl_add_u64 v[230:231], v[244:245], 0, s[24:25]
	s_mov_b32 m0, s77
	s_nop 0
	global_load_lds_dwordx4 v[230:231], off
	v_lshl_add_u64 v[230:231], v[246:247], 0, s[24:25]
	s_mov_b32 m0, s84
	s_nop 0
	global_load_lds_dwordx4 v[230:231], off
	s_waitcnt vmcnt(8)
	s_waitcnt lgkmcnt(0)
	s_barrier
	s_setprio 1
	s_waitcnt lgkmcnt(0)
	v_mfma_i32_16x16x64_i8 v[60:63], v[128:131], v[188:191], v[60:63]
	v_mfma_i32_16x16x64_i8 v[56:59], v[136:139], v[188:191], v[56:59]
	v_mfma_i32_16x16x64_i8 v[52:55], v[128:131], v[196:199], v[52:55]
	v_mfma_i32_16x16x64_i8 v[48:51], v[136:139], v[196:199], v[48:51]
	v_mfma_i32_16x16x64_i8 v[44:47], v[128:131], v[204:207], v[44:47]
	v_mfma_i32_16x16x64_i8 v[40:43], v[136:139], v[204:207], v[40:43]
	v_mfma_i32_16x16x64_i8 v[36:39], v[128:131], v[234:237], v[36:39]
	v_mfma_i32_16x16x64_i8 v[32:35], v[136:139], v[234:237], v[32:35]
	v_mfma_i32_16x16x64_i8 v[60:63], v[132:135], v[192:195], v[60:63]
	v_mfma_i32_16x16x64_i8 v[56:59], v[140:143], v[192:195], v[56:59]
	v_mfma_i32_16x16x64_i8 v[52:55], v[132:135], v[200:203], v[52:55]
	v_mfma_i32_16x16x64_i8 v[48:51], v[140:143], v[200:203], v[48:51]
	v_mfma_i32_16x16x64_i8 v[44:47], v[132:135], v[208:211], v[44:47]
	v_mfma_i32_16x16x64_i8 v[40:43], v[140:143], v[208:211], v[40:43]
	v_mfma_i32_16x16x64_i8 v[36:39], v[132:135], v[238:241], v[36:39]
	v_mfma_i32_16x16x64_i8 v[32:35], v[140:143], v[238:241], v[32:35]
	s_setprio 0
	s_setprio 1
	v_mfma_i32_16x16x64_i8 v[28:31], v[172:175], v[188:191], v[28:31]
	v_mfma_i32_16x16x64_i8 v[24:27], v[180:183], v[188:191], v[24:27]
	v_mfma_i32_16x16x64_i8 v[20:23], v[172:175], v[196:199], v[20:23]
	v_mfma_i32_16x16x64_i8 v[16:19], v[180:183], v[196:199], v[16:19]
	v_mfma_i32_16x16x64_i8 v[12:15], v[172:175], v[204:207], v[12:15]
	v_mfma_i32_16x16x64_i8 v[8:11], v[180:183], v[204:207], v[8:11]
	v_mfma_i32_16x16x64_i8 v[4:7], v[172:175], v[234:237], v[4:7]
	v_mfma_i32_16x16x64_i8 v[0:3], v[180:183], v[234:237], v[0:3]
	v_mfma_i32_16x16x64_i8 v[28:31], v[176:179], v[192:195], v[28:31]
	v_mfma_i32_16x16x64_i8 v[24:27], v[184:187], v[192:195], v[24:27]
	v_mfma_i32_16x16x64_i8 v[20:23], v[176:179], v[200:203], v[20:23]
	v_mfma_i32_16x16x64_i8 v[16:19], v[184:187], v[200:203], v[16:19]
	v_mfma_i32_16x16x64_i8 v[12:15], v[176:179], v[208:211], v[12:15]
	v_mfma_i32_16x16x64_i8 v[8:11], v[184:187], v[208:211], v[8:11]
	v_mfma_i32_16x16x64_i8 v[4:7], v[176:179], v[238:241], v[4:7]
	v_mfma_i32_16x16x64_i8 v[0:3], v[184:187], v[238:241], v[0:3]
	s_setprio 0
	s_barrier
	s_add_i32 vcc_lo, vcc_lo, 2
	s_add_u32 s48, s48, 0x100
	s_addc_u32 s49, s49, 0
	s_add_u32 s74, s74, 0x100
	s_addc_u32 s75, s75, 0
	s_cmp_gt_u32 vcc_lo, 5
	s_cbranch_scc0 .LBB0_2189
	s_and_b64 vcc, exec, s[58:59]
	s_cbranch_vccz .LBB0_2192
	s_barrier

.LBB0_2510:
	s_add_u32 s28, s4, 0x40000
	s_addc_u32 s29, s5, 0
	s_add_u32 s30, s4, 0x4700000
	s_addc_u32 s31, s5, 0
	s_add_u32 s34, s4, 0x7700000
	s_addc_u32 s35, s5, 0
	s_add_u32 s36, s4, 0x7b00000
	s_addc_u32 s37, s5, 0
	s_add_u32 s38, s4, 0x6700000
	s_addc_u32 s39, s5, 0
	s_add_u32 s40, s4, 0xaf00000
	s_addc_u32 s41, s5, 0
	s_add_u32 s42, s4, 0xbf00000
	s_addc_u32 s43, s5, 0
	s_add_u32 s44, s4, 0x7f00000
	s_addc_u32 s45, s5, 0
	s_add_i32 m0, s63, 0x18000
	v_lshl_add_u64 v[6:7], v[6:7], 0, s[12:13]
	s_lshl_b32 s7, s52, 13
	s_lshl_b32 s53, s70, 12
	s_waitcnt vmcnt(2)
	s_barrier
	global_load_lds_dwordx4 v[6:7], off
	v_lshl_add_u64 v[4:5], v[4:5], 0, s[12:13]
	s_add_i32 m0, s63, 0x1a000
	s_add_i32 s79, s63, 0x8000
	s_add_i32 s80, s63, 0xa000
	global_load_lds_dwordx4 v[4:5], off
	v_lshl_add_u64 v[0:1], v[0:1], 0, s[12:13]
	s_mov_b32 m0, s79
	s_add_u32 s54, s48, 0x40080
	global_load_lds_dwordx4 v[0:1], off
	v_lshl_add_u64 v[0:1], v[2:3], 0, s[12:13]
	s_mov_b32 m0, s80
	s_addc_u32 s55, s49, 0
	global_load_lds_dwordx4 v[0:1], off
	s_add_i32 m0, s63, 0x1c000
	s_nop 0
	global_load_lds_dwordx4 v136, s[54:55]
	s_add_i32 m0, s63, 0x1e000
	v_and_b32_e32 v2, 15, v8
	global_load_lds_dwordx4 v140, s[54:55]
	v_or_b32_e32 v169, s51, v2
	v_lshlrev_b32_e32 v0, 6, v169
	v_and_b32_e32 v1, 48, v8
	s_movk_i32 s51, 0x3c0
	v_lshlrev_b32_e32 v3, 2, v169
	v_and_or_b32 v0, v0, s51, v1
	v_and_b32_e32 v3, 32, v3
	v_lshrrev_b32_e32 v165, 4, v9
	v_bitop3_b32 v3, v0, s7, v3 bitop3:0xde
	v_lshl_or_b32 v0, v2, 6, v1
	v_lshlrev_b32_e32 v1, 2, v8
	v_and_b32_e32 v1, 32, v1
	v_lshlrev_b32_e32 v128, 5, v165
	v_bitop3_b32 v173, s53, v0, v1 bitop3:0xf6
	v_lshl_add_u64 v[0:1], s[4:5], 0, v[128:129]
	s_mov_b64 s[4:5], 0x80200
	v_lshl_add_u64 v[144:145], v[0:1], 0, s[4:5]
	v_lshlrev_b32_e32 v0, 14, v10
	v_and_b32_e32 v0, 0xffff8000, v0
	v_lshl_add_u32 v0, v11, 11, v0
	v_and_b32_e32 v1, 1, v10
	v_lshl_or_b32 v0, v1, 6, v0
	s_cmpk_lt_u32 s50, 0x100
	s_waitcnt vmcnt(0)
	v_lshl_add_u32 v148, v12, 1, v0
	v_lshlrev_b32_e32 v0, 14, v13
	s_cselect_b64 s[50:51], -1, 0
	s_lshl_b32 s7, s52, 11
	v_and_b32_e32 v0, 0xffff8000, v0
	s_waitcnt vmcnt(6)
	s_add_i32 s81, s7, 0
	v_lshl_add_u32 v0, v14, 11, v0
	v_and_b32_e32 v1, 1, v13
	v_lshlrev_b32_e32 v142, 3, v165
	s_add_i32 s81, s81, 0x21000
	v_lshl_or_b32 v0, v1, 6, v0
	s_ashr_i32 s82, s69, 31
	v_lshl_add_u64 v[146:147], s[28:29], 0, v[128:129]
	v_lshl_add_u32 v179, v2, 4, s81
	v_mov_b32_e32 v149, v129
	v_lshl_add_u32 v150, v15, 1, v0
	v_mov_b32_e32 v151, v129
	s_mov_b32 s85, 0
	v_add_u32_e32 v203, 0, v3
	v_lshlrev_b32_e32 v152, 2, v142
	s_barrier
	s_branch .LBB0_2513

.LBB0_2520:
	s_add_u32 s48, s8, 0xfffc0080
	s_addc_u32 s49, s9, -1
	s_add_i32 s84, 0, 0x10000
	s_cmp_eq_u32 s67, 12
	s_cselect_b32 s61, s7, s49
	s_cselect_b32 s60, s55, s48
	v_add_u32_e32 v128, s84, v173
	s_cselect_b32 s49, s53, s66
	s_cselect_b32 s48, s64, s65
	s_add_i32 s88, 0, 0x14000
	ds_read_b128 v[174:177], v128
	ds_read_b128 v[180:183], v128 offset:1024
	ds_read_b128 v[184:187], v128 offset:2048
	ds_read_b128 v[188:191], v128 offset:3072
	v_add_u32_e32 v128, s88, v173
	ds_read_b128 v[192:195], v128
	ds_read_b128 v[196:199], v128 offset:1024
	ds_read_b128 v[204:207], v128 offset:2048
	ds_read_b128 v[208:211], v128 offset:3072
	s_add_i32 m0, s63, 0xc000
	ds_read_b128 v[212:215], v203
	ds_read_b128 v[216:219], v203 offset:1024
	ds_read_b128 v[220:223], v203 offset:2048
	ds_read_b128 v[224:227], v203 offset:3072
	ds_read_b128 v[228:231], v203 offset:4096
	ds_read_b128 v[234:237], v203 offset:5120
	ds_read_b128 v[238:241], v203 offset:6144
	ds_read_b128 v[242:245], v203 offset:7168
	global_load_lds_dwordx4 v148, s[8:9]
	s_add_i32 m0, s63, 0xe000
	s_nop 0
	global_load_lds_dwordx4 v150, s[8:9]
	s_waitcnt vmcnt(8)
	s_waitcnt lgkmcnt(0)
	s_barrier
	s_setprio 1
	s_waitcnt lgkmcnt(0)
	v_mfma_f32_16x16x32_bf16 v[124:127], v[174:177], v[212:215], v[124:127]
	v_mfma_f32_16x16x32_bf16 v[120:123], v[184:187], v[212:215], v[120:123]
	v_mfma_f32_16x16x32_bf16 v[108:111], v[174:177], v[220:223], v[108:111]
	v_mfma_f32_16x16x32_bf16 v[104:107], v[184:187], v[220:223], v[104:107]
	v_mfma_f32_16x16x32_bf16 v[92:95], v[174:177], v[228:231], v[92:95]
	v_mfma_f32_16x16x32_bf16 v[88:91], v[184:187], v[228:231], v[88:91]
	v_mfma_f32_16x16x32_bf16 v[76:79], v[174:177], v[238:241], v[76:79]
	v_mfma_f32_16x16x32_bf16 v[72:75], v[184:187], v[238:241], v[72:75]
	v_mfma_f32_16x16x32_bf16 v[124:127], v[180:183], v[216:219], v[124:127]
	v_mfma_f32_16x16x32_bf16 v[120:123], v[188:191], v[216:219], v[120:123]
	v_mfma_f32_16x16x32_bf16 v[108:111], v[180:183], v[224:227], v[108:111]
	v_mfma_f32_16x16x32_bf16 v[104:107], v[188:191], v[224:227], v[104:107]
	v_mfma_f32_16x16x32_bf16 v[92:95], v[180:183], v[234:237], v[92:95]
	v_mfma_f32_16x16x32_bf16 v[88:91], v[188:191], v[234:237], v[88:91]
	v_mfma_f32_16x16x32_bf16 v[76:79], v[180:183], v[242:245], v[76:79]
	v_mfma_f32_16x16x32_bf16 v[72:75], v[188:191], v[242:245], v[72:75]
	s_setprio 0
	s_setprio 1
	v_mfma_f32_16x16x32_bf16 v[116:119], v[192:195], v[212:215], v[116:119]
	v_mfma_f32_16x16x32_bf16 v[112:115], v[204:207], v[212:215], v[112:115]
	v_mfma_f32_16x16x32_bf16 v[100:103], v[192:195], v[220:223], v[100:103]
	v_mfma_f32_16x16x32_bf16 v[96:99], v[204:207], v[220:223], v[96:99]
	v_mfma_f32_16x16x32_bf16 v[84:87], v[192:195], v[228:231], v[84:87]
	v_mfma_f32_16x16x32_bf16 v[80:83], v[204:207], v[228:231], v[80:83]
	v_mfma_f32_16x16x32_bf16 v[68:71], v[192:195], v[238:241], v[68:71]
	v_mfma_f32_16x16x32_bf16 v[64:67], v[204:207], v[238:241], v[64:67]
	v_mfma_f32_16x16x32_bf16 v[116:119], v[196:199], v[216:219], v[116:119]
	v_mfma_f32_16x16x32_bf16 v[112:115], v[208:211], v[216:219], v[112:115]
	v_mfma_f32_16x16x32_bf16 v[100:103], v[196:199], v[224:227], v[100:103]
	v_mfma_f32_16x16x32_bf16 v[96:99], v[208:211], v[224:227], v[96:99]
	v_mfma_f32_16x16x32_bf16 v[84:87], v[196:199], v[234:237], v[84:87]
	v_mfma_f32_16x16x32_bf16 v[80:83], v[208:211], v[234:237], v[80:83]
	v_mfma_f32_16x16x32_bf16 v[68:71], v[196:199], v[242:245], v[68:71]
	v_mfma_f32_16x16x32_bf16 v[64:67], v[208:211], v[242:245], v[64:67]
	s_setprio 0
	s_barrier
	s_add_i32 s84, s84, s75
	v_lshl_add_u64 v[156:157], s[48:49], 0, v[136:137]
	s_mov_b32 m0, s84
	ds_read_b128 v[212:215], v203 offset:16384
	ds_read_b128 v[216:219], v203 offset:17408
	ds_read_b128 v[220:223], v203 offset:18432
	ds_read_b128 v[224:227], v203 offset:19456
	ds_read_b128 v[228:231], v203 offset:20480
	ds_read_b128 v[234:237], v203 offset:21504
	ds_read_b128 v[238:241], v203 offset:22528
	ds_read_b128 v[242:245], v203 offset:23552
	global_load_lds_dwordx4 v[156:157], off
	s_add_i32 m0, s84, 0x2000
	s_add_u32 s86, s48, 0x40000
	v_lshl_add_u64 v[166:167], s[48:49], 0, v[140:141]
	s_addc_u32 s87, s49, 0
	s_add_i32 s84, s88, s75
	global_load_lds_dwordx4 v[166:167], off
	s_mov_b32 m0, s84
	v_lshl_add_u64 v[246:247], s[60:61], 0, v[138:139]
	global_load_lds_dwordx4 v136, s[86:87]
	s_add_i32 m0, s84, 0x2000
	s_nop 0
	global_load_lds_dwordx4 v140, s[86:87]
	v_lshl_add_u64 v[170:171], s[60:61], 0, v[134:135]
	s_mov_b32 m0, s63
	s_nop 0
	global_load_lds_dwordx4 v[170:171], off
	s_mov_b32 m0, s76
	s_nop 0
	global_load_lds_dwordx4 v[246:247], off
	s_waitcnt vmcnt(8)
	s_waitcnt lgkmcnt(0)
	s_barrier
	s_setprio 1
	s_waitcnt lgkmcnt(0)
	v_mfma_f32_16x16x32_bf16 v[60:63], v[174:177], v[212:215], v[60:63]
	v_mfma_f32_16x16x32_bf16 v[56:59], v[184:187], v[212:215], v[56:59]
	v_mfma_f32_16x16x32_bf16 v[44:47], v[174:177], v[220:223], v[44:47]
	v_mfma_f32_16x16x32_bf16 v[40:43], v[184:187], v[220:223], v[40:43]
	v_mfma_f32_16x16x32_bf16 v[28:31], v[174:177], v[228:231], v[28:31]
	v_mfma_f32_16x16x32_bf16 v[24:27], v[184:187], v[228:231], v[24:27]
	v_mfma_f32_16x16x32_bf16 v[12:15], v[174:177], v[238:241], v[12:15]
	v_mfma_f32_16x16x32_bf16 v[8:11], v[184:187], v[238:241], v[8:11]
	v_mfma_f32_16x16x32_bf16 v[60:63], v[180:183], v[216:219], v[60:63]
	v_mfma_f32_16x16x32_bf16 v[56:59], v[188:191], v[216:219], v[56:59]
	v_mfma_f32_16x16x32_bf16 v[44:47], v[180:183], v[224:227], v[44:47]
	v_mfma_f32_16x16x32_bf16 v[40:43], v[188:191], v[224:227], v[40:43]
	v_mfma_f32_16x16x32_bf16 v[28:31], v[180:183], v[234:237], v[28:31]
	v_mfma_f32_16x16x32_bf16 v[24:27], v[188:191], v[234:237], v[24:27]
	v_mfma_f32_16x16x32_bf16 v[12:15], v[180:183], v[242:245], v[12:15]
	v_mfma_f32_16x16x32_bf16 v[8:11], v[188:191], v[242:245], v[8:11]
	s_setprio 0
	s_setprio 1
	v_mfma_f32_16x16x32_bf16 v[52:55], v[192:195], v[212:215], v[52:55]
	v_mfma_f32_16x16x32_bf16 v[48:51], v[204:207], v[212:215], v[48:51]
	v_mfma_f32_16x16x32_bf16 v[36:39], v[192:195], v[220:223], v[36:39]
	v_mfma_f32_16x16x32_bf16 v[32:35], v[204:207], v[220:223], v[32:35]
	v_mfma_f32_16x16x32_bf16 v[20:23], v[192:195], v[228:231], v[20:23]
	v_mfma_f32_16x16x32_bf16 v[16:19], v[204:207], v[228:231], v[16:19]
	v_mfma_f32_16x16x32_bf16 v[4:7], v[192:195], v[238:241], v[4:7]
	v_mfma_f32_16x16x32_bf16 v[0:3], v[204:207], v[238:241], v[0:3]
	v_mfma_f32_16x16x32_bf16 v[52:55], v[196:199], v[216:219], v[52:55]
	v_mfma_f32_16x16x32_bf16 v[48:51], v[208:211], v[216:219], v[48:51]
	v_mfma_f32_16x16x32_bf16 v[36:39], v[196:199], v[224:227], v[36:39]
	v_mfma_f32_16x16x32_bf16 v[32:35], v[208:211], v[224:227], v[32:35]
	v_mfma_f32_16x16x32_bf16 v[20:23], v[196:199], v[234:237], v[20:23]
	v_mfma_f32_16x16x32_bf16 v[16:19], v[208:211], v[234:237], v[16:19]
	v_mfma_f32_16x16x32_bf16 v[4:7], v[196:199], v[242:245], v[4:7]
	v_mfma_f32_16x16x32_bf16 v[0:3], v[208:211], v[242:245], v[0:3]
	s_setprio 0
	s_barrier
	v_add_u32_e32 v128, s0, v173
	s_add_i32 s84, 0, 0x1c000
	ds_read_b128 v[174:177], v128
	ds_read_b128 v[180:183], v128 offset:1024
	ds_read_b128 v[184:187], v128 offset:2048
	ds_read_b128 v[188:191], v128 offset:3072
	v_add_u32_e32 v128, s84, v173
	ds_read_b128 v[192:195], v128
	ds_read_b128 v[196:199], v128 offset:1024
	ds_read_b128 v[204:207], v128 offset:2048
	ds_read_b128 v[208:211], v128 offset:3072
	s_add_u32 s60, s60, 0x40000
	s_addc_u32 s61, s61, 0
	s_mov_b32 m0, s77
	ds_read_b128 v[212:215], v203 offset:32768
	ds_read_b128 v[216:219], v203 offset:33792
	ds_read_b128 v[220:223], v203 offset:34816
	ds_read_b128 v[224:227], v203 offset:35840
	ds_read_b128 v[228:231], v203 offset:36864
	ds_read_b128 v[234:237], v203 offset:37888
	ds_read_b128 v[238:241], v203 offset:38912
	ds_read_b128 v[242:245], v203 offset:39936
	global_load_lds_dwordx4 v134, s[60:61]
	s_mov_b32 m0, s78
	s_nop 0
	global_load_lds_dwordx4 v138, s[60:61]
	s_waitcnt vmcnt(8)
	s_waitcnt lgkmcnt(0)
	s_barrier
	s_setprio 1
	s_waitcnt lgkmcnt(0)
	v_mfma_f32_16x16x32_bf16 v[124:127], v[174:177], v[212:215], v[124:127]
	v_mfma_f32_16x16x32_bf16 v[120:123], v[184:187], v[212:215], v[120:123]
	v_mfma_f32_16x16x32_bf16 v[108:111], v[174:177], v[220:223], v[108:111]
	v_mfma_f32_16x16x32_bf16 v[104:107], v[184:187], v[220:223], v[104:107]
	v_mfma_f32_16x16x32_bf16 v[92:95], v[174:177], v[228:231], v[92:95]
	v_mfma_f32_16x16x32_bf16 v[88:91], v[184:187], v[228:231], v[88:91]
	v_mfma_f32_16x16x32_bf16 v[76:79], v[174:177], v[238:241], v[76:79]
	v_mfma_f32_16x16x32_bf16 v[72:75], v[184:187], v[238:241], v[72:75]
	v_mfma_f32_16x16x32_bf16 v[124:127], v[180:183], v[216:219], v[124:127]
	v_mfma_f32_16x16x32_bf16 v[120:123], v[188:191], v[216:219], v[120:123]
	v_mfma_f32_16x16x32_bf16 v[108:111], v[180:183], v[224:227], v[108:111]
	v_mfma_f32_16x16x32_bf16 v[104:107], v[188:191], v[224:227], v[104:107]
	v_mfma_f32_16x16x32_bf16 v[92:95], v[180:183], v[234:237], v[92:95]
	v_mfma_f32_16x16x32_bf16 v[88:91], v[188:191], v[234:237], v[88:91]
	v_mfma_f32_16x16x32_bf16 v[76:79], v[180:183], v[242:245], v[76:79]
	v_mfma_f32_16x16x32_bf16 v[72:75], v[188:191], v[242:245], v[72:75]
	s_setprio 0
	s_setprio 1
	v_mfma_f32_16x16x32_bf16 v[116:119], v[192:195], v[212:215], v[116:119]
	v_mfma_f32_16x16x32_bf16 v[112:115], v[204:207], v[212:215], v[112:115]
	v_mfma_f32_16x16x32_bf16 v[100:103], v[192:195], v[220:223], v[100:103]
	v_mfma_f32_16x16x32_bf16 v[96:99], v[204:207], v[220:223], v[96:99]
	v_mfma_f32_16x16x32_bf16 v[84:87], v[192:195], v[228:231], v[84:87]
	v_mfma_f32_16x16x32_bf16 v[80:83], v[204:207], v[228:231], v[80:83]
	v_mfma_f32_16x16x32_bf16 v[68:71], v[192:195], v[238:241], v[68:71]
	v_mfma_f32_16x16x32_bf16 v[64:67], v[204:207], v[238:241], v[64:67]
	v_mfma_f32_16x16x32_bf16 v[116:119], v[196:199], v[216:219], v[116:119]
	v_mfma_f32_16x16x32_bf16 v[112:115], v[208:211], v[216:219], v[112:115]
	v_mfma_f32_16x16x32_bf16 v[100:103], v[196:199], v[224:227], v[100:103]
	v_mfma_f32_16x16x32_bf16 v[96:99], v[208:211], v[224:227], v[96:99]
	v_mfma_f32_16x16x32_bf16 v[84:87], v[196:199], v[234:237], v[84:87]
	v_mfma_f32_16x16x32_bf16 v[80:83], v[208:211], v[234:237], v[80:83]
	v_mfma_f32_16x16x32_bf16 v[68:71], v[196:199], v[242:245], v[68:71]
	v_mfma_f32_16x16x32_bf16 v[64:67], v[208:211], v[242:245], v[64:67]
	s_setprio 0
	s_barrier
	s_add_i32 s60, s0, s75
	v_lshl_add_u64 v[156:157], v[156:157], 0, s[12:13]
	s_mov_b32 m0, s60
	ds_read_b128 v[212:215], v203 offset:49152
	ds_read_b128 v[216:219], v203 offset:50176
	ds_read_b128 v[220:223], v203 offset:51200
	ds_read_b128 v[224:227], v203 offset:52224
	ds_read_b128 v[228:231], v203 offset:53248
	ds_read_b128 v[234:237], v203 offset:54272
	ds_read_b128 v[238:241], v203 offset:55296
	ds_read_b128 v[242:245], v203 offset:56320
	global_load_lds_dwordx4 v[156:157], off
	s_add_i32 m0, s60, 0x2000
	s_add_u32 s48, s48, 0x40080
	v_lshl_add_u64 v[156:157], v[166:167], 0, s[12:13]
	s_addc_u32 s49, s49, 0
	s_add_i32 s60, s84, s75
	global_load_lds_dwordx4 v[156:157], off
	s_mov_b32 m0, s60
	s_nop 0
	global_load_lds_dwordx4 v136, s[48:49]
	s_add_i32 m0, s60, 0x2000
	s_nop 0
	global_load_lds_dwordx4 v140, s[48:49]
	v_lshl_add_u64 v[156:157], v[170:171], 0, s[12:13]
	s_mov_b32 m0, s79
	s_nop 0
	global_load_lds_dwordx4 v[156:157], off
	v_lshl_add_u64 v[156:157], v[246:247], 0, s[12:13]
	s_mov_b32 m0, s80
	s_nop 0
	global_load_lds_dwordx4 v[156:157], off
	s_waitcnt vmcnt(8)
	s_waitcnt lgkmcnt(0)
	s_barrier
	s_setprio 1
	s_waitcnt lgkmcnt(0)
	v_mfma_f32_16x16x32_bf16 v[60:63], v[174:177], v[212:215], v[60:63]
	v_mfma_f32_16x16x32_bf16 v[56:59], v[184:187], v[212:215], v[56:59]
	v_mfma_f32_16x16x32_bf16 v[44:47], v[174:177], v[220:223], v[44:47]
	v_mfma_f32_16x16x32_bf16 v[40:43], v[184:187], v[220:223], v[40:43]
	v_mfma_f32_16x16x32_bf16 v[28:31], v[174:177], v[228:231], v[28:31]
	v_mfma_f32_16x16x32_bf16 v[24:27], v[184:187], v[228:231], v[24:27]
	v_mfma_f32_16x16x32_bf16 v[12:15], v[174:177], v[238:241], v[12:15]
	v_mfma_f32_16x16x32_bf16 v[8:11], v[184:187], v[238:241], v[8:11]
	v_mfma_f32_16x16x32_bf16 v[60:63], v[180:183], v[216:219], v[60:63]
	v_mfma_f32_16x16x32_bf16 v[56:59], v[188:191], v[216:219], v[56:59]
	v_mfma_f32_16x16x32_bf16 v[44:47], v[180:183], v[224:227], v[44:47]
	v_mfma_f32_16x16x32_bf16 v[40:43], v[188:191], v[224:227], v[40:43]
	v_mfma_f32_16x16x32_bf16 v[28:31], v[180:183], v[234:237], v[28:31]
	v_mfma_f32_16x16x32_bf16 v[24:27], v[188:191], v[234:237], v[24:27]
	v_mfma_f32_16x16x32_bf16 v[12:15], v[180:183], v[242:245], v[12:15]
	v_mfma_f32_16x16x32_bf16 v[8:11], v[188:191], v[242:245], v[8:11]
	s_setprio 0
	s_setprio 1
	v_mfma_f32_16x16x32_bf16 v[52:55], v[192:195], v[212:215], v[52:55]
	v_mfma_f32_16x16x32_bf16 v[48:51], v[204:207], v[212:215], v[48:51]
	v_mfma_f32_16x16x32_bf16 v[36:39], v[192:195], v[220:223], v[36:39]
	v_mfma_f32_16x16x32_bf16 v[32:35], v[204:207], v[220:223], v[32:35]
	v_mfma_f32_16x16x32_bf16 v[20:23], v[192:195], v[228:231], v[20:23]
	v_mfma_f32_16x16x32_bf16 v[16:19], v[204:207], v[228:231], v[16:19]
	v_mfma_f32_16x16x32_bf16 v[4:7], v[192:195], v[238:241], v[4:7]
	v_mfma_f32_16x16x32_bf16 v[0:3], v[204:207], v[238:241], v[0:3]
	v_mfma_f32_16x16x32_bf16 v[52:55], v[196:199], v[216:219], v[52:55]
	v_mfma_f32_16x16x32_bf16 v[48:51], v[208:211], v[216:219], v[48:51]
	v_mfma_f32_16x16x32_bf16 v[36:39], v[196:199], v[224:227], v[36:39]
	v_mfma_f32_16x16x32_bf16 v[32:35], v[208:211], v[224:227], v[32:35]
	v_mfma_f32_16x16x32_bf16 v[20:23], v[196:199], v[234:237], v[20:23]
	v_mfma_f32_16x16x32_bf16 v[16:19], v[208:211], v[234:237], v[16:19]
	v_mfma_f32_16x16x32_bf16 v[4:7], v[196:199], v[242:245], v[4:7]
	v_mfma_f32_16x16x32_bf16 v[0:3], v[208:211], v[242:245], v[0:3]
	s_setprio 0
	s_barrier
	s_add_i32 s67, s67, 2
	s_add_u32 s8, s8, 0x100
	s_addc_u32 s9, s9, 0
	s_add_u32 s65, s65, 0x100
	s_addc_u32 s66, s66, 0
	s_cmp_gt_u32 s67, 13
	s_cbranch_scc0 .LBB0_2520
	s_and_b64 vcc, exec, s[50:51]
	s_cbranch_vccz .LBB0_2523
	s_barrier

.LBB0_2596:
	s_add_u32 s24, s4, 0x40000
	s_addc_u32 s25, s5, 0
	s_add_u32 s26, s4, 0x4700000
	s_addc_u32 s27, s5, 0
	s_add_u32 s28, s4, 0x7700000
	s_addc_u32 s29, s5, 0
	s_add_u32 s30, s4, 0x7b00000
	s_addc_u32 s31, s5, 0
	s_add_u32 s34, s4, 0x6700000
	s_addc_u32 s35, s5, 0
	s_add_u32 s36, s4, 0xaf00000
	s_addc_u32 s37, s5, 0
	s_add_u32 s38, s4, 0xbf00000
	s_addc_u32 s39, s5, 0
	s_add_u32 s40, s4, 0x7f00000
	s_addc_u32 s41, s5, 0
	s_add_i32 m0, s76, 0x18000
	v_lshl_add_u64 v[8:9], v[8:9], 0, s[10:11]
	s_lshl_b32 s7, s50, 13
	s_lshl_b32 s51, s70, 12
	s_waitcnt vmcnt(2)
	s_barrier
	global_load_lds_dwordx4 v[8:9], off
	v_lshl_add_u64 v[6:7], v[6:7], 0, s[10:11]
	s_add_i32 m0, s76, 0x1a000
	s_add_i32 s80, s76, 0x8000
	s_add_i32 s81, s76, 0xa000
	global_load_lds_dwordx4 v[6:7], off
	v_lshl_add_u64 v[2:3], v[2:3], 0, s[10:11]
	s_mov_b32 m0, s80
	s_add_u32 s52, s56, 0x20080
	global_load_lds_dwordx4 v[2:3], off
	v_lshl_add_u64 v[2:3], v[4:5], 0, s[10:11]
	s_mov_b32 m0, s81
	s_addc_u32 s53, s57, 0
	global_load_lds_dwordx4 v[2:3], off
	s_add_i32 m0, s76, 0x1c000
	s_nop 0
	global_load_lds_dwordx4 v152, s[52:53]
	s_add_i32 m0, s76, 0x1e000
	v_and_b32_e32 v4, 15, v1
	global_load_lds_dwordx4 v156, s[52:53]
	v_or_b32_e32 v199, s43, v4
	v_lshlrev_b32_e32 v2, 6, v199
	v_and_b32_e32 v3, 48, v1
	s_movk_i32 s43, 0x3c0
	v_lshlrev_b32_e32 v5, 2, v199
	v_and_or_b32 v2, v2, s43, v3
	v_and_b32_e32 v5, 32, v5
	v_lshlrev_b32_e32 v1, 2, v1
	v_bitop3_b32 v5, v2, s7, v5 bitop3:0xde
	v_lshl_or_b32 v2, v4, 6, v3
	v_and_b32_e32 v1, 32, v1
	v_bitop3_b32 v203, s51, v2, v1 bitop3:0xf6
	v_mov_b32_e32 v1, v145
	v_lshl_add_u64 v[164:165], s[44:45], 0, v[0:1]
	v_lshlrev_b32_e32 v0, 13, v11
	v_and_b32_e32 v0, 0xffffc000, v0
	v_lshl_add_u32 v0, v12, 10, v0
	v_and_b32_e32 v1, 1, v11
	s_cmpk_lt_u32 s42, 0x100
	v_lshl_or_b32 v0, v1, 6, v0
	s_cselect_b64 s[42:43], -1, 0
	s_lshl_b32 s7, s50, 11
	v_lshl_add_u32 v166, v13, 1, v0
	v_lshlrev_b32_e32 v0, 13, v14
	v_lshrrev_b32_e32 v198, 4, v10
	s_add_i32 s82, s7, 0
	s_lshl_b32 s7, s70, 7
	v_and_b32_e32 v0, 0xffffc000, v0
	s_waitcnt vmcnt(6)
	s_add_i32 s7, s7, 0
	v_lshlrev_b32_e32 v144, 5, v198
	v_lshl_add_u32 v0, v15, 10, v0
	v_and_b32_e32 v1, 1, v14
	v_lshlrev_b32_e32 v158, 3, v198
	s_add_i32 s82, s82, 0x21000
	s_add_i32 s7, s7, 0x23000
	v_lshl_add_u64 v[2:3], s[4:5], 0, v[144:145]
	s_mov_b64 s[4:5], 0x80200
	v_lshl_or_b32 v0, v1, 6, v0
	s_ashr_i32 s83, s69, 31
	v_add_u32_e32 v204, s7, v144
	v_lshl_add_u64 v[160:161], v[2:3], 0, s[4:5]
	v_lshl_add_u64 v[162:163], s[24:25], 0, v[144:145]
	v_lshl_add_u32 v205, v4, 4, s82
	v_mov_b32_e32 v167, v145
	v_lshl_add_u32 v168, v16, 1, v0
	v_mov_b32_e32 v169, v145
	s_mov_b32 s59, 0
	v_add_u32_e32 v206, 0, v5
	v_lshlrev_b32_e32 v170, 2, v158
	s_barrier
	s_branch .LBB0_2599

.LBB0_2602:
	s_add_u32 s56, s48, 0xfffe0080
	s_addc_u32 s57, s49, -1
	s_add_i32 s87, 0, 0x10000
	s_cmp_eq_u32 s86, 4
	s_cselect_b32 s61, s7, s57
	s_cselect_b32 s60, s51, s56
	s_cselect_b32 s57, s45, s85
	s_cselect_b32 s56, s62, s63
	s_add_i32 s90, 0, 0x14000
	v_add_u32_e32 v140, s87, v203
	v_add_u32_e32 v144, s90, v203
	ds_read_b128 v[128:131], v140
	ds_read_b128 v[132:135], v140 offset:1024
	ds_read_b128 v[136:139], v140 offset:2048
	ds_read_b128 v[140:143], v140 offset:3072
	ds_read_b128 v[172:175], v144
	ds_read_b128 v[176:179], v144 offset:1024
	ds_read_b128 v[180:183], v144 offset:2048
	ds_read_b128 v[184:187], v144 offset:3072
	s_add_i32 m0, s76, 0xc000
	ds_read_b128 v[188:191], v206
	ds_read_b128 v[208:211], v206 offset:1024
	ds_read_b128 v[212:215], v206 offset:2048
	ds_read_b128 v[216:219], v206 offset:3072
	ds_read_b128 v[220:223], v206 offset:4096
	ds_read_b128 v[224:227], v206 offset:5120
	ds_read_b128 v[228:231], v206 offset:6144
	ds_read_b128 v[234:237], v206 offset:7168
	global_load_lds_dwordx4 v166, s[48:49]
	s_add_i32 m0, s76, 0xe000
	s_nop 0
	global_load_lds_dwordx4 v168, s[48:49]
	s_waitcnt vmcnt(8)
	s_waitcnt lgkmcnt(0)
	s_barrier
	s_setprio 1
	s_waitcnt lgkmcnt(0)
	v_mfma_i32_16x16x64_i8 v[124:127], v[128:131], v[188:191], v[124:127]
	v_mfma_i32_16x16x64_i8 v[120:123], v[136:139], v[188:191], v[120:123]
	v_mfma_i32_16x16x64_i8 v[116:119], v[128:131], v[212:215], v[116:119]
	v_mfma_i32_16x16x64_i8 v[112:115], v[136:139], v[212:215], v[112:115]
	v_mfma_i32_16x16x64_i8 v[108:111], v[128:131], v[220:223], v[108:111]
	v_mfma_i32_16x16x64_i8 v[104:107], v[136:139], v[220:223], v[104:107]
	v_mfma_i32_16x16x64_i8 v[100:103], v[128:131], v[228:231], v[100:103]
	v_mfma_i32_16x16x64_i8 v[96:99], v[136:139], v[228:231], v[96:99]
	v_mfma_i32_16x16x64_i8 v[124:127], v[132:135], v[208:211], v[124:127]
	v_mfma_i32_16x16x64_i8 v[120:123], v[140:143], v[208:211], v[120:123]
	v_mfma_i32_16x16x64_i8 v[116:119], v[132:135], v[216:219], v[116:119]
	v_mfma_i32_16x16x64_i8 v[112:115], v[140:143], v[216:219], v[112:115]
	v_mfma_i32_16x16x64_i8 v[108:111], v[132:135], v[224:227], v[108:111]
	v_mfma_i32_16x16x64_i8 v[104:107], v[140:143], v[224:227], v[104:107]
	v_mfma_i32_16x16x64_i8 v[100:103], v[132:135], v[234:237], v[100:103]
	v_mfma_i32_16x16x64_i8 v[96:99], v[140:143], v[234:237], v[96:99]
	s_setprio 0
	s_setprio 1
	v_mfma_i32_16x16x64_i8 v[92:95], v[172:175], v[188:191], v[92:95]
	v_mfma_i32_16x16x64_i8 v[88:91], v[180:183], v[188:191], v[88:91]
	v_mfma_i32_16x16x64_i8 v[84:87], v[172:175], v[212:215], v[84:87]
	v_mfma_i32_16x16x64_i8 v[80:83], v[180:183], v[212:215], v[80:83]
	v_mfma_i32_16x16x64_i8 v[76:79], v[172:175], v[220:223], v[76:79]
	v_mfma_i32_16x16x64_i8 v[72:75], v[180:183], v[220:223], v[72:75]
	v_mfma_i32_16x16x64_i8 v[68:71], v[172:175], v[228:231], v[68:71]
	v_mfma_i32_16x16x64_i8 v[64:67], v[180:183], v[228:231], v[64:67]
	v_mfma_i32_16x16x64_i8 v[92:95], v[176:179], v[208:211], v[92:95]
	v_mfma_i32_16x16x64_i8 v[88:91], v[184:187], v[208:211], v[88:91]
	v_mfma_i32_16x16x64_i8 v[84:87], v[176:179], v[216:219], v[84:87]
	v_mfma_i32_16x16x64_i8 v[80:83], v[184:187], v[216:219], v[80:83]
	v_mfma_i32_16x16x64_i8 v[76:79], v[176:179], v[224:227], v[76:79]
	v_mfma_i32_16x16x64_i8 v[72:75], v[184:187], v[224:227], v[72:75]
	v_mfma_i32_16x16x64_i8 v[68:71], v[176:179], v[234:237], v[68:71]
	v_mfma_i32_16x16x64_i8 v[64:67], v[184:187], v[234:237], v[64:67]
	s_setprio 0
	s_barrier
	s_add_i32 s87, s87, s75
	v_lshl_add_u64 v[192:193], s[56:57], 0, v[152:153]
	s_mov_b32 m0, s87
	ds_read_b128 v[188:191], v206 offset:16384
	ds_read_b128 v[208:211], v206 offset:17408
	ds_read_b128 v[212:215], v206 offset:18432
	ds_read_b128 v[216:219], v206 offset:19456
	ds_read_b128 v[220:223], v206 offset:20480
	ds_read_b128 v[224:227], v206 offset:21504
	ds_read_b128 v[228:231], v206 offset:22528
	ds_read_b128 v[234:237], v206 offset:23552
	global_load_lds_dwordx4 v[192:193], off
	s_add_i32 m0, s87, 0x2000
	s_add_u32 s88, s56, 0x20000
	v_lshl_add_u64 v[238:239], s[56:57], 0, v[156:157]
	s_addc_u32 s89, s57, 0
	s_add_i32 s87, s90, s75
	global_load_lds_dwordx4 v[238:239], off
	s_mov_b32 m0, s87
	v_lshl_add_u64 v[242:243], s[60:61], 0, v[154:155]
	global_load_lds_dwordx4 v152, s[88:89]
	s_add_i32 m0, s87, 0x2000
	s_nop 0
	global_load_lds_dwordx4 v156, s[88:89]
	v_lshl_add_u64 v[240:241], s[60:61], 0, v[150:151]
	s_mov_b32 m0, s76
	s_nop 0
	global_load_lds_dwordx4 v[240:241], off
	s_mov_b32 m0, s77
	s_nop 0
	global_load_lds_dwordx4 v[242:243], off
	s_waitcnt vmcnt(8)
	s_waitcnt lgkmcnt(0)
	s_barrier
	s_setprio 1
	s_waitcnt lgkmcnt(0)
	v_mfma_i32_16x16x64_i8 v[60:63], v[128:131], v[188:191], v[60:63]
	v_mfma_i32_16x16x64_i8 v[56:59], v[136:139], v[188:191], v[56:59]
	v_mfma_i32_16x16x64_i8 v[52:55], v[128:131], v[212:215], v[52:55]
	v_mfma_i32_16x16x64_i8 v[48:51], v[136:139], v[212:215], v[48:51]
	v_mfma_i32_16x16x64_i8 v[44:47], v[128:131], v[220:223], v[44:47]
	v_mfma_i32_16x16x64_i8 v[40:43], v[136:139], v[220:223], v[40:43]
	v_mfma_i32_16x16x64_i8 v[36:39], v[128:131], v[228:231], v[36:39]
	v_mfma_i32_16x16x64_i8 v[32:35], v[136:139], v[228:231], v[32:35]
	v_mfma_i32_16x16x64_i8 v[60:63], v[132:135], v[208:211], v[60:63]
	v_mfma_i32_16x16x64_i8 v[56:59], v[140:143], v[208:211], v[56:59]
	v_mfma_i32_16x16x64_i8 v[52:55], v[132:135], v[216:219], v[52:55]
	v_mfma_i32_16x16x64_i8 v[48:51], v[140:143], v[216:219], v[48:51]
	v_mfma_i32_16x16x64_i8 v[44:47], v[132:135], v[224:227], v[44:47]
	v_mfma_i32_16x16x64_i8 v[40:43], v[140:143], v[224:227], v[40:43]
	v_mfma_i32_16x16x64_i8 v[36:39], v[132:135], v[234:237], v[36:39]
	v_mfma_i32_16x16x64_i8 v[32:35], v[140:143], v[234:237], v[32:35]
	s_setprio 0
	s_setprio 1
	v_mfma_i32_16x16x64_i8 v[28:31], v[172:175], v[188:191], v[28:31]
	v_mfma_i32_16x16x64_i8 v[24:27], v[180:183], v[188:191], v[24:27]
	v_mfma_i32_16x16x64_i8 v[20:23], v[172:175], v[212:215], v[20:23]
	v_mfma_i32_16x16x64_i8 v[16:19], v[180:183], v[212:215], v[16:19]
	v_mfma_i32_16x16x64_i8 v[12:15], v[172:175], v[220:223], v[12:15]
	v_mfma_i32_16x16x64_i8 v[8:11], v[180:183], v[220:223], v[8:11]
	v_mfma_i32_16x16x64_i8 v[4:7], v[172:175], v[228:231], v[4:7]
	v_mfma_i32_16x16x64_i8 v[0:3], v[180:183], v[228:231], v[0:3]
	v_mfma_i32_16x16x64_i8 v[28:31], v[176:179], v[208:211], v[28:31]
	v_mfma_i32_16x16x64_i8 v[24:27], v[184:187], v[208:211], v[24:27]
	v_mfma_i32_16x16x64_i8 v[20:23], v[176:179], v[216:219], v[20:23]
	v_mfma_i32_16x16x64_i8 v[16:19], v[184:187], v[216:219], v[16:19]
	v_mfma_i32_16x16x64_i8 v[12:15], v[176:179], v[224:227], v[12:15]
	v_mfma_i32_16x16x64_i8 v[8:11], v[184:187], v[224:227], v[8:11]
	v_mfma_i32_16x16x64_i8 v[4:7], v[176:179], v[234:237], v[4:7]
	v_mfma_i32_16x16x64_i8 v[0:3], v[184:187], v[234:237], v[0:3]
	s_setprio 0
	s_barrier
	s_add_i32 s87, 0, 0x1c000
	v_add_u32_e32 v140, s0, v203
	v_add_u32_e32 v144, s87, v203
	ds_read_b128 v[128:131], v140
	ds_read_b128 v[132:135], v140 offset:1024
	ds_read_b128 v[136:139], v140 offset:2048
	ds_read_b128 v[140:143], v140 offset:3072
	ds_read_b128 v[172:175], v144
	ds_read_b128 v[176:179], v144 offset:1024
	ds_read_b128 v[180:183], v144 offset:2048
	ds_read_b128 v[184:187], v144 offset:3072
	s_add_u32 s60, s60, 0x20000
	s_addc_u32 s61, s61, 0
	s_mov_b32 m0, s78
	ds_read_b128 v[188:191], v206 offset:32768
	ds_read_b128 v[208:211], v206 offset:33792
	ds_read_b128 v[212:215], v206 offset:34816
	ds_read_b128 v[216:219], v206 offset:35840
	ds_read_b128 v[220:223], v206 offset:36864
	ds_read_b128 v[224:227], v206 offset:37888
	ds_read_b128 v[228:231], v206 offset:38912
	ds_read_b128 v[234:237], v206 offset:39936
	global_load_lds_dwordx4 v150, s[60:61]
	s_mov_b32 m0, s79
	s_nop 0
	global_load_lds_dwordx4 v154, s[60:61]
	s_waitcnt vmcnt(8)
	s_waitcnt lgkmcnt(0)
	s_barrier
	s_setprio 1
	s_waitcnt lgkmcnt(0)
	v_mfma_i32_16x16x64_i8 v[124:127], v[128:131], v[188:191], v[124:127]
	v_mfma_i32_16x16x64_i8 v[120:123], v[136:139], v[188:191], v[120:123]
	v_mfma_i32_16x16x64_i8 v[116:119], v[128:131], v[212:215], v[116:119]
	v_mfma_i32_16x16x64_i8 v[112:115], v[136:139], v[212:215], v[112:115]
	v_mfma_i32_16x16x64_i8 v[108:111], v[128:131], v[220:223], v[108:111]
	v_mfma_i32_16x16x64_i8 v[104:107], v[136:139], v[220:223], v[104:107]
	v_mfma_i32_16x16x64_i8 v[100:103], v[128:131], v[228:231], v[100:103]
	v_mfma_i32_16x16x64_i8 v[96:99], v[136:139], v[228:231], v[96:99]
	v_mfma_i32_16x16x64_i8 v[124:127], v[132:135], v[208:211], v[124:127]
	v_mfma_i32_16x16x64_i8 v[120:123], v[140:143], v[208:211], v[120:123]
	v_mfma_i32_16x16x64_i8 v[116:119], v[132:135], v[216:219], v[116:119]
	v_mfma_i32_16x16x64_i8 v[112:115], v[140:143], v[216:219], v[112:115]
	v_mfma_i32_16x16x64_i8 v[108:111], v[132:135], v[224:227], v[108:111]
	v_mfma_i32_16x16x64_i8 v[104:107], v[140:143], v[224:227], v[104:107]
	v_mfma_i32_16x16x64_i8 v[100:103], v[132:135], v[234:237], v[100:103]
	v_mfma_i32_16x16x64_i8 v[96:99], v[140:143], v[234:237], v[96:99]
	s_setprio 0
	s_setprio 1
	v_mfma_i32_16x16x64_i8 v[92:95], v[172:175], v[188:191], v[92:95]
	v_mfma_i32_16x16x64_i8 v[88:91], v[180:183], v[188:191], v[88:91]
	v_mfma_i32_16x16x64_i8 v[84:87], v[172:175], v[212:215], v[84:87]
	v_mfma_i32_16x16x64_i8 v[80:83], v[180:183], v[212:215], v[80:83]
	v_mfma_i32_16x16x64_i8 v[76:79], v[172:175], v[220:223], v[76:79]
	v_mfma_i32_16x16x64_i8 v[72:75], v[180:183], v[220:223], v[72:75]
	v_mfma_i32_16x16x64_i8 v[68:71], v[172:175], v[228:231], v[68:71]
	v_mfma_i32_16x16x64_i8 v[64:67], v[180:183], v[228:231], v[64:67]
	v_mfma_i32_16x16x64_i8 v[92:95], v[176:179], v[208:211], v[92:95]
	v_mfma_i32_16x16x64_i8 v[88:91], v[184:187], v[208:211], v[88:91]
	v_mfma_i32_16x16x64_i8 v[84:87], v[176:179], v[216:219], v[84:87]
	v_mfma_i32_16x16x64_i8 v[80:83], v[184:187], v[216:219], v[80:83]
	v_mfma_i32_16x16x64_i8 v[76:79], v[176:179], v[224:227], v[76:79]
	v_mfma_i32_16x16x64_i8 v[72:75], v[184:187], v[224:227], v[72:75]
	v_mfma_i32_16x16x64_i8 v[68:71], v[176:179], v[234:237], v[68:71]
	v_mfma_i32_16x16x64_i8 v[64:67], v[184:187], v[234:237], v[64:67]
	s_setprio 0
	s_barrier
	s_add_i32 s60, s0, s75
	v_lshl_add_u64 v[192:193], v[192:193], 0, s[10:11]
	s_mov_b32 m0, s60
	ds_read_b128 v[188:191], v206 offset:49152
	ds_read_b128 v[208:211], v206 offset:50176
	ds_read_b128 v[212:215], v206 offset:51200
	ds_read_b128 v[216:219], v206 offset:52224
	ds_read_b128 v[220:223], v206 offset:53248
	ds_read_b128 v[224:227], v206 offset:54272
	ds_read_b128 v[228:231], v206 offset:55296
	ds_read_b128 v[234:237], v206 offset:56320
	global_load_lds_dwordx4 v[192:193], off
	s_add_i32 m0, s60, 0x2000
	s_add_u32 s56, s56, 0x20080
	v_lshl_add_u64 v[192:193], v[238:239], 0, s[10:11]
	s_addc_u32 s57, s57, 0
	s_add_i32 s60, s87, s75
	global_load_lds_dwordx4 v[192:193], off
	s_mov_b32 m0, s60
	s_nop 0
	global_load_lds_dwordx4 v152, s[56:57]
	s_add_i32 m0, s60, 0x2000
	s_nop 0
	global_load_lds_dwordx4 v156, s[56:57]
	v_lshl_add_u64 v[192:193], v[240:241], 0, s[10:11]
	s_mov_b32 m0, s80
	s_nop 0
	global_load_lds_dwordx4 v[192:193], off
	v_lshl_add_u64 v[192:193], v[242:243], 0, s[10:11]
	s_mov_b32 m0, s81
	s_nop 0
	global_load_lds_dwordx4 v[192:193], off
	s_waitcnt vmcnt(8)
	s_waitcnt lgkmcnt(0)
	s_barrier
	s_setprio 1
	s_waitcnt lgkmcnt(0)
	v_mfma_i32_16x16x64_i8 v[60:63], v[128:131], v[188:191], v[60:63]
	v_mfma_i32_16x16x64_i8 v[56:59], v[136:139], v[188:191], v[56:59]
	v_mfma_i32_16x16x64_i8 v[52:55], v[128:131], v[212:215], v[52:55]
	v_mfma_i32_16x16x64_i8 v[48:51], v[136:139], v[212:215], v[48:51]
	v_mfma_i32_16x16x64_i8 v[44:47], v[128:131], v[220:223], v[44:47]
	v_mfma_i32_16x16x64_i8 v[40:43], v[136:139], v[220:223], v[40:43]
	v_mfma_i32_16x16x64_i8 v[36:39], v[128:131], v[228:231], v[36:39]
	v_mfma_i32_16x16x64_i8 v[32:35], v[136:139], v[228:231], v[32:35]
	v_mfma_i32_16x16x64_i8 v[60:63], v[132:135], v[208:211], v[60:63]
	v_mfma_i32_16x16x64_i8 v[56:59], v[140:143], v[208:211], v[56:59]
	v_mfma_i32_16x16x64_i8 v[52:55], v[132:135], v[216:219], v[52:55]
	v_mfma_i32_16x16x64_i8 v[48:51], v[140:143], v[216:219], v[48:51]
	v_mfma_i32_16x16x64_i8 v[44:47], v[132:135], v[224:227], v[44:47]
	v_mfma_i32_16x16x64_i8 v[40:43], v[140:143], v[224:227], v[40:43]
	v_mfma_i32_16x16x64_i8 v[36:39], v[132:135], v[234:237], v[36:39]
	v_mfma_i32_16x16x64_i8 v[32:35], v[140:143], v[234:237], v[32:35]
	s_setprio 0
	s_setprio 1
	v_mfma_i32_16x16x64_i8 v[28:31], v[172:175], v[188:191], v[28:31]
	v_mfma_i32_16x16x64_i8 v[24:27], v[180:183], v[188:191], v[24:27]
	v_mfma_i32_16x16x64_i8 v[20:23], v[172:175], v[212:215], v[20:23]
	v_mfma_i32_16x16x64_i8 v[16:19], v[180:183], v[212:215], v[16:19]
	v_mfma_i32_16x16x64_i8 v[12:15], v[172:175], v[220:223], v[12:15]
	v_mfma_i32_16x16x64_i8 v[8:11], v[180:183], v[220:223], v[8:11]
	v_mfma_i32_16x16x64_i8 v[4:7], v[172:175], v[228:231], v[4:7]
	v_mfma_i32_16x16x64_i8 v[0:3], v[180:183], v[228:231], v[0:3]
	v_mfma_i32_16x16x64_i8 v[28:31], v[176:179], v[208:211], v[28:31]
	v_mfma_i32_16x16x64_i8 v[24:27], v[184:187], v[208:211], v[24:27]
	v_mfma_i32_16x16x64_i8 v[20:23], v[176:179], v[216:219], v[20:23]
	v_mfma_i32_16x16x64_i8 v[16:19], v[184:187], v[216:219], v[16:19]
	v_mfma_i32_16x16x64_i8 v[12:15], v[176:179], v[224:227], v[12:15]
	v_mfma_i32_16x16x64_i8 v[8:11], v[184:187], v[224:227], v[8:11]
	v_mfma_i32_16x16x64_i8 v[4:7], v[176:179], v[234:237], v[4:7]
	v_mfma_i32_16x16x64_i8 v[0:3], v[184:187], v[234:237], v[0:3]
	s_setprio 0
	s_barrier
	s_add_i32 s86, s86, 2
	s_add_u32 s48, s48, 0x100
	s_addc_u32 s49, s49, 0
	s_add_u32 s63, s63, 0x100
	s_addc_u32 s85, s85, 0
	s_cmp_gt_u32 s86, 5
	s_cbranch_scc0 .LBB0_2602
	s_and_b64 vcc, exec, s[42:43]
	s_cbranch_vccz .LBB0_2605
	s_barrier

.LBB0_2975:
	s_add_i32 m0, s12, 0x18000
	v_lshl_add_u64 v[8:9], v[8:9], 0, s[14:15]
	s_lshl_b32 s44, s5, 13
	s_lshl_b32 s45, s4, 12
	s_waitcnt vmcnt(2)
	s_barrier
	global_load_lds_dwordx4 v[8:9], off
	v_lshl_add_u64 v[6:7], v[6:7], 0, s[14:15]
	s_add_i32 m0, s12, 0x1a000
	s_add_i32 s74, s12, 0x8000
	s_add_i32 s75, s12, 0xa000
	global_load_lds_dwordx4 v[6:7], off
	v_lshl_add_u64 v[2:3], v[2:3], 0, s[14:15]
	s_mov_b32 m0, s74
	s_add_u32 s42, s58, 0x20080
	global_load_lds_dwordx4 v[2:3], off
	v_lshl_add_u64 v[2:3], v[4:5], 0, s[14:15]
	s_mov_b32 m0, s75
	s_addc_u32 s43, s59, 0
	global_load_lds_dwordx4 v[2:3], off
	s_add_i32 m0, s12, 0x1c000
	s_nop 0
	global_load_lds_dwordx4 v0, s[42:43]
	s_add_i32 m0, s12, 0x1e000
	s_cmpk_lt_u32 s40, 0x100
	global_load_lds_dwordx4 v164, s[42:43]
	v_or_b32_e32 v2, s41, v179
	v_and_b32_e32 v3, 48, v130
	v_lshlrev_b32_e32 v4, 6, v2
	s_movk_i32 s41, 0x3c0
	v_lshlrev_b32_e32 v2, 2, v2
	v_and_or_b32 v4, v4, s41, v3
	v_and_b32_e32 v2, 32, v2
	v_bitop3_b32 v4, v4, s44, v2 bitop3:0xde
	v_or_b32_e32 v2, v178, v3
	s_cselect_b64 s[40:41], -1, 0
	s_lshl_b32 s4, s4, 7
	v_bitop3_b32 v182, s45, v2, v180 bitop3:0xf6
	v_lshlrev_b32_e32 v2, 1, v10
	s_add_i32 s4, s4, 0
	v_and_b32_e32 v3, 0x60, v2
	s_add_i32 s4, s4, 0x23000
	v_add_u32_e32 v183, s4, v3
	v_lshlrev_b32_e32 v3, 13, v172
	v_and_b32_e32 v3, 0xffffc000, v3
	v_lshl_add_u32 v3, v173, 10, v3
	v_and_b32_e32 v5, 1, v172
	v_lshl_or_b32 v3, v5, 6, v3
	v_lshl_add_u32 v134, v174, 1, v3
	v_lshlrev_b32_e32 v3, 13, v175
	s_lshl_b32 s5, s5, 11
	v_and_b32_e32 v3, 0xffffc000, v3
	s_waitcnt vmcnt(6)
	s_add_i32 s76, s5, 0
	v_lshl_add_u32 v3, v176, 10, v3
	v_and_b32_e32 v5, 1, v175
	s_add_i32 s76, s76, 0x21000
	v_lshlrev_b32_e32 v2, 2, v10
	v_lshl_or_b32 v3, v5, 6, v3
	v_lshl_add_u64 v[132:133], v[130:131], 4, s[6:7]
	v_lshl_add_u32 v184, v179, 4, s76
	v_mov_b32_e32 v135, v1
	v_lshl_add_u32 v136, v177, 1, v3
	v_mov_b32_e32 v137, v1
	s_mov_b32 s79, 0
	v_add_u32_e32 v185, 0, v4
	v_lshlrev_b32_e32 v188, 2, v2
	s_mov_b32 s80, 0
	s_barrier
	s_branch .LBB0_2978

.LBB0_2985:
	s_add_u32 s58, s56, 0xfffe0080
	s_addc_u32 s59, s57, -1
	s_add_i32 s85, 0, 0x10000
	s_cmp_eq_u32 s84, 4
	s_cselect_b32 s61, s51, s59
	s_cselect_b32 s60, s81, s58
	s_cselect_b32 s59, s43, s83
	s_cselect_b32 s58, s45, s82
	s_add_i32 s88, 0, 0x14000
	v_add_u32_e32 v150, s85, v182
	v_add_u32_e32 v154, s88, v182
	ds_read_b128 v[138:141], v150
	ds_read_b128 v[142:145], v150 offset:1024
	ds_read_b128 v[146:149], v150 offset:2048
	ds_read_b128 v[150:153], v150 offset:3072
	ds_read_b128 v[166:169], v154
	ds_read_b128 v[190:193], v154 offset:1024
	ds_read_b128 v[194:197], v154 offset:2048
	ds_read_b128 v[198:201], v154 offset:3072
	s_add_i32 m0, s12, 0xc000
	ds_read_b128 v[202:205], v185
	ds_read_b128 v[206:209], v185 offset:1024
	ds_read_b128 v[210:213], v185 offset:2048
	ds_read_b128 v[214:217], v185 offset:3072
	ds_read_b128 v[218:221], v185 offset:4096
	ds_read_b128 v[222:225], v185 offset:5120
	ds_read_b128 v[226:229], v185 offset:6144
	ds_read_b128 v[234:237], v185 offset:7168
	global_load_lds_dwordx4 v134, s[56:57]
	s_add_i32 m0, s12, 0xe000
	s_nop 0
	global_load_lds_dwordx4 v136, s[56:57]
	s_waitcnt vmcnt(8)
	s_waitcnt lgkmcnt(0)
	s_barrier
	s_setprio 1
	s_waitcnt lgkmcnt(0)
	v_mfma_i32_16x16x64_i8 v[126:129], v[138:141], v[202:205], v[126:129]
	v_mfma_i32_16x16x64_i8 v[122:125], v[146:149], v[202:205], v[122:125]
	v_mfma_i32_16x16x64_i8 v[110:113], v[138:141], v[210:213], v[110:113]
	v_mfma_i32_16x16x64_i8 v[106:109], v[146:149], v[210:213], v[106:109]
	v_mfma_i32_16x16x64_i8 v[94:97], v[138:141], v[218:221], v[94:97]
	v_mfma_i32_16x16x64_i8 v[90:93], v[146:149], v[218:221], v[90:93]
	v_mfma_i32_16x16x64_i8 v[78:81], v[138:141], v[226:229], v[78:81]
	v_mfma_i32_16x16x64_i8 v[74:77], v[146:149], v[226:229], v[74:77]
	v_mfma_i32_16x16x64_i8 v[126:129], v[142:145], v[206:209], v[126:129]
	v_mfma_i32_16x16x64_i8 v[122:125], v[150:153], v[206:209], v[122:125]
	v_mfma_i32_16x16x64_i8 v[110:113], v[142:145], v[214:217], v[110:113]
	v_mfma_i32_16x16x64_i8 v[106:109], v[150:153], v[214:217], v[106:109]
	v_mfma_i32_16x16x64_i8 v[94:97], v[142:145], v[222:225], v[94:97]
	v_mfma_i32_16x16x64_i8 v[90:93], v[150:153], v[222:225], v[90:93]
	v_mfma_i32_16x16x64_i8 v[78:81], v[142:145], v[234:237], v[78:81]
	v_mfma_i32_16x16x64_i8 v[74:77], v[150:153], v[234:237], v[74:77]
	s_setprio 0
	s_setprio 1
	v_mfma_i32_16x16x64_i8 v[118:121], v[166:169], v[202:205], v[118:121]
	v_mfma_i32_16x16x64_i8 v[114:117], v[194:197], v[202:205], v[114:117]
	v_mfma_i32_16x16x64_i8 v[102:105], v[166:169], v[210:213], v[102:105]
	v_mfma_i32_16x16x64_i8 v[98:101], v[194:197], v[210:213], v[98:101]
	v_mfma_i32_16x16x64_i8 v[86:89], v[166:169], v[218:221], v[86:89]
	v_mfma_i32_16x16x64_i8 v[82:85], v[194:197], v[218:221], v[82:85]
	v_mfma_i32_16x16x64_i8 v[70:73], v[166:169], v[226:229], v[70:73]
	v_mfma_i32_16x16x64_i8 v[66:69], v[194:197], v[226:229], v[66:69]
	v_mfma_i32_16x16x64_i8 v[118:121], v[190:193], v[206:209], v[118:121]
	v_mfma_i32_16x16x64_i8 v[114:117], v[198:201], v[206:209], v[114:117]
	v_mfma_i32_16x16x64_i8 v[102:105], v[190:193], v[214:217], v[102:105]
	v_mfma_i32_16x16x64_i8 v[98:101], v[198:201], v[214:217], v[98:101]
	v_mfma_i32_16x16x64_i8 v[86:89], v[190:193], v[222:225], v[86:89]
	v_mfma_i32_16x16x64_i8 v[82:85], v[198:201], v[222:225], v[82:85]
	v_mfma_i32_16x16x64_i8 v[70:73], v[190:193], v[234:237], v[70:73]
	v_mfma_i32_16x16x64_i8 v[66:69], v[198:201], v[234:237], v[66:69]
	s_setprio 0
	s_barrier
	s_add_i32 s85, s85, s71
	v_lshl_add_u64 v[154:155], s[58:59], 0, v[0:1]
	s_mov_b32 m0, s85
	ds_read_b128 v[202:205], v185 offset:16384
	ds_read_b128 v[206:209], v185 offset:17408
	ds_read_b128 v[210:213], v185 offset:18432
	ds_read_b128 v[214:217], v185 offset:19456
	ds_read_b128 v[218:221], v185 offset:20480
	ds_read_b128 v[222:225], v185 offset:21504
	ds_read_b128 v[226:229], v185 offset:22528
	ds_read_b128 v[234:237], v185 offset:23552
	global_load_lds_dwordx4 v[154:155], off
	s_add_i32 m0, s85, 0x2000
	s_add_u32 s86, s58, 0x20000
	v_lshl_add_u64 v[170:171], s[58:59], 0, v[164:165]
	s_addc_u32 s87, s59, 0
	s_add_i32 s85, s88, s71
	global_load_lds_dwordx4 v[170:171], off
	s_mov_b32 m0, s85
	v_lshl_add_u64 v[238:239], s[60:61], 0, v[162:163]
	global_load_lds_dwordx4 v0, s[86:87]
	s_add_i32 m0, s85, 0x2000
	s_nop 0
	global_load_lds_dwordx4 v164, s[86:87]
	v_lshl_add_u64 v[230:231], s[60:61], 0, v[160:161]
	s_mov_b32 m0, s12
	s_nop 0
	global_load_lds_dwordx4 v[230:231], off
	s_mov_b32 m0, s49
	s_nop 0
	global_load_lds_dwordx4 v[238:239], off
	s_waitcnt vmcnt(8)
	s_waitcnt lgkmcnt(0)
	s_barrier
	s_setprio 1
	s_waitcnt lgkmcnt(0)
	v_mfma_i32_16x16x64_i8 v[62:65], v[138:141], v[202:205], v[62:65]
	v_mfma_i32_16x16x64_i8 v[58:61], v[146:149], v[202:205], v[58:61]
	v_mfma_i32_16x16x64_i8 v[46:49], v[138:141], v[210:213], v[46:49]
	v_mfma_i32_16x16x64_i8 v[42:45], v[146:149], v[210:213], v[42:45]
	v_mfma_i32_16x16x64_i8 v[30:33], v[138:141], v[218:221], v[30:33]
	v_mfma_i32_16x16x64_i8 v[26:29], v[146:149], v[218:221], v[26:29]
	v_mfma_i32_16x16x64_i8 v[10:13], v[138:141], v[226:229], v[10:13]
	v_mfma_i32_16x16x64_i8 v[2:5], v[146:149], v[226:229], v[2:5]
	v_mfma_i32_16x16x64_i8 v[62:65], v[142:145], v[206:209], v[62:65]
	v_mfma_i32_16x16x64_i8 v[58:61], v[150:153], v[206:209], v[58:61]
	v_mfma_i32_16x16x64_i8 v[46:49], v[142:145], v[214:217], v[46:49]
	v_mfma_i32_16x16x64_i8 v[42:45], v[150:153], v[214:217], v[42:45]
	v_mfma_i32_16x16x64_i8 v[30:33], v[142:145], v[222:225], v[30:33]
	v_mfma_i32_16x16x64_i8 v[26:29], v[150:153], v[222:225], v[26:29]
	v_mfma_i32_16x16x64_i8 v[10:13], v[142:145], v[234:237], v[10:13]
	v_mfma_i32_16x16x64_i8 v[2:5], v[150:153], v[234:237], v[2:5]
	s_setprio 0
	s_setprio 1
	v_mfma_i32_16x16x64_i8 v[54:57], v[166:169], v[202:205], v[54:57]
	v_mfma_i32_16x16x64_i8 v[50:53], v[194:197], v[202:205], v[50:53]
	v_mfma_i32_16x16x64_i8 v[38:41], v[166:169], v[210:213], v[38:41]
	v_mfma_i32_16x16x64_i8 v[34:37], v[194:197], v[210:213], v[34:37]
	v_mfma_i32_16x16x64_i8 v[22:25], v[166:169], v[218:221], v[22:25]
	v_mfma_i32_16x16x64_i8 v[18:21], v[194:197], v[218:221], v[18:21]
	v_mfma_i32_16x16x64_i8 v[14:17], v[166:169], v[226:229], v[14:17]
	v_mfma_i32_16x16x64_i8 v[6:9], v[194:197], v[226:229], v[6:9]
	v_mfma_i32_16x16x64_i8 v[54:57], v[190:193], v[206:209], v[54:57]
	v_mfma_i32_16x16x64_i8 v[50:53], v[198:201], v[206:209], v[50:53]
	v_mfma_i32_16x16x64_i8 v[38:41], v[190:193], v[214:217], v[38:41]
	v_mfma_i32_16x16x64_i8 v[34:37], v[198:201], v[214:217], v[34:37]
	v_mfma_i32_16x16x64_i8 v[22:25], v[190:193], v[222:225], v[22:25]
	v_mfma_i32_16x16x64_i8 v[18:21], v[198:201], v[222:225], v[18:21]
	v_mfma_i32_16x16x64_i8 v[14:17], v[190:193], v[234:237], v[14:17]
	v_mfma_i32_16x16x64_i8 v[6:9], v[198:201], v[234:237], v[6:9]
	s_setprio 0
	s_barrier
	s_add_i32 s85, 0, 0x18000
	s_add_i32 s86, 0, 0x1c000
	v_add_u32_e32 v150, s85, v182
	v_add_u32_e32 v189, s86, v182
	ds_read_b128 v[138:141], v150
	ds_read_b128 v[142:145], v150 offset:1024
	ds_read_b128 v[146:149], v150 offset:2048
	ds_read_b128 v[150:153], v150 offset:3072
	ds_read_b128 v[166:169], v189
	ds_read_b128 v[190:193], v189 offset:1024
	ds_read_b128 v[194:197], v189 offset:2048
	ds_read_b128 v[198:201], v189 offset:3072
	s_add_u32 s60, s60, 0x20000
	s_addc_u32 s61, s61, 0
	s_mov_b32 m0, s72
	ds_read_b128 v[202:205], v185 offset:32768
	ds_read_b128 v[206:209], v185 offset:33792
	ds_read_b128 v[210:213], v185 offset:34816
	ds_read_b128 v[214:217], v185 offset:35840
	ds_read_b128 v[218:221], v185 offset:36864
	ds_read_b128 v[222:225], v185 offset:37888
	ds_read_b128 v[226:229], v185 offset:38912
	ds_read_b128 v[234:237], v185 offset:39936
	global_load_lds_dwordx4 v160, s[60:61]
	s_mov_b32 m0, s73
	s_nop 0
	global_load_lds_dwordx4 v162, s[60:61]
	s_waitcnt vmcnt(8)
	s_waitcnt lgkmcnt(0)
	s_barrier
	s_setprio 1
	s_waitcnt lgkmcnt(0)
	v_mfma_i32_16x16x64_i8 v[126:129], v[138:141], v[202:205], v[126:129]
	v_mfma_i32_16x16x64_i8 v[122:125], v[146:149], v[202:205], v[122:125]
	v_mfma_i32_16x16x64_i8 v[110:113], v[138:141], v[210:213], v[110:113]
	v_mfma_i32_16x16x64_i8 v[106:109], v[146:149], v[210:213], v[106:109]
	v_mfma_i32_16x16x64_i8 v[94:97], v[138:141], v[218:221], v[94:97]
	v_mfma_i32_16x16x64_i8 v[90:93], v[146:149], v[218:221], v[90:93]
	v_mfma_i32_16x16x64_i8 v[78:81], v[138:141], v[226:229], v[78:81]
	v_mfma_i32_16x16x64_i8 v[74:77], v[146:149], v[226:229], v[74:77]
	v_mfma_i32_16x16x64_i8 v[126:129], v[142:145], v[206:209], v[126:129]
	v_mfma_i32_16x16x64_i8 v[122:125], v[150:153], v[206:209], v[122:125]
	v_mfma_i32_16x16x64_i8 v[110:113], v[142:145], v[214:217], v[110:113]
	v_mfma_i32_16x16x64_i8 v[106:109], v[150:153], v[214:217], v[106:109]
	v_mfma_i32_16x16x64_i8 v[94:97], v[142:145], v[222:225], v[94:97]
	v_mfma_i32_16x16x64_i8 v[90:93], v[150:153], v[222:225], v[90:93]
	v_mfma_i32_16x16x64_i8 v[78:81], v[142:145], v[234:237], v[78:81]
	v_mfma_i32_16x16x64_i8 v[74:77], v[150:153], v[234:237], v[74:77]
	s_setprio 0
	s_setprio 1
	v_mfma_i32_16x16x64_i8 v[118:121], v[166:169], v[202:205], v[118:121]
	v_mfma_i32_16x16x64_i8 v[114:117], v[194:197], v[202:205], v[114:117]
	v_mfma_i32_16x16x64_i8 v[102:105], v[166:169], v[210:213], v[102:105]
	v_mfma_i32_16x16x64_i8 v[98:101], v[194:197], v[210:213], v[98:101]
	v_mfma_i32_16x16x64_i8 v[86:89], v[166:169], v[218:221], v[86:89]
	v_mfma_i32_16x16x64_i8 v[82:85], v[194:197], v[218:221], v[82:85]
	v_mfma_i32_16x16x64_i8 v[70:73], v[166:169], v[226:229], v[70:73]
	v_mfma_i32_16x16x64_i8 v[66:69], v[194:197], v[226:229], v[66:69]
	v_mfma_i32_16x16x64_i8 v[118:121], v[190:193], v[206:209], v[118:121]
	v_mfma_i32_16x16x64_i8 v[114:117], v[198:201], v[206:209], v[114:117]
	v_mfma_i32_16x16x64_i8 v[102:105], v[190:193], v[214:217], v[102:105]
	v_mfma_i32_16x16x64_i8 v[98:101], v[198:201], v[214:217], v[98:101]
	v_mfma_i32_16x16x64_i8 v[86:89], v[190:193], v[222:225], v[86:89]
	v_mfma_i32_16x16x64_i8 v[82:85], v[198:201], v[222:225], v[82:85]
	v_mfma_i32_16x16x64_i8 v[70:73], v[190:193], v[234:237], v[70:73]
	v_mfma_i32_16x16x64_i8 v[66:69], v[198:201], v[234:237], v[66:69]
	s_setprio 0
	s_barrier
	s_add_i32 s60, s85, s71
	v_lshl_add_u64 v[154:155], v[154:155], 0, s[14:15]
	s_mov_b32 m0, s60
	ds_read_b128 v[202:205], v185 offset:49152
	ds_read_b128 v[206:209], v185 offset:50176
	ds_read_b128 v[210:213], v185 offset:51200
	ds_read_b128 v[214:217], v185 offset:52224
	ds_read_b128 v[218:221], v185 offset:53248
	ds_read_b128 v[222:225], v185 offset:54272
	ds_read_b128 v[226:229], v185 offset:55296
	ds_read_b128 v[234:237], v185 offset:56320
	global_load_lds_dwordx4 v[154:155], off
	s_add_i32 m0, s60, 0x2000
	s_add_u32 s58, s58, 0x20080
	v_lshl_add_u64 v[154:155], v[170:171], 0, s[14:15]
	s_addc_u32 s59, s59, 0
	s_add_i32 s60, s86, s71
	global_load_lds_dwordx4 v[154:155], off
	s_mov_b32 m0, s60
	s_nop 0
	global_load_lds_dwordx4 v0, s[58:59]
	s_add_i32 m0, s60, 0x2000
	s_nop 0
	global_load_lds_dwordx4 v164, s[58:59]
	v_lshl_add_u64 v[154:155], v[230:231], 0, s[14:15]
	s_mov_b32 m0, s74
	s_nop 0
	global_load_lds_dwordx4 v[154:155], off
	v_lshl_add_u64 v[154:155], v[238:239], 0, s[14:15]
	s_mov_b32 m0, s75
	s_nop 0
	global_load_lds_dwordx4 v[154:155], off
	s_waitcnt vmcnt(8)
	s_waitcnt lgkmcnt(0)
	s_barrier
	s_setprio 1
	s_waitcnt lgkmcnt(0)
	v_mfma_i32_16x16x64_i8 v[62:65], v[138:141], v[202:205], v[62:65]
	v_mfma_i32_16x16x64_i8 v[58:61], v[146:149], v[202:205], v[58:61]
	v_mfma_i32_16x16x64_i8 v[46:49], v[138:141], v[210:213], v[46:49]
	v_mfma_i32_16x16x64_i8 v[42:45], v[146:149], v[210:213], v[42:45]
	v_mfma_i32_16x16x64_i8 v[30:33], v[138:141], v[218:221], v[30:33]
	v_mfma_i32_16x16x64_i8 v[26:29], v[146:149], v[218:221], v[26:29]
	v_mfma_i32_16x16x64_i8 v[10:13], v[138:141], v[226:229], v[10:13]
	v_mfma_i32_16x16x64_i8 v[2:5], v[146:149], v[226:229], v[2:5]
	v_mfma_i32_16x16x64_i8 v[62:65], v[142:145], v[206:209], v[62:65]
	v_mfma_i32_16x16x64_i8 v[58:61], v[150:153], v[206:209], v[58:61]
	v_mfma_i32_16x16x64_i8 v[46:49], v[142:145], v[214:217], v[46:49]
	v_mfma_i32_16x16x64_i8 v[42:45], v[150:153], v[214:217], v[42:45]
	v_mfma_i32_16x16x64_i8 v[30:33], v[142:145], v[222:225], v[30:33]
	v_mfma_i32_16x16x64_i8 v[26:29], v[150:153], v[222:225], v[26:29]
	v_mfma_i32_16x16x64_i8 v[10:13], v[142:145], v[234:237], v[10:13]
	v_mfma_i32_16x16x64_i8 v[2:5], v[150:153], v[234:237], v[2:5]
	s_setprio 0
	s_setprio 1
	v_mfma_i32_16x16x64_i8 v[54:57], v[166:169], v[202:205], v[54:57]
	v_mfma_i32_16x16x64_i8 v[50:53], v[194:197], v[202:205], v[50:53]
	v_mfma_i32_16x16x64_i8 v[38:41], v[166:169], v[210:213], v[38:41]
	v_mfma_i32_16x16x64_i8 v[34:37], v[194:197], v[210:213], v[34:37]
	v_mfma_i32_16x16x64_i8 v[22:25], v[166:169], v[218:221], v[22:25]
	v_mfma_i32_16x16x64_i8 v[18:21], v[194:197], v[218:221], v[18:21]
	v_mfma_i32_16x16x64_i8 v[14:17], v[166:169], v[226:229], v[14:17]
	v_mfma_i32_16x16x64_i8 v[6:9], v[194:197], v[226:229], v[6:9]
	v_mfma_i32_16x16x64_i8 v[54:57], v[190:193], v[206:209], v[54:57]
	v_mfma_i32_16x16x64_i8 v[50:53], v[198:201], v[206:209], v[50:53]
	v_mfma_i32_16x16x64_i8 v[38:41], v[190:193], v[214:217], v[38:41]
	v_mfma_i32_16x16x64_i8 v[34:37], v[198:201], v[214:217], v[34:37]
	v_mfma_i32_16x16x64_i8 v[22:25], v[190:193], v[222:225], v[22:25]
	v_mfma_i32_16x16x64_i8 v[18:21], v[198:201], v[222:225], v[18:21]
	v_mfma_i32_16x16x64_i8 v[14:17], v[190:193], v[234:237], v[14:17]
	v_mfma_i32_16x16x64_i8 v[6:9], v[198:201], v[234:237], v[6:9]
	s_setprio 0
	s_barrier
	s_add_i32 s84, s84, 2
	s_add_u32 s56, s56, 0x100
	s_addc_u32 s57, s57, 0
	s_add_u32 s82, s82, 0x100
	s_addc_u32 s83, s83, 0
	s_cmp_gt_u32 s84, 5
	s_cbranch_scc0 .LBB0_2985
	s_and_b64 vcc, exec, s[40:41]
	s_cbranch_vccz .LBB0_2988
	s_barrier

.LBB0_3005:
	s_add_u32 s34, s64, 0xcf00000
	s_addc_u32 s35, s65, 0
	s_lshl_b32 s5, s5, 5
	s_and_b32 s64, s5, 0x60
	s_add_i32 m0, s45, 0x18000
	v_lshl_add_u64 v[8:9], v[8:9], 0, s[14:15]
	s_lshl_b32 s38, s4, 13
	s_lshl_b32 s5, s64, 7
	s_waitcnt vmcnt(2)
	s_barrier
	global_load_lds_dwordx4 v[8:9], off
	v_lshl_add_u64 v[6:7], v[6:7], 0, s[14:15]
	s_add_i32 m0, s45, 0x1a000
	s_add_i32 s65, s45, 0x8000
	s_add_i32 s66, s45, 0xa000
	global_load_lds_dwordx4 v[6:7], off
	v_lshl_add_u64 v[2:3], v[2:3], 0, s[14:15]
	s_mov_b32 m0, s65
	s_add_u32 s36, s8, 0x20080
	global_load_lds_dwordx4 v[2:3], off
	v_lshl_add_u64 v[2:3], v[4:5], 0, s[14:15]
	s_mov_b32 m0, s66
	s_addc_u32 s37, s9, 0
	global_load_lds_dwordx4 v[2:3], off
	s_add_i32 m0, s45, 0x1c000
	s_nop 0
	global_load_lds_dwordx4 v166, s[36:37]
	s_add_i32 m0, s45, 0x1e000
	v_lshrrev_b32_e32 v0, 1, v130
	global_load_lds_dwordx4 v164, s[36:37]
	v_and_b32_e32 v168, 24, v0
	v_lshlrev_b32_e32 v0, 1, v168
	v_lshl_or_b32 v2, v179, 6, v0
	v_or_b32_e32 v0, v0, v178
	v_lshlrev_b32_e32 v3, 2, v179
	v_bitop3_b32 v188, s5, v0, v180 bitop3:0xf6
	v_lshlrev_b32_e32 v0, 13, v172
	v_and_b32_e32 v3, 32, v3
	v_and_b32_e32 v0, 0xffffc000, v0
	v_bitop3_b32 v4, v2, s38, v3 bitop3:0xde
	v_lshl_add_u32 v0, v173, 10, v0
	v_and_b32_e32 v2, 1, v172
	v_lshl_or_b32 v0, v2, 6, v0
	v_lshl_add_u32 v172, v174, 1, v0
	v_lshlrev_b32_e32 v0, 13, v175
	v_and_b32_e32 v0, 0xffffc000, v0
	v_lshl_add_u32 v0, v176, 10, v0
	v_and_b32_e32 v2, 1, v175
	s_waitcnt vmcnt(6)
	v_lshl_or_b32 v0, v2, 6, v0
	v_mov_b32_e32 v2, v1
	v_mov_b32_e32 v3, v1
	v_lshl_or_b32 v169, s4, 6, v179
	s_cmpk_lt_u32 s12, 0x100
	v_lshl_add_u64 v[170:171], v[130:131], 4, s[6:7]
	v_lshl_add_u32 v174, v177, 1, v0
	v_mov_b32_e32 v0, v1
	v_add_u32_e32 v196, 0, v4
	v_mov_b64_e32 v[6:7], v[2:3]
	v_mov_b64_e32 v[10:11], v[2:3]
	v_mov_b64_e32 v[14:15], v[2:3]
	v_mov_b64_e32 v[18:19], v[2:3]
	v_mov_b64_e32 v[22:23], v[2:3]
	v_mov_b64_e32 v[26:27], v[2:3]
	v_mov_b64_e32 v[30:31], v[2:3]
	v_mov_b64_e32 v[34:35], v[2:3]
	v_mov_b64_e32 v[38:39], v[2:3]
	v_mov_b64_e32 v[42:43], v[2:3]
	v_mov_b64_e32 v[46:47], v[2:3]
	v_mov_b64_e32 v[50:51], v[2:3]
	v_mov_b64_e32 v[54:55], v[2:3]
	v_mov_b64_e32 v[58:59], v[2:3]
	v_mov_b64_e32 v[62:63], v[2:3]
	v_mov_b64_e32 v[66:67], v[2:3]
	v_mov_b64_e32 v[70:71], v[2:3]
	v_mov_b64_e32 v[74:75], v[2:3]
	v_mov_b64_e32 v[78:79], v[2:3]
	v_mov_b64_e32 v[82:83], v[2:3]
	v_mov_b64_e32 v[86:87], v[2:3]
	v_mov_b64_e32 v[90:91], v[2:3]
	v_mov_b64_e32 v[94:95], v[2:3]
	v_mov_b64_e32 v[98:99], v[2:3]
	v_mov_b64_e32 v[102:103], v[2:3]
	v_mov_b64_e32 v[106:107], v[2:3]
	v_mov_b64_e32 v[110:111], v[2:3]
	v_mov_b64_e32 v[114:115], v[2:3]
	v_mov_b64_e32 v[118:119], v[2:3]
	v_mov_b64_e32 v[122:123], v[2:3]
	v_mov_b64_e32 v[126:127], v[2:3]
	v_mov_b64_e32 v[130:131], v[2:3]
	s_cselect_b64 s[36:37], -1, 0
	v_or_b32_e32 v189, 16, v169
	v_or_b32_e32 v190, 32, v169
	v_or_b32_e32 v191, 48, v169
	v_add_u32_e32 v192, 0x80, v169
	v_add_u32_e32 v193, 0x90, v169
	v_add_u32_e32 v194, 0xa0, v169
	v_add_u32_e32 v195, 0xb0, v169
	s_ashr_i32 s67, s33, 31
	v_mov_b32_e32 v173, v1
	v_mov_b32_e32 v175, v1
	s_mov_b32 s12, 0
	v_mov_b64_e32 v[4:5], v[0:1]
	v_mov_b64_e32 v[8:9], v[0:1]
	v_mov_b64_e32 v[12:13], v[0:1]
	v_mov_b64_e32 v[16:17], v[0:1]
	v_mov_b64_e32 v[20:21], v[0:1]
	v_mov_b64_e32 v[24:25], v[0:1]
	v_mov_b64_e32 v[28:29], v[0:1]
	v_mov_b64_e32 v[32:33], v[0:1]
	v_mov_b64_e32 v[36:37], v[0:1]
	v_mov_b64_e32 v[40:41], v[0:1]
	v_mov_b64_e32 v[44:45], v[0:1]
	v_mov_b64_e32 v[48:49], v[0:1]
	v_mov_b64_e32 v[52:53], v[0:1]
	v_mov_b64_e32 v[56:57], v[0:1]
	v_mov_b64_e32 v[60:61], v[0:1]
	v_mov_b64_e32 v[64:65], v[0:1]
	v_mov_b64_e32 v[68:69], v[0:1]
	v_mov_b64_e32 v[72:73], v[0:1]
	v_mov_b64_e32 v[76:77], v[0:1]
	v_mov_b64_e32 v[80:81], v[0:1]
	v_mov_b64_e32 v[84:85], v[0:1]
	v_mov_b64_e32 v[88:89], v[0:1]
	v_mov_b64_e32 v[92:93], v[0:1]
	v_mov_b64_e32 v[96:97], v[0:1]
	v_mov_b64_e32 v[100:101], v[0:1]
	v_mov_b64_e32 v[104:105], v[0:1]
	v_mov_b64_e32 v[108:109], v[0:1]
	v_mov_b64_e32 v[112:113], v[0:1]
	v_mov_b64_e32 v[116:117], v[0:1]
	v_mov_b64_e32 v[120:121], v[0:1]
	v_mov_b64_e32 v[124:125], v[0:1]
	v_mov_b64_e32 v[128:129], v[0:1]
	s_mov_b32 s68, 0
	s_barrier
	s_branch .LBB0_3008

.LBB0_3015:
	s_add_u32 s8, s6, 0xfffe0080
	s_addc_u32 s9, s7, -1
	s_add_i32 s72, 0, 0x10000
	s_cmp_eq_u32 s71, 4
	s_cselect_b32 s55, s43, s9
	s_cselect_b32 s54, s49, s8
	v_add_u32_e32 v0, s72, v188
	s_cselect_b32 s9, s39, s70
	s_cselect_b32 s8, s41, s69
	s_add_i32 s74, 0, 0x14000
	ds_read_b128 v[132:135], v0
	ds_read_b128 v[136:139], v0 offset:1024
	ds_read_b128 v[140:143], v0 offset:2048
	ds_read_b128 v[144:147], v0 offset:3072
	v_add_u32_e32 v0, s74, v188
	ds_read_b128 v[148:151], v0
	ds_read_b128 v[152:155], v0 offset:1024
	ds_read_b128 v[176:179], v0 offset:2048
	ds_read_b128 v[180:183], v0 offset:3072
	s_add_i32 m0, s45, 0xc000
	ds_read_b128 v[198:201], v196
	ds_read_b128 v[202:205], v196 offset:1024
	ds_read_b128 v[206:209], v196 offset:2048
	ds_read_b128 v[210:213], v196 offset:3072
	ds_read_b128 v[214:217], v196 offset:4096
	ds_read_b128 v[218:221], v196 offset:5120
	ds_read_b128 v[222:225], v196 offset:6144
	ds_read_b128 v[226:229], v196 offset:7168
	global_load_lds_dwordx4 v172, s[6:7]
	s_add_i32 m0, s45, 0xe000
	s_nop 0
	global_load_lds_dwordx4 v174, s[6:7]
	s_waitcnt vmcnt(8)
	s_waitcnt lgkmcnt(0)
	s_barrier
	s_setprio 1
	s_waitcnt lgkmcnt(0)
	v_mfma_f32_16x16x32_bf16 v[128:131], v[132:135], v[198:201], v[128:131]
	v_mfma_f32_16x16x32_bf16 v[124:127], v[140:143], v[198:201], v[124:127]
	v_mfma_f32_16x16x32_bf16 v[120:123], v[132:135], v[206:209], v[120:123]
	v_mfma_f32_16x16x32_bf16 v[116:119], v[140:143], v[206:209], v[116:119]
	v_mfma_f32_16x16x32_bf16 v[112:115], v[132:135], v[214:217], v[112:115]
	v_mfma_f32_16x16x32_bf16 v[108:111], v[140:143], v[214:217], v[108:111]
	v_mfma_f32_16x16x32_bf16 v[104:107], v[132:135], v[222:225], v[104:107]
	v_mfma_f32_16x16x32_bf16 v[100:103], v[140:143], v[222:225], v[100:103]
	v_mfma_f32_16x16x32_bf16 v[128:131], v[136:139], v[202:205], v[128:131]
	v_mfma_f32_16x16x32_bf16 v[124:127], v[144:147], v[202:205], v[124:127]
	v_mfma_f32_16x16x32_bf16 v[120:123], v[136:139], v[210:213], v[120:123]
	v_mfma_f32_16x16x32_bf16 v[116:119], v[144:147], v[210:213], v[116:119]
	v_mfma_f32_16x16x32_bf16 v[112:115], v[136:139], v[218:221], v[112:115]
	v_mfma_f32_16x16x32_bf16 v[108:111], v[144:147], v[218:221], v[108:111]
	v_mfma_f32_16x16x32_bf16 v[104:107], v[136:139], v[226:229], v[104:107]
	v_mfma_f32_16x16x32_bf16 v[100:103], v[144:147], v[226:229], v[100:103]
	s_setprio 0
	s_setprio 1
	v_mfma_f32_16x16x32_bf16 v[96:99], v[148:151], v[198:201], v[96:99]
	v_mfma_f32_16x16x32_bf16 v[92:95], v[176:179], v[198:201], v[92:95]
	v_mfma_f32_16x16x32_bf16 v[88:91], v[148:151], v[206:209], v[88:91]
	v_mfma_f32_16x16x32_bf16 v[84:87], v[176:179], v[206:209], v[84:87]
	v_mfma_f32_16x16x32_bf16 v[80:83], v[148:151], v[214:217], v[80:83]
	v_mfma_f32_16x16x32_bf16 v[76:79], v[176:179], v[214:217], v[76:79]
	v_mfma_f32_16x16x32_bf16 v[72:75], v[148:151], v[222:225], v[72:75]
	v_mfma_f32_16x16x32_bf16 v[68:71], v[176:179], v[222:225], v[68:71]
	v_mfma_f32_16x16x32_bf16 v[96:99], v[152:155], v[202:205], v[96:99]
	v_mfma_f32_16x16x32_bf16 v[92:95], v[180:183], v[202:205], v[92:95]
	v_mfma_f32_16x16x32_bf16 v[88:91], v[152:155], v[210:213], v[88:91]
	v_mfma_f32_16x16x32_bf16 v[84:87], v[180:183], v[210:213], v[84:87]
	v_mfma_f32_16x16x32_bf16 v[80:83], v[152:155], v[218:221], v[80:83]
	v_mfma_f32_16x16x32_bf16 v[76:79], v[180:183], v[218:221], v[76:79]
	v_mfma_f32_16x16x32_bf16 v[72:75], v[152:155], v[226:229], v[72:75]
	v_mfma_f32_16x16x32_bf16 v[68:71], v[180:183], v[226:229], v[68:71]
	s_setprio 0
	s_barrier
	s_add_i32 s72, s72, s60
	v_lshl_add_u64 v[184:185], s[8:9], 0, v[166:167]
	s_mov_b32 m0, s72
	ds_read_b128 v[198:201], v196 offset:16384
	ds_read_b128 v[202:205], v196 offset:17408
	ds_read_b128 v[206:209], v196 offset:18432
	ds_read_b128 v[210:213], v196 offset:19456
	ds_read_b128 v[214:217], v196 offset:20480
	ds_read_b128 v[218:221], v196 offset:21504
	ds_read_b128 v[222:225], v196 offset:22528
	ds_read_b128 v[226:229], v196 offset:23552
	global_load_lds_dwordx4 v[184:185], off
	s_add_i32 m0, s72, 0x2000
	s_add_u32 s72, s8, 0x20000
	v_lshl_add_u64 v[230:231], s[8:9], 0, v[164:165]
	s_addc_u32 s73, s9, 0
	s_add_i32 s74, s74, s60
	global_load_lds_dwordx4 v[230:231], off
	s_mov_b32 m0, s74
	v_lshl_add_u64 v[234:235], s[54:55], 0, v[160:161]
	global_load_lds_dwordx4 v166, s[72:73]
	s_add_i32 m0, s74, 0x2000
	v_lshl_add_u64 v[236:237], s[54:55], 0, v[162:163]
	global_load_lds_dwordx4 v164, s[72:73]
	s_mov_b32 m0, s45
	s_nop 0
	global_load_lds_dwordx4 v[234:235], off
	s_mov_b32 m0, s61
	s_nop 0
	global_load_lds_dwordx4 v[236:237], off
	s_waitcnt vmcnt(8)
	s_waitcnt lgkmcnt(0)
	s_barrier
	s_setprio 1
	s_waitcnt lgkmcnt(0)
	v_mfma_f32_16x16x32_bf16 v[64:67], v[132:135], v[198:201], v[64:67]
	v_mfma_f32_16x16x32_bf16 v[60:63], v[140:143], v[198:201], v[60:63]
	v_mfma_f32_16x16x32_bf16 v[56:59], v[132:135], v[206:209], v[56:59]
	v_mfma_f32_16x16x32_bf16 v[52:55], v[140:143], v[206:209], v[52:55]
	v_mfma_f32_16x16x32_bf16 v[48:51], v[132:135], v[214:217], v[48:51]
	v_mfma_f32_16x16x32_bf16 v[44:47], v[140:143], v[214:217], v[44:47]
	v_mfma_f32_16x16x32_bf16 v[40:43], v[132:135], v[222:225], v[40:43]
	v_mfma_f32_16x16x32_bf16 v[36:39], v[140:143], v[222:225], v[36:39]
	v_mfma_f32_16x16x32_bf16 v[64:67], v[136:139], v[202:205], v[64:67]
	v_mfma_f32_16x16x32_bf16 v[60:63], v[144:147], v[202:205], v[60:63]
	v_mfma_f32_16x16x32_bf16 v[56:59], v[136:139], v[210:213], v[56:59]
	v_mfma_f32_16x16x32_bf16 v[52:55], v[144:147], v[210:213], v[52:55]
	v_mfma_f32_16x16x32_bf16 v[48:51], v[136:139], v[218:221], v[48:51]
	v_mfma_f32_16x16x32_bf16 v[44:47], v[144:147], v[218:221], v[44:47]
	v_mfma_f32_16x16x32_bf16 v[40:43], v[136:139], v[226:229], v[40:43]
	v_mfma_f32_16x16x32_bf16 v[36:39], v[144:147], v[226:229], v[36:39]
	s_setprio 0
	s_setprio 1
	v_mfma_f32_16x16x32_bf16 v[32:35], v[148:151], v[198:201], v[32:35]
	v_mfma_f32_16x16x32_bf16 v[28:31], v[176:179], v[198:201], v[28:31]
	v_mfma_f32_16x16x32_bf16 v[24:27], v[148:151], v[206:209], v[24:27]
	v_mfma_f32_16x16x32_bf16 v[20:23], v[176:179], v[206:209], v[20:23]
	v_mfma_f32_16x16x32_bf16 v[16:19], v[148:151], v[214:217], v[16:19]
	v_mfma_f32_16x16x32_bf16 v[12:15], v[176:179], v[214:217], v[12:15]
	v_mfma_f32_16x16x32_bf16 v[8:11], v[148:151], v[222:225], v[8:11]
	v_mfma_f32_16x16x32_bf16 v[2:5], v[176:179], v[222:225], v[4:7]
	v_mfma_f32_16x16x32_bf16 v[32:35], v[152:155], v[202:205], v[32:35]
	v_mfma_f32_16x16x32_bf16 v[28:31], v[180:183], v[202:205], v[28:31]
	v_mfma_f32_16x16x32_bf16 v[24:27], v[152:155], v[210:213], v[24:27]
	v_mfma_f32_16x16x32_bf16 v[20:23], v[180:183], v[210:213], v[20:23]
	v_mfma_f32_16x16x32_bf16 v[16:19], v[152:155], v[218:221], v[16:19]
	v_mfma_f32_16x16x32_bf16 v[12:15], v[180:183], v[218:221], v[12:15]
	v_mfma_f32_16x16x32_bf16 v[8:11], v[152:155], v[226:229], v[8:11]
	v_mfma_f32_16x16x32_bf16 v[2:5], v[180:183], v[226:229], v[2:5]
	s_setprio 0
	s_barrier
	s_add_i32 s72, 0, 0x18000
	v_add_u32_e32 v0, s72, v188
	s_add_i32 s73, 0, 0x1c000
	ds_read_b128 v[132:135], v0
	ds_read_b128 v[136:139], v0 offset:1024
	ds_read_b128 v[140:143], v0 offset:2048
	ds_read_b128 v[144:147], v0 offset:3072
	v_add_u32_e32 v0, s73, v188
	ds_read_b128 v[148:151], v0
	ds_read_b128 v[152:155], v0 offset:1024
	ds_read_b128 v[176:179], v0 offset:2048
	ds_read_b128 v[180:183], v0 offset:3072
	s_add_u32 s54, s54, 0x20000
	s_addc_u32 s55, s55, 0
	s_mov_b32 m0, s62
	ds_read_b128 v[198:201], v196 offset:32768
	ds_read_b128 v[202:205], v196 offset:33792
	ds_read_b128 v[206:209], v196 offset:34816
	ds_read_b128 v[210:213], v196 offset:35840
	ds_read_b128 v[214:217], v196 offset:36864
	ds_read_b128 v[218:221], v196 offset:37888
	ds_read_b128 v[222:225], v196 offset:38912
	ds_read_b128 v[226:229], v196 offset:39936
	global_load_lds_dwordx4 v160, s[54:55]
	s_mov_b32 m0, s63
	s_nop 0
	global_load_lds_dwordx4 v162, s[54:55]
	s_waitcnt vmcnt(8)
	s_waitcnt lgkmcnt(0)
	s_barrier
	s_setprio 1
	s_waitcnt lgkmcnt(0)
	v_mfma_f32_16x16x32_bf16 v[128:131], v[132:135], v[198:201], v[128:131]
	v_mfma_f32_16x16x32_bf16 v[124:127], v[140:143], v[198:201], v[124:127]
	v_mfma_f32_16x16x32_bf16 v[120:123], v[132:135], v[206:209], v[120:123]
	v_mfma_f32_16x16x32_bf16 v[116:119], v[140:143], v[206:209], v[116:119]
	v_mfma_f32_16x16x32_bf16 v[112:115], v[132:135], v[214:217], v[112:115]
	v_mfma_f32_16x16x32_bf16 v[108:111], v[140:143], v[214:217], v[108:111]
	v_mfma_f32_16x16x32_bf16 v[104:107], v[132:135], v[222:225], v[104:107]
	v_mfma_f32_16x16x32_bf16 v[100:103], v[140:143], v[222:225], v[100:103]
	v_mfma_f32_16x16x32_bf16 v[128:131], v[136:139], v[202:205], v[128:131]
	v_mfma_f32_16x16x32_bf16 v[124:127], v[144:147], v[202:205], v[124:127]
	v_mfma_f32_16x16x32_bf16 v[120:123], v[136:139], v[210:213], v[120:123]
	v_mfma_f32_16x16x32_bf16 v[116:119], v[144:147], v[210:213], v[116:119]
	v_mfma_f32_16x16x32_bf16 v[112:115], v[136:139], v[218:221], v[112:115]
	v_mfma_f32_16x16x32_bf16 v[108:111], v[144:147], v[218:221], v[108:111]
	v_mfma_f32_16x16x32_bf16 v[104:107], v[136:139], v[226:229], v[104:107]
	v_mfma_f32_16x16x32_bf16 v[100:103], v[144:147], v[226:229], v[100:103]
	s_setprio 0
	s_setprio 1
	v_mfma_f32_16x16x32_bf16 v[96:99], v[148:151], v[198:201], v[96:99]
	v_mfma_f32_16x16x32_bf16 v[92:95], v[176:179], v[198:201], v[92:95]
	v_mfma_f32_16x16x32_bf16 v[88:91], v[148:151], v[206:209], v[88:91]
	v_mfma_f32_16x16x32_bf16 v[84:87], v[176:179], v[206:209], v[84:87]
	v_mfma_f32_16x16x32_bf16 v[80:83], v[148:151], v[214:217], v[80:83]
	v_mfma_f32_16x16x32_bf16 v[76:79], v[176:179], v[214:217], v[76:79]
	v_mfma_f32_16x16x32_bf16 v[72:75], v[148:151], v[222:225], v[72:75]
	v_mfma_f32_16x16x32_bf16 v[68:71], v[176:179], v[222:225], v[68:71]
	v_mfma_f32_16x16x32_bf16 v[96:99], v[152:155], v[202:205], v[96:99]
	v_mfma_f32_16x16x32_bf16 v[92:95], v[180:183], v[202:205], v[92:95]
	v_mfma_f32_16x16x32_bf16 v[88:91], v[152:155], v[210:213], v[88:91]
	v_mfma_f32_16x16x32_bf16 v[84:87], v[180:183], v[210:213], v[84:87]
	v_mfma_f32_16x16x32_bf16 v[80:83], v[152:155], v[218:221], v[80:83]
	v_mfma_f32_16x16x32_bf16 v[76:79], v[180:183], v[218:221], v[76:79]
	v_mfma_f32_16x16x32_bf16 v[72:75], v[152:155], v[226:229], v[72:75]
	v_mfma_f32_16x16x32_bf16 v[68:71], v[180:183], v[226:229], v[68:71]
	s_setprio 0
	s_barrier
	s_add_i32 s54, s72, s60
	v_lshl_add_u64 v[6:7], v[184:185], 0, s[14:15]
	s_mov_b32 m0, s54
	ds_read_b128 v[198:201], v196 offset:49152
	ds_read_b128 v[202:205], v196 offset:50176
	ds_read_b128 v[206:209], v196 offset:51200
	ds_read_b128 v[210:213], v196 offset:52224
	ds_read_b128 v[214:217], v196 offset:53248
	ds_read_b128 v[218:221], v196 offset:54272
	ds_read_b128 v[222:225], v196 offset:55296
	ds_read_b128 v[226:229], v196 offset:56320
	global_load_lds_dwordx4 v[6:7], off
	s_add_i32 m0, s54, 0x2000
	s_add_u32 s8, s8, 0x20080
	v_lshl_add_u64 v[6:7], v[230:231], 0, s[14:15]
	s_addc_u32 s9, s9, 0
	s_add_i32 s54, s73, s60
	global_load_lds_dwordx4 v[6:7], off
	s_mov_b32 m0, s54
	s_nop 0
	global_load_lds_dwordx4 v166, s[8:9]
	s_add_i32 m0, s54, 0x2000
	s_nop 0
	global_load_lds_dwordx4 v164, s[8:9]
	v_lshl_add_u64 v[6:7], v[234:235], 0, s[14:15]
	s_mov_b32 m0, s65
	s_nop 0
	global_load_lds_dwordx4 v[6:7], off
	v_lshl_add_u64 v[6:7], v[236:237], 0, s[14:15]
	s_mov_b32 m0, s66
	s_nop 0
	global_load_lds_dwordx4 v[6:7], off
	s_waitcnt vmcnt(8)
	s_waitcnt lgkmcnt(0)
	s_barrier
	s_setprio 1
	s_waitcnt lgkmcnt(0)
	v_mfma_f32_16x16x32_bf16 v[64:67], v[132:135], v[198:201], v[64:67]
	v_mfma_f32_16x16x32_bf16 v[60:63], v[140:143], v[198:201], v[60:63]
	v_mfma_f32_16x16x32_bf16 v[56:59], v[132:135], v[206:209], v[56:59]
	v_mfma_f32_16x16x32_bf16 v[52:55], v[140:143], v[206:209], v[52:55]
	v_mfma_f32_16x16x32_bf16 v[48:51], v[132:135], v[214:217], v[48:51]
	v_mfma_f32_16x16x32_bf16 v[44:47], v[140:143], v[214:217], v[44:47]
	v_mfma_f32_16x16x32_bf16 v[40:43], v[132:135], v[222:225], v[40:43]
	v_mfma_f32_16x16x32_bf16 v[36:39], v[140:143], v[222:225], v[36:39]
	v_mfma_f32_16x16x32_bf16 v[64:67], v[136:139], v[202:205], v[64:67]
	v_mfma_f32_16x16x32_bf16 v[60:63], v[144:147], v[202:205], v[60:63]
	v_mfma_f32_16x16x32_bf16 v[56:59], v[136:139], v[210:213], v[56:59]
	v_mfma_f32_16x16x32_bf16 v[52:55], v[144:147], v[210:213], v[52:55]
	v_mfma_f32_16x16x32_bf16 v[48:51], v[136:139], v[218:221], v[48:51]
	v_mfma_f32_16x16x32_bf16 v[44:47], v[144:147], v[218:221], v[44:47]
	v_mfma_f32_16x16x32_bf16 v[40:43], v[136:139], v[226:229], v[40:43]
	v_mfma_f32_16x16x32_bf16 v[36:39], v[144:147], v[226:229], v[36:39]
	s_setprio 0
	s_setprio 1
	v_mfma_f32_16x16x32_bf16 v[32:35], v[148:151], v[198:201], v[32:35]
	v_mfma_f32_16x16x32_bf16 v[28:31], v[176:179], v[198:201], v[28:31]
	v_mfma_f32_16x16x32_bf16 v[24:27], v[148:151], v[206:209], v[24:27]
	v_mfma_f32_16x16x32_bf16 v[20:23], v[176:179], v[206:209], v[20:23]
	v_mfma_f32_16x16x32_bf16 v[16:19], v[148:151], v[214:217], v[16:19]
	v_mfma_f32_16x16x32_bf16 v[12:15], v[176:179], v[214:217], v[12:15]
	v_mfma_f32_16x16x32_bf16 v[6:9], v[148:151], v[222:225], v[8:11]
	v_mfma_f32_16x16x32_bf16 v[2:5], v[176:179], v[222:225], v[2:5]
	v_mfma_f32_16x16x32_bf16 v[32:35], v[152:155], v[202:205], v[32:35]
	v_mfma_f32_16x16x32_bf16 v[28:31], v[180:183], v[202:205], v[28:31]
	v_mfma_f32_16x16x32_bf16 v[24:27], v[152:155], v[210:213], v[24:27]
	v_mfma_f32_16x16x32_bf16 v[20:23], v[180:183], v[210:213], v[20:23]
	v_mfma_f32_16x16x32_bf16 v[16:19], v[152:155], v[218:221], v[16:19]
	v_mfma_f32_16x16x32_bf16 v[12:15], v[180:183], v[218:221], v[12:15]
	v_mfma_f32_16x16x32_bf16 v[8:11], v[152:155], v[226:229], v[6:9]
	v_mfma_f32_16x16x32_bf16 v[4:7], v[180:183], v[226:229], v[2:5]
	s_setprio 0
	s_barrier
	s_add_i32 s71, s71, 2
	s_add_u32 s6, s6, 0x100
	s_addc_u32 s7, s7, 0
	s_add_u32 s69, s69, 0x100
	s_addc_u32 s70, s70, 0
	s_cmp_gt_u32 s71, 5
	s_cbranch_scc0 .LBB0_3015
	s_and_b64 vcc, exec, s[36:37]
	s_cbranch_vccz .LBB0_3018
	s_barrier

.LBB0_3217:
	s_cmp_ge_u32 s73, s1
	s_cselect_b64 s[20:21], -1, 0
	s_add_u32 s22, s10, 0x2700000
	s_addc_u32 s23, s11, 0
	s_add_u32 s24, s10, 0x300000
	s_addc_u32 s25, s11, 0
	s_add_u32 s9, s10, 0xef00000
	v_readlane_b32 s6, v254, 6
	s_addc_u32 s14, s11, 0
	v_readlane_b32 s7, v254, 7
	s_and_b64 s[6:7], s[6:7], exec
	s_cselect_b32 s27, s14, 0
	s_cselect_b32 s26, s9, 0
	s_add_u32 s28, s10, 0x380000
	s_addc_u32 s29, s11, 0
	s_add_u32 s30, s10, 0xff00000
	s_addc_u32 s31, s11, 0
	s_add_u32 s84, s10, 0x208000
	s_addc_u32 s85, s11, 0
	s_and_b32 s9, s4, 3
	s_add_i32 m0, s80, 0x18000
	v_lshl_add_u64 v[8:9], v[8:9], 0, s[16:17]
	s_lshl_b32 s4, s5, 13
	s_lshl_b32 s34, s9, 5
	s_lshl_b32 s14, s9, 12
	s_waitcnt vmcnt(2)
	s_barrier
	global_load_lds_dwordx4 v[8:9], off
	v_lshl_add_u64 v[6:7], v[6:7], 0, s[16:17]
	s_add_i32 m0, s80, 0x1a000
	s_add_i32 s86, s80, 0x8000
	s_add_i32 s87, s80, 0xa000
	global_load_lds_dwordx4 v[6:7], off
	v_lshl_add_u64 v[2:3], v[2:3], 0, s[16:17]
	s_mov_b32 m0, s86
	s_add_u32 s6, s58, 0x40080
	global_load_lds_dwordx4 v[2:3], off
	v_lshl_add_u64 v[2:3], v[4:5], 0, s[16:17]
	s_mov_b32 m0, s87
	s_addc_u32 s7, s59, 0
	global_load_lds_dwordx4 v[2:3], off
	s_add_i32 m0, s80, 0x1c000
	s_nop 0
	global_load_lds_dwordx4 v136, s[6:7]
	s_add_i32 m0, s80, 0x1e000
	v_lshlrev_b32_e32 v6, 2, v166
	global_load_lds_dwordx4 v140, s[6:7]
	v_bfe_u32 v2, v166, 4, 2
	v_and_b32_e32 v3, 15, v166
	v_lshl_or_b32 v168, s5, 6, v3
	v_lshlrev_b32_e32 v4, 4, v2
	v_lshl_or_b32 v3, v3, 6, v4
	v_lshlrev_b32_e32 v4, 2, v168
	v_and_b32_e32 v5, 32, v4
	v_and_b32_e32 v6, 32, v6
	v_bitop3_b32 v5, v3, s4, v5 bitop3:0xde
	v_bitop3_b32 v169, v3, s14, v6 bitop3:0xde
	v_lshlrev_b32_e32 v3, 14, v0
	s_cmpk_lt_u32 s8, 0x100
	v_and_b32_e32 v3, 0xffff8000, v3
	s_cselect_b64 s[36:37], -1, 0
	s_lshl_b32 s6, s9, 2
	v_lshl_add_u32 v3, v10, 11, v3
	v_and_b32_e32 v0, 1, v0
	v_add_u32_e32 v170, 0x80, v168
	s_add_i32 s6, s6, s33
	v_lshl_or_b32 v0, v0, 6, v3
	v_lshlrev_b32_e32 v142, 3, v2
	v_cmp_eq_u32_e64 s[4:5], 0, v2
	v_lshl_add_u32 v177, v168, 4, s6
	v_lshl_add_u32 v178, v170, 4, s6
	s_movk_i32 s6, 0x100
	v_and_b32_e32 v2, 63, v166
	v_lshl_add_u32 v144, v11, 1, v0
	v_lshlrev_b32_e32 v0, 14, v12
	v_cmp_gt_i32_e64 s[6:7], s6, v166
	v_cmp_eq_u32_e32 vcc, 0, v2
	v_and_b32_e32 v0, 0xffff8000, v0
	s_waitcnt vmcnt(6)
	s_ashr_i32 s89, s74, 31
	s_and_b64 s[38:39], s[6:7], vcc
	v_lshl_add_u32 v0, v13, 11, v0
	v_and_b32_e32 v3, 1, v12
	v_or_b32_e32 v171, 16, v168
	v_or_b32_e32 v172, 32, v168
	v_or_b32_e32 v173, 48, v168
	v_add_u32_e32 v174, 0x90, v168
	v_add_u32_e32 v175, 0xa0, v168
	v_add_u32_e32 v176, 0xb0, v168
	v_add_u32_e32 v179, s33, v167
	s_add_u32 s40, s10, 0x200200
	v_mul_lo_u32 v2, v166, -12
	v_lshl_or_b32 v0, v3, 6, v0
	s_mov_b32 s88, 0
	s_mov_b32 s35, s15
	v_mov_b32_e32 v143, v1
	v_cmp_eq_u32_e64 s[8:9], 0, v166
	s_addc_u32 s41, s11, 0
	s_waitcnt vmcnt(0)
	v_add_u32_e32 v180, s33, v4
	v_lshl_add_u32 v181, v171, 2, s33
	v_lshl_add_u32 v182, v172, 2, s33
	v_lshl_add_u32 v183, v173, 2, s33
	v_lshl_add_u32 v184, v170, 2, s33
	v_lshl_add_u32 v185, v174, 2, s33
	v_lshl_add_u32 v186, v175, 2, s33
	v_lshl_add_u32 v187, v176, 2, s33
	v_mov_b32_e32 v145, v1
	v_lshl_add_u32 v146, v14, 1, v0
	v_mov_b32_e32 v147, v1
	v_add_u32_e32 v188, 0, v5
	v_add_u32_e32 v189, v179, v2
	s_barrier
	s_branch .LBB0_3220

.LBB0_3227:
	s_add_u32 s58, s48, 0xfffc0080
	s_addc_u32 s59, s49, -1
	s_add_i32 s64, 0, 0x10000
	s_cmp_eq_u32 s63, 12
	s_cselect_b32 s61, s14, s59
	s_cselect_b32 s60, s45, s58
	v_add_u32_e32 v0, s64, v169
	s_cselect_b32 s59, s43, s62
	s_cselect_b32 s58, s55, s57
	s_add_i32 s66, 0, 0x14000
	ds_read_b128 v[148:151], v0
	ds_read_b128 v[152:155], v0 offset:1024
	ds_read_b128 v[156:159], v0 offset:2048
	ds_read_b128 v[190:193], v0 offset:3072
	v_add_u32_e32 v0, s66, v169
	ds_read_b128 v[194:197], v0
	ds_read_b128 v[198:201], v0 offset:1024
	ds_read_b128 v[202:205], v0 offset:2048
	ds_read_b128 v[206:209], v0 offset:3072
	s_add_i32 m0, s80, 0xc000
	ds_read_b128 v[210:213], v188
	ds_read_b128 v[214:217], v188 offset:1024
	ds_read_b128 v[218:221], v188 offset:2048
	ds_read_b128 v[222:225], v188 offset:3072
	ds_read_b128 v[226:229], v188 offset:4096
	ds_read_b128 v[234:237], v188 offset:5120
	ds_read_b128 v[238:241], v188 offset:6144
	ds_read_b128 v[242:245], v188 offset:7168
	global_load_lds_dwordx4 v144, s[48:49]
	s_add_i32 m0, s80, 0xe000
	s_nop 0
	global_load_lds_dwordx4 v146, s[48:49]
	s_waitcnt vmcnt(8)
	s_waitcnt lgkmcnt(0)
	s_barrier
	s_setprio 1
	s_waitcnt lgkmcnt(0)
	v_mfma_f32_16x16x32_bf16 v[126:129], v[148:151], v[210:213], v[126:129]
	v_mfma_f32_16x16x32_bf16 v[122:125], v[156:159], v[210:213], v[122:125]
	v_mfma_f32_16x16x32_bf16 v[110:113], v[148:151], v[218:221], v[110:113]
	v_mfma_f32_16x16x32_bf16 v[106:109], v[156:159], v[218:221], v[106:109]
	v_mfma_f32_16x16x32_bf16 v[94:97], v[148:151], v[226:229], v[94:97]
	v_mfma_f32_16x16x32_bf16 v[90:93], v[156:159], v[226:229], v[90:93]
	v_mfma_f32_16x16x32_bf16 v[78:81], v[148:151], v[238:241], v[78:81]
	v_mfma_f32_16x16x32_bf16 v[74:77], v[156:159], v[238:241], v[74:77]
	v_mfma_f32_16x16x32_bf16 v[126:129], v[152:155], v[214:217], v[126:129]
	v_mfma_f32_16x16x32_bf16 v[122:125], v[190:193], v[214:217], v[122:125]
	v_mfma_f32_16x16x32_bf16 v[110:113], v[152:155], v[222:225], v[110:113]
	v_mfma_f32_16x16x32_bf16 v[106:109], v[190:193], v[222:225], v[106:109]
	v_mfma_f32_16x16x32_bf16 v[94:97], v[152:155], v[234:237], v[94:97]
	v_mfma_f32_16x16x32_bf16 v[90:93], v[190:193], v[234:237], v[90:93]
	v_mfma_f32_16x16x32_bf16 v[78:81], v[152:155], v[242:245], v[78:81]
	v_mfma_f32_16x16x32_bf16 v[74:77], v[190:193], v[242:245], v[74:77]
	s_setprio 0
	s_setprio 1
	v_mfma_f32_16x16x32_bf16 v[118:121], v[194:197], v[210:213], v[118:121]
	v_mfma_f32_16x16x32_bf16 v[114:117], v[202:205], v[210:213], v[114:117]
	v_mfma_f32_16x16x32_bf16 v[102:105], v[194:197], v[218:221], v[102:105]
	v_mfma_f32_16x16x32_bf16 v[98:101], v[202:205], v[218:221], v[98:101]
	v_mfma_f32_16x16x32_bf16 v[86:89], v[194:197], v[226:229], v[86:89]
	v_mfma_f32_16x16x32_bf16 v[82:85], v[202:205], v[226:229], v[82:85]
	v_mfma_f32_16x16x32_bf16 v[70:73], v[194:197], v[238:241], v[70:73]
	v_mfma_f32_16x16x32_bf16 v[66:69], v[202:205], v[238:241], v[66:69]
	v_mfma_f32_16x16x32_bf16 v[118:121], v[198:201], v[214:217], v[118:121]
	v_mfma_f32_16x16x32_bf16 v[114:117], v[206:209], v[214:217], v[114:117]
	v_mfma_f32_16x16x32_bf16 v[102:105], v[198:201], v[222:225], v[102:105]
	v_mfma_f32_16x16x32_bf16 v[98:101], v[206:209], v[222:225], v[98:101]
	v_mfma_f32_16x16x32_bf16 v[86:89], v[198:201], v[234:237], v[86:89]
	v_mfma_f32_16x16x32_bf16 v[82:85], v[206:209], v[234:237], v[82:85]
	v_mfma_f32_16x16x32_bf16 v[70:73], v[198:201], v[242:245], v[70:73]
	v_mfma_f32_16x16x32_bf16 v[66:69], v[206:209], v[242:245], v[66:69]
	s_setprio 0
	s_barrier
	s_add_i32 s64, s64, s79
	v_lshl_add_u64 v[230:231], s[58:59], 0, v[136:137]
	s_mov_b32 m0, s64
	ds_read_b128 v[210:213], v188 offset:16384
	ds_read_b128 v[214:217], v188 offset:17408
	ds_read_b128 v[218:221], v188 offset:18432
	ds_read_b128 v[222:225], v188 offset:19456
	ds_read_b128 v[226:229], v188 offset:20480
	ds_read_b128 v[234:237], v188 offset:21504
	ds_read_b128 v[238:241], v188 offset:22528
	ds_read_b128 v[242:245], v188 offset:23552
	global_load_lds_dwordx4 v[230:231], off
	s_add_i32 m0, s64, 0x2000
	s_add_u32 s64, s58, 0x40000
	v_lshl_add_u64 v[246:247], s[58:59], 0, v[140:141]
	s_addc_u32 s65, s59, 0
	s_add_i32 s66, s66, s79
	global_load_lds_dwordx4 v[246:247], off
	s_mov_b32 m0, s66
	v_lshl_add_u64 v[250:251], s[60:61], 0, v[138:139]
	global_load_lds_dwordx4 v136, s[64:65]
	s_add_i32 m0, s66, 0x2000
	s_nop 0
	global_load_lds_dwordx4 v140, s[64:65]
	v_lshl_add_u64 v[248:249], s[60:61], 0, v[134:135]
	s_mov_b32 m0, s80
	s_nop 0
	global_load_lds_dwordx4 v[248:249], off
	s_mov_b32 m0, s81
	s_nop 0
	global_load_lds_dwordx4 v[250:251], off
	s_waitcnt vmcnt(8)
	s_waitcnt lgkmcnt(0)
	s_barrier
	s_setprio 1
	s_waitcnt lgkmcnt(0)
	v_mfma_f32_16x16x32_bf16 v[62:65], v[148:151], v[210:213], v[62:65]
	v_mfma_f32_16x16x32_bf16 v[58:61], v[156:159], v[210:213], v[58:61]
	v_mfma_f32_16x16x32_bf16 v[46:49], v[148:151], v[218:221], v[46:49]
	v_mfma_f32_16x16x32_bf16 v[42:45], v[156:159], v[218:221], v[42:45]
	v_mfma_f32_16x16x32_bf16 v[30:33], v[148:151], v[226:229], v[30:33]
	v_mfma_f32_16x16x32_bf16 v[26:29], v[156:159], v[226:229], v[26:29]
	v_mfma_f32_16x16x32_bf16 v[14:17], v[148:151], v[238:241], v[14:17]
	v_mfma_f32_16x16x32_bf16 v[10:13], v[156:159], v[238:241], v[10:13]
	v_mfma_f32_16x16x32_bf16 v[62:65], v[152:155], v[214:217], v[62:65]
	v_mfma_f32_16x16x32_bf16 v[58:61], v[190:193], v[214:217], v[58:61]
	v_mfma_f32_16x16x32_bf16 v[46:49], v[152:155], v[222:225], v[46:49]
	v_mfma_f32_16x16x32_bf16 v[42:45], v[190:193], v[222:225], v[42:45]
	v_mfma_f32_16x16x32_bf16 v[30:33], v[152:155], v[234:237], v[30:33]
	v_mfma_f32_16x16x32_bf16 v[26:29], v[190:193], v[234:237], v[26:29]
	v_mfma_f32_16x16x32_bf16 v[14:17], v[152:155], v[242:245], v[14:17]
	v_mfma_f32_16x16x32_bf16 v[10:13], v[190:193], v[242:245], v[10:13]
	s_setprio 0
	s_setprio 1
	v_mfma_f32_16x16x32_bf16 v[54:57], v[194:197], v[210:213], v[54:57]
	v_mfma_f32_16x16x32_bf16 v[50:53], v[202:205], v[210:213], v[50:53]
	v_mfma_f32_16x16x32_bf16 v[38:41], v[194:197], v[218:221], v[38:41]
	v_mfma_f32_16x16x32_bf16 v[34:37], v[202:205], v[218:221], v[34:37]
	v_mfma_f32_16x16x32_bf16 v[22:25], v[194:197], v[226:229], v[22:25]
	v_mfma_f32_16x16x32_bf16 v[18:21], v[202:205], v[226:229], v[18:21]
	v_mfma_f32_16x16x32_bf16 v[6:9], v[194:197], v[238:241], v[6:9]
	v_mfma_f32_16x16x32_bf16 v[2:5], v[202:205], v[238:241], v[2:5]
	v_mfma_f32_16x16x32_bf16 v[54:57], v[198:201], v[214:217], v[54:57]
	v_mfma_f32_16x16x32_bf16 v[50:53], v[206:209], v[214:217], v[50:53]
	v_mfma_f32_16x16x32_bf16 v[38:41], v[198:201], v[222:225], v[38:41]
	v_mfma_f32_16x16x32_bf16 v[34:37], v[206:209], v[222:225], v[34:37]
	v_mfma_f32_16x16x32_bf16 v[22:25], v[198:201], v[234:237], v[22:25]
	v_mfma_f32_16x16x32_bf16 v[18:21], v[206:209], v[234:237], v[18:21]
	v_mfma_f32_16x16x32_bf16 v[6:9], v[198:201], v[242:245], v[6:9]
	v_mfma_f32_16x16x32_bf16 v[2:5], v[206:209], v[242:245], v[2:5]
	s_setprio 0
	s_barrier
	s_add_i32 s64, 0, 0x18000
	v_add_u32_e32 v0, s64, v169
	s_add_i32 s65, 0, 0x1c000
	ds_read_b128 v[148:151], v0
	ds_read_b128 v[152:155], v0 offset:1024
	ds_read_b128 v[156:159], v0 offset:2048
	ds_read_b128 v[190:193], v0 offset:3072
	v_add_u32_e32 v0, s65, v169
	ds_read_b128 v[194:197], v0
	ds_read_b128 v[198:201], v0 offset:1024
	ds_read_b128 v[202:205], v0 offset:2048
	ds_read_b128 v[206:209], v0 offset:3072
	s_add_u32 s60, s60, 0x40000
	s_addc_u32 s61, s61, 0
	s_mov_b32 m0, s82
	ds_read_b128 v[210:213], v188 offset:32768
	ds_read_b128 v[214:217], v188 offset:33792
	ds_read_b128 v[218:221], v188 offset:34816
	ds_read_b128 v[222:225], v188 offset:35840
	ds_read_b128 v[226:229], v188 offset:36864
	ds_read_b128 v[234:237], v188 offset:37888
	ds_read_b128 v[238:241], v188 offset:38912
	ds_read_b128 v[242:245], v188 offset:39936
	global_load_lds_dwordx4 v134, s[60:61]
	s_mov_b32 m0, s83
	s_nop 0
	global_load_lds_dwordx4 v138, s[60:61]
	s_waitcnt vmcnt(8)
	s_waitcnt lgkmcnt(0)
	s_barrier
	s_setprio 1
	s_waitcnt lgkmcnt(0)
	v_mfma_f32_16x16x32_bf16 v[126:129], v[148:151], v[210:213], v[126:129]
	v_mfma_f32_16x16x32_bf16 v[122:125], v[156:159], v[210:213], v[122:125]
	v_mfma_f32_16x16x32_bf16 v[110:113], v[148:151], v[218:221], v[110:113]
	v_mfma_f32_16x16x32_bf16 v[106:109], v[156:159], v[218:221], v[106:109]
	v_mfma_f32_16x16x32_bf16 v[94:97], v[148:151], v[226:229], v[94:97]
	v_mfma_f32_16x16x32_bf16 v[90:93], v[156:159], v[226:229], v[90:93]
	v_mfma_f32_16x16x32_bf16 v[78:81], v[148:151], v[238:241], v[78:81]
	v_mfma_f32_16x16x32_bf16 v[74:77], v[156:159], v[238:241], v[74:77]
	v_mfma_f32_16x16x32_bf16 v[126:129], v[152:155], v[214:217], v[126:129]
	v_mfma_f32_16x16x32_bf16 v[122:125], v[190:193], v[214:217], v[122:125]
	v_mfma_f32_16x16x32_bf16 v[110:113], v[152:155], v[222:225], v[110:113]
	v_mfma_f32_16x16x32_bf16 v[106:109], v[190:193], v[222:225], v[106:109]
	v_mfma_f32_16x16x32_bf16 v[94:97], v[152:155], v[234:237], v[94:97]
	v_mfma_f32_16x16x32_bf16 v[90:93], v[190:193], v[234:237], v[90:93]
	v_mfma_f32_16x16x32_bf16 v[78:81], v[152:155], v[242:245], v[78:81]
	v_mfma_f32_16x16x32_bf16 v[74:77], v[190:193], v[242:245], v[74:77]
	s_setprio 0
	s_setprio 1
	v_mfma_f32_16x16x32_bf16 v[118:121], v[194:197], v[210:213], v[118:121]
	v_mfma_f32_16x16x32_bf16 v[114:117], v[202:205], v[210:213], v[114:117]
	v_mfma_f32_16x16x32_bf16 v[102:105], v[194:197], v[218:221], v[102:105]
	v_mfma_f32_16x16x32_bf16 v[98:101], v[202:205], v[218:221], v[98:101]
	v_mfma_f32_16x16x32_bf16 v[86:89], v[194:197], v[226:229], v[86:89]
	v_mfma_f32_16x16x32_bf16 v[82:85], v[202:205], v[226:229], v[82:85]
	v_mfma_f32_16x16x32_bf16 v[70:73], v[194:197], v[238:241], v[70:73]
	v_mfma_f32_16x16x32_bf16 v[66:69], v[202:205], v[238:241], v[66:69]
	v_mfma_f32_16x16x32_bf16 v[118:121], v[198:201], v[214:217], v[118:121]
	v_mfma_f32_16x16x32_bf16 v[114:117], v[206:209], v[214:217], v[114:117]
	v_mfma_f32_16x16x32_bf16 v[102:105], v[198:201], v[222:225], v[102:105]
	v_mfma_f32_16x16x32_bf16 v[98:101], v[206:209], v[222:225], v[98:101]
	v_mfma_f32_16x16x32_bf16 v[86:89], v[198:201], v[234:237], v[86:89]
	v_mfma_f32_16x16x32_bf16 v[82:85], v[206:209], v[234:237], v[82:85]
	v_mfma_f32_16x16x32_bf16 v[70:73], v[198:201], v[242:245], v[70:73]
	v_mfma_f32_16x16x32_bf16 v[66:69], v[206:209], v[242:245], v[66:69]
	s_setprio 0
	s_barrier
	s_add_i32 s60, s64, s79
	v_lshl_add_u64 v[230:231], v[230:231], 0, s[16:17]
	s_mov_b32 m0, s60
	ds_read_b128 v[210:213], v188 offset:49152
	ds_read_b128 v[214:217], v188 offset:50176
	ds_read_b128 v[218:221], v188 offset:51200
	ds_read_b128 v[222:225], v188 offset:52224
	ds_read_b128 v[226:229], v188 offset:53248
	ds_read_b128 v[234:237], v188 offset:54272
	ds_read_b128 v[238:241], v188 offset:55296
	ds_read_b128 v[242:245], v188 offset:56320
	global_load_lds_dwordx4 v[230:231], off
	s_add_i32 m0, s60, 0x2000
	s_add_u32 s58, s58, 0x40080
	v_lshl_add_u64 v[230:231], v[246:247], 0, s[16:17]
	s_addc_u32 s59, s59, 0
	s_add_i32 s60, s65, s79
	global_load_lds_dwordx4 v[230:231], off
	s_mov_b32 m0, s60
	s_nop 0
	global_load_lds_dwordx4 v136, s[58:59]
	s_add_i32 m0, s60, 0x2000
	s_nop 0
	global_load_lds_dwordx4 v140, s[58:59]
	v_lshl_add_u64 v[230:231], v[248:249], 0, s[16:17]
	s_mov_b32 m0, s86
	s_nop 0
	global_load_lds_dwordx4 v[230:231], off
	v_lshl_add_u64 v[230:231], v[250:251], 0, s[16:17]
	s_mov_b32 m0, s87
	s_nop 0
	global_load_lds_dwordx4 v[230:231], off
	s_waitcnt vmcnt(8)
	s_waitcnt lgkmcnt(0)
	s_barrier
	s_setprio 1
	s_waitcnt lgkmcnt(0)
	v_mfma_f32_16x16x32_bf16 v[62:65], v[148:151], v[210:213], v[62:65]
	v_mfma_f32_16x16x32_bf16 v[58:61], v[156:159], v[210:213], v[58:61]
	v_mfma_f32_16x16x32_bf16 v[46:49], v[148:151], v[218:221], v[46:49]
	v_mfma_f32_16x16x32_bf16 v[42:45], v[156:159], v[218:221], v[42:45]
	v_mfma_f32_16x16x32_bf16 v[30:33], v[148:151], v[226:229], v[30:33]
	v_mfma_f32_16x16x32_bf16 v[26:29], v[156:159], v[226:229], v[26:29]
	v_mfma_f32_16x16x32_bf16 v[14:17], v[148:151], v[238:241], v[14:17]
	v_mfma_f32_16x16x32_bf16 v[10:13], v[156:159], v[238:241], v[10:13]
	v_mfma_f32_16x16x32_bf16 v[62:65], v[152:155], v[214:217], v[62:65]
	v_mfma_f32_16x16x32_bf16 v[58:61], v[190:193], v[214:217], v[58:61]
	v_mfma_f32_16x16x32_bf16 v[46:49], v[152:155], v[222:225], v[46:49]
	v_mfma_f32_16x16x32_bf16 v[42:45], v[190:193], v[222:225], v[42:45]
	v_mfma_f32_16x16x32_bf16 v[30:33], v[152:155], v[234:237], v[30:33]
	v_mfma_f32_16x16x32_bf16 v[26:29], v[190:193], v[234:237], v[26:29]
	v_mfma_f32_16x16x32_bf16 v[14:17], v[152:155], v[242:245], v[14:17]
	v_mfma_f32_16x16x32_bf16 v[10:13], v[190:193], v[242:245], v[10:13]
	s_setprio 0
	s_setprio 1
	v_mfma_f32_16x16x32_bf16 v[54:57], v[194:197], v[210:213], v[54:57]
	v_mfma_f32_16x16x32_bf16 v[50:53], v[202:205], v[210:213], v[50:53]
	v_mfma_f32_16x16x32_bf16 v[38:41], v[194:197], v[218:221], v[38:41]
	v_mfma_f32_16x16x32_bf16 v[34:37], v[202:205], v[218:221], v[34:37]
	v_mfma_f32_16x16x32_bf16 v[22:25], v[194:197], v[226:229], v[22:25]
	v_mfma_f32_16x16x32_bf16 v[18:21], v[202:205], v[226:229], v[18:21]
	v_mfma_f32_16x16x32_bf16 v[6:9], v[194:197], v[238:241], v[6:9]
	v_mfma_f32_16x16x32_bf16 v[2:5], v[202:205], v[238:241], v[2:5]
	v_mfma_f32_16x16x32_bf16 v[54:57], v[198:201], v[214:217], v[54:57]
	v_mfma_f32_16x16x32_bf16 v[50:53], v[206:209], v[214:217], v[50:53]
	v_mfma_f32_16x16x32_bf16 v[38:41], v[198:201], v[222:225], v[38:41]
	v_mfma_f32_16x16x32_bf16 v[34:37], v[206:209], v[222:225], v[34:37]
	v_mfma_f32_16x16x32_bf16 v[22:25], v[198:201], v[234:237], v[22:25]
	v_mfma_f32_16x16x32_bf16 v[18:21], v[206:209], v[234:237], v[18:21]
	v_mfma_f32_16x16x32_bf16 v[6:9], v[198:201], v[242:245], v[6:9]
	v_mfma_f32_16x16x32_bf16 v[2:5], v[206:209], v[242:245], v[2:5]
	s_setprio 0
	s_barrier
	s_add_i32 s63, s63, 2
	s_add_u32 s48, s48, 0x100
	s_addc_u32 s49, s49, 0
	s_add_u32 s57, s57, 0x100
	s_addc_u32 s62, s62, 0
	s_cmp_gt_u32 s63, 13
	s_cbranch_scc0 .LBB0_3227
	s_and_b64 vcc, exec, s[36:37]
	s_cbranch_vccz .LBB0_3231
	s_barrier
	s_andn2_b64 vcc, exec, s[20:21]
	s_cbranch_vccz .LBB0_3232

.LBB0_3524:
	s_cmp_ge_u32 s67, s33
	v_and_b32_e32 v18, 15, v1
	s_cselect_b64 s[30:31], -1, 0
	s_add_u32 s28, s28, 0x7700000
	v_or_b32_e32 v221, s34, v18
	s_addc_u32 s29, s29, 0
	v_lshlrev_b32_e32 v19, 6, v221
	v_and_b32_e32 v20, 48, v1
	s_movk_i32 s34, 0x3c0
	v_lshlrev_b32_e32 v21, 2, v221
	s_add_i32 s80, s49, 0x18000
	v_and_or_b32 v19, v19, s34, v20
	s_lshl_b32 s34, s37, 13
	v_and_b32_e32 v21, 32, v21
	v_lshlrev_b32_e32 v1, 2, v1
	v_lshl_add_u64 v[10:11], v[10:11], 0, s[18:19]
	s_mov_b32 m0, s80
	s_add_i32 s81, s49, 0x1a000
	s_or_b64 s[30:31], s[30:31], s[16:17]
	v_bitop3_b32 v19, v19, s34, v21 bitop3:0xde
	s_lshl_b32 s79, s36, 5
	v_lshl_or_b32 v20, v18, 6, v20
	s_lshl_b32 s34, s36, 12
	v_and_b32_e32 v1, 32, v1
	s_waitcnt vmcnt(2)
	s_barrier
	global_load_lds_dwordx4 v[10:11], off
	v_lshl_add_u64 v[8:9], v[8:9], 0, s[18:19]
	s_mov_b32 m0, s81
	s_add_i32 s82, s49, 0x8000
	s_add_i32 s83, s49, 0xa000
	v_bitop3_b32 v1, s34, v20, v1 bitop3:0xf6
	global_load_lds_dwordx4 v[8:9], off
	v_lshl_add_u64 v[4:5], v[4:5], 0, s[18:19]
	s_mov_b32 m0, s82
	s_add_u32 s34, s4, 0x20080
	global_load_lds_dwordx4 v[4:5], off
	v_lshl_add_u64 v[4:5], v[6:7], 0, s[18:19]
	s_mov_b32 m0, s83
	s_addc_u32 s35, s5, 0
	s_add_i32 s84, s49, 0x1c000
	global_load_lds_dwordx4 v[4:5], off
	s_mov_b32 m0, s84
	s_add_i32 s85, s49, 0x1e000
	global_load_lds_dwordx4 v200, s[34:35]
	v_lshl_add_u64 v[4:5], s[34:35], 0, v[204:205]
	s_mov_b32 m0, s85
	s_cmpk_lt_u32 s10, 0x100
	global_load_lds_dwordx4 v[4:5], off
	s_cselect_b64 s[34:35], -1, 0
	s_lshl_b32 s10, s37, 11
	s_add_i32 s86, s10, 0
	s_lshl_b32 s10, s36, 7
	s_add_i32 s10, s10, 0
	v_lshrrev_b32_e32 v3, 4, v3
	s_add_i32 s10, s10, 0x23000
	v_lshl_add_u32 v229, v3, 5, s10
	s_ashr_i32 s10, s68, 1
	s_add_i32 s10, s12, s10
	s_ashr_i32 s36, s10, 31
	s_lshr_b32 s36, s36, 29
	s_add_i32 s36, s10, s36
	s_ashr_i32 s37, s36, 3
	s_and_b32 s36, s36, -8
	s_and_b32 s88, s68, 1
	s_add_i32 s86, s86, 0x21000
	s_ashr_i32 s87, s68, 31
	s_sub_i32 s10, s10, s36
	s_add_i32 s88, s88, 1
	s_cmp_lt_i32 s10, 0
	s_cselect_b32 s36, s62, 0xb0
	s_mul_i32 s10, s36, s10
	s_add_i32 s36, s10, s37
	s_mul_hi_i32 s10, s36, 0x2e8ba2e9
	s_lshr_b32 s37, s10, 31
	s_ashr_i32 s10, s10, 5
	s_add_i32 s37, s10, s37
	s_lshl_b32 s38, s37, 3
	s_sub_i32 s10, 64, s38
	s_min_i32 s39, s10, 8
	s_abs_i32 s40, s39
	v_cvt_f32_u32_e32 v4, s40
	v_lshlrev_b32_e32 v206, 3, v3
	v_mov_b32_e32 v3, v0
	v_lshl_add_u64 v[208:209], s[0:1], 0, v[2:3]
	v_rcp_iflag_f32_e32 v2, v4
	s_mulk_i32 s37, 0xb0
	s_sub_i32 s0, s36, s37
	s_sub_i32 s37, 0, s40
	v_mul_f32_e32 v2, 0x4f7ffffe, v2
	v_cvt_u32_f32_e32 v2, v2
	s_abs_i32 s36, s0
	s_xor_b32 s1, s0, s39
	s_ashr_i32 s1, s1, 31
	v_readfirstlane_b32 s41, v2
	s_mul_i32 s37, s37, s41
	s_mul_hi_u32 s37, s41, s37
	s_add_i32 s41, s41, s37
	s_mul_hi_u32 s37, s36, s41
	s_mul_i32 s41, s37, s40
	s_sub_i32 s36, s36, s41
	s_add_i32 s41, s37, 1
	s_sub_i32 s42, s36, s40
	s_cmp_ge_u32 s36, s40
	s_cselect_b32 s37, s41, s37
	v_lshlrev_b32_e32 v2, 13, v12
	s_cselect_b32 s36, s42, s36
	s_add_i32 s41, s37, 1
	v_and_b32_e32 v2, 0xffffc000, v2
	s_cmp_ge_u32 s36, s40
	v_lshl_add_u32 v2, v13, 10, v2
	v_and_b32_e32 v3, 1, v12
	s_cselect_b32 s36, s41, s37
	v_lshl_or_b32 v2, v3, 6, v2
	s_xor_b32 s36, s36, s1
	v_lshl_add_u32 v210, v14, 1, v2
	v_lshlrev_b32_e32 v2, 13, v15
	s_sub_i32 s89, s36, s1
	v_and_b32_e32 v2, 0xffffc000, v2
	s_waitcnt vmcnt(6)
	s_mul_i32 s1, s89, s39
	v_lshl_add_u32 v2, v16, 10, v2
	v_and_b32_e32 v3, 1, v15
	s_sub_i32 s90, s0, s1
	v_lshl_or_b32 v2, v3, 6, v2
	v_or_b32_e32 v222, 16, v221
	v_or_b32_e32 v223, 32, v221
	v_or_b32_e32 v224, 48, v221
	v_add_u32_e32 v225, 0x80, v221
	v_add_u32_e32 v226, 0x90, v221
	v_add_u32_e32 v227, 0xa0, v221
	v_add_u32_e32 v228, 0xb0, v221
	s_mov_b32 s10, 0
	s_add_i32 s90, s90, s38
	v_lshl_add_u32 v230, v18, 4, s86
	v_mov_b32_e32 v211, v0
	v_lshl_add_u32 v212, v17, 1, v2
	v_mov_b32_e32 v213, v0
	v_add_u32_e32 v231, 0, v1
	v_add_u32_e32 v233, 0, v19
	s_barrier
	s_branch .LBB0_3527

.LBB0_3538:
	s_add_i32 m0, s49, 0xc000
	s_and_b64 vcc, exec, s[6:7]
	global_load_lds_dwordx4 v210, s[54:55]
	s_add_i32 m0, s49, 0xe000
	s_nop 0
	global_load_lds_dwordx4 v212, s[54:55]
	s_waitcnt vmcnt(8)
	s_waitcnt lgkmcnt(0)
	s_barrier
	s_cbranch_vccnz .LBB0_3540
	s_setprio 1
	s_waitcnt lgkmcnt(0)
	v_mfma_i32_16x16x64_i8 v[176:179], v[180:183], v[4:7], v[176:179]
	v_mfma_i32_16x16x64_i8 v[168:171], v[188:191], v[4:7], v[168:171]
	v_mfma_i32_16x16x64_i8 v[160:163], v[180:183], v[12:15], v[160:163]
	v_mfma_i32_16x16x64_i8 v[152:155], v[188:191], v[12:15], v[152:155]
	v_mfma_i32_16x16x64_i8 v[144:147], v[180:183], v[20:23], v[144:147]
	v_mfma_i32_16x16x64_i8 v[136:139], v[188:191], v[20:23], v[136:139]
	v_mfma_i32_16x16x64_i8 v[120:123], v[180:183], v[28:31], v[120:123]
	v_mfma_i32_16x16x64_i8 v[104:107], v[188:191], v[28:31], v[104:107]
	v_mfma_i32_16x16x64_i8 v[176:179], v[184:187], v[8:11], v[176:179]
	v_mfma_i32_16x16x64_i8 v[168:171], v[192:195], v[8:11], v[168:171]
	v_mfma_i32_16x16x64_i8 v[160:163], v[184:187], v[16:19], v[160:163]
	v_mfma_i32_16x16x64_i8 v[152:155], v[192:195], v[16:19], v[152:155]
	v_mfma_i32_16x16x64_i8 v[144:147], v[184:187], v[24:27], v[144:147]
	v_mfma_i32_16x16x64_i8 v[136:139], v[192:195], v[24:27], v[136:139]
	v_mfma_i32_16x16x64_i8 v[120:123], v[184:187], v[32:35], v[120:123]
	v_mfma_i32_16x16x64_i8 v[104:107], v[192:195], v[32:35], v[104:107]
	s_setprio 0
	s_setprio 1
	v_mfma_i32_16x16x64_i8 v[172:175], v[108:111], v[4:7], v[172:175]
	v_mfma_i32_16x16x64_i8 v[164:167], v[124:127], v[4:7], v[164:167]
	v_mfma_i32_16x16x64_i8 v[156:159], v[108:111], v[12:15], v[156:159]
	v_mfma_i32_16x16x64_i8 v[148:151], v[124:127], v[12:15], v[148:151]
	v_mfma_i32_16x16x64_i8 v[140:143], v[108:111], v[20:23], v[140:143]
	v_mfma_i32_16x16x64_i8 v[132:135], v[124:127], v[20:23], v[132:135]
	v_mfma_i32_16x16x64_i8 v[116:119], v[108:111], v[28:31], v[116:119]
	v_mfma_i32_16x16x64_i8 v[100:103], v[124:127], v[28:31], v[100:103]
	v_mfma_i32_16x16x64_i8 v[172:175], v[112:115], v[8:11], v[172:175]
	v_mfma_i32_16x16x64_i8 v[164:167], v[128:131], v[8:11], v[164:167]
	v_mfma_i32_16x16x64_i8 v[156:159], v[112:115], v[16:19], v[156:159]
	v_mfma_i32_16x16x64_i8 v[148:151], v[128:131], v[16:19], v[148:151]
	v_mfma_i32_16x16x64_i8 v[140:143], v[112:115], v[24:27], v[140:143]
	v_mfma_i32_16x16x64_i8 v[132:135], v[128:131], v[24:27], v[132:135]
	v_mfma_i32_16x16x64_i8 v[116:119], v[112:115], v[32:35], v[116:119]
	v_mfma_i32_16x16x64_i8 v[100:103], v[128:131], v[32:35], v[100:103]
	s_setprio 0

.LBB0_3546:
	s_add_u32 s58, s58, 0x20000
	s_addc_u32 s59, s59, 0
	s_mov_b32 m0, s77
	s_nop 0
	global_load_lds_dwordx4 v198, s[58:59]
	s_mov_b32 m0, s78
	s_and_b64 vcc, exec, s[6:7]
	global_load_lds_dwordx4 v202, s[58:59]
	s_waitcnt vmcnt(8)
	s_waitcnt lgkmcnt(0)
	s_barrier
	s_cbranch_vccnz .LBB0_3548
	s_setprio 1
	s_waitcnt lgkmcnt(0)
	v_mfma_i32_16x16x64_i8 v[176:179], v[180:183], v[4:7], v[176:179]
	v_mfma_i32_16x16x64_i8 v[168:171], v[188:191], v[4:7], v[168:171]
	v_mfma_i32_16x16x64_i8 v[160:163], v[180:183], v[12:15], v[160:163]
	v_mfma_i32_16x16x64_i8 v[152:155], v[188:191], v[12:15], v[152:155]
	v_mfma_i32_16x16x64_i8 v[144:147], v[180:183], v[20:23], v[144:147]
	v_mfma_i32_16x16x64_i8 v[136:139], v[188:191], v[20:23], v[136:139]
	v_mfma_i32_16x16x64_i8 v[120:123], v[180:183], v[28:31], v[120:123]
	v_mfma_i32_16x16x64_i8 v[104:107], v[188:191], v[28:31], v[104:107]
	v_mfma_i32_16x16x64_i8 v[176:179], v[184:187], v[8:11], v[176:179]
	v_mfma_i32_16x16x64_i8 v[168:171], v[192:195], v[8:11], v[168:171]
	v_mfma_i32_16x16x64_i8 v[160:163], v[184:187], v[16:19], v[160:163]
	v_mfma_i32_16x16x64_i8 v[152:155], v[192:195], v[16:19], v[152:155]
	v_mfma_i32_16x16x64_i8 v[144:147], v[184:187], v[24:27], v[144:147]
	v_mfma_i32_16x16x64_i8 v[136:139], v[192:195], v[24:27], v[136:139]
	v_mfma_i32_16x16x64_i8 v[120:123], v[184:187], v[32:35], v[120:123]
	v_mfma_i32_16x16x64_i8 v[104:107], v[192:195], v[32:35], v[104:107]
	s_setprio 0
	s_setprio 1
	v_mfma_i32_16x16x64_i8 v[172:175], v[108:111], v[4:7], v[172:175]
	v_mfma_i32_16x16x64_i8 v[164:167], v[124:127], v[4:7], v[164:167]
	v_mfma_i32_16x16x64_i8 v[156:159], v[108:111], v[12:15], v[156:159]
	v_mfma_i32_16x16x64_i8 v[148:151], v[124:127], v[12:15], v[148:151]
	v_mfma_i32_16x16x64_i8 v[140:143], v[108:111], v[20:23], v[140:143]
	v_mfma_i32_16x16x64_i8 v[132:135], v[124:127], v[20:23], v[132:135]
	v_mfma_i32_16x16x64_i8 v[116:119], v[108:111], v[28:31], v[116:119]
	v_mfma_i32_16x16x64_i8 v[100:103], v[124:127], v[28:31], v[100:103]
	v_mfma_i32_16x16x64_i8 v[172:175], v[112:115], v[8:11], v[172:175]
	v_mfma_i32_16x16x64_i8 v[164:167], v[128:131], v[8:11], v[164:167]
	v_mfma_i32_16x16x64_i8 v[156:159], v[112:115], v[16:19], v[156:159]
	v_mfma_i32_16x16x64_i8 v[148:151], v[128:131], v[16:19], v[148:151]
	v_mfma_i32_16x16x64_i8 v[140:143], v[112:115], v[24:27], v[140:143]
	v_mfma_i32_16x16x64_i8 v[132:135], v[128:131], v[24:27], v[132:135]
	v_mfma_i32_16x16x64_i8 v[116:119], v[112:115], v[32:35], v[116:119]
	v_mfma_i32_16x16x64_i8 v[100:103], v[128:131], v[32:35], v[100:103]
	s_setprio 0

.LBB0_3550:
	s_mov_b32 m0, s80
	v_lshl_add_u64 v[2:3], v[2:3], 0, s[18:19]
	s_add_u32 s6, s56, 0x20080
	global_load_lds_dwordx4 v[2:3], off
	v_lshl_add_u64 v[2:3], v[214:215], 0, s[18:19]
	s_mov_b32 m0, s81
	s_addc_u32 s7, s57, 0
	global_load_lds_dwordx4 v[2:3], off
	s_mov_b32 m0, s84
	s_and_b64 vcc, exec, s[4:5]
	global_load_lds_dwordx4 v200, s[6:7]
	s_mov_b32 m0, s85
	s_nop 0
	global_load_lds_dwordx4 v204, s[6:7]
	v_lshl_add_u64 v[2:3], v[216:217], 0, s[18:19]
	s_mov_b32 m0, s82
	s_nop 0
	global_load_lds_dwordx4 v[2:3], off
	v_lshl_add_u64 v[2:3], v[218:219], 0, s[18:19]
	s_mov_b32 m0, s83
	s_nop 0
	global_load_lds_dwordx4 v[2:3], off
	s_waitcnt vmcnt(8)
	s_waitcnt lgkmcnt(0)
	s_barrier
	s_cbranch_vccnz .LBB0_3535
	s_setprio 1
	s_waitcnt lgkmcnt(0)
	v_mfma_i32_16x16x64_i8 v[96:99], v[180:183], v[4:7], v[96:99]
	v_mfma_i32_16x16x64_i8 v[88:91], v[188:191], v[4:7], v[88:91]
	v_mfma_i32_16x16x64_i8 v[80:83], v[180:183], v[12:15], v[80:83]
	v_mfma_i32_16x16x64_i8 v[72:75], v[188:191], v[12:15], v[72:75]
	v_mfma_i32_16x16x64_i8 v[64:67], v[180:183], v[20:23], v[64:67]
	v_mfma_i32_16x16x64_i8 v[56:59], v[188:191], v[20:23], v[56:59]
	v_mfma_i32_16x16x64_i8 v[48:51], v[180:183], v[28:31], v[48:51]
	v_mfma_i32_16x16x64_i8 v[40:43], v[188:191], v[28:31], v[40:43]
	v_mfma_i32_16x16x64_i8 v[96:99], v[184:187], v[8:11], v[96:99]
	v_mfma_i32_16x16x64_i8 v[88:91], v[192:195], v[8:11], v[88:91]
	v_mfma_i32_16x16x64_i8 v[80:83], v[184:187], v[16:19], v[80:83]
	v_mfma_i32_16x16x64_i8 v[72:75], v[192:195], v[16:19], v[72:75]
	v_mfma_i32_16x16x64_i8 v[64:67], v[184:187], v[24:27], v[64:67]
	v_mfma_i32_16x16x64_i8 v[56:59], v[192:195], v[24:27], v[56:59]
	v_mfma_i32_16x16x64_i8 v[48:51], v[184:187], v[32:35], v[48:51]
	v_mfma_i32_16x16x64_i8 v[40:43], v[192:195], v[32:35], v[40:43]
	s_setprio 0
	s_setprio 1
	v_mfma_i32_16x16x64_i8 v[92:95], v[108:111], v[4:7], v[92:95]
	v_mfma_i32_16x16x64_i8 v[84:87], v[124:127], v[4:7], v[84:87]
	v_mfma_i32_16x16x64_i8 v[76:79], v[108:111], v[12:15], v[76:79]
	v_mfma_i32_16x16x64_i8 v[68:71], v[124:127], v[12:15], v[68:71]
	v_mfma_i32_16x16x64_i8 v[60:63], v[108:111], v[20:23], v[60:63]
	v_mfma_i32_16x16x64_i8 v[52:55], v[124:127], v[20:23], v[52:55]
	v_mfma_i32_16x16x64_i8 v[44:47], v[108:111], v[28:31], v[44:47]
	v_mfma_i32_16x16x64_i8 v[36:39], v[124:127], v[28:31], v[36:39]
	v_mfma_i32_16x16x64_i8 v[92:95], v[112:115], v[8:11], v[92:95]
	v_mfma_i32_16x16x64_i8 v[84:87], v[128:131], v[8:11], v[84:87]
	v_mfma_i32_16x16x64_i8 v[76:79], v[112:115], v[16:19], v[76:79]
	v_mfma_i32_16x16x64_i8 v[68:71], v[128:131], v[16:19], v[68:71]
	v_mfma_i32_16x16x64_i8 v[60:63], v[112:115], v[24:27], v[60:63]
	v_mfma_i32_16x16x64_i8 v[52:55], v[128:131], v[24:27], v[52:55]
	v_mfma_i32_16x16x64_i8 v[44:47], v[112:115], v[32:35], v[44:47]
	v_mfma_i32_16x16x64_i8 v[36:39], v[128:131], v[32:35], v[36:39]
	s_setprio 0
	s_branch .LBB0_3535

.LBB0_3680:
	s_cmp_ge_u32 s27, s28
	s_cselect_b64 s[12:13], -1, 0
	s_add_u32 s14, s4, 0x2700000
	s_addc_u32 s15, s5, 0
	s_lshl_b32 s4, s17, 5
	s_and_b32 s19, s4, 0x60
	s_add_i32 m0, s41, 0x18000
	v_lshl_add_u64 v[6:7], v[6:7], 0, s[6:7]
	s_lshl_b32 s18, s3, 13
	s_lshl_b32 s17, s19, 7
	s_waitcnt vmcnt(2)
	s_barrier
	global_load_lds_dwordx4 v[6:7], off
	v_lshl_add_u64 v[4:5], v[4:5], 0, s[6:7]
	s_add_i32 m0, s41, 0x1a000
	s_add_i32 s45, s41, 0x8000
	s_add_i32 s48, s41, 0xa000
	global_load_lds_dwordx4 v[4:5], off
	v_lshl_add_u64 v[0:1], v[0:1], 0, s[6:7]
	s_mov_b32 m0, s45
	s_add_u32 s4, s22, 0xb0080
	global_load_lds_dwordx4 v[0:1], off
	v_lshl_add_u64 v[0:1], v[2:3], 0, s[6:7]
	s_mov_b32 m0, s48
	s_addc_u32 s5, s23, 0
	global_load_lds_dwordx4 v[0:1], off
	s_add_i32 m0, s41, 0x1c000
	s_nop 0
	global_load_lds_dwordx4 v128, s[4:5]
	s_add_i32 m0, s41, 0x1e000
	s_cmpk_lt_u32 s2, 0x100
	global_load_lds_dwordx4 v138, s[4:5]
	v_lshrrev_b32_e32 v1, 1, v8
	v_and_b32_e32 v1, 24, v1
	v_and_b32_e32 v0, 15, v8
	v_lshlrev_b32_e32 v2, 1, v1
	s_waitcnt vmcnt(0)
	v_lshl_or_b32 v150, s3, 6, v0
	v_lshl_or_b32 v0, v0, 6, v2
	v_lshlrev_b32_e32 v2, 2, v8
	v_and_b32_e32 v2, 32, v2
	v_bitop3_b32 v3, v0, s18, v2 bitop3:0xde
	v_bitop3_b32 v151, s17, v0, v2 bitop3:0xf6
	v_or_b32_e32 v140, s19, v1
	v_lshrrev_b32_e32 v1, 1, v9
	v_mul_lo_u32 v0, v10, s31
	v_mad_u64_u32 v[0:1], s[2:3], v1, s33, v[0:1]
	v_and_b32_e32 v1, 1, v9
	v_lshl_or_b32 v0, v1, 6, v0
	v_lshl_add_u32 v142, v11, 1, v0
	v_lshrrev_b32_e32 v1, 1, v12
	v_mul_lo_u32 v0, v13, s31
	v_mad_u64_u32 v[0:1], s[2:3], v1, s33, v[0:1]
	s_waitcnt vmcnt(6)
	v_and_b32_e32 v1, 1, v12
	v_lshl_or_b32 v0, v1, 6, v0
	s_sext_i32_i8 s53, s16
	s_cselect_b64 s[16:17], -1, 0
	v_mov_b32_e32 v143, v129
	v_lshl_add_u32 v144, v14, 1, v0
	v_mov_b32_e32 v145, v129
	s_mov_b32 s49, 0
	v_add_u32_e32 v152, 0, v3
	s_barrier
	s_branch .LBB0_3683

.LBB0_3694:
	s_add_u32 s22, s20, 0xfff50080
	s_addc_u32 s23, s21, -1
	s_add_i32 s57, 0, 0x10000
	s_cmp_eq_u32 s56, 40
	s_cselect_b32 s25, s5, s23
	s_cselect_b32 s24, s4, s22
	v_add_u32_e32 v153, s57, v151
	s_cselect_b32 s23, s19, s55
	s_cselect_b32 s22, s18, s54
	s_add_i32 s60, 0, 0x14000
	ds_read_b128 v[146:149], v153
	ds_read_b128 v[154:157], v153 offset:1024
	ds_read_b128 v[158:161], v153 offset:2048
	ds_read_b128 v[162:165], v153 offset:3072
	v_add_u32_e32 v153, s60, v151
	ds_read_b128 v[166:169], v153
	ds_read_b128 v[170:173], v153 offset:1024
	ds_read_b128 v[174:177], v153 offset:2048
	ds_read_b128 v[178:181], v153 offset:3072
	s_add_i32 m0, s41, 0xc000
	ds_read_b128 v[182:185], v152
	ds_read_b128 v[186:189], v152 offset:1024
	ds_read_b128 v[190:193], v152 offset:2048
	ds_read_b128 v[194:197], v152 offset:3072
	ds_read_b128 v[198:201], v152 offset:4096
	ds_read_b128 v[202:205], v152 offset:5120
	ds_read_b128 v[206:209], v152 offset:6144
	ds_read_b128 v[210:213], v152 offset:7168
	global_load_lds_dwordx4 v142, s[20:21]
	s_add_i32 m0, s41, 0xe000
	s_nop 0
	global_load_lds_dwordx4 v144, s[20:21]
	s_waitcnt vmcnt(8)
	s_waitcnt lgkmcnt(0)
	s_barrier
	s_setprio 1
	s_waitcnt lgkmcnt(0)
	v_mfma_f32_16x16x32_bf16 v[124:127], v[146:149], v[182:185], v[124:127]
	v_mfma_f32_16x16x32_bf16 v[120:123], v[158:161], v[182:185], v[120:123]
	v_mfma_f32_16x16x32_bf16 v[108:111], v[146:149], v[190:193], v[108:111]
	v_mfma_f32_16x16x32_bf16 v[104:107], v[158:161], v[190:193], v[104:107]
	v_mfma_f32_16x16x32_bf16 v[92:95], v[146:149], v[198:201], v[92:95]
	v_mfma_f32_16x16x32_bf16 v[88:91], v[158:161], v[198:201], v[88:91]
	v_mfma_f32_16x16x32_bf16 v[76:79], v[146:149], v[206:209], v[76:79]
	v_mfma_f32_16x16x32_bf16 v[72:75], v[158:161], v[206:209], v[72:75]
	v_mfma_f32_16x16x32_bf16 v[124:127], v[154:157], v[186:189], v[124:127]
	v_mfma_f32_16x16x32_bf16 v[120:123], v[162:165], v[186:189], v[120:123]
	v_mfma_f32_16x16x32_bf16 v[108:111], v[154:157], v[194:197], v[108:111]
	v_mfma_f32_16x16x32_bf16 v[104:107], v[162:165], v[194:197], v[104:107]
	v_mfma_f32_16x16x32_bf16 v[92:95], v[154:157], v[202:205], v[92:95]
	v_mfma_f32_16x16x32_bf16 v[88:91], v[162:165], v[202:205], v[88:91]
	v_mfma_f32_16x16x32_bf16 v[76:79], v[154:157], v[210:213], v[76:79]
	v_mfma_f32_16x16x32_bf16 v[72:75], v[162:165], v[210:213], v[72:75]
	s_setprio 0
	s_setprio 1
	v_mfma_f32_16x16x32_bf16 v[116:119], v[166:169], v[182:185], v[116:119]
	v_mfma_f32_16x16x32_bf16 v[112:115], v[174:177], v[182:185], v[112:115]
	v_mfma_f32_16x16x32_bf16 v[100:103], v[166:169], v[190:193], v[100:103]
	v_mfma_f32_16x16x32_bf16 v[96:99], v[174:177], v[190:193], v[96:99]
	v_mfma_f32_16x16x32_bf16 v[84:87], v[166:169], v[198:201], v[84:87]
	v_mfma_f32_16x16x32_bf16 v[80:83], v[174:177], v[198:201], v[80:83]
	v_mfma_f32_16x16x32_bf16 v[68:71], v[166:169], v[206:209], v[68:71]
	v_mfma_f32_16x16x32_bf16 v[64:67], v[174:177], v[206:209], v[64:67]
	v_mfma_f32_16x16x32_bf16 v[116:119], v[170:173], v[186:189], v[116:119]
	v_mfma_f32_16x16x32_bf16 v[112:115], v[178:181], v[186:189], v[112:115]
	v_mfma_f32_16x16x32_bf16 v[100:103], v[170:173], v[194:197], v[100:103]
	v_mfma_f32_16x16x32_bf16 v[96:99], v[178:181], v[194:197], v[96:99]
	v_mfma_f32_16x16x32_bf16 v[84:87], v[170:173], v[202:205], v[84:87]
	v_mfma_f32_16x16x32_bf16 v[80:83], v[178:181], v[202:205], v[80:83]
	v_mfma_f32_16x16x32_bf16 v[68:71], v[170:173], v[210:213], v[68:71]
	v_mfma_f32_16x16x32_bf16 v[64:67], v[178:181], v[210:213], v[64:67]
	s_setprio 0
	s_barrier
	s_add_i32 s57, s57, s40
	v_lshl_add_u64 v[214:215], s[22:23], 0, v[128:129]
	s_mov_b32 m0, s57
	ds_read_b128 v[182:185], v152 offset:16384
	ds_read_b128 v[186:189], v152 offset:17408
	ds_read_b128 v[190:193], v152 offset:18432
	ds_read_b128 v[194:197], v152 offset:19456
	ds_read_b128 v[198:201], v152 offset:20480
	ds_read_b128 v[202:205], v152 offset:21504
	ds_read_b128 v[206:209], v152 offset:22528
	ds_read_b128 v[210:213], v152 offset:23552
	global_load_lds_dwordx4 v[214:215], off
	s_add_i32 m0, s57, 0x2000
	s_add_u32 s58, s22, 0xb0000
	v_lshl_add_u64 v[216:217], s[22:23], 0, v[138:139]
	s_addc_u32 s59, s23, 0
	s_add_i32 s57, s60, s40
	global_load_lds_dwordx4 v[216:217], off
	s_mov_b32 m0, s57
	v_lshl_add_u64 v[220:221], s[24:25], 0, v[136:137]
	global_load_lds_dwordx4 v128, s[58:59]
	s_add_i32 m0, s57, 0x2000
	s_nop 0
	global_load_lds_dwordx4 v138, s[58:59]
	v_lshl_add_u64 v[218:219], s[24:25], 0, v[134:135]
	s_mov_b32 m0, s41
	s_nop 0
	global_load_lds_dwordx4 v[218:219], off
	s_mov_b32 m0, s42
	s_nop 0
	global_load_lds_dwordx4 v[220:221], off
	s_waitcnt vmcnt(8)
	s_waitcnt lgkmcnt(0)
	s_barrier
	s_setprio 1
	s_waitcnt lgkmcnt(0)
	v_mfma_f32_16x16x32_bf16 v[60:63], v[146:149], v[182:185], v[60:63]
	v_mfma_f32_16x16x32_bf16 v[56:59], v[158:161], v[182:185], v[56:59]
	v_mfma_f32_16x16x32_bf16 v[44:47], v[146:149], v[190:193], v[44:47]
	v_mfma_f32_16x16x32_bf16 v[40:43], v[158:161], v[190:193], v[40:43]
	v_mfma_f32_16x16x32_bf16 v[28:31], v[146:149], v[198:201], v[28:31]
	v_mfma_f32_16x16x32_bf16 v[24:27], v[158:161], v[198:201], v[24:27]
	v_mfma_f32_16x16x32_bf16 v[12:15], v[146:149], v[206:209], v[12:15]
	v_mfma_f32_16x16x32_bf16 v[8:11], v[158:161], v[206:209], v[8:11]
	v_mfma_f32_16x16x32_bf16 v[60:63], v[154:157], v[186:189], v[60:63]
	v_mfma_f32_16x16x32_bf16 v[56:59], v[162:165], v[186:189], v[56:59]
	v_mfma_f32_16x16x32_bf16 v[44:47], v[154:157], v[194:197], v[44:47]
	v_mfma_f32_16x16x32_bf16 v[40:43], v[162:165], v[194:197], v[40:43]
	v_mfma_f32_16x16x32_bf16 v[28:31], v[154:157], v[202:205], v[28:31]
	v_mfma_f32_16x16x32_bf16 v[24:27], v[162:165], v[202:205], v[24:27]
	v_mfma_f32_16x16x32_bf16 v[12:15], v[154:157], v[210:213], v[12:15]
	v_mfma_f32_16x16x32_bf16 v[8:11], v[162:165], v[210:213], v[8:11]
	s_setprio 0
	s_setprio 1
	v_mfma_f32_16x16x32_bf16 v[52:55], v[166:169], v[182:185], v[52:55]
	v_mfma_f32_16x16x32_bf16 v[48:51], v[174:177], v[182:185], v[48:51]
	v_mfma_f32_16x16x32_bf16 v[36:39], v[166:169], v[190:193], v[36:39]
	v_mfma_f32_16x16x32_bf16 v[32:35], v[174:177], v[190:193], v[32:35]
	v_mfma_f32_16x16x32_bf16 v[20:23], v[166:169], v[198:201], v[20:23]
	v_mfma_f32_16x16x32_bf16 v[16:19], v[174:177], v[198:201], v[16:19]
	v_mfma_f32_16x16x32_bf16 v[4:7], v[166:169], v[206:209], v[4:7]
	v_mfma_f32_16x16x32_bf16 v[0:3], v[174:177], v[206:209], v[0:3]
	v_mfma_f32_16x16x32_bf16 v[52:55], v[170:173], v[186:189], v[52:55]
	v_mfma_f32_16x16x32_bf16 v[48:51], v[178:181], v[186:189], v[48:51]
	v_mfma_f32_16x16x32_bf16 v[36:39], v[170:173], v[194:197], v[36:39]
	v_mfma_f32_16x16x32_bf16 v[32:35], v[178:181], v[194:197], v[32:35]
	v_mfma_f32_16x16x32_bf16 v[20:23], v[170:173], v[202:205], v[20:23]
	v_mfma_f32_16x16x32_bf16 v[16:19], v[178:181], v[202:205], v[16:19]
	v_mfma_f32_16x16x32_bf16 v[4:7], v[170:173], v[210:213], v[4:7]
	v_mfma_f32_16x16x32_bf16 v[0:3], v[178:181], v[210:213], v[0:3]
	s_setprio 0
	s_barrier
	s_add_i32 s57, 0, 0x18000
	v_add_u32_e32 v153, s57, v151
	s_add_i32 s58, 0, 0x1c000
	ds_read_b128 v[146:149], v153
	ds_read_b128 v[154:157], v153 offset:1024
	ds_read_b128 v[158:161], v153 offset:2048
	ds_read_b128 v[162:165], v153 offset:3072
	v_add_u32_e32 v153, s58, v151
	ds_read_b128 v[166:169], v153
	ds_read_b128 v[170:173], v153 offset:1024
	ds_read_b128 v[174:177], v153 offset:2048
	ds_read_b128 v[178:181], v153 offset:3072
	s_add_u32 s24, s24, 0xb0000
	s_addc_u32 s25, s25, 0
	s_mov_b32 m0, s43
	ds_read_b128 v[182:185], v152 offset:32768
	ds_read_b128 v[186:189], v152 offset:33792
	ds_read_b128 v[190:193], v152 offset:34816
	ds_read_b128 v[194:197], v152 offset:35840
	ds_read_b128 v[198:201], v152 offset:36864
	ds_read_b128 v[202:205], v152 offset:37888
	ds_read_b128 v[206:209], v152 offset:38912
	ds_read_b128 v[210:213], v152 offset:39936
	global_load_lds_dwordx4 v134, s[24:25]
	s_mov_b32 m0, s44
	s_nop 0
	global_load_lds_dwordx4 v136, s[24:25]
	s_waitcnt vmcnt(8)
	s_waitcnt lgkmcnt(0)
	s_barrier
	s_setprio 1
	s_waitcnt lgkmcnt(0)
	v_mfma_f32_16x16x32_bf16 v[124:127], v[146:149], v[182:185], v[124:127]
	v_mfma_f32_16x16x32_bf16 v[120:123], v[158:161], v[182:185], v[120:123]
	v_mfma_f32_16x16x32_bf16 v[108:111], v[146:149], v[190:193], v[108:111]
	v_mfma_f32_16x16x32_bf16 v[104:107], v[158:161], v[190:193], v[104:107]
	v_mfma_f32_16x16x32_bf16 v[92:95], v[146:149], v[198:201], v[92:95]
	v_mfma_f32_16x16x32_bf16 v[88:91], v[158:161], v[198:201], v[88:91]
	v_mfma_f32_16x16x32_bf16 v[76:79], v[146:149], v[206:209], v[76:79]
	v_mfma_f32_16x16x32_bf16 v[72:75], v[158:161], v[206:209], v[72:75]
	v_mfma_f32_16x16x32_bf16 v[124:127], v[154:157], v[186:189], v[124:127]
	v_mfma_f32_16x16x32_bf16 v[120:123], v[162:165], v[186:189], v[120:123]
	v_mfma_f32_16x16x32_bf16 v[108:111], v[154:157], v[194:197], v[108:111]
	v_mfma_f32_16x16x32_bf16 v[104:107], v[162:165], v[194:197], v[104:107]
	v_mfma_f32_16x16x32_bf16 v[92:95], v[154:157], v[202:205], v[92:95]
	v_mfma_f32_16x16x32_bf16 v[88:91], v[162:165], v[202:205], v[88:91]
	v_mfma_f32_16x16x32_bf16 v[76:79], v[154:157], v[210:213], v[76:79]
	v_mfma_f32_16x16x32_bf16 v[72:75], v[162:165], v[210:213], v[72:75]
	s_setprio 0
	s_setprio 1
	v_mfma_f32_16x16x32_bf16 v[116:119], v[166:169], v[182:185], v[116:119]
	v_mfma_f32_16x16x32_bf16 v[112:115], v[174:177], v[182:185], v[112:115]
	v_mfma_f32_16x16x32_bf16 v[100:103], v[166:169], v[190:193], v[100:103]
	v_mfma_f32_16x16x32_bf16 v[96:99], v[174:177], v[190:193], v[96:99]
	v_mfma_f32_16x16x32_bf16 v[84:87], v[166:169], v[198:201], v[84:87]
	v_mfma_f32_16x16x32_bf16 v[80:83], v[174:177], v[198:201], v[80:83]
	v_mfma_f32_16x16x32_bf16 v[68:71], v[166:169], v[206:209], v[68:71]
	v_mfma_f32_16x16x32_bf16 v[64:67], v[174:177], v[206:209], v[64:67]
	v_mfma_f32_16x16x32_bf16 v[116:119], v[170:173], v[186:189], v[116:119]
	v_mfma_f32_16x16x32_bf16 v[112:115], v[178:181], v[186:189], v[112:115]
	v_mfma_f32_16x16x32_bf16 v[100:103], v[170:173], v[194:197], v[100:103]
	v_mfma_f32_16x16x32_bf16 v[96:99], v[178:181], v[194:197], v[96:99]
	v_mfma_f32_16x16x32_bf16 v[84:87], v[170:173], v[202:205], v[84:87]
	v_mfma_f32_16x16x32_bf16 v[80:83], v[178:181], v[202:205], v[80:83]
	v_mfma_f32_16x16x32_bf16 v[68:71], v[170:173], v[210:213], v[68:71]
	v_mfma_f32_16x16x32_bf16 v[64:67], v[178:181], v[210:213], v[64:67]
	s_setprio 0
	s_barrier
	s_add_i32 s24, s57, s40
	v_lshl_add_u64 v[214:215], v[214:215], 0, s[6:7]
	s_mov_b32 m0, s24
	ds_read_b128 v[182:185], v152 offset:49152
	ds_read_b128 v[186:189], v152 offset:50176
	ds_read_b128 v[190:193], v152 offset:51200
	ds_read_b128 v[194:197], v152 offset:52224
	ds_read_b128 v[198:201], v152 offset:53248
	ds_read_b128 v[202:205], v152 offset:54272
	ds_read_b128 v[206:209], v152 offset:55296
	ds_read_b128 v[210:213], v152 offset:56320
	global_load_lds_dwordx4 v[214:215], off
	s_add_i32 m0, s24, 0x2000
	s_add_u32 s22, s22, 0xb0080
	v_lshl_add_u64 v[214:215], v[216:217], 0, s[6:7]
	s_addc_u32 s23, s23, 0
	s_add_i32 s24, s58, s40
	global_load_lds_dwordx4 v[214:215], off
	s_mov_b32 m0, s24
	s_nop 0
	global_load_lds_dwordx4 v128, s[22:23]
	s_add_i32 m0, s24, 0x2000
	s_nop 0
	global_load_lds_dwordx4 v138, s[22:23]
	v_lshl_add_u64 v[214:215], v[218:219], 0, s[6:7]
	s_mov_b32 m0, s45
	s_nop 0
	global_load_lds_dwordx4 v[214:215], off
	v_lshl_add_u64 v[214:215], v[220:221], 0, s[6:7]
	s_mov_b32 m0, s48
	s_nop 0
	global_load_lds_dwordx4 v[214:215], off
	s_waitcnt vmcnt(8)
	s_waitcnt lgkmcnt(0)
	s_barrier
	s_setprio 1
	s_waitcnt lgkmcnt(0)
	v_mfma_f32_16x16x32_bf16 v[60:63], v[146:149], v[182:185], v[60:63]
	v_mfma_f32_16x16x32_bf16 v[56:59], v[158:161], v[182:185], v[56:59]
	v_mfma_f32_16x16x32_bf16 v[44:47], v[146:149], v[190:193], v[44:47]
	v_mfma_f32_16x16x32_bf16 v[40:43], v[158:161], v[190:193], v[40:43]
	v_mfma_f32_16x16x32_bf16 v[28:31], v[146:149], v[198:201], v[28:31]
	v_mfma_f32_16x16x32_bf16 v[24:27], v[158:161], v[198:201], v[24:27]
	v_mfma_f32_16x16x32_bf16 v[12:15], v[146:149], v[206:209], v[12:15]
	v_mfma_f32_16x16x32_bf16 v[8:11], v[158:161], v[206:209], v[8:11]
	v_mfma_f32_16x16x32_bf16 v[60:63], v[154:157], v[186:189], v[60:63]
	v_mfma_f32_16x16x32_bf16 v[56:59], v[162:165], v[186:189], v[56:59]
	v_mfma_f32_16x16x32_bf16 v[44:47], v[154:157], v[194:197], v[44:47]
	v_mfma_f32_16x16x32_bf16 v[40:43], v[162:165], v[194:197], v[40:43]
	v_mfma_f32_16x16x32_bf16 v[28:31], v[154:157], v[202:205], v[28:31]
	v_mfma_f32_16x16x32_bf16 v[24:27], v[162:165], v[202:205], v[24:27]
	v_mfma_f32_16x16x32_bf16 v[12:15], v[154:157], v[210:213], v[12:15]
	v_mfma_f32_16x16x32_bf16 v[8:11], v[162:165], v[210:213], v[8:11]
	s_setprio 0
	s_setprio 1
	v_mfma_f32_16x16x32_bf16 v[52:55], v[166:169], v[182:185], v[52:55]
	v_mfma_f32_16x16x32_bf16 v[48:51], v[174:177], v[182:185], v[48:51]
	v_mfma_f32_16x16x32_bf16 v[36:39], v[166:169], v[190:193], v[36:39]
	v_mfma_f32_16x16x32_bf16 v[32:35], v[174:177], v[190:193], v[32:35]
	v_mfma_f32_16x16x32_bf16 v[20:23], v[166:169], v[198:201], v[20:23]
	v_mfma_f32_16x16x32_bf16 v[16:19], v[174:177], v[198:201], v[16:19]
	v_mfma_f32_16x16x32_bf16 v[4:7], v[166:169], v[206:209], v[4:7]
	v_mfma_f32_16x16x32_bf16 v[0:3], v[174:177], v[206:209], v[0:3]
	v_mfma_f32_16x16x32_bf16 v[52:55], v[170:173], v[186:189], v[52:55]
	v_mfma_f32_16x16x32_bf16 v[48:51], v[178:181], v[186:189], v[48:51]
	v_mfma_f32_16x16x32_bf16 v[36:39], v[170:173], v[194:197], v[36:39]
	v_mfma_f32_16x16x32_bf16 v[32:35], v[178:181], v[194:197], v[32:35]
	v_mfma_f32_16x16x32_bf16 v[20:23], v[170:173], v[202:205], v[20:23]
	v_mfma_f32_16x16x32_bf16 v[16:19], v[178:181], v[202:205], v[16:19]
	v_mfma_f32_16x16x32_bf16 v[4:7], v[170:173], v[210:213], v[4:7]
	v_mfma_f32_16x16x32_bf16 v[0:3], v[178:181], v[210:213], v[0:3]
	s_setprio 0
	s_barrier
	s_add_i32 s56, s56, 2
	s_add_u32 s20, s20, 0x100
	s_addc_u32 s21, s21, 0
	s_add_u32 s54, s54, 0x100
	s_addc_u32 s55, s55, 0
	s_cmp_gt_u32 s56, 41
	s_cbranch_scc0 .LBB0_3694
	s_and_b64 vcc, exec, s[16:17]
	s_cbranch_vccz .LBB0_3698
	s_barrier
	s_andn2_b64 vcc, exec, s[12:13]
	s_cbranch_vccz .LBB0_3699
